# v26 + GEMM K-loop: counter/pointer updates and exit compare issued in front of the iteration's last barrier (back-edge rotation)
# baseline (speedup 1.0000x reference)
; #define PG8_STAGE(bufoff, gbase, voff) do { _Pragma("unroll") for (int _i = 0; _i < 2; ++_i) \
;         __builtin_amdgcn_global_load_lds((const unsigned*)((const char*)(gbase) + (voff)[_i]), (PG8_LAS unsigned*)(lds + (bufoff) + ldsw + _i * 8192), 16, 0, 0); } while (0)
; #define PG8_LDA(dst, b, h) do { _Pragma("unroll") for (int m = 0; m < 4; ++m) _Pragma("unroll") for (int k = 0; k < 2; ++k) dst[m][k] = *(const PG8_LAS bf16x8*)(lds + PG8_SA(b, h) + aoff + m * 2048 + k * 1024); } while (0)
; #define PG8_LDB(dst, b, h) do { _Pragma("unroll") for (int n = 0; n < 2; ++n) _Pragma("unroll") for (int k = 0; k < 2; ++k) dst[n][k] = *(const PG8_LAS bf16x8*)(lds + PG8_SB(b, h) + boff + n * 2048 + k * 1024); } while (0)
; #define PG8_MMA(ai, bj, At, Bt) do { __builtin_amdgcn_s_setprio(1); _Pragma("unroll") for (int m = 0; m < 4; ++m) _Pragma("unroll") for (int n = 0; n < 2; ++n) _Pragma("unroll") for (int k = 0; k < 2; ++k) \
;         acc[ai][bj][m][n] = __builtin_amdgcn_mfma_f32_16x16x32_bf16(Bt[n][k], At[m][k], acc[ai][bj][m][n], 0, 0, 0); __builtin_amdgcn_s_setprio(0); } while (0)
; template <class Epi, class Sched, bool ALIGN_EPI = false, bool SP2 = false>
; __device__ __forceinline__ void gemm_phase(PG8_LAS unsigned char* lds, const Gemm g, const Sched& S, const Epi& E, const int tid) {
;     ...
;         const char* nA = has_next ? S.aptr(nxt) : cA; const char* nB = has_next ? S.bptr(nxt) : cB;
;         for (int t = 0; t < nt; t += 2) {
;             const bool last = (t == nt - 2);
;             const char* a1 = cA + (size_t)(t + 1) * kstep;
;             const char* a2 = last ? nA : cA + (size_t)(t + 2) * kstep; const char* b2 = last ? nB : cB + (size_t)(t + 2) * kstep;
;             const char* a3 = a2 + kstep; const char* b3 = b2 + kstep;
;             if (last && has_next) S.a_ready(nxt);
;             if constexpr (SP2) {
;             PG8_LDB(B0, 0, 0); PG8_LDB(B1, 0, 1); PG8_SCHED; PG8_LDA(At, 0, 0); PG8_STAGE(PG8_SA(1, 1), a1 + hstep, voffA);
;             PG8_WAIT_V(8); PG8_WAIT_L(0); PG8_BAR; PG8_MMA(0, 0, At, B0); PG8_MMA(0, 1, At, B1); PG8_BAR; PG8_SCHED;
;             PG8_LDA(At, 0, 1); PG8_STAGE(PG8_SB(0, 0), b2, voffB); PG8_STAGE(PG8_SB(0, 1), b2 + hstep, voffB); PG8_STAGE(PG8_SA(0, 0), a2, voffA);
;             PG8_WAIT_V(8); PG8_WAIT_L(0); PG8_BAR; PG8_MMA(1, 0, At, B0); PG8_MMA(1, 1, At, B1); PG8_BAR; PG8_SCHED;
.LBB0_338:
	s_ashr_i32 s29, s28, 31
	s_lshl_b64 s[18:19], s[28:29], 19
	s_add_u32 s30, s46, s18
	s_addc_u32 s31, s47, s19
	s_and_b64 s[18:19], s[2:3], exec
	s_cselect_b32 s29, s31, s41
	s_cselect_b32 s62, s30, s40
	s_ashr_i32 s27, s26, 31
	s_lshl_b64 s[18:19], s[26:27], 19
	s_add_u32 s34, s48, s18
	s_addc_u32 s35, s49, s19
	s_and_b64 s[18:19], s[2:3], exec
	s_cselect_b32 s27, s35, s39
	s_cselect_b32 s63, s34, s38
	s_add_u32 s64, s38, 0x100
	s_addc_u32 s65, s39, 0
	s_add_u32 s38, s40, 0x40080
	s_addc_u32 s39, s41, 0
	s_mov_b32 s66, -2
	s_add_u32 s15, s38, 0xfffc0080
	s_addc_u32 s18, s39, -1
	s_cmp_eq_u32 s66, 12
	s_cselect_b32 s43, s29, s18
	s_cselect_b32 s42, s62, s15
	s_cselect_b32 s41, s27, s65
	s_cselect_b32 s40, s63, s64
	v_lshl_add_u64 v[154:155], s[38:39], 0, v[144:145]
	s_add_i32 m0, s51, 0xc000
	global_load_lds_dwordx4 v[154:155], off
	v_lshl_add_u64 v[154:155], s[38:39], 0, v[142:143]
	s_add_i32 m0, s51, 0xe000
	s_nop 0
	global_load_lds_dwordx4 v[154:155], off
	s_waitcnt vmcnt(16)
	s_waitcnt lgkmcnt(0)
	s_barrier
	s_setprio 1
	s_waitcnt lgkmcnt(0)
	v_mfma_f32_16x16x32_bf16 v[126:129], v[150:153], v[204:207], 0
	v_mfma_f32_16x16x32_bf16 v[122:125], v[176:179], v[204:207], 0
	v_mfma_f32_16x16x32_bf16 v[110:113], v[150:153], v[212:215], 0
	v_mfma_f32_16x16x32_bf16 v[106:109], v[176:179], v[212:215], 0
	v_mfma_f32_16x16x32_bf16 v[94:97], v[150:153], v[220:223], 0
	v_mfma_f32_16x16x32_bf16 v[90:93], v[176:179], v[220:223], 0
	v_mfma_f32_16x16x32_bf16 v[78:81], v[150:153], v[228:231], 0
	v_mfma_f32_16x16x32_bf16 v[74:77], v[176:179], v[228:231], 0
	v_mfma_f32_16x16x32_bf16 v[126:129], v[172:175], v[208:211], v[126:129]
	v_mfma_f32_16x16x32_bf16 v[122:125], v[180:183], v[208:211], v[122:125]
	v_mfma_f32_16x16x32_bf16 v[110:113], v[172:175], v[216:219], v[110:113]
	v_mfma_f32_16x16x32_bf16 v[106:109], v[180:183], v[216:219], v[106:109]
	v_mfma_f32_16x16x32_bf16 v[94:97], v[172:175], v[224:227], v[94:97]
	v_mfma_f32_16x16x32_bf16 v[90:93], v[180:183], v[224:227], v[90:93]
	v_mfma_f32_16x16x32_bf16 v[78:81], v[172:175], v[232:235], v[78:81]
	v_mfma_f32_16x16x32_bf16 v[74:77], v[180:183], v[232:235], v[74:77]
	s_setprio 0
	s_setprio 1
	v_mfma_f32_16x16x32_bf16 v[118:121], v[184:187], v[204:207], 0
	v_mfma_f32_16x16x32_bf16 v[114:117], v[196:199], v[204:207], 0
	v_mfma_f32_16x16x32_bf16 v[102:105], v[184:187], v[212:215], 0
	v_mfma_f32_16x16x32_bf16 v[98:101], v[196:199], v[212:215], 0
	v_mfma_f32_16x16x32_bf16 v[86:89], v[184:187], v[220:223], 0
	v_mfma_f32_16x16x32_bf16 v[82:85], v[196:199], v[220:223], 0
	v_mfma_f32_16x16x32_bf16 v[70:73], v[184:187], v[228:231], 0
	v_mfma_f32_16x16x32_bf16 v[66:69], v[196:199], v[228:231], 0
	v_mfma_f32_16x16x32_bf16 v[118:121], v[192:195], v[208:211], v[118:121]
	v_mfma_f32_16x16x32_bf16 v[114:117], v[200:203], v[208:211], v[114:117]
	v_mfma_f32_16x16x32_bf16 v[102:105], v[192:195], v[216:219], v[102:105]
	v_mfma_f32_16x16x32_bf16 v[98:101], v[200:203], v[216:219], v[98:101]
	v_mfma_f32_16x16x32_bf16 v[86:89], v[192:195], v[224:227], v[86:89]
	v_mfma_f32_16x16x32_bf16 v[82:85], v[200:203], v[224:227], v[82:85]
	v_mfma_f32_16x16x32_bf16 v[70:73], v[192:195], v[232:235], v[70:73]
	v_mfma_f32_16x16x32_bf16 v[66:69], v[200:203], v[232:235], v[66:69]
	s_setprio 0
	s_barrier
	s_add_i32 s15, s58, s50
	v_lshl_add_u64 v[154:155], s[40:41], 0, v[132:133]
	s_mov_b32 m0, s15
	ds_read_b128 v[204:207], v167 offset:16384
	ds_read_b128 v[208:211], v167 offset:17408
	ds_read_b128 v[212:215], v167 offset:18432
	ds_read_b128 v[216:219], v167 offset:19456
	ds_read_b128 v[220:223], v167 offset:20480
	ds_read_b128 v[224:227], v167 offset:21504
	ds_read_b128 v[228:231], v167 offset:22528
	ds_read_b128 v[232:235], v167 offset:23552
	global_load_lds_dwordx4 v[154:155], off
	s_add_i32 m0, s15, 0x2000
	s_add_u32 s18, s40, 0x40000
	v_lshl_add_u64 v[158:159], s[40:41], 0, v[136:137]
	s_addc_u32 s19, s41, 0
	s_add_i32 s15, s59, s50
	global_load_lds_dwordx4 v[158:159], off
	v_lshl_add_u64 v[164:165], s[18:19], 0, v[132:133]
	s_mov_b32 m0, s15
	v_lshl_add_u64 v[168:169], s[42:43], 0, v[134:135]
	global_load_lds_dwordx4 v[164:165], off
	v_lshl_add_u64 v[164:165], s[18:19], 0, v[136:137]
	s_add_i32 m0, s15, 0x2000
	s_nop 0
	global_load_lds_dwordx4 v[164:165], off
	v_lshl_add_u64 v[164:165], s[42:43], 0, v[130:131]
	s_mov_b32 m0, s51
	s_nop 0
	global_load_lds_dwordx4 v[164:165], off
	s_mov_b32 m0, s52
	s_nop 0
	global_load_lds_dwordx4 v[168:169], off
	s_waitcnt vmcnt(8)
; #define PG8_STAGE(bufoff, gbase, voff) do { _Pragma("unroll") for (int _i = 0; _i < 2; ++_i) \
;         __builtin_amdgcn_global_load_lds((const unsigned*)((const char*)(gbase) + (voff)[_i]), (PG8_LAS unsigned*)(lds + (bufoff) + ldsw + _i * 8192), 16, 0, 0); } while (0)
; #define PG8_LDA(dst, b, h) do { _Pragma("unroll") for (int m = 0; m < 4; ++m) _Pragma("unroll") for (int k = 0; k < 2; ++k) dst[m][k] = *(const PG8_LAS bf16x8*)(lds + PG8_SA(b, h) + aoff + m * 2048 + k * 1024); } while (0)
; #define PG8_LDB(dst, b, h) do { _Pragma("unroll") for (int n = 0; n < 2; ++n) _Pragma("unroll") for (int k = 0; k < 2; ++k) dst[n][k] = *(const PG8_LAS bf16x8*)(lds + PG8_SB(b, h) + boff + n * 2048 + k * 1024); } while (0)
; #define PG8_MMA(ai, bj, At, Bt) do { __builtin_amdgcn_s_setprio(1); _Pragma("unroll") for (int m = 0; m < 4; ++m) _Pragma("unroll") for (int n = 0; n < 2; ++n) _Pragma("unroll") for (int k = 0; k < 2; ++k) \
;         acc[ai][bj][m][n] = __builtin_amdgcn_mfma_f32_16x16x32_bf16(Bt[n][k], At[m][k], acc[ai][bj][m][n], 0, 0, 0); __builtin_amdgcn_s_setprio(0); } while (0)
; #define PG8_WAIT_V(n) asm volatile("s_waitcnt vmcnt(" #n ")" ::: "memory")
; #define PG8_WAIT_L(n) asm volatile("s_waitcnt lgkmcnt(" #n ")" ::: "memory")
; #define PG8_BAR __builtin_amdgcn_s_barrier()
; #define PG8_SCHED __builtin_amdgcn_sched_barrier(0)
; template <class Epi, class Sched, bool ALIGN_EPI = false, bool SP2 = false>
; __device__ __forceinline__ void gemm_phase(PG8_LAS unsigned char* lds, const Gemm g, const Sched& S, const Epi& E, const int tid) {
;     ...
;             PG8_WAIT_V(8); PG8_WAIT_L(0); PG8_BAR; PG8_MMA(1, 0, At, B0); PG8_MMA(1, 1, At, B1); PG8_BAR; PG8_SCHED;
;             PG8_LDB(B0, 1, 0); PG8_LDB(B1, 1, 1); PG8_SCHED; PG8_LDA(At, 1, 0); PG8_STAGE(PG8_SA(0, 1), a2 + hstep, voffA);
;             PG8_WAIT_V(8); PG8_WAIT_L(0); PG8_BAR; PG8_MMA(0, 0, At, B0); PG8_MMA(0, 1, At, B1); PG8_BAR; PG8_SCHED;
; __device__ __forceinline__ void rstd8(const float* ssq, int row0, int fq, float (&rs)[8]) {
;     f32x4 pr[8];
; #pragma unroll
;     for (int i = 0; i < 8; ++i) pr[i] = *(const f32x4*)(ssq + (size_t)(row0 + (i >> 2) * 128 + (i & 3) * 16) * 16 + 4 * fq);
; #pragma unroll
;     for (int i = 0; i < 8; ++i) { float s = (pr[i][0] + pr[i][1]) + (pr[i][2] + pr[i][3]); s = xsum16(s); s = xsum32(s); rs[i] = __builtin_amdgcn_rsqf(s * (1.0f / DM) + NORM_EPS); }
; }
	v_add_f32_e32 v6, v6, v7
	v_add_f32_e32 v18, v18, v19
	v_add_f32_e32 v22, v22, v23
	v_add_f32_e32 v34, v34, v35
	v_add_f32_e32 v38, v38, v39
	v_add_f32_e32 v50, v50, v51
	v_add_f32_e32 v54, v54, v55
	v_add_f32_e32 v58, v58, v59
	v_add_f32_e32 v8, v8, v9
	v_add_f32_e32 v20, v20, v21
	v_add_f32_e32 v24, v24, v25
	v_add_f32_e32 v36, v36, v37
	v_add_f32_e32 v40, v40, v41
	v_add_f32_e32 v52, v52, v53
	v_add_f32_e32 v56, v56, v57
	v_add_f32_e32 v60, v60, v61
	v_add_f32_e32 v243, v6, v8
	v_add_f32_e32 v244, v18, v20
	v_add_f32_e32 v245, v22, v24
	v_add_f32_e32 v246, v34, v36
	v_add_f32_e32 v247, v38, v40
	v_add_f32_e32 v248, v50, v52
	v_add_f32_e32 v249, v54, v56
	v_add_f32_e32 v250, v58, v60
	v_mov_b32_e32 v6, v243
	v_mov_b32_e32 v18, v244
	v_mov_b32_e32 v22, v245
	v_mov_b32_e32 v34, v246
	v_mov_b32_e32 v38, v247
	v_mov_b32_e32 v50, v248
	v_mov_b32_e32 v54, v249
	v_mov_b32_e32 v58, v250
	v_permlane16_swap_b32_e32 v243, v6
	v_permlane16_swap_b32_e32 v244, v18
	v_permlane16_swap_b32_e32 v245, v22
	v_permlane16_swap_b32_e32 v246, v34
	v_permlane16_swap_b32_e32 v247, v38
	v_permlane16_swap_b32_e32 v248, v50
	v_permlane16_swap_b32_e32 v249, v54
	v_permlane16_swap_b32_e32 v250, v58
	v_add_f32_e32 v243, v243, v6
	v_add_f32_e32 v244, v244, v18
	v_add_f32_e32 v245, v245, v22
	v_add_f32_e32 v246, v246, v34
	v_add_f32_e32 v247, v247, v38
	v_add_f32_e32 v248, v248, v50
	v_add_f32_e32 v249, v249, v54
	v_add_f32_e32 v250, v250, v58
	v_mov_b32_e32 v6, v243
	v_mov_b32_e32 v18, v244
	v_mov_b32_e32 v22, v245
	v_mov_b32_e32 v34, v246
	v_mov_b32_e32 v38, v247
	v_mov_b32_e32 v50, v248
	v_mov_b32_e32 v54, v249
	v_mov_b32_e32 v58, v250
	v_permlane32_swap_b32_e32 v243, v6
	v_permlane32_swap_b32_e32 v244, v18
	v_permlane32_swap_b32_e32 v245, v22
	v_permlane32_swap_b32_e32 v246, v34
	v_permlane32_swap_b32_e32 v247, v38
	v_permlane32_swap_b32_e32 v248, v50
	v_permlane32_swap_b32_e32 v249, v54
	v_permlane32_swap_b32_e32 v250, v58
	v_add_f32_e32 v243, v243, v6
	v_add_f32_e32 v244, v244, v18
	v_add_f32_e32 v245, v245, v22
	v_add_f32_e32 v246, v246, v34
	v_add_f32_e32 v247, v247, v38
	v_add_f32_e32 v248, v248, v50
	v_add_f32_e32 v249, v249, v54
	v_add_f32_e32 v250, v250, v58
	v_fmamk_f32 v243, v243, 0x3a800000, v171
	v_fmamk_f32 v244, v244, 0x3a800000, v171
	v_fmamk_f32 v245, v245, 0x3a800000, v171
	v_fmamk_f32 v246, v246, 0x3a800000, v171
	v_fmamk_f32 v247, v247, 0x3a800000, v171
	v_fmamk_f32 v248, v248, 0x3a800000, v171
	v_fmamk_f32 v249, v249, 0x3a800000, v171
	v_fmamk_f32 v250, v250, 0x3a800000, v171
	v_rsq_f32_e32 v243, v243
	v_rsq_f32_e32 v244, v244
	v_rsq_f32_e32 v245, v245
	v_rsq_f32_e32 v246, v246
	v_rsq_f32_e32 v247, v247
	v_rsq_f32_e32 v248, v248
	v_rsq_f32_e32 v249, v249
	v_rsq_f32_e32 v250, v250
	s_waitcnt lgkmcnt(0)
	s_barrier
	s_setprio 1
	s_waitcnt lgkmcnt(0)
	v_mfma_f32_16x16x32_bf16 v[62:65], v[150:153], v[204:207], 0
	v_mfma_f32_16x16x32_bf16 v[58:61], v[176:179], v[204:207], 0
	v_mfma_f32_16x16x32_bf16 v[46:49], v[150:153], v[212:215], 0
	v_mfma_f32_16x16x32_bf16 v[42:45], v[176:179], v[212:215], 0
	v_mfma_f32_16x16x32_bf16 v[30:33], v[150:153], v[220:223], 0
	v_mfma_f32_16x16x32_bf16 v[26:29], v[176:179], v[220:223], 0
	v_mfma_f32_16x16x32_bf16 v[14:17], v[150:153], v[228:231], 0
	v_mfma_f32_16x16x32_bf16 v[10:13], v[176:179], v[228:231], 0
	v_mfma_f32_16x16x32_bf16 v[62:65], v[172:175], v[208:211], v[62:65]
	v_mfma_f32_16x16x32_bf16 v[58:61], v[180:183], v[208:211], v[58:61]
	v_mfma_f32_16x16x32_bf16 v[46:49], v[172:175], v[216:219], v[46:49]
	v_mfma_f32_16x16x32_bf16 v[42:45], v[180:183], v[216:219], v[42:45]
	v_mfma_f32_16x16x32_bf16 v[30:33], v[172:175], v[224:227], v[30:33]
	v_mfma_f32_16x16x32_bf16 v[26:29], v[180:183], v[224:227], v[26:29]
	v_mfma_f32_16x16x32_bf16 v[14:17], v[172:175], v[232:235], v[14:17]
	v_mfma_f32_16x16x32_bf16 v[10:13], v[180:183], v[232:235], v[10:13]
	s_setprio 0
	s_setprio 1
	v_mfma_f32_16x16x32_bf16 v[54:57], v[184:187], v[204:207], 0
	v_mfma_f32_16x16x32_bf16 v[50:53], v[196:199], v[204:207], 0
	v_mfma_f32_16x16x32_bf16 v[38:41], v[184:187], v[212:215], 0
	v_mfma_f32_16x16x32_bf16 v[34:37], v[196:199], v[212:215], 0
	v_mfma_f32_16x16x32_bf16 v[22:25], v[184:187], v[220:223], 0
	v_mfma_f32_16x16x32_bf16 v[18:21], v[196:199], v[220:223], 0
	v_mfma_f32_16x16x32_bf16 v[6:9], v[184:187], v[228:231], 0
	v_mfma_f32_16x16x32_bf16 v[2:5], v[196:199], v[228:231], 0
	v_mfma_f32_16x16x32_bf16 v[54:57], v[192:195], v[208:211], v[54:57]
	v_mfma_f32_16x16x32_bf16 v[50:53], v[200:203], v[208:211], v[50:53]
	v_mfma_f32_16x16x32_bf16 v[38:41], v[192:195], v[216:219], v[38:41]
	v_mfma_f32_16x16x32_bf16 v[34:37], v[200:203], v[216:219], v[34:37]
	v_mfma_f32_16x16x32_bf16 v[22:25], v[192:195], v[224:227], v[22:25]
	v_mfma_f32_16x16x32_bf16 v[18:21], v[200:203], v[224:227], v[18:21]
	v_mfma_f32_16x16x32_bf16 v[6:9], v[192:195], v[232:235], v[6:9]
	v_mfma_f32_16x16x32_bf16 v[2:5], v[200:203], v[232:235], v[2:5]
	s_setprio 0
	s_barrier
	s_add_i32 s15, 0, 0x18000
	v_add_u32_e32 v156, s15, v157
	s_add_i32 s67, 0, 0x1c000
	ds_read_b128 v[150:153], v156
	ds_read_b128 v[172:175], v156 offset:1024
	ds_read_b128 v[176:179], v156 offset:2048
	ds_read_b128 v[180:183], v156 offset:3072
	v_add_u32_e32 v156, s67, v157
	ds_read_b128 v[184:187], v156
	ds_read_b128 v[192:195], v156 offset:1024
	ds_read_b128 v[196:199], v156 offset:2048
	ds_read_b128 v[200:203], v156 offset:3072
	s_add_u32 s18, s42, 0x40000
	s_addc_u32 s19, s43, 0
	s_mov_b32 m0, s53
	v_lshl_add_u64 v[188:189], s[18:19], 0, v[130:131]
	ds_read_b128 v[204:207], v167 offset:32768
	ds_read_b128 v[208:211], v167 offset:33792
	ds_read_b128 v[212:215], v167 offset:34816
	ds_read_b128 v[216:219], v167 offset:35840
	ds_read_b128 v[220:223], v167 offset:36864
	ds_read_b128 v[224:227], v167 offset:37888
	ds_read_b128 v[228:231], v167 offset:38912
	ds_read_b128 v[232:235], v167 offset:39936
	global_load_lds_dwordx4 v[188:189], off
	v_lshl_add_u64 v[188:189], s[18:19], 0, v[134:135]
	s_mov_b32 m0, s54
	s_nop 0
	global_load_lds_dwordx4 v[188:189], off
	s_waitcnt vmcnt(8)
	s_waitcnt lgkmcnt(0)
	s_barrier
; #define PG8_STAGE(bufoff, gbase, voff) do { _Pragma("unroll") for (int _i = 0; _i < 2; ++_i) \
;         __builtin_amdgcn_global_load_lds((const unsigned*)((const char*)(gbase) + (voff)[_i]), (PG8_LAS unsigned*)(lds + (bufoff) + ldsw + _i * 8192), 16, 0, 0); } while (0)
; #define PG8_LDA(dst, b, h) do { _Pragma("unroll") for (int m = 0; m < 4; ++m) _Pragma("unroll") for (int k = 0; k < 2; ++k) dst[m][k] = *(const PG8_LAS bf16x8*)(lds + PG8_SA(b, h) + aoff + m * 2048 + k * 1024); } while (0)
; #define PG8_MMA(ai, bj, At, Bt) do { __builtin_amdgcn_s_setprio(1); _Pragma("unroll") for (int m = 0; m < 4; ++m) _Pragma("unroll") for (int n = 0; n < 2; ++n) _Pragma("unroll") for (int k = 0; k < 2; ++k) \
;         acc[ai][bj][m][n] = __builtin_amdgcn_mfma_f32_16x16x32_bf16(Bt[n][k], At[m][k], acc[ai][bj][m][n], 0, 0, 0); __builtin_amdgcn_s_setprio(0); } while (0)
; #define PG8_WAIT_V(n) asm volatile("s_waitcnt vmcnt(" #n ")" ::: "memory")
; #define PG8_WAIT_L(n) asm volatile("s_waitcnt lgkmcnt(" #n ")" ::: "memory")
; #define PG8_BAR __builtin_amdgcn_s_barrier()
; #define PG8_SCHED __builtin_amdgcn_sched_barrier(0)
; template <class Epi, class Sched, bool ALIGN_EPI = false, bool SP2 = false>
; __device__ __forceinline__ void gemm_phase(PG8_LAS unsigned char* lds, const Gemm g, const Sched& S, const Epi& E, const int tid) {
;     ...
;         for (int t = 0; t < nt; t += 2) {
;     ...
;             PG8_WAIT_V(8); PG8_WAIT_L(0); PG8_BAR; PG8_MMA(0, 0, At, B0); PG8_MMA(0, 1, At, B1); PG8_BAR; PG8_SCHED;
;             PG8_LDA(At, 1, 1); PG8_STAGE(PG8_SB(1, 0), b3, voffB); PG8_STAGE(PG8_SB(1, 1), b3 + hstep, voffB); PG8_STAGE(PG8_SA(1, 0), a3, voffA);
;             PG8_WAIT_V(8); PG8_WAIT_L(0); PG8_BAR; PG8_MMA(1, 0, At, B0); PG8_MMA(1, 1, At, B1); PG8_BAR; PG8_SCHED;
	s_setprio 1
	s_waitcnt lgkmcnt(0)
	v_mfma_f32_16x16x32_bf16 v[126:129], v[150:153], v[204:207], v[126:129]
	v_mfma_f32_16x16x32_bf16 v[122:125], v[176:179], v[204:207], v[122:125]
	v_mfma_f32_16x16x32_bf16 v[110:113], v[150:153], v[212:215], v[110:113]
	v_mfma_f32_16x16x32_bf16 v[106:109], v[176:179], v[212:215], v[106:109]
	v_mfma_f32_16x16x32_bf16 v[94:97], v[150:153], v[220:223], v[94:97]
	v_mfma_f32_16x16x32_bf16 v[90:93], v[176:179], v[220:223], v[90:93]
	v_mfma_f32_16x16x32_bf16 v[78:81], v[150:153], v[228:231], v[78:81]
	v_mfma_f32_16x16x32_bf16 v[74:77], v[176:179], v[228:231], v[74:77]
	v_mfma_f32_16x16x32_bf16 v[126:129], v[172:175], v[208:211], v[126:129]
	v_mfma_f32_16x16x32_bf16 v[122:125], v[180:183], v[208:211], v[122:125]
	v_mfma_f32_16x16x32_bf16 v[110:113], v[172:175], v[216:219], v[110:113]
	v_mfma_f32_16x16x32_bf16 v[106:109], v[180:183], v[216:219], v[106:109]
	v_mfma_f32_16x16x32_bf16 v[94:97], v[172:175], v[224:227], v[94:97]
	v_mfma_f32_16x16x32_bf16 v[90:93], v[180:183], v[224:227], v[90:93]
	v_mfma_f32_16x16x32_bf16 v[78:81], v[172:175], v[232:235], v[78:81]
	v_mfma_f32_16x16x32_bf16 v[74:77], v[180:183], v[232:235], v[74:77]
	s_setprio 0
	s_setprio 1
	v_mfma_f32_16x16x32_bf16 v[118:121], v[184:187], v[204:207], v[118:121]
	v_mfma_f32_16x16x32_bf16 v[114:117], v[196:199], v[204:207], v[114:117]
	v_mfma_f32_16x16x32_bf16 v[102:105], v[184:187], v[212:215], v[102:105]
	v_mfma_f32_16x16x32_bf16 v[98:101], v[196:199], v[212:215], v[98:101]
	v_mfma_f32_16x16x32_bf16 v[86:89], v[184:187], v[220:223], v[86:89]
	v_mfma_f32_16x16x32_bf16 v[82:85], v[196:199], v[220:223], v[82:85]
	v_mfma_f32_16x16x32_bf16 v[70:73], v[184:187], v[228:231], v[70:73]
	v_mfma_f32_16x16x32_bf16 v[66:69], v[196:199], v[228:231], v[66:69]
	v_mfma_f32_16x16x32_bf16 v[118:121], v[192:195], v[208:211], v[118:121]
	v_mfma_f32_16x16x32_bf16 v[114:117], v[200:203], v[208:211], v[114:117]
	v_mfma_f32_16x16x32_bf16 v[102:105], v[192:195], v[216:219], v[102:105]
	v_mfma_f32_16x16x32_bf16 v[98:101], v[200:203], v[216:219], v[98:101]
	v_mfma_f32_16x16x32_bf16 v[86:89], v[192:195], v[224:227], v[86:89]
	v_mfma_f32_16x16x32_bf16 v[82:85], v[200:203], v[224:227], v[82:85]
	v_mfma_f32_16x16x32_bf16 v[70:73], v[192:195], v[232:235], v[70:73]
	v_mfma_f32_16x16x32_bf16 v[66:69], v[200:203], v[232:235], v[66:69]
	s_setprio 0
	s_barrier
	s_add_i32 s15, s15, s50
	v_lshl_add_u64 v[154:155], v[154:155], 0, s[8:9]
	s_mov_b32 m0, s15
	ds_read_b128 v[204:207], v167 offset:49152
	ds_read_b128 v[208:211], v167 offset:50176
	ds_read_b128 v[212:215], v167 offset:51200
	ds_read_b128 v[216:219], v167 offset:52224
	ds_read_b128 v[220:223], v167 offset:53248
	ds_read_b128 v[224:227], v167 offset:54272
	ds_read_b128 v[228:231], v167 offset:55296
	ds_read_b128 v[232:235], v167 offset:56320
	global_load_lds_dwordx4 v[154:155], off
	s_add_i32 m0, s15, 0x2000
	s_add_u32 s18, s40, 0x40080
	v_lshl_add_u64 v[154:155], v[158:159], 0, s[8:9]
	s_addc_u32 s19, s41, 0
	s_add_i32 s15, s67, s50
	global_load_lds_dwordx4 v[154:155], off
	v_lshl_add_u64 v[154:155], s[18:19], 0, v[132:133]
	s_mov_b32 m0, s15
	s_nop 0
	global_load_lds_dwordx4 v[154:155], off
	v_lshl_add_u64 v[154:155], s[18:19], 0, v[136:137]
	s_add_i32 m0, s15, 0x2000
	s_nop 0
	global_load_lds_dwordx4 v[154:155], off
	v_lshl_add_u64 v[154:155], v[164:165], 0, s[8:9]
	s_mov_b32 m0, s55
	s_nop 0
	global_load_lds_dwordx4 v[154:155], off
	v_lshl_add_u64 v[154:155], v[168:169], 0, s[8:9]
	s_mov_b32 m0, s56
	s_nop 0
	global_load_lds_dwordx4 v[154:155], off
	s_waitcnt vmcnt(8)
	s_waitcnt lgkmcnt(0)
	s_barrier
	s_setprio 1
	s_waitcnt lgkmcnt(0)
	v_mfma_f32_16x16x32_bf16 v[62:65], v[150:153], v[204:207], v[62:65]
	v_mfma_f32_16x16x32_bf16 v[58:61], v[176:179], v[204:207], v[58:61]
	v_mfma_f32_16x16x32_bf16 v[46:49], v[150:153], v[212:215], v[46:49]
	v_mfma_f32_16x16x32_bf16 v[42:45], v[176:179], v[212:215], v[42:45]
	v_mfma_f32_16x16x32_bf16 v[30:33], v[150:153], v[220:223], v[30:33]
	v_mfma_f32_16x16x32_bf16 v[26:29], v[176:179], v[220:223], v[26:29]
	v_mfma_f32_16x16x32_bf16 v[14:17], v[150:153], v[228:231], v[14:17]
	v_mfma_f32_16x16x32_bf16 v[10:13], v[176:179], v[228:231], v[10:13]
	v_mfma_f32_16x16x32_bf16 v[62:65], v[172:175], v[208:211], v[62:65]
	v_mfma_f32_16x16x32_bf16 v[58:61], v[180:183], v[208:211], v[58:61]
	v_mfma_f32_16x16x32_bf16 v[46:49], v[172:175], v[216:219], v[46:49]
	v_mfma_f32_16x16x32_bf16 v[42:45], v[180:183], v[216:219], v[42:45]
	v_mfma_f32_16x16x32_bf16 v[30:33], v[172:175], v[224:227], v[30:33]
	v_mfma_f32_16x16x32_bf16 v[26:29], v[180:183], v[224:227], v[26:29]
	v_mfma_f32_16x16x32_bf16 v[14:17], v[172:175], v[232:235], v[14:17]
	v_mfma_f32_16x16x32_bf16 v[10:13], v[180:183], v[232:235], v[10:13]
	s_setprio 0
	s_setprio 1
	v_mfma_f32_16x16x32_bf16 v[54:57], v[184:187], v[204:207], v[54:57]
	v_mfma_f32_16x16x32_bf16 v[50:53], v[196:199], v[204:207], v[50:53]
	v_mfma_f32_16x16x32_bf16 v[38:41], v[184:187], v[212:215], v[38:41]
	v_mfma_f32_16x16x32_bf16 v[34:37], v[196:199], v[212:215], v[34:37]
	v_mfma_f32_16x16x32_bf16 v[22:25], v[184:187], v[220:223], v[22:25]
	v_mfma_f32_16x16x32_bf16 v[18:21], v[196:199], v[220:223], v[18:21]
	v_mfma_f32_16x16x32_bf16 v[6:9], v[184:187], v[228:231], v[6:9]
	v_mfma_f32_16x16x32_bf16 v[2:5], v[196:199], v[228:231], v[2:5]
	v_mfma_f32_16x16x32_bf16 v[54:57], v[192:195], v[208:211], v[54:57]
	v_mfma_f32_16x16x32_bf16 v[50:53], v[200:203], v[208:211], v[50:53]
	v_mfma_f32_16x16x32_bf16 v[38:41], v[192:195], v[216:219], v[38:41]
	v_mfma_f32_16x16x32_bf16 v[34:37], v[200:203], v[216:219], v[34:37]
	v_mfma_f32_16x16x32_bf16 v[22:25], v[192:195], v[224:227], v[22:25]
	v_mfma_f32_16x16x32_bf16 v[18:21], v[200:203], v[224:227], v[18:21]
	v_mfma_f32_16x16x32_bf16 v[6:9], v[192:195], v[232:235], v[6:9]
	v_mfma_f32_16x16x32_bf16 v[2:5], v[200:203], v[232:235], v[2:5]
	s_setprio 0
	s_add_i32 s66, s66, 2
	s_add_u32 s64, s64, 0x100
	s_addc_u32 s65, s65, 0
	s_add_u32 s38, s38, 0x100
	s_addc_u32 s39, s39, 0
	s_barrier
; #define PG8_STAGE(bufoff, gbase, voff) do { _Pragma("unroll") for (int _i = 0; _i < 2; ++_i) \
;         __builtin_amdgcn_global_load_lds((const unsigned*)((const char*)(gbase) + (voff)[_i]), (PG8_LAS unsigned*)(lds + (bufoff) + ldsw + _i * 8192), 16, 0, 0); } while (0)
; #define PG8_LDA(dst, b, h) do { _Pragma("unroll") for (int m = 0; m < 4; ++m) _Pragma("unroll") for (int k = 0; k < 2; ++k) dst[m][k] = *(const PG8_LAS bf16x8*)(lds + PG8_SA(b, h) + aoff + m * 2048 + k * 1024); } while (0)
; #define PG8_LDB(dst, b, h) do { _Pragma("unroll") for (int n = 0; n < 2; ++n) _Pragma("unroll") for (int k = 0; k < 2; ++k) dst[n][k] = *(const PG8_LAS bf16x8*)(lds + PG8_SB(b, h) + boff + n * 2048 + k * 1024); } while (0)
; #define PG8_MMA(ai, bj, At, Bt) do { __builtin_amdgcn_s_setprio(1); _Pragma("unroll") for (int m = 0; m < 4; ++m) _Pragma("unroll") for (int n = 0; n < 2; ++n) _Pragma("unroll") for (int k = 0; k < 2; ++k) \
;         acc[ai][bj][m][n] = __builtin_amdgcn_mfma_f32_16x16x32_bf16(Bt[n][k], At[m][k], acc[ai][bj][m][n], 0, 0, 0); __builtin_amdgcn_s_setprio(0); } while (0)
; #define PG8_WAIT_V(n) asm volatile("s_waitcnt vmcnt(" #n ")" ::: "memory")
; #define PG8_BAR __builtin_amdgcn_s_barrier()
; template <class Epi, class Sched, bool ALIGN_EPI = false, bool SP2 = false>
; __device__ __forceinline__ void gemm_phase(PG8_LAS unsigned char* lds, const Gemm g, const Sched& S, const Epi& E, const int tid) {
;     ...
;         for (int t = 0; t < nt; t += 2) {
;             const bool last = (t == nt - 2);
;             const char* a1 = cA + (size_t)(t + 1) * kstep;
;             const char* a2 = last ? nA : cA + (size_t)(t + 2) * kstep; const char* b2 = last ? nB : cB + (size_t)(t + 2) * kstep;
;             const char* a3 = a2 + kstep; const char* b3 = b2 + kstep;
;             if (last && has_next) S.a_ready(nxt);
;             if constexpr (SP2) {
;             PG8_LDB(B0, 0, 0); PG8_LDB(B1, 0, 1); PG8_SCHED; PG8_LDA(At, 0, 0); PG8_STAGE(PG8_SA(1, 1), a1 + hstep, voffA);
;             PG8_WAIT_V(8); PG8_WAIT_L(0); PG8_BAR; PG8_MMA(0, 0, At, B0); PG8_MMA(0, 1, At, B1); PG8_BAR; PG8_SCHED;
;             PG8_LDA(At, 0, 1); PG8_STAGE(PG8_SB(0, 0), b2, voffB); PG8_STAGE(PG8_SB(0, 1), b2 + hstep, voffB); PG8_STAGE(PG8_SA(0, 0), a2, voffA);
;             PG8_WAIT_V(8); PG8_WAIT_L(0); PG8_BAR; PG8_MMA(1, 0, At, B0); PG8_MMA(1, 1, At, B1); PG8_BAR; PG8_SCHED;
.LBB0_339:
	ds_read_b128 v[150:153], v161
	ds_read_b128 v[172:175], v161 offset:1024
	ds_read_b128 v[176:179], v161 offset:2048
	ds_read_b128 v[180:183], v161 offset:3072
	ds_read_b128 v[184:187], v163
	ds_read_b128 v[192:195], v163 offset:1024
	ds_read_b128 v[196:199], v163 offset:2048
	ds_read_b128 v[200:203], v163 offset:3072
	s_add_u32 s15, s38, 0xfffc0080
	s_addc_u32 s18, s39, -1
	s_cmp_eq_u32 s66, 12
	s_cselect_b32 s43, s29, s18
	s_cselect_b32 s42, s62, s15
	s_cselect_b32 s41, s27, s65
	s_cselect_b32 s40, s63, s64
	v_lshl_add_u64 v[154:155], s[38:39], 0, v[144:145]
	s_add_i32 m0, s51, 0xc000
	ds_read_b128 v[204:207], v167
	ds_read_b128 v[208:211], v167 offset:1024
	ds_read_b128 v[212:215], v167 offset:2048
	ds_read_b128 v[216:219], v167 offset:3072
	ds_read_b128 v[220:223], v167 offset:4096
	ds_read_b128 v[224:227], v167 offset:5120
	ds_read_b128 v[228:231], v167 offset:6144
	ds_read_b128 v[232:235], v167 offset:7168
	global_load_lds_dwordx4 v[154:155], off
	v_lshl_add_u64 v[154:155], s[38:39], 0, v[142:143]
	s_add_i32 m0, s51, 0xe000
	s_nop 0
	global_load_lds_dwordx4 v[154:155], off
	s_waitcnt vmcnt(8)
	s_waitcnt lgkmcnt(0)
	s_barrier
	s_setprio 1
	s_waitcnt lgkmcnt(0)
	v_mfma_f32_16x16x32_bf16 v[126:129], v[150:153], v[204:207], v[126:129]
	v_mfma_f32_16x16x32_bf16 v[122:125], v[176:179], v[204:207], v[122:125]
	v_mfma_f32_16x16x32_bf16 v[110:113], v[150:153], v[212:215], v[110:113]
	v_mfma_f32_16x16x32_bf16 v[106:109], v[176:179], v[212:215], v[106:109]
	v_mfma_f32_16x16x32_bf16 v[94:97], v[150:153], v[220:223], v[94:97]
	v_mfma_f32_16x16x32_bf16 v[90:93], v[176:179], v[220:223], v[90:93]
	v_mfma_f32_16x16x32_bf16 v[78:81], v[150:153], v[228:231], v[78:81]
	v_mfma_f32_16x16x32_bf16 v[74:77], v[176:179], v[228:231], v[74:77]
	v_mfma_f32_16x16x32_bf16 v[126:129], v[172:175], v[208:211], v[126:129]
	v_mfma_f32_16x16x32_bf16 v[122:125], v[180:183], v[208:211], v[122:125]
	v_mfma_f32_16x16x32_bf16 v[110:113], v[172:175], v[216:219], v[110:113]
	v_mfma_f32_16x16x32_bf16 v[106:109], v[180:183], v[216:219], v[106:109]
	v_mfma_f32_16x16x32_bf16 v[94:97], v[172:175], v[224:227], v[94:97]
	v_mfma_f32_16x16x32_bf16 v[90:93], v[180:183], v[224:227], v[90:93]
	v_mfma_f32_16x16x32_bf16 v[78:81], v[172:175], v[232:235], v[78:81]
	v_mfma_f32_16x16x32_bf16 v[74:77], v[180:183], v[232:235], v[74:77]
	s_setprio 0
	s_setprio 1
	v_mfma_f32_16x16x32_bf16 v[118:121], v[184:187], v[204:207], v[118:121]
	v_mfma_f32_16x16x32_bf16 v[114:117], v[196:199], v[204:207], v[114:117]
	v_mfma_f32_16x16x32_bf16 v[102:105], v[184:187], v[212:215], v[102:105]
	v_mfma_f32_16x16x32_bf16 v[98:101], v[196:199], v[212:215], v[98:101]
	v_mfma_f32_16x16x32_bf16 v[86:89], v[184:187], v[220:223], v[86:89]
	v_mfma_f32_16x16x32_bf16 v[82:85], v[196:199], v[220:223], v[82:85]
	v_mfma_f32_16x16x32_bf16 v[70:73], v[184:187], v[228:231], v[70:73]
	v_mfma_f32_16x16x32_bf16 v[66:69], v[196:199], v[228:231], v[66:69]
	v_mfma_f32_16x16x32_bf16 v[118:121], v[192:195], v[208:211], v[118:121]
	v_mfma_f32_16x16x32_bf16 v[114:117], v[200:203], v[208:211], v[114:117]
	v_mfma_f32_16x16x32_bf16 v[102:105], v[192:195], v[216:219], v[102:105]
	v_mfma_f32_16x16x32_bf16 v[98:101], v[200:203], v[216:219], v[98:101]
	v_mfma_f32_16x16x32_bf16 v[86:89], v[192:195], v[224:227], v[86:89]
	v_mfma_f32_16x16x32_bf16 v[82:85], v[200:203], v[224:227], v[82:85]
	v_mfma_f32_16x16x32_bf16 v[70:73], v[192:195], v[232:235], v[70:73]
	v_mfma_f32_16x16x32_bf16 v[66:69], v[200:203], v[232:235], v[66:69]
	s_setprio 0
	s_barrier
	s_add_i32 s15, s58, s50
	v_lshl_add_u64 v[154:155], s[40:41], 0, v[132:133]
	s_mov_b32 m0, s15
	ds_read_b128 v[204:207], v167 offset:16384
	ds_read_b128 v[208:211], v167 offset:17408
	ds_read_b128 v[212:215], v167 offset:18432
	ds_read_b128 v[216:219], v167 offset:19456
	ds_read_b128 v[220:223], v167 offset:20480
	ds_read_b128 v[224:227], v167 offset:21504
	ds_read_b128 v[228:231], v167 offset:22528
	ds_read_b128 v[232:235], v167 offset:23552
	global_load_lds_dwordx4 v[154:155], off
	s_add_i32 m0, s15, 0x2000
	s_add_u32 s18, s40, 0x40000
	v_lshl_add_u64 v[158:159], s[40:41], 0, v[136:137]
	s_addc_u32 s19, s41, 0
	s_add_i32 s15, s59, s50
	global_load_lds_dwordx4 v[158:159], off
	v_lshl_add_u64 v[164:165], s[18:19], 0, v[132:133]
	s_mov_b32 m0, s15
	v_lshl_add_u64 v[168:169], s[42:43], 0, v[134:135]
	global_load_lds_dwordx4 v[164:165], off
	v_lshl_add_u64 v[164:165], s[18:19], 0, v[136:137]
	s_add_i32 m0, s15, 0x2000
	s_nop 0
	global_load_lds_dwordx4 v[164:165], off
	v_lshl_add_u64 v[164:165], s[42:43], 0, v[130:131]
	s_mov_b32 m0, s51
	s_nop 0
	global_load_lds_dwordx4 v[164:165], off
	s_mov_b32 m0, s52
	s_nop 0
	global_load_lds_dwordx4 v[168:169], off
	s_waitcnt vmcnt(8)
	s_waitcnt lgkmcnt(0)
	s_barrier
; #define PG8_STAGE(bufoff, gbase, voff) do { _Pragma("unroll") for (int _i = 0; _i < 2; ++_i) \
;         __builtin_amdgcn_global_load_lds((const unsigned*)((const char*)(gbase) + (voff)[_i]), (PG8_LAS unsigned*)(lds + (bufoff) + ldsw + _i * 8192), 16, 0, 0); } while (0)
; #define PG8_LDA(dst, b, h) do { _Pragma("unroll") for (int m = 0; m < 4; ++m) _Pragma("unroll") for (int k = 0; k < 2; ++k) dst[m][k] = *(const PG8_LAS bf16x8*)(lds + PG8_SA(b, h) + aoff + m * 2048 + k * 1024); } while (0)
; #define PG8_LDB(dst, b, h) do { _Pragma("unroll") for (int n = 0; n < 2; ++n) _Pragma("unroll") for (int k = 0; k < 2; ++k) dst[n][k] = *(const PG8_LAS bf16x8*)(lds + PG8_SB(b, h) + boff + n * 2048 + k * 1024); } while (0)
; #define PG8_MMA(ai, bj, At, Bt) do { __builtin_amdgcn_s_setprio(1); _Pragma("unroll") for (int m = 0; m < 4; ++m) _Pragma("unroll") for (int n = 0; n < 2; ++n) _Pragma("unroll") for (int k = 0; k < 2; ++k) \
;         acc[ai][bj][m][n] = __builtin_amdgcn_mfma_f32_16x16x32_bf16(Bt[n][k], At[m][k], acc[ai][bj][m][n], 0, 0, 0); __builtin_amdgcn_s_setprio(0); } while (0)
; #define PG8_WAIT_V(n) asm volatile("s_waitcnt vmcnt(" #n ")" ::: "memory")
; #define PG8_WAIT_L(n) asm volatile("s_waitcnt lgkmcnt(" #n ")" ::: "memory")
; #define PG8_BAR __builtin_amdgcn_s_barrier()
; #define PG8_SCHED __builtin_amdgcn_sched_barrier(0)
; template <class Epi, class Sched, bool ALIGN_EPI = false, bool SP2 = false>
; __device__ __forceinline__ void gemm_phase(PG8_LAS unsigned char* lds, const Gemm g, const Sched& S, const Epi& E, const int tid) {
;     ...
;             PG8_WAIT_V(8); PG8_WAIT_L(0); PG8_BAR; PG8_MMA(1, 0, At, B0); PG8_MMA(1, 1, At, B1); PG8_BAR; PG8_SCHED;
;             PG8_LDB(B0, 1, 0); PG8_LDB(B1, 1, 1); PG8_SCHED; PG8_LDA(At, 1, 0); PG8_STAGE(PG8_SA(0, 1), a2 + hstep, voffA);
;             PG8_WAIT_V(8); PG8_WAIT_L(0); PG8_BAR; PG8_MMA(0, 0, At, B0); PG8_MMA(0, 1, At, B1); PG8_BAR; PG8_SCHED;
	s_setprio 1
	s_waitcnt lgkmcnt(0)
	v_mfma_f32_16x16x32_bf16 v[62:65], v[150:153], v[204:207], v[62:65]
	v_mfma_f32_16x16x32_bf16 v[58:61], v[176:179], v[204:207], v[58:61]
	v_mfma_f32_16x16x32_bf16 v[46:49], v[150:153], v[212:215], v[46:49]
	v_mfma_f32_16x16x32_bf16 v[42:45], v[176:179], v[212:215], v[42:45]
	v_mfma_f32_16x16x32_bf16 v[30:33], v[150:153], v[220:223], v[30:33]
	v_mfma_f32_16x16x32_bf16 v[26:29], v[176:179], v[220:223], v[26:29]
	v_mfma_f32_16x16x32_bf16 v[14:17], v[150:153], v[228:231], v[14:17]
	v_mfma_f32_16x16x32_bf16 v[10:13], v[176:179], v[228:231], v[10:13]
	v_mfma_f32_16x16x32_bf16 v[62:65], v[172:175], v[208:211], v[62:65]
	v_mfma_f32_16x16x32_bf16 v[58:61], v[180:183], v[208:211], v[58:61]
	v_mfma_f32_16x16x32_bf16 v[46:49], v[172:175], v[216:219], v[46:49]
	v_mfma_f32_16x16x32_bf16 v[42:45], v[180:183], v[216:219], v[42:45]
	v_mfma_f32_16x16x32_bf16 v[30:33], v[172:175], v[224:227], v[30:33]
	v_mfma_f32_16x16x32_bf16 v[26:29], v[180:183], v[224:227], v[26:29]
	v_mfma_f32_16x16x32_bf16 v[14:17], v[172:175], v[232:235], v[14:17]
	v_mfma_f32_16x16x32_bf16 v[10:13], v[180:183], v[232:235], v[10:13]
	s_setprio 0
	s_setprio 1
	v_mfma_f32_16x16x32_bf16 v[54:57], v[184:187], v[204:207], v[54:57]
	v_mfma_f32_16x16x32_bf16 v[50:53], v[196:199], v[204:207], v[50:53]
	v_mfma_f32_16x16x32_bf16 v[38:41], v[184:187], v[212:215], v[38:41]
	v_mfma_f32_16x16x32_bf16 v[34:37], v[196:199], v[212:215], v[34:37]
	v_mfma_f32_16x16x32_bf16 v[22:25], v[184:187], v[220:223], v[22:25]
	v_mfma_f32_16x16x32_bf16 v[18:21], v[196:199], v[220:223], v[18:21]
	v_mfma_f32_16x16x32_bf16 v[6:9], v[184:187], v[228:231], v[6:9]
	v_mfma_f32_16x16x32_bf16 v[2:5], v[196:199], v[228:231], v[2:5]
	v_mfma_f32_16x16x32_bf16 v[54:57], v[192:195], v[208:211], v[54:57]
	v_mfma_f32_16x16x32_bf16 v[50:53], v[200:203], v[208:211], v[50:53]
	v_mfma_f32_16x16x32_bf16 v[38:41], v[192:195], v[216:219], v[38:41]
	v_mfma_f32_16x16x32_bf16 v[34:37], v[200:203], v[216:219], v[34:37]
	v_mfma_f32_16x16x32_bf16 v[22:25], v[192:195], v[224:227], v[22:25]
	v_mfma_f32_16x16x32_bf16 v[18:21], v[200:203], v[224:227], v[18:21]
	v_mfma_f32_16x16x32_bf16 v[6:9], v[192:195], v[232:235], v[6:9]
	v_mfma_f32_16x16x32_bf16 v[2:5], v[200:203], v[232:235], v[2:5]
	s_setprio 0
	s_barrier
	s_add_i32 s15, 0, 0x18000
	v_add_u32_e32 v156, s15, v157
	s_add_i32 s67, 0, 0x1c000
	ds_read_b128 v[150:153], v156
	ds_read_b128 v[172:175], v156 offset:1024
	ds_read_b128 v[176:179], v156 offset:2048
	ds_read_b128 v[180:183], v156 offset:3072
	v_add_u32_e32 v156, s67, v157
	ds_read_b128 v[184:187], v156
	ds_read_b128 v[192:195], v156 offset:1024
	ds_read_b128 v[196:199], v156 offset:2048
	ds_read_b128 v[200:203], v156 offset:3072
	s_add_u32 s18, s42, 0x40000
	s_addc_u32 s19, s43, 0
	s_mov_b32 m0, s53
	v_lshl_add_u64 v[188:189], s[18:19], 0, v[130:131]
	ds_read_b128 v[204:207], v167 offset:32768
	ds_read_b128 v[208:211], v167 offset:33792
	ds_read_b128 v[212:215], v167 offset:34816
	ds_read_b128 v[216:219], v167 offset:35840
	ds_read_b128 v[220:223], v167 offset:36864
	ds_read_b128 v[224:227], v167 offset:37888
	ds_read_b128 v[228:231], v167 offset:38912
	ds_read_b128 v[232:235], v167 offset:39936
	global_load_lds_dwordx4 v[188:189], off
	v_lshl_add_u64 v[188:189], s[18:19], 0, v[134:135]
	s_mov_b32 m0, s54
	s_nop 0
	global_load_lds_dwordx4 v[188:189], off
	s_waitcnt vmcnt(8)
	s_waitcnt lgkmcnt(0)
	s_barrier
	s_setprio 1
	s_waitcnt lgkmcnt(0)
	v_mfma_f32_16x16x32_bf16 v[126:129], v[150:153], v[204:207], v[126:129]
	v_mfma_f32_16x16x32_bf16 v[122:125], v[176:179], v[204:207], v[122:125]
	v_mfma_f32_16x16x32_bf16 v[110:113], v[150:153], v[212:215], v[110:113]
	v_mfma_f32_16x16x32_bf16 v[106:109], v[176:179], v[212:215], v[106:109]
	v_mfma_f32_16x16x32_bf16 v[94:97], v[150:153], v[220:223], v[94:97]
	v_mfma_f32_16x16x32_bf16 v[90:93], v[176:179], v[220:223], v[90:93]
	v_mfma_f32_16x16x32_bf16 v[78:81], v[150:153], v[228:231], v[78:81]
	v_mfma_f32_16x16x32_bf16 v[74:77], v[176:179], v[228:231], v[74:77]
	v_mfma_f32_16x16x32_bf16 v[126:129], v[172:175], v[208:211], v[126:129]
	v_mfma_f32_16x16x32_bf16 v[122:125], v[180:183], v[208:211], v[122:125]
	v_mfma_f32_16x16x32_bf16 v[110:113], v[172:175], v[216:219], v[110:113]
	v_mfma_f32_16x16x32_bf16 v[106:109], v[180:183], v[216:219], v[106:109]
	v_mfma_f32_16x16x32_bf16 v[94:97], v[172:175], v[224:227], v[94:97]
	v_mfma_f32_16x16x32_bf16 v[90:93], v[180:183], v[224:227], v[90:93]
	v_mfma_f32_16x16x32_bf16 v[78:81], v[172:175], v[232:235], v[78:81]
	v_mfma_f32_16x16x32_bf16 v[74:77], v[180:183], v[232:235], v[74:77]
	s_setprio 0
	s_setprio 1
	v_mfma_f32_16x16x32_bf16 v[118:121], v[184:187], v[204:207], v[118:121]
	v_mfma_f32_16x16x32_bf16 v[114:117], v[196:199], v[204:207], v[114:117]
	v_mfma_f32_16x16x32_bf16 v[102:105], v[184:187], v[212:215], v[102:105]
	v_mfma_f32_16x16x32_bf16 v[98:101], v[196:199], v[212:215], v[98:101]
	v_mfma_f32_16x16x32_bf16 v[86:89], v[184:187], v[220:223], v[86:89]
	v_mfma_f32_16x16x32_bf16 v[82:85], v[196:199], v[220:223], v[82:85]
	v_mfma_f32_16x16x32_bf16 v[70:73], v[184:187], v[228:231], v[70:73]
	v_mfma_f32_16x16x32_bf16 v[66:69], v[196:199], v[228:231], v[66:69]
	v_mfma_f32_16x16x32_bf16 v[118:121], v[192:195], v[208:211], v[118:121]
	v_mfma_f32_16x16x32_bf16 v[114:117], v[200:203], v[208:211], v[114:117]
	v_mfma_f32_16x16x32_bf16 v[102:105], v[192:195], v[216:219], v[102:105]
	v_mfma_f32_16x16x32_bf16 v[98:101], v[200:203], v[216:219], v[98:101]
	v_mfma_f32_16x16x32_bf16 v[86:89], v[192:195], v[224:227], v[86:89]
	v_mfma_f32_16x16x32_bf16 v[82:85], v[200:203], v[224:227], v[82:85]
	v_mfma_f32_16x16x32_bf16 v[70:73], v[192:195], v[232:235], v[70:73]
	v_mfma_f32_16x16x32_bf16 v[66:69], v[200:203], v[232:235], v[66:69]
	s_setprio 0
	s_barrier
; #define PG8_STAGE(bufoff, gbase, voff) do { _Pragma("unroll") for (int _i = 0; _i < 2; ++_i) \
;         __builtin_amdgcn_global_load_lds((const unsigned*)((const char*)(gbase) + (voff)[_i]), (PG8_LAS unsigned*)(lds + (bufoff) + ldsw + _i * 8192), 16, 0, 0); } while (0)
; #define PG8_LDA(dst, b, h) do { _Pragma("unroll") for (int m = 0; m < 4; ++m) _Pragma("unroll") for (int k = 0; k < 2; ++k) dst[m][k] = *(const PG8_LAS bf16x8*)(lds + PG8_SA(b, h) + aoff + m * 2048 + k * 1024); } while (0)
; #define PG8_MMA(ai, bj, At, Bt) do { __builtin_amdgcn_s_setprio(1); _Pragma("unroll") for (int m = 0; m < 4; ++m) _Pragma("unroll") for (int n = 0; n < 2; ++n) _Pragma("unroll") for (int k = 0; k < 2; ++k) \
;         acc[ai][bj][m][n] = __builtin_amdgcn_mfma_f32_16x16x32_bf16(Bt[n][k], At[m][k], acc[ai][bj][m][n], 0, 0, 0); __builtin_amdgcn_s_setprio(0); } while (0)
; #define PG8_WAIT_V(n) asm volatile("s_waitcnt vmcnt(" #n ")" ::: "memory")
; #define PG8_WAIT_L(n) asm volatile("s_waitcnt lgkmcnt(" #n ")" ::: "memory")
; #define PG8_BAR __builtin_amdgcn_s_barrier()
; #define PG8_SCHED __builtin_amdgcn_sched_barrier(0)
; template <class Epi, class Sched, bool ALIGN_EPI = false, bool SP2 = false>
; __device__ __forceinline__ void gemm_phase(PG8_LAS unsigned char* lds, const Gemm g, const Sched& S, const Epi& E, const int tid) {
;     ...
;             PG8_LDA(At, 1, 1); PG8_STAGE(PG8_SB(1, 0), b3, voffB); PG8_STAGE(PG8_SB(1, 1), b3 + hstep, voffB); PG8_STAGE(PG8_SA(1, 0), a3, voffA);
;             PG8_WAIT_V(8); PG8_WAIT_L(0); PG8_BAR; PG8_MMA(1, 0, At, B0); PG8_MMA(1, 1, At, B1); PG8_BAR; PG8_SCHED;
;     ...
;         if constexpr (ALIGN_EPI) { if (wr == 0) PG8_BAR; }
	s_add_i32 s15, s15, s50
	v_lshl_add_u64 v[154:155], v[154:155], 0, s[8:9]
	s_mov_b32 m0, s15
	ds_read_b128 v[204:207], v167 offset:49152
	ds_read_b128 v[208:211], v167 offset:50176
	ds_read_b128 v[212:215], v167 offset:51200
	ds_read_b128 v[216:219], v167 offset:52224
	ds_read_b128 v[220:223], v167 offset:53248
	ds_read_b128 v[224:227], v167 offset:54272
	ds_read_b128 v[228:231], v167 offset:55296
	ds_read_b128 v[232:235], v167 offset:56320
	global_load_lds_dwordx4 v[154:155], off
	s_add_i32 m0, s15, 0x2000
	s_add_u32 s18, s40, 0x40080
	v_lshl_add_u64 v[154:155], v[158:159], 0, s[8:9]
	s_addc_u32 s19, s41, 0
	s_add_i32 s15, s67, s50
	global_load_lds_dwordx4 v[154:155], off
	v_lshl_add_u64 v[154:155], s[18:19], 0, v[132:133]
	s_mov_b32 m0, s15
	s_nop 0
	global_load_lds_dwordx4 v[154:155], off
	v_lshl_add_u64 v[154:155], s[18:19], 0, v[136:137]
	s_add_i32 m0, s15, 0x2000
	s_nop 0
	global_load_lds_dwordx4 v[154:155], off
	v_lshl_add_u64 v[154:155], v[164:165], 0, s[8:9]
	s_mov_b32 m0, s55
	s_nop 0
	global_load_lds_dwordx4 v[154:155], off
	v_lshl_add_u64 v[154:155], v[168:169], 0, s[8:9]
	s_mov_b32 m0, s56
	s_nop 0
	global_load_lds_dwordx4 v[154:155], off
	s_waitcnt vmcnt(8)
	s_waitcnt lgkmcnt(0)
	s_barrier
	s_setprio 1
	s_waitcnt lgkmcnt(0)
	v_mfma_f32_16x16x32_bf16 v[62:65], v[150:153], v[204:207], v[62:65]
	v_mfma_f32_16x16x32_bf16 v[58:61], v[176:179], v[204:207], v[58:61]
	v_mfma_f32_16x16x32_bf16 v[46:49], v[150:153], v[212:215], v[46:49]
	v_mfma_f32_16x16x32_bf16 v[42:45], v[176:179], v[212:215], v[42:45]
	v_mfma_f32_16x16x32_bf16 v[30:33], v[150:153], v[220:223], v[30:33]
	v_mfma_f32_16x16x32_bf16 v[26:29], v[176:179], v[220:223], v[26:29]
	v_mfma_f32_16x16x32_bf16 v[14:17], v[150:153], v[228:231], v[14:17]
	v_mfma_f32_16x16x32_bf16 v[10:13], v[176:179], v[228:231], v[10:13]
	v_mfma_f32_16x16x32_bf16 v[62:65], v[172:175], v[208:211], v[62:65]
	v_mfma_f32_16x16x32_bf16 v[58:61], v[180:183], v[208:211], v[58:61]
	v_mfma_f32_16x16x32_bf16 v[46:49], v[172:175], v[216:219], v[46:49]
	v_mfma_f32_16x16x32_bf16 v[42:45], v[180:183], v[216:219], v[42:45]
	v_mfma_f32_16x16x32_bf16 v[30:33], v[172:175], v[224:227], v[30:33]
	v_mfma_f32_16x16x32_bf16 v[26:29], v[180:183], v[224:227], v[26:29]
	v_mfma_f32_16x16x32_bf16 v[14:17], v[172:175], v[232:235], v[14:17]
	v_mfma_f32_16x16x32_bf16 v[10:13], v[180:183], v[232:235], v[10:13]
	s_setprio 0
	s_setprio 1
	v_mfma_f32_16x16x32_bf16 v[54:57], v[184:187], v[204:207], v[54:57]
	v_mfma_f32_16x16x32_bf16 v[50:53], v[196:199], v[204:207], v[50:53]
	v_mfma_f32_16x16x32_bf16 v[38:41], v[184:187], v[212:215], v[38:41]
	v_mfma_f32_16x16x32_bf16 v[34:37], v[196:199], v[212:215], v[34:37]
	v_mfma_f32_16x16x32_bf16 v[22:25], v[184:187], v[220:223], v[22:25]
	v_mfma_f32_16x16x32_bf16 v[18:21], v[196:199], v[220:223], v[18:21]
	v_mfma_f32_16x16x32_bf16 v[6:9], v[184:187], v[228:231], v[6:9]
	v_mfma_f32_16x16x32_bf16 v[2:5], v[196:199], v[228:231], v[2:5]
	v_mfma_f32_16x16x32_bf16 v[54:57], v[192:195], v[208:211], v[54:57]
	v_mfma_f32_16x16x32_bf16 v[50:53], v[200:203], v[208:211], v[50:53]
	v_mfma_f32_16x16x32_bf16 v[38:41], v[192:195], v[216:219], v[38:41]
	v_mfma_f32_16x16x32_bf16 v[34:37], v[200:203], v[216:219], v[34:37]
	v_mfma_f32_16x16x32_bf16 v[22:25], v[192:195], v[224:227], v[22:25]
	v_mfma_f32_16x16x32_bf16 v[18:21], v[200:203], v[224:227], v[18:21]
	v_mfma_f32_16x16x32_bf16 v[6:9], v[192:195], v[232:235], v[6:9]
	v_mfma_f32_16x16x32_bf16 v[2:5], v[200:203], v[232:235], v[2:5]
	s_setprio 0
	s_add_i32 s66, s66, 2
	s_add_u32 s64, s64, 0x100
	s_addc_u32 s65, s65, 0
	s_add_u32 s38, s38, 0x100
	s_addc_u32 s39, s39, 0
	s_cmp_gt_u32 s66, 13
	s_barrier
	s_cbranch_scc0 .LBB0_339
	s_and_b64 vcc, exec, s[10:11]
	s_cbranch_vccz .LBB0_342
	s_barrier

; #define PG8_STAGE(bufoff, gbase, voff) do { _Pragma("unroll") for (int _i = 0; _i < 2; ++_i) \
;         __builtin_amdgcn_global_load_lds((const unsigned*)((const char*)(gbase) + (voff)[_i]), (PG8_LAS unsigned*)(lds + (bufoff) + ldsw + _i * 8192), 16, 0, 0); } while (0)
; #define PG8_LDA(dst, b, h) do { _Pragma("unroll") for (int m = 0; m < 4; ++m) _Pragma("unroll") for (int k = 0; k < 2; ++k) dst[m][k] = *(const PG8_LAS bf16x8*)(lds + PG8_SA(b, h) + aoff + m * 2048 + k * 1024); } while (0)
; #define PG8_LDB(dst, b, h) do { _Pragma("unroll") for (int n = 0; n < 2; ++n) _Pragma("unroll") for (int k = 0; k < 2; ++k) dst[n][k] = *(const PG8_LAS bf16x8*)(lds + PG8_SB(b, h) + boff + n * 2048 + k * 1024); } while (0)
; #define PG8_MMA(ai, bj, At, Bt) do { __builtin_amdgcn_s_setprio(1); _Pragma("unroll") for (int m = 0; m < 4; ++m) _Pragma("unroll") for (int n = 0; n < 2; ++n) _Pragma("unroll") for (int k = 0; k < 2; ++k) \
;         acc[ai][bj][m][n] = __builtin_amdgcn_mfma_f32_16x16x32_bf16(Bt[n][k], At[m][k], acc[ai][bj][m][n], 0, 0, 0); __builtin_amdgcn_s_setprio(0); } while (0)
; #define PG8_WAIT_V(n) asm volatile("s_waitcnt vmcnt(" #n ")" ::: "memory")
; #define PG8_WAIT_L(n) asm volatile("s_waitcnt lgkmcnt(" #n ")" ::: "memory")
; #define PG8_BAR __builtin_amdgcn_s_barrier()
; template <class Epi, class Sched, bool ALIGN_EPI = false, bool SP2 = false>
; __device__ __forceinline__ void gemm_phase(PG8_LAS unsigned char* lds, const Gemm g, const Sched& S, const Epi& E, const int tid) {
;     ...
;             const char* a1 = cA + (size_t)(t + 1) * kstep;
;             const char* a2 = last ? nA : cA + (size_t)(t + 2) * kstep; const char* b2 = last ? nB : cB + (size_t)(t + 2) * kstep;
;             const char* a3 = a2 + kstep; const char* b3 = b2 + kstep;
;             if (last && has_next) S.a_ready(nxt);
;             if constexpr (SP2) {
;             PG8_LDB(B0, 0, 0); PG8_LDB(B1, 0, 1); PG8_SCHED; PG8_LDA(At, 0, 0); PG8_STAGE(PG8_SA(1, 1), a1 + hstep, voffA);
;             PG8_WAIT_V(8); PG8_WAIT_L(0); PG8_BAR; PG8_MMA(0, 0, At, B0); PG8_MMA(0, 1, At, B1); PG8_BAR; PG8_SCHED;
;             PG8_LDA(At, 0, 1); PG8_STAGE(PG8_SB(0, 0), b2, voffB); PG8_STAGE(PG8_SB(0, 1), b2 + hstep, voffB); PG8_STAGE(PG8_SA(0, 0), a2, voffA);
;             PG8_WAIT_V(8); PG8_WAIT_L(0); PG8_BAR; PG8_MMA(1, 0, At, B0); PG8_MMA(1, 1, At, B1); PG8_BAR; PG8_SCHED;
.LBB0_422:
	s_add_u32 s45, s8, 0x100
	s_addc_u32 s47, s9, 0
	s_mov_b32 s77, -2
	s_add_u32 s8, s6, 0x100
	s_addc_u32 s9, s7, 0
	s_cmp_eq_u32 s77, 40
	s_cselect_b32 s43, s1, s9
	s_cselect_b32 s42, s0, s8
	s_cselect_b32 s11, s41, s47
	s_cselect_b32 s10, s40, s45
	v_lshl_add_u64 v[220:221], s[6:7], 0, v[176:177]
	s_add_i32 m0, s56, 0xc000
	global_load_lds_dwordx4 v[220:221], off
	v_lshl_add_u64 v[220:221], s[6:7], 0, v[174:175]
	s_add_i32 m0, s56, 0xe000
	s_nop 0
	global_load_lds_dwordx4 v[220:221], off
	s_waitcnt vmcnt(8)
	s_waitcnt lgkmcnt(0)
	s_barrier
	s_setprio 1
	s_waitcnt lgkmcnt(0)
	v_mfma_f32_16x16x32_bf16 v[126:129], v[130:133], v[182:185], 0
	v_mfma_f32_16x16x32_bf16 v[122:125], v[138:141], v[182:185], 0
	v_mfma_f32_16x16x32_bf16 v[110:113], v[130:133], v[192:195], 0
	v_mfma_f32_16x16x32_bf16 v[106:109], v[138:141], v[192:195], 0
	v_mfma_f32_16x16x32_bf16 v[94:97], v[130:133], v[200:203], 0
	v_mfma_f32_16x16x32_bf16 v[90:93], v[138:141], v[200:203], 0
	v_mfma_f32_16x16x32_bf16 v[78:81], v[130:133], v[212:215], 0
	v_mfma_f32_16x16x32_bf16 v[74:77], v[138:141], v[212:215], 0
	v_mfma_f32_16x16x32_bf16 v[126:129], v[134:137], v[186:189], v[126:129]
	v_mfma_f32_16x16x32_bf16 v[122:125], v[142:145], v[186:189], v[122:125]
	v_mfma_f32_16x16x32_bf16 v[110:113], v[134:137], v[196:199], v[110:113]
	v_mfma_f32_16x16x32_bf16 v[106:109], v[142:145], v[196:199], v[106:109]
	v_mfma_f32_16x16x32_bf16 v[94:97], v[134:137], v[208:211], v[94:97]
	v_mfma_f32_16x16x32_bf16 v[90:93], v[142:145], v[208:211], v[90:93]
	v_mfma_f32_16x16x32_bf16 v[78:81], v[134:137], v[216:219], v[78:81]
	v_mfma_f32_16x16x32_bf16 v[74:77], v[142:145], v[216:219], v[74:77]
	s_setprio 0
	s_setprio 1
	v_mfma_f32_16x16x32_bf16 v[118:121], v[146:149], v[182:185], 0
	v_mfma_f32_16x16x32_bf16 v[114:117], v[154:157], v[182:185], 0
	v_mfma_f32_16x16x32_bf16 v[102:105], v[146:149], v[192:195], 0
	v_mfma_f32_16x16x32_bf16 v[98:101], v[154:157], v[192:195], 0
	v_mfma_f32_16x16x32_bf16 v[86:89], v[146:149], v[200:203], 0
	v_mfma_f32_16x16x32_bf16 v[82:85], v[154:157], v[200:203], 0
	v_mfma_f32_16x16x32_bf16 v[70:73], v[146:149], v[212:215], 0
	v_mfma_f32_16x16x32_bf16 v[66:69], v[154:157], v[212:215], 0
	v_mfma_f32_16x16x32_bf16 v[118:121], v[150:153], v[186:189], v[118:121]
	v_mfma_f32_16x16x32_bf16 v[114:117], v[158:161], v[186:189], v[114:117]
	v_mfma_f32_16x16x32_bf16 v[102:105], v[150:153], v[196:199], v[102:105]
	v_mfma_f32_16x16x32_bf16 v[98:101], v[158:161], v[196:199], v[98:101]
	v_mfma_f32_16x16x32_bf16 v[86:89], v[150:153], v[208:211], v[86:89]
	v_mfma_f32_16x16x32_bf16 v[82:85], v[158:161], v[208:211], v[82:85]
	v_mfma_f32_16x16x32_bf16 v[70:73], v[150:153], v[216:219], v[70:73]
	v_mfma_f32_16x16x32_bf16 v[66:69], v[158:161], v[216:219], v[66:69]
	s_setprio 0
	s_barrier
	s_add_i32 s6, s66, s55
	v_lshl_add_u64 v[220:221], s[10:11], 0, v[164:165]
	s_mov_b32 m0, s6
	ds_read_b128 v[182:185], v207 offset:16384
	ds_read_b128 v[186:189], v207 offset:17408
	ds_read_b128 v[192:195], v207 offset:18432
	ds_read_b128 v[196:199], v207 offset:19456
	ds_read_b128 v[200:203], v207 offset:20480
	ds_read_b128 v[208:211], v207 offset:21504
	ds_read_b128 v[212:215], v207 offset:22528
	ds_read_b128 v[216:219], v207 offset:23552
	global_load_lds_dwordx4 v[220:221], off
	s_add_i32 m0, s6, 0x2000
	s_add_u32 s6, s10, 0xb0000
	v_lshl_add_u64 v[222:223], s[10:11], 0, v[168:169]
	s_addc_u32 s7, s11, 0
	s_add_i32 s15, s67, s55
	global_load_lds_dwordx4 v[222:223], off
	v_lshl_add_u64 v[224:225], s[6:7], 0, v[164:165]
	s_mov_b32 m0, s15
	v_lshl_add_u64 v[226:227], s[42:43], 0, v[166:167]
	global_load_lds_dwordx4 v[224:225], off
	v_lshl_add_u64 v[224:225], s[6:7], 0, v[168:169]
	s_add_i32 m0, s15, 0x2000
	s_nop 0
	global_load_lds_dwordx4 v[224:225], off
	v_lshl_add_u64 v[224:225], s[42:43], 0, v[162:163]
	s_mov_b32 m0, s56
	s_nop 0
	global_load_lds_dwordx4 v[224:225], off
	s_mov_b32 m0, s57
	s_nop 0
	global_load_lds_dwordx4 v[226:227], off
	s_waitcnt vmcnt(8)
	s_waitcnt lgkmcnt(0)
	s_barrier
	s_setprio 1
	s_waitcnt lgkmcnt(0)
	v_mfma_f32_16x16x32_bf16 v[62:65], v[130:133], v[182:185], 0
	v_mfma_f32_16x16x32_bf16 v[58:61], v[138:141], v[182:185], 0
	v_mfma_f32_16x16x32_bf16 v[46:49], v[130:133], v[192:195], 0
	v_mfma_f32_16x16x32_bf16 v[42:45], v[138:141], v[192:195], 0
	v_mfma_f32_16x16x32_bf16 v[30:33], v[130:133], v[200:203], 0
	v_mfma_f32_16x16x32_bf16 v[26:29], v[138:141], v[200:203], 0
	v_mfma_f32_16x16x32_bf16 v[14:17], v[130:133], v[212:215], 0
	v_mfma_f32_16x16x32_bf16 v[10:13], v[138:141], v[212:215], 0
	v_mfma_f32_16x16x32_bf16 v[62:65], v[134:137], v[186:189], v[62:65]
	v_mfma_f32_16x16x32_bf16 v[58:61], v[142:145], v[186:189], v[58:61]
	v_mfma_f32_16x16x32_bf16 v[46:49], v[134:137], v[196:199], v[46:49]
	v_mfma_f32_16x16x32_bf16 v[42:45], v[142:145], v[196:199], v[42:45]
	v_mfma_f32_16x16x32_bf16 v[30:33], v[134:137], v[208:211], v[30:33]
	v_mfma_f32_16x16x32_bf16 v[26:29], v[142:145], v[208:211], v[26:29]
	v_mfma_f32_16x16x32_bf16 v[14:17], v[134:137], v[216:219], v[14:17]
	v_mfma_f32_16x16x32_bf16 v[10:13], v[142:145], v[216:219], v[10:13]
	s_setprio 0
	s_setprio 1
	v_mfma_f32_16x16x32_bf16 v[54:57], v[146:149], v[182:185], 0
	v_mfma_f32_16x16x32_bf16 v[50:53], v[154:157], v[182:185], 0
	v_mfma_f32_16x16x32_bf16 v[38:41], v[146:149], v[192:195], 0
	v_mfma_f32_16x16x32_bf16 v[34:37], v[154:157], v[192:195], 0
	v_mfma_f32_16x16x32_bf16 v[22:25], v[146:149], v[200:203], 0
	v_mfma_f32_16x16x32_bf16 v[18:21], v[154:157], v[200:203], 0
	v_mfma_f32_16x16x32_bf16 v[6:9], v[146:149], v[212:215], 0
	v_mfma_f32_16x16x32_bf16 v[2:5], v[154:157], v[212:215], 0
	v_mfma_f32_16x16x32_bf16 v[54:57], v[150:153], v[186:189], v[54:57]
	v_mfma_f32_16x16x32_bf16 v[50:53], v[158:161], v[186:189], v[50:53]
	v_mfma_f32_16x16x32_bf16 v[38:41], v[150:153], v[196:199], v[38:41]
	v_mfma_f32_16x16x32_bf16 v[34:37], v[158:161], v[196:199], v[34:37]
	v_mfma_f32_16x16x32_bf16 v[22:25], v[150:153], v[208:211], v[22:25]
	v_mfma_f32_16x16x32_bf16 v[18:21], v[158:161], v[208:211], v[18:21]
	v_mfma_f32_16x16x32_bf16 v[6:9], v[150:153], v[216:219], v[6:9]
	v_mfma_f32_16x16x32_bf16 v[2:5], v[158:161], v[216:219], v[2:5]
	s_setprio 0
	s_barrier
; #define PG8_STAGE(bufoff, gbase, voff) do { _Pragma("unroll") for (int _i = 0; _i < 2; ++_i) \
;         __builtin_amdgcn_global_load_lds((const unsigned*)((const char*)(gbase) + (voff)[_i]), (PG8_LAS unsigned*)(lds + (bufoff) + ldsw + _i * 8192), 16, 0, 0); } while (0)
; #define PG8_LDA(dst, b, h) do { _Pragma("unroll") for (int m = 0; m < 4; ++m) _Pragma("unroll") for (int k = 0; k < 2; ++k) dst[m][k] = *(const PG8_LAS bf16x8*)(lds + PG8_SA(b, h) + aoff + m * 2048 + k * 1024); } while (0)
; #define PG8_LDB(dst, b, h) do { _Pragma("unroll") for (int n = 0; n < 2; ++n) _Pragma("unroll") for (int k = 0; k < 2; ++k) dst[n][k] = *(const PG8_LAS bf16x8*)(lds + PG8_SB(b, h) + boff + n * 2048 + k * 1024); } while (0)
; #define PG8_MMA(ai, bj, At, Bt) do { __builtin_amdgcn_s_setprio(1); _Pragma("unroll") for (int m = 0; m < 4; ++m) _Pragma("unroll") for (int n = 0; n < 2; ++n) _Pragma("unroll") for (int k = 0; k < 2; ++k) \
;         acc[ai][bj][m][n] = __builtin_amdgcn_mfma_f32_16x16x32_bf16(Bt[n][k], At[m][k], acc[ai][bj][m][n], 0, 0, 0); __builtin_amdgcn_s_setprio(0); } while (0)
; #define PG8_WAIT_V(n) asm volatile("s_waitcnt vmcnt(" #n ")" ::: "memory")
; #define PG8_WAIT_L(n) asm volatile("s_waitcnt lgkmcnt(" #n ")" ::: "memory")
; #define PG8_BAR __builtin_amdgcn_s_barrier()
; #define PG8_SCHED __builtin_amdgcn_sched_barrier(0)
; template <class Epi, class Sched, bool ALIGN_EPI = false, bool SP2 = false>
; __device__ __forceinline__ void gemm_phase(PG8_LAS unsigned char* lds, const Gemm g, const Sched& S, const Epi& E, const int tid) {
;     ...
;             PG8_WAIT_V(8); PG8_WAIT_L(0); PG8_BAR; PG8_MMA(1, 0, At, B0); PG8_MMA(1, 1, At, B1); PG8_BAR; PG8_SCHED;
;             PG8_LDB(B0, 1, 0); PG8_LDB(B1, 1, 1); PG8_SCHED; PG8_LDA(At, 1, 0); PG8_STAGE(PG8_SA(0, 1), a2 + hstep, voffA);
;             PG8_WAIT_V(8); PG8_WAIT_L(0); PG8_BAR; PG8_MMA(0, 0, At, B0); PG8_MMA(0, 1, At, B1); PG8_BAR; PG8_SCHED;
;             PG8_LDA(At, 1, 1); PG8_STAGE(PG8_SB(1, 0), b3, voffB); PG8_STAGE(PG8_SB(1, 1), b3 + hstep, voffB); PG8_STAGE(PG8_SA(1, 0), a3, voffA);
	s_add_i32 s15, 0, 0x18000
	s_add_i32 s18, 0, 0x1c000
	v_add_u32_e32 v142, s15, v204
	v_add_u32_e32 v158, s18, v204
	ds_read_b128 v[130:133], v142
	ds_read_b128 v[134:137], v142 offset:1024
	ds_read_b128 v[138:141], v142 offset:2048
	ds_read_b128 v[142:145], v142 offset:3072
	ds_read_b128 v[146:149], v158
	ds_read_b128 v[150:153], v158 offset:1024
	ds_read_b128 v[154:157], v158 offset:2048
	ds_read_b128 v[158:161], v158 offset:3072
	s_add_u32 s6, s42, 0xb0000
	s_addc_u32 s7, s43, 0
	s_mov_b32 m0, s58
	v_lshl_add_u64 v[228:229], s[6:7], 0, v[162:163]
	ds_read_b128 v[182:185], v207 offset:32768
	ds_read_b128 v[186:189], v207 offset:33792
	ds_read_b128 v[192:195], v207 offset:34816
	ds_read_b128 v[196:199], v207 offset:35840
	ds_read_b128 v[200:203], v207 offset:36864
	ds_read_b128 v[208:211], v207 offset:37888
	ds_read_b128 v[212:215], v207 offset:38912
	ds_read_b128 v[216:219], v207 offset:39936
	global_load_lds_dwordx4 v[228:229], off
	v_lshl_add_u64 v[228:229], s[6:7], 0, v[166:167]
	s_mov_b32 m0, s59
	s_nop 0
	global_load_lds_dwordx4 v[228:229], off
	s_waitcnt vmcnt(8)
	s_waitcnt lgkmcnt(0)
	s_barrier
	s_setprio 1
	s_waitcnt lgkmcnt(0)
	v_mfma_f32_16x16x32_bf16 v[126:129], v[130:133], v[182:185], v[126:129]
	v_mfma_f32_16x16x32_bf16 v[122:125], v[138:141], v[182:185], v[122:125]
	v_mfma_f32_16x16x32_bf16 v[110:113], v[130:133], v[192:195], v[110:113]
	v_mfma_f32_16x16x32_bf16 v[106:109], v[138:141], v[192:195], v[106:109]
	v_mfma_f32_16x16x32_bf16 v[94:97], v[130:133], v[200:203], v[94:97]
	v_mfma_f32_16x16x32_bf16 v[90:93], v[138:141], v[200:203], v[90:93]
	v_mfma_f32_16x16x32_bf16 v[78:81], v[130:133], v[212:215], v[78:81]
	v_mfma_f32_16x16x32_bf16 v[74:77], v[138:141], v[212:215], v[74:77]
	v_mfma_f32_16x16x32_bf16 v[126:129], v[134:137], v[186:189], v[126:129]
	v_mfma_f32_16x16x32_bf16 v[122:125], v[142:145], v[186:189], v[122:125]
	v_mfma_f32_16x16x32_bf16 v[110:113], v[134:137], v[196:199], v[110:113]
	v_mfma_f32_16x16x32_bf16 v[106:109], v[142:145], v[196:199], v[106:109]
	v_mfma_f32_16x16x32_bf16 v[94:97], v[134:137], v[208:211], v[94:97]
	v_mfma_f32_16x16x32_bf16 v[90:93], v[142:145], v[208:211], v[90:93]
	v_mfma_f32_16x16x32_bf16 v[78:81], v[134:137], v[216:219], v[78:81]
	v_mfma_f32_16x16x32_bf16 v[74:77], v[142:145], v[216:219], v[74:77]
	s_setprio 0
	s_setprio 1
	v_mfma_f32_16x16x32_bf16 v[118:121], v[146:149], v[182:185], v[118:121]
	v_mfma_f32_16x16x32_bf16 v[114:117], v[154:157], v[182:185], v[114:117]
	v_mfma_f32_16x16x32_bf16 v[102:105], v[146:149], v[192:195], v[102:105]
	v_mfma_f32_16x16x32_bf16 v[98:101], v[154:157], v[192:195], v[98:101]
	v_mfma_f32_16x16x32_bf16 v[86:89], v[146:149], v[200:203], v[86:89]
	v_mfma_f32_16x16x32_bf16 v[82:85], v[154:157], v[200:203], v[82:85]
	v_mfma_f32_16x16x32_bf16 v[70:73], v[146:149], v[212:215], v[70:73]
	v_mfma_f32_16x16x32_bf16 v[66:69], v[154:157], v[212:215], v[66:69]
	v_mfma_f32_16x16x32_bf16 v[118:121], v[150:153], v[186:189], v[118:121]
	v_mfma_f32_16x16x32_bf16 v[114:117], v[158:161], v[186:189], v[114:117]
	v_mfma_f32_16x16x32_bf16 v[102:105], v[150:153], v[196:199], v[102:105]
	v_mfma_f32_16x16x32_bf16 v[98:101], v[158:161], v[196:199], v[98:101]
	v_mfma_f32_16x16x32_bf16 v[86:89], v[150:153], v[208:211], v[86:89]
	v_mfma_f32_16x16x32_bf16 v[82:85], v[158:161], v[208:211], v[82:85]
	v_mfma_f32_16x16x32_bf16 v[70:73], v[150:153], v[216:219], v[70:73]
	v_mfma_f32_16x16x32_bf16 v[66:69], v[158:161], v[216:219], v[66:69]
	s_setprio 0
	s_barrier
	s_add_i32 s6, s15, s55
	v_lshl_add_u64 v[220:221], v[220:221], 0, s[36:37]
	s_mov_b32 m0, s6
	ds_read_b128 v[182:185], v207 offset:49152
	ds_read_b128 v[186:189], v207 offset:50176
	ds_read_b128 v[192:195], v207 offset:51200
	ds_read_b128 v[196:199], v207 offset:52224
	ds_read_b128 v[200:203], v207 offset:53248
	ds_read_b128 v[208:211], v207 offset:54272
	ds_read_b128 v[212:215], v207 offset:55296
	ds_read_b128 v[216:219], v207 offset:56320
	global_load_lds_dwordx4 v[220:221], off
	s_add_i32 m0, s6, 0x2000
	s_add_u32 s6, s10, 0xb0080
	v_lshl_add_u64 v[220:221], v[222:223], 0, s[36:37]
	s_addc_u32 s7, s11, 0
	s_add_i32 s10, s18, s55
	global_load_lds_dwordx4 v[220:221], off
	v_lshl_add_u64 v[220:221], s[6:7], 0, v[164:165]
	s_mov_b32 m0, s10
	s_nop 0
	global_load_lds_dwordx4 v[220:221], off
	v_lshl_add_u64 v[220:221], s[6:7], 0, v[168:169]
	s_add_i32 m0, s10, 0x2000
	s_nop 0
	global_load_lds_dwordx4 v[220:221], off
	v_lshl_add_u64 v[220:221], v[224:225], 0, s[36:37]
	s_mov_b32 m0, s61
	s_nop 0
	global_load_lds_dwordx4 v[220:221], off
	v_lshl_add_u64 v[220:221], v[226:227], 0, s[36:37]
	s_mov_b32 m0, s62
	s_nop 0
	global_load_lds_dwordx4 v[220:221], off
	s_waitcnt vmcnt(8)
	s_waitcnt lgkmcnt(0)
	s_barrier
; #define PG8_STAGE(bufoff, gbase, voff) do { _Pragma("unroll") for (int _i = 0; _i < 2; ++_i) \
;         __builtin_amdgcn_global_load_lds((const unsigned*)((const char*)(gbase) + (voff)[_i]), (PG8_LAS unsigned*)(lds + (bufoff) + ldsw + _i * 8192), 16, 0, 0); } while (0)
; #define PG8_LDA(dst, b, h) do { _Pragma("unroll") for (int m = 0; m < 4; ++m) _Pragma("unroll") for (int k = 0; k < 2; ++k) dst[m][k] = *(const PG8_LAS bf16x8*)(lds + PG8_SA(b, h) + aoff + m * 2048 + k * 1024); } while (0)
; #define PG8_WAIT_V(n) asm volatile("s_waitcnt vmcnt(" #n ")" ::: "memory")
; #define PG8_WAIT_L(n) asm volatile("s_waitcnt lgkmcnt(" #n ")" ::: "memory")
; #define PG8_BAR __builtin_amdgcn_s_barrier()
; template <class Epi, class Sched, bool ALIGN_EPI = false, bool SP2 = false>
; __device__ __forceinline__ void gemm_phase(PG8_LAS unsigned char* lds, const Gemm g, const Sched& S, const Epi& E, const int tid) {
;     ...
;         for (int t = 0; t < nt; t += 2) {
;             const bool last = (t == nt - 2);
;             const char* a1 = cA + (size_t)(t + 1) * kstep;
;             const char* a2 = last ? nA : cA + (size_t)(t + 2) * kstep; const char* b2 = last ? nB : cB + (size_t)(t + 2) * kstep;
;             const char* a3 = a2 + kstep; const char* b3 = b2 + kstep;
;             if (last && has_next) S.a_ready(nxt);
;             if constexpr (SP2) {
;             PG8_LDB(B0, 0, 0); PG8_LDB(B1, 0, 1); PG8_SCHED; PG8_LDA(At, 0, 0); PG8_STAGE(PG8_SA(1, 1), a1 + hstep, voffA);
;             PG8_WAIT_V(8); PG8_WAIT_L(0); PG8_BAR; PG8_MMA(0, 0, At, B0); PG8_MMA(0, 1, At, B1); PG8_BAR; PG8_SCHED;
;             PG8_LDA(At, 0, 1); PG8_STAGE(PG8_SB(0, 0), b2, voffB); PG8_STAGE(PG8_SB(0, 1), b2 + hstep, voffB); PG8_STAGE(PG8_SA(0, 0), a2, voffA);
;             PG8_WAIT_V(8); PG8_WAIT_L(0); PG8_BAR; PG8_MMA(1, 0, At, B0); PG8_MMA(1, 1, At, B1); PG8_BAR; PG8_SCHED;
;             PG8_LDB(B0, 1, 0); PG8_LDB(B1, 1, 1); PG8_SCHED; PG8_LDA(At, 1, 0); PG8_STAGE(PG8_SA(0, 1), a2 + hstep, voffA);
;             PG8_WAIT_V(8); PG8_WAIT_L(0); PG8_BAR; PG8_MMA(0, 0, At, B0); PG8_MMA(0, 1, At, B1); PG8_BAR; PG8_SCHED;
;             PG8_LDA(At, 1, 1); PG8_STAGE(PG8_SB(1, 0), b3, voffB); PG8_STAGE(PG8_SB(1, 1), b3 + hstep, voffB); PG8_STAGE(PG8_SA(1, 0), a3, voffA);
;             PG8_WAIT_V(8); PG8_WAIT_L(0); PG8_BAR; PG8_MMA(1, 0, At, B0); PG8_MMA(1, 1, At, B1); PG8_BAR; PG8_SCHED;
	s_setprio 1
	s_waitcnt lgkmcnt(0)
	v_mfma_f32_16x16x32_bf16 v[62:65], v[130:133], v[182:185], v[62:65]
	v_mfma_f32_16x16x32_bf16 v[58:61], v[138:141], v[182:185], v[58:61]
	v_mfma_f32_16x16x32_bf16 v[46:49], v[130:133], v[192:195], v[46:49]
	v_mfma_f32_16x16x32_bf16 v[42:45], v[138:141], v[192:195], v[42:45]
	v_mfma_f32_16x16x32_bf16 v[30:33], v[130:133], v[200:203], v[30:33]
	v_mfma_f32_16x16x32_bf16 v[26:29], v[138:141], v[200:203], v[26:29]
	v_mfma_f32_16x16x32_bf16 v[14:17], v[130:133], v[212:215], v[14:17]
	v_mfma_f32_16x16x32_bf16 v[10:13], v[138:141], v[212:215], v[10:13]
	v_mfma_f32_16x16x32_bf16 v[62:65], v[134:137], v[186:189], v[62:65]
	v_mfma_f32_16x16x32_bf16 v[58:61], v[142:145], v[186:189], v[58:61]
	v_mfma_f32_16x16x32_bf16 v[46:49], v[134:137], v[196:199], v[46:49]
	v_mfma_f32_16x16x32_bf16 v[42:45], v[142:145], v[196:199], v[42:45]
	v_mfma_f32_16x16x32_bf16 v[30:33], v[134:137], v[208:211], v[30:33]
	v_mfma_f32_16x16x32_bf16 v[26:29], v[142:145], v[208:211], v[26:29]
	v_mfma_f32_16x16x32_bf16 v[14:17], v[134:137], v[216:219], v[14:17]
	v_mfma_f32_16x16x32_bf16 v[10:13], v[142:145], v[216:219], v[10:13]
	s_setprio 0
	s_setprio 1
	v_mfma_f32_16x16x32_bf16 v[54:57], v[146:149], v[182:185], v[54:57]
	v_mfma_f32_16x16x32_bf16 v[50:53], v[154:157], v[182:185], v[50:53]
	v_mfma_f32_16x16x32_bf16 v[38:41], v[146:149], v[192:195], v[38:41]
	v_mfma_f32_16x16x32_bf16 v[34:37], v[154:157], v[192:195], v[34:37]
	v_mfma_f32_16x16x32_bf16 v[22:25], v[146:149], v[200:203], v[22:25]
	v_mfma_f32_16x16x32_bf16 v[18:21], v[154:157], v[200:203], v[18:21]
	v_mfma_f32_16x16x32_bf16 v[6:9], v[146:149], v[212:215], v[6:9]
	v_mfma_f32_16x16x32_bf16 v[2:5], v[154:157], v[212:215], v[2:5]
	v_mfma_f32_16x16x32_bf16 v[54:57], v[150:153], v[186:189], v[54:57]
	v_mfma_f32_16x16x32_bf16 v[50:53], v[158:161], v[186:189], v[50:53]
	v_mfma_f32_16x16x32_bf16 v[38:41], v[150:153], v[196:199], v[38:41]
	v_mfma_f32_16x16x32_bf16 v[34:37], v[158:161], v[196:199], v[34:37]
	v_mfma_f32_16x16x32_bf16 v[22:25], v[150:153], v[208:211], v[22:25]
	v_mfma_f32_16x16x32_bf16 v[18:21], v[158:161], v[208:211], v[18:21]
	v_mfma_f32_16x16x32_bf16 v[6:9], v[150:153], v[216:219], v[6:9]
	v_mfma_f32_16x16x32_bf16 v[2:5], v[158:161], v[216:219], v[2:5]
	s_setprio 0
	s_add_i32 s77, s77, 2
	s_add_u32 s45, s45, 0x100
	s_addc_u32 s47, s47, 0
	s_mov_b64 s[6:7], s[8:9]
	s_barrier
.LBB0_423:
	ds_read_b128 v[130:133], v205
	ds_read_b128 v[134:137], v205 offset:1024
	ds_read_b128 v[138:141], v205 offset:2048
	ds_read_b128 v[142:145], v205 offset:3072
	ds_read_b128 v[146:149], v206
	ds_read_b128 v[150:153], v206 offset:1024
	ds_read_b128 v[154:157], v206 offset:2048
	ds_read_b128 v[158:161], v206 offset:3072
	s_add_u32 s8, s6, 0x100
	s_addc_u32 s9, s7, 0
	s_cmp_eq_u32 s77, 40
	s_cselect_b32 s43, s1, s9
	s_cselect_b32 s42, s0, s8
	s_cselect_b32 s11, s41, s47
	s_cselect_b32 s10, s40, s45
	v_lshl_add_u64 v[220:221], s[6:7], 0, v[176:177]
	s_add_i32 m0, s56, 0xc000
	ds_read_b128 v[182:185], v207
	ds_read_b128 v[186:189], v207 offset:1024
	ds_read_b128 v[192:195], v207 offset:2048
	ds_read_b128 v[196:199], v207 offset:3072
	ds_read_b128 v[200:203], v207 offset:4096
	ds_read_b128 v[208:211], v207 offset:5120
	ds_read_b128 v[212:215], v207 offset:6144
	ds_read_b128 v[216:219], v207 offset:7168
	global_load_lds_dwordx4 v[220:221], off
	v_lshl_add_u64 v[220:221], s[6:7], 0, v[174:175]
	s_add_i32 m0, s56, 0xe000
	s_nop 0
	global_load_lds_dwordx4 v[220:221], off
	s_waitcnt vmcnt(8)
	s_waitcnt lgkmcnt(0)
	s_barrier
	s_setprio 1
	s_waitcnt lgkmcnt(0)
	v_mfma_f32_16x16x32_bf16 v[126:129], v[130:133], v[182:185], v[126:129]
	v_mfma_f32_16x16x32_bf16 v[122:125], v[138:141], v[182:185], v[122:125]
	v_mfma_f32_16x16x32_bf16 v[110:113], v[130:133], v[192:195], v[110:113]
	v_mfma_f32_16x16x32_bf16 v[106:109], v[138:141], v[192:195], v[106:109]
	v_mfma_f32_16x16x32_bf16 v[94:97], v[130:133], v[200:203], v[94:97]
	v_mfma_f32_16x16x32_bf16 v[90:93], v[138:141], v[200:203], v[90:93]
	v_mfma_f32_16x16x32_bf16 v[78:81], v[130:133], v[212:215], v[78:81]
	v_mfma_f32_16x16x32_bf16 v[74:77], v[138:141], v[212:215], v[74:77]
	v_mfma_f32_16x16x32_bf16 v[126:129], v[134:137], v[186:189], v[126:129]
	v_mfma_f32_16x16x32_bf16 v[122:125], v[142:145], v[186:189], v[122:125]
	v_mfma_f32_16x16x32_bf16 v[110:113], v[134:137], v[196:199], v[110:113]
	v_mfma_f32_16x16x32_bf16 v[106:109], v[142:145], v[196:199], v[106:109]
	v_mfma_f32_16x16x32_bf16 v[94:97], v[134:137], v[208:211], v[94:97]
	v_mfma_f32_16x16x32_bf16 v[90:93], v[142:145], v[208:211], v[90:93]
	v_mfma_f32_16x16x32_bf16 v[78:81], v[134:137], v[216:219], v[78:81]
	v_mfma_f32_16x16x32_bf16 v[74:77], v[142:145], v[216:219], v[74:77]
	s_setprio 0
	s_setprio 1
	v_mfma_f32_16x16x32_bf16 v[118:121], v[146:149], v[182:185], v[118:121]
	v_mfma_f32_16x16x32_bf16 v[114:117], v[154:157], v[182:185], v[114:117]
	v_mfma_f32_16x16x32_bf16 v[102:105], v[146:149], v[192:195], v[102:105]
	v_mfma_f32_16x16x32_bf16 v[98:101], v[154:157], v[192:195], v[98:101]
	v_mfma_f32_16x16x32_bf16 v[86:89], v[146:149], v[200:203], v[86:89]
	v_mfma_f32_16x16x32_bf16 v[82:85], v[154:157], v[200:203], v[82:85]
	v_mfma_f32_16x16x32_bf16 v[70:73], v[146:149], v[212:215], v[70:73]
	v_mfma_f32_16x16x32_bf16 v[66:69], v[154:157], v[212:215], v[66:69]
	v_mfma_f32_16x16x32_bf16 v[118:121], v[150:153], v[186:189], v[118:121]
	v_mfma_f32_16x16x32_bf16 v[114:117], v[158:161], v[186:189], v[114:117]
	v_mfma_f32_16x16x32_bf16 v[102:105], v[150:153], v[196:199], v[102:105]
	v_mfma_f32_16x16x32_bf16 v[98:101], v[158:161], v[196:199], v[98:101]
	v_mfma_f32_16x16x32_bf16 v[86:89], v[150:153], v[208:211], v[86:89]
	v_mfma_f32_16x16x32_bf16 v[82:85], v[158:161], v[208:211], v[82:85]
	v_mfma_f32_16x16x32_bf16 v[70:73], v[150:153], v[216:219], v[70:73]
	v_mfma_f32_16x16x32_bf16 v[66:69], v[158:161], v[216:219], v[66:69]
	s_setprio 0
	s_barrier
; #define PG8_STAGE(bufoff, gbase, voff) do { _Pragma("unroll") for (int _i = 0; _i < 2; ++_i) \
;         __builtin_amdgcn_global_load_lds((const unsigned*)((const char*)(gbase) + (voff)[_i]), (PG8_LAS unsigned*)(lds + (bufoff) + ldsw + _i * 8192), 16, 0, 0); } while (0)
; #define PG8_LDA(dst, b, h) do { _Pragma("unroll") for (int m = 0; m < 4; ++m) _Pragma("unroll") for (int k = 0; k < 2; ++k) dst[m][k] = *(const PG8_LAS bf16x8*)(lds + PG8_SA(b, h) + aoff + m * 2048 + k * 1024); } while (0)
; #define PG8_LDB(dst, b, h) do { _Pragma("unroll") for (int n = 0; n < 2; ++n) _Pragma("unroll") for (int k = 0; k < 2; ++k) dst[n][k] = *(const PG8_LAS bf16x8*)(lds + PG8_SB(b, h) + boff + n * 2048 + k * 1024); } while (0)
; #define PG8_MMA(ai, bj, At, Bt) do { __builtin_amdgcn_s_setprio(1); _Pragma("unroll") for (int m = 0; m < 4; ++m) _Pragma("unroll") for (int n = 0; n < 2; ++n) _Pragma("unroll") for (int k = 0; k < 2; ++k) \
;         acc[ai][bj][m][n] = __builtin_amdgcn_mfma_f32_16x16x32_bf16(Bt[n][k], At[m][k], acc[ai][bj][m][n], 0, 0, 0); __builtin_amdgcn_s_setprio(0); } while (0)
; #define PG8_WAIT_V(n) asm volatile("s_waitcnt vmcnt(" #n ")" ::: "memory")
; #define PG8_WAIT_L(n) asm volatile("s_waitcnt lgkmcnt(" #n ")" ::: "memory")
; #define PG8_BAR __builtin_amdgcn_s_barrier()
; #define PG8_SCHED __builtin_amdgcn_sched_barrier(0)
; template <class Epi, class Sched, bool ALIGN_EPI = false, bool SP2 = false>
; __device__ __forceinline__ void gemm_phase(PG8_LAS unsigned char* lds, const Gemm g, const Sched& S, const Epi& E, const int tid) {
;     ...
;             PG8_LDA(At, 0, 1); PG8_STAGE(PG8_SB(0, 0), b2, voffB); PG8_STAGE(PG8_SB(0, 1), b2 + hstep, voffB); PG8_STAGE(PG8_SA(0, 0), a2, voffA);
;             PG8_WAIT_V(8); PG8_WAIT_L(0); PG8_BAR; PG8_MMA(1, 0, At, B0); PG8_MMA(1, 1, At, B1); PG8_BAR; PG8_SCHED;
;             PG8_LDB(B0, 1, 0); PG8_LDB(B1, 1, 1); PG8_SCHED; PG8_LDA(At, 1, 0); PG8_STAGE(PG8_SA(0, 1), a2 + hstep, voffA);
;             PG8_WAIT_V(8); PG8_WAIT_L(0); PG8_BAR; PG8_MMA(0, 0, At, B0); PG8_MMA(0, 1, At, B1); PG8_BAR; PG8_SCHED;
	s_add_i32 s6, s66, s55
	v_lshl_add_u64 v[220:221], s[10:11], 0, v[164:165]
	s_mov_b32 m0, s6
	ds_read_b128 v[182:185], v207 offset:16384
	ds_read_b128 v[186:189], v207 offset:17408
	ds_read_b128 v[192:195], v207 offset:18432
	ds_read_b128 v[196:199], v207 offset:19456
	ds_read_b128 v[200:203], v207 offset:20480
	ds_read_b128 v[208:211], v207 offset:21504
	ds_read_b128 v[212:215], v207 offset:22528
	ds_read_b128 v[216:219], v207 offset:23552
	global_load_lds_dwordx4 v[220:221], off
	s_add_i32 m0, s6, 0x2000
	s_add_u32 s6, s10, 0xb0000
	v_lshl_add_u64 v[222:223], s[10:11], 0, v[168:169]
	s_addc_u32 s7, s11, 0
	s_add_i32 s15, s67, s55
	global_load_lds_dwordx4 v[222:223], off
	v_lshl_add_u64 v[224:225], s[6:7], 0, v[164:165]
	s_mov_b32 m0, s15
	v_lshl_add_u64 v[226:227], s[42:43], 0, v[166:167]
	global_load_lds_dwordx4 v[224:225], off
	v_lshl_add_u64 v[224:225], s[6:7], 0, v[168:169]
	s_add_i32 m0, s15, 0x2000
	s_nop 0
	global_load_lds_dwordx4 v[224:225], off
	v_lshl_add_u64 v[224:225], s[42:43], 0, v[162:163]
	s_mov_b32 m0, s56
	s_nop 0
	global_load_lds_dwordx4 v[224:225], off
	s_mov_b32 m0, s57
	s_nop 0
	global_load_lds_dwordx4 v[226:227], off
	s_waitcnt vmcnt(8)
	s_waitcnt lgkmcnt(0)
	s_barrier
	s_setprio 1
	s_waitcnt lgkmcnt(0)
	v_mfma_f32_16x16x32_bf16 v[62:65], v[130:133], v[182:185], v[62:65]
	v_mfma_f32_16x16x32_bf16 v[58:61], v[138:141], v[182:185], v[58:61]
	v_mfma_f32_16x16x32_bf16 v[46:49], v[130:133], v[192:195], v[46:49]
	v_mfma_f32_16x16x32_bf16 v[42:45], v[138:141], v[192:195], v[42:45]
	v_mfma_f32_16x16x32_bf16 v[30:33], v[130:133], v[200:203], v[30:33]
	v_mfma_f32_16x16x32_bf16 v[26:29], v[138:141], v[200:203], v[26:29]
	v_mfma_f32_16x16x32_bf16 v[14:17], v[130:133], v[212:215], v[14:17]
	v_mfma_f32_16x16x32_bf16 v[10:13], v[138:141], v[212:215], v[10:13]
	v_mfma_f32_16x16x32_bf16 v[62:65], v[134:137], v[186:189], v[62:65]
	v_mfma_f32_16x16x32_bf16 v[58:61], v[142:145], v[186:189], v[58:61]
	v_mfma_f32_16x16x32_bf16 v[46:49], v[134:137], v[196:199], v[46:49]
	v_mfma_f32_16x16x32_bf16 v[42:45], v[142:145], v[196:199], v[42:45]
	v_mfma_f32_16x16x32_bf16 v[30:33], v[134:137], v[208:211], v[30:33]
	v_mfma_f32_16x16x32_bf16 v[26:29], v[142:145], v[208:211], v[26:29]
	v_mfma_f32_16x16x32_bf16 v[14:17], v[134:137], v[216:219], v[14:17]
	v_mfma_f32_16x16x32_bf16 v[10:13], v[142:145], v[216:219], v[10:13]
	s_setprio 0
	s_setprio 1
	v_mfma_f32_16x16x32_bf16 v[54:57], v[146:149], v[182:185], v[54:57]
	v_mfma_f32_16x16x32_bf16 v[50:53], v[154:157], v[182:185], v[50:53]
	v_mfma_f32_16x16x32_bf16 v[38:41], v[146:149], v[192:195], v[38:41]
	v_mfma_f32_16x16x32_bf16 v[34:37], v[154:157], v[192:195], v[34:37]
	v_mfma_f32_16x16x32_bf16 v[22:25], v[146:149], v[200:203], v[22:25]
	v_mfma_f32_16x16x32_bf16 v[18:21], v[154:157], v[200:203], v[18:21]
	v_mfma_f32_16x16x32_bf16 v[6:9], v[146:149], v[212:215], v[6:9]
	v_mfma_f32_16x16x32_bf16 v[2:5], v[154:157], v[212:215], v[2:5]
	v_mfma_f32_16x16x32_bf16 v[54:57], v[150:153], v[186:189], v[54:57]
	v_mfma_f32_16x16x32_bf16 v[50:53], v[158:161], v[186:189], v[50:53]
	v_mfma_f32_16x16x32_bf16 v[38:41], v[150:153], v[196:199], v[38:41]
	v_mfma_f32_16x16x32_bf16 v[34:37], v[158:161], v[196:199], v[34:37]
	v_mfma_f32_16x16x32_bf16 v[22:25], v[150:153], v[208:211], v[22:25]
	v_mfma_f32_16x16x32_bf16 v[18:21], v[158:161], v[208:211], v[18:21]
	v_mfma_f32_16x16x32_bf16 v[6:9], v[150:153], v[216:219], v[6:9]
	v_mfma_f32_16x16x32_bf16 v[2:5], v[158:161], v[216:219], v[2:5]
	s_setprio 0
	s_barrier
	s_add_i32 s15, 0, 0x18000
	s_add_i32 s18, 0, 0x1c000
	v_add_u32_e32 v142, s15, v204
	v_add_u32_e32 v158, s18, v204
	ds_read_b128 v[130:133], v142
	ds_read_b128 v[134:137], v142 offset:1024
	ds_read_b128 v[138:141], v142 offset:2048
	ds_read_b128 v[142:145], v142 offset:3072
	ds_read_b128 v[146:149], v158
	ds_read_b128 v[150:153], v158 offset:1024
	ds_read_b128 v[154:157], v158 offset:2048
	ds_read_b128 v[158:161], v158 offset:3072
	s_add_u32 s6, s42, 0xb0000
	s_addc_u32 s7, s43, 0
	s_mov_b32 m0, s58
	v_lshl_add_u64 v[228:229], s[6:7], 0, v[162:163]
	ds_read_b128 v[182:185], v207 offset:32768
	ds_read_b128 v[186:189], v207 offset:33792
	ds_read_b128 v[192:195], v207 offset:34816
	ds_read_b128 v[196:199], v207 offset:35840
	ds_read_b128 v[200:203], v207 offset:36864
	ds_read_b128 v[208:211], v207 offset:37888
	ds_read_b128 v[212:215], v207 offset:38912
	ds_read_b128 v[216:219], v207 offset:39936
	global_load_lds_dwordx4 v[228:229], off
	v_lshl_add_u64 v[228:229], s[6:7], 0, v[166:167]
	s_mov_b32 m0, s59
	s_nop 0
	global_load_lds_dwordx4 v[228:229], off
	s_waitcnt vmcnt(8)
	s_waitcnt lgkmcnt(0)
	s_barrier
; #define PG8_STAGE(bufoff, gbase, voff) do { _Pragma("unroll") for (int _i = 0; _i < 2; ++_i) \
;         __builtin_amdgcn_global_load_lds((const unsigned*)((const char*)(gbase) + (voff)[_i]), (PG8_LAS unsigned*)(lds + (bufoff) + ldsw + _i * 8192), 16, 0, 0); } while (0)
; #define PG8_LDA(dst, b, h) do { _Pragma("unroll") for (int m = 0; m < 4; ++m) _Pragma("unroll") for (int k = 0; k < 2; ++k) dst[m][k] = *(const PG8_LAS bf16x8*)(lds + PG8_SA(b, h) + aoff + m * 2048 + k * 1024); } while (0)
; #define PG8_MMA(ai, bj, At, Bt) do { __builtin_amdgcn_s_setprio(1); _Pragma("unroll") for (int m = 0; m < 4; ++m) _Pragma("unroll") for (int n = 0; n < 2; ++n) _Pragma("unroll") for (int k = 0; k < 2; ++k) \
;         acc[ai][bj][m][n] = __builtin_amdgcn_mfma_f32_16x16x32_bf16(Bt[n][k], At[m][k], acc[ai][bj][m][n], 0, 0, 0); __builtin_amdgcn_s_setprio(0); } while (0)
; #define PG8_WAIT_V(n) asm volatile("s_waitcnt vmcnt(" #n ")" ::: "memory")
; #define PG8_WAIT_L(n) asm volatile("s_waitcnt lgkmcnt(" #n ")" ::: "memory")
; #define PG8_BAR __builtin_amdgcn_s_barrier()
; #define PG8_SCHED __builtin_amdgcn_sched_barrier(0)
; template <class Epi, class Sched, bool ALIGN_EPI = false, bool SP2 = false>
; __device__ __forceinline__ void gemm_phase(PG8_LAS unsigned char* lds, const Gemm g, const Sched& S, const Epi& E, const int tid) {
;     ...
;             PG8_WAIT_V(8); PG8_WAIT_L(0); PG8_BAR; PG8_MMA(0, 0, At, B0); PG8_MMA(0, 1, At, B1); PG8_BAR; PG8_SCHED;
;             PG8_LDA(At, 1, 1); PG8_STAGE(PG8_SB(1, 0), b3, voffB); PG8_STAGE(PG8_SB(1, 1), b3 + hstep, voffB); PG8_STAGE(PG8_SA(1, 0), a3, voffA);
;             PG8_WAIT_V(8); PG8_WAIT_L(0); PG8_BAR; PG8_MMA(1, 0, At, B0); PG8_MMA(1, 1, At, B1); PG8_BAR; PG8_SCHED;
;     ...
;         if constexpr (ALIGN_EPI) { if (wr == 0) PG8_BAR; }
	s_setprio 1
	s_waitcnt lgkmcnt(0)
	v_mfma_f32_16x16x32_bf16 v[126:129], v[130:133], v[182:185], v[126:129]
	v_mfma_f32_16x16x32_bf16 v[122:125], v[138:141], v[182:185], v[122:125]
	v_mfma_f32_16x16x32_bf16 v[110:113], v[130:133], v[192:195], v[110:113]
	v_mfma_f32_16x16x32_bf16 v[106:109], v[138:141], v[192:195], v[106:109]
	v_mfma_f32_16x16x32_bf16 v[94:97], v[130:133], v[200:203], v[94:97]
	v_mfma_f32_16x16x32_bf16 v[90:93], v[138:141], v[200:203], v[90:93]
	v_mfma_f32_16x16x32_bf16 v[78:81], v[130:133], v[212:215], v[78:81]
	v_mfma_f32_16x16x32_bf16 v[74:77], v[138:141], v[212:215], v[74:77]
	v_mfma_f32_16x16x32_bf16 v[126:129], v[134:137], v[186:189], v[126:129]
	v_mfma_f32_16x16x32_bf16 v[122:125], v[142:145], v[186:189], v[122:125]
	v_mfma_f32_16x16x32_bf16 v[110:113], v[134:137], v[196:199], v[110:113]
	v_mfma_f32_16x16x32_bf16 v[106:109], v[142:145], v[196:199], v[106:109]
	v_mfma_f32_16x16x32_bf16 v[94:97], v[134:137], v[208:211], v[94:97]
	v_mfma_f32_16x16x32_bf16 v[90:93], v[142:145], v[208:211], v[90:93]
	v_mfma_f32_16x16x32_bf16 v[78:81], v[134:137], v[216:219], v[78:81]
	v_mfma_f32_16x16x32_bf16 v[74:77], v[142:145], v[216:219], v[74:77]
	s_setprio 0
	s_setprio 1
	v_mfma_f32_16x16x32_bf16 v[118:121], v[146:149], v[182:185], v[118:121]
	v_mfma_f32_16x16x32_bf16 v[114:117], v[154:157], v[182:185], v[114:117]
	v_mfma_f32_16x16x32_bf16 v[102:105], v[146:149], v[192:195], v[102:105]
	v_mfma_f32_16x16x32_bf16 v[98:101], v[154:157], v[192:195], v[98:101]
	v_mfma_f32_16x16x32_bf16 v[86:89], v[146:149], v[200:203], v[86:89]
	v_mfma_f32_16x16x32_bf16 v[82:85], v[154:157], v[200:203], v[82:85]
	v_mfma_f32_16x16x32_bf16 v[70:73], v[146:149], v[212:215], v[70:73]
	v_mfma_f32_16x16x32_bf16 v[66:69], v[154:157], v[212:215], v[66:69]
	v_mfma_f32_16x16x32_bf16 v[118:121], v[150:153], v[186:189], v[118:121]
	v_mfma_f32_16x16x32_bf16 v[114:117], v[158:161], v[186:189], v[114:117]
	v_mfma_f32_16x16x32_bf16 v[102:105], v[150:153], v[196:199], v[102:105]
	v_mfma_f32_16x16x32_bf16 v[98:101], v[158:161], v[196:199], v[98:101]
	v_mfma_f32_16x16x32_bf16 v[86:89], v[150:153], v[208:211], v[86:89]
	v_mfma_f32_16x16x32_bf16 v[82:85], v[158:161], v[208:211], v[82:85]
	v_mfma_f32_16x16x32_bf16 v[70:73], v[150:153], v[216:219], v[70:73]
	v_mfma_f32_16x16x32_bf16 v[66:69], v[158:161], v[216:219], v[66:69]
	s_setprio 0
	s_barrier
	s_add_i32 s6, s15, s55
	v_lshl_add_u64 v[220:221], v[220:221], 0, s[36:37]
	s_mov_b32 m0, s6
	ds_read_b128 v[182:185], v207 offset:49152
	ds_read_b128 v[186:189], v207 offset:50176
	ds_read_b128 v[192:195], v207 offset:51200
	ds_read_b128 v[196:199], v207 offset:52224
	ds_read_b128 v[200:203], v207 offset:53248
	ds_read_b128 v[208:211], v207 offset:54272
	ds_read_b128 v[212:215], v207 offset:55296
	ds_read_b128 v[216:219], v207 offset:56320
	global_load_lds_dwordx4 v[220:221], off
	s_add_i32 m0, s6, 0x2000
	s_add_u32 s6, s10, 0xb0080
	v_lshl_add_u64 v[220:221], v[222:223], 0, s[36:37]
	s_addc_u32 s7, s11, 0
	s_add_i32 s10, s18, s55
	global_load_lds_dwordx4 v[220:221], off
	v_lshl_add_u64 v[220:221], s[6:7], 0, v[164:165]
	s_mov_b32 m0, s10
	s_nop 0
	global_load_lds_dwordx4 v[220:221], off
	v_lshl_add_u64 v[220:221], s[6:7], 0, v[168:169]
	s_add_i32 m0, s10, 0x2000
	s_nop 0
	global_load_lds_dwordx4 v[220:221], off
	v_lshl_add_u64 v[220:221], v[224:225], 0, s[36:37]
	s_mov_b32 m0, s61
	s_nop 0
	global_load_lds_dwordx4 v[220:221], off
	v_lshl_add_u64 v[220:221], v[226:227], 0, s[36:37]
	s_mov_b32 m0, s62
	s_nop 0
	global_load_lds_dwordx4 v[220:221], off
	s_waitcnt vmcnt(8)
	s_waitcnt lgkmcnt(0)
	s_barrier
	s_setprio 1
	s_waitcnt lgkmcnt(0)
	v_mfma_f32_16x16x32_bf16 v[62:65], v[130:133], v[182:185], v[62:65]
	v_mfma_f32_16x16x32_bf16 v[58:61], v[138:141], v[182:185], v[58:61]
	v_mfma_f32_16x16x32_bf16 v[46:49], v[130:133], v[192:195], v[46:49]
	v_mfma_f32_16x16x32_bf16 v[42:45], v[138:141], v[192:195], v[42:45]
	v_mfma_f32_16x16x32_bf16 v[30:33], v[130:133], v[200:203], v[30:33]
	v_mfma_f32_16x16x32_bf16 v[26:29], v[138:141], v[200:203], v[26:29]
	v_mfma_f32_16x16x32_bf16 v[14:17], v[130:133], v[212:215], v[14:17]
	v_mfma_f32_16x16x32_bf16 v[10:13], v[138:141], v[212:215], v[10:13]
	v_mfma_f32_16x16x32_bf16 v[62:65], v[134:137], v[186:189], v[62:65]
	v_mfma_f32_16x16x32_bf16 v[58:61], v[142:145], v[186:189], v[58:61]
	v_mfma_f32_16x16x32_bf16 v[46:49], v[134:137], v[196:199], v[46:49]
	v_mfma_f32_16x16x32_bf16 v[42:45], v[142:145], v[196:199], v[42:45]
	v_mfma_f32_16x16x32_bf16 v[30:33], v[134:137], v[208:211], v[30:33]
	v_mfma_f32_16x16x32_bf16 v[26:29], v[142:145], v[208:211], v[26:29]
	v_mfma_f32_16x16x32_bf16 v[14:17], v[134:137], v[216:219], v[14:17]
	v_mfma_f32_16x16x32_bf16 v[10:13], v[142:145], v[216:219], v[10:13]
	s_setprio 0
	s_setprio 1
	v_mfma_f32_16x16x32_bf16 v[54:57], v[146:149], v[182:185], v[54:57]
	v_mfma_f32_16x16x32_bf16 v[50:53], v[154:157], v[182:185], v[50:53]
	v_mfma_f32_16x16x32_bf16 v[38:41], v[146:149], v[192:195], v[38:41]
	v_mfma_f32_16x16x32_bf16 v[34:37], v[154:157], v[192:195], v[34:37]
	v_mfma_f32_16x16x32_bf16 v[22:25], v[146:149], v[200:203], v[22:25]
	v_mfma_f32_16x16x32_bf16 v[18:21], v[154:157], v[200:203], v[18:21]
	v_mfma_f32_16x16x32_bf16 v[6:9], v[146:149], v[212:215], v[6:9]
	v_mfma_f32_16x16x32_bf16 v[2:5], v[154:157], v[212:215], v[2:5]
	v_mfma_f32_16x16x32_bf16 v[54:57], v[150:153], v[186:189], v[54:57]
	v_mfma_f32_16x16x32_bf16 v[50:53], v[158:161], v[186:189], v[50:53]
	v_mfma_f32_16x16x32_bf16 v[38:41], v[150:153], v[196:199], v[38:41]
	v_mfma_f32_16x16x32_bf16 v[34:37], v[158:161], v[196:199], v[34:37]
	v_mfma_f32_16x16x32_bf16 v[22:25], v[150:153], v[208:211], v[22:25]
	v_mfma_f32_16x16x32_bf16 v[18:21], v[158:161], v[208:211], v[18:21]
	v_mfma_f32_16x16x32_bf16 v[6:9], v[150:153], v[216:219], v[6:9]
	v_mfma_f32_16x16x32_bf16 v[2:5], v[158:161], v[216:219], v[2:5]
	s_setprio 0
	s_add_i32 s77, s77, 2
	s_add_u32 s45, s45, 0x100
	s_addc_u32 s47, s47, 0
	s_cmp_gt_u32 s77, 41
	s_mov_b64 s[6:7], s[8:9]
	s_barrier
	s_cbranch_scc0 .LBB0_423
	s_and_b64 vcc, exec, s[38:39]
	s_cbranch_vccz .LBB0_426
	s_barrier

; #define PG8_STAGE(bufoff, gbase, voff) do { _Pragma("unroll") for (int _i = 0; _i < 2; ++_i) \
;         __builtin_amdgcn_global_load_lds((const unsigned*)((const char*)(gbase) + (voff)[_i]), (PG8_LAS unsigned*)(lds + (bufoff) + ldsw + _i * 8192), 16, 0, 0); } while (0)
; #define PG8_LDA(dst, b, h) do { _Pragma("unroll") for (int m = 0; m < 4; ++m) _Pragma("unroll") for (int k = 0; k < 2; ++k) dst[m][k] = *(const PG8_LAS bf16x8*)(lds + PG8_SA(b, h) + aoff + m * 2048 + k * 1024); } while (0)
; #define PG8_LDB(dst, b, h) do { _Pragma("unroll") for (int n = 0; n < 2; ++n) _Pragma("unroll") for (int k = 0; k < 2; ++k) dst[n][k] = *(const PG8_LAS bf16x8*)(lds + PG8_SB(b, h) + boff + n * 2048 + k * 1024); } while (0)
; #define PG8_MMA(ai, bj, At, Bt) do { __builtin_amdgcn_s_setprio(1); _Pragma("unroll") for (int m = 0; m < 4; ++m) _Pragma("unroll") for (int n = 0; n < 2; ++n) _Pragma("unroll") for (int k = 0; k < 2; ++k) \
;         acc[ai][bj][m][n] = __builtin_amdgcn_mfma_f32_16x16x32_bf16(Bt[n][k], At[m][k], acc[ai][bj][m][n], 0, 0, 0); __builtin_amdgcn_s_setprio(0); } while (0)
; template <class Epi, class Sched, bool ALIGN_EPI = false, bool SP2 = false>
; __device__ __forceinline__ void gemm_phase(PG8_LAS unsigned char* lds, const Gemm g, const Sched& S, const Epi& E, const int tid) {
;     ...
;         const char* nA = has_next ? S.aptr(nxt) : cA; const char* nB = has_next ? S.bptr(nxt) : cB;
;         for (int t = 0; t < nt; t += 2) {
;             const bool last = (t == nt - 2);
;             const char* a1 = cA + (size_t)(t + 1) * kstep;
;             const char* a2 = last ? nA : cA + (size_t)(t + 2) * kstep; const char* b2 = last ? nB : cB + (size_t)(t + 2) * kstep;
;             const char* a3 = a2 + kstep; const char* b3 = b2 + kstep;
;             if (last && has_next) S.a_ready(nxt);
;             if constexpr (SP2) {
;             PG8_LDB(B0, 0, 0); PG8_LDB(B1, 0, 1); PG8_SCHED; PG8_LDA(At, 0, 0); PG8_STAGE(PG8_SA(1, 1), a1 + hstep, voffA);
;             PG8_WAIT_V(8); PG8_WAIT_L(0); PG8_BAR; PG8_MMA(0, 0, At, B0); PG8_MMA(0, 1, At, B1); PG8_BAR; PG8_SCHED;
;             PG8_LDA(At, 0, 1); PG8_STAGE(PG8_SB(0, 0), b2, voffB); PG8_STAGE(PG8_SB(0, 1), b2 + hstep, voffB); PG8_STAGE(PG8_SA(0, 0), a2, voffA);
;             PG8_WAIT_V(8); PG8_WAIT_L(0); PG8_BAR; PG8_MMA(1, 0, At, B0); PG8_MMA(1, 1, At, B1); PG8_BAR; PG8_SCHED;
.LBB0_732:
	s_ashr_i32 s29, s28, 31
	s_lshl_b64 s[18:19], s[28:29], 19
	s_add_u32 s30, s50, s18
	s_addc_u32 s31, s51, s19
	s_and_b64 s[18:19], s[2:3], exec
	s_cselect_b32 s29, s31, s41
	s_cselect_b32 s37, s30, s40
	s_ashr_i32 s27, s26, 31
	s_lshl_b64 s[18:19], s[26:27], 19
	s_add_u32 s34, s52, s18
	s_addc_u32 s35, s53, s19
	s_and_b64 s[18:19], s[2:3], exec
	s_cselect_b32 s27, s35, s39
	s_cselect_b32 s79, s34, s38
	s_add_u32 s80, s38, 0x100
	s_addc_u32 s81, s39, 0
	s_add_u32 s38, s40, 0x40080
	s_addc_u32 s39, s41, 0
	s_mov_b32 s82, -2
	s_add_u32 s15, s38, 0xfffc0080
	s_addc_u32 s18, s39, -1
	s_cmp_eq_u32 s82, 12
	s_cselect_b32 s43, s29, s18
	s_cselect_b32 s42, s37, s15
	s_cselect_b32 s41, s27, s81
	s_cselect_b32 s40, s79, s80
	v_lshl_add_u64 v[194:195], s[38:39], 0, v[180:181]
	s_add_i32 m0, s55, 0xc000
	global_load_lds_dwordx4 v[194:195], off
	v_lshl_add_u64 v[194:195], s[38:39], 0, v[178:179]
	s_add_i32 m0, s55, 0xe000
	s_nop 0
	global_load_lds_dwordx4 v[194:195], off
	s_waitcnt vmcnt(8)
	s_waitcnt lgkmcnt(0)
	s_barrier
	s_setprio 1
	s_waitcnt lgkmcnt(0)
	v_mfma_f32_16x16x32_bf16 v[126:129], v[130:133], v[186:189], 0
	v_mfma_f32_16x16x32_bf16 v[122:125], v[138:141], v[186:189], 0
	v_mfma_f32_16x16x32_bf16 v[110:113], v[130:133], v[206:209], 0
	v_mfma_f32_16x16x32_bf16 v[106:109], v[138:141], v[206:209], 0
	v_mfma_f32_16x16x32_bf16 v[94:97], v[130:133], v[216:219], 0
	v_mfma_f32_16x16x32_bf16 v[90:93], v[138:141], v[216:219], 0
	v_mfma_f32_16x16x32_bf16 v[78:81], v[130:133], v[224:227], 0
	v_mfma_f32_16x16x32_bf16 v[74:77], v[138:141], v[224:227], 0
	v_mfma_f32_16x16x32_bf16 v[126:129], v[134:137], v[198:201], v[126:129]
	v_mfma_f32_16x16x32_bf16 v[122:125], v[142:145], v[198:201], v[122:125]
	v_mfma_f32_16x16x32_bf16 v[110:113], v[134:137], v[212:215], v[110:113]
	v_mfma_f32_16x16x32_bf16 v[106:109], v[142:145], v[212:215], v[106:109]
	v_mfma_f32_16x16x32_bf16 v[94:97], v[134:137], v[220:223], v[94:97]
	v_mfma_f32_16x16x32_bf16 v[90:93], v[142:145], v[220:223], v[90:93]
	v_mfma_f32_16x16x32_bf16 v[78:81], v[134:137], v[228:231], v[78:81]
	v_mfma_f32_16x16x32_bf16 v[74:77], v[142:145], v[228:231], v[74:77]
	s_setprio 0
	s_setprio 1
	v_mfma_f32_16x16x32_bf16 v[118:121], v[146:149], v[186:189], 0
	v_mfma_f32_16x16x32_bf16 v[114:117], v[154:157], v[186:189], 0
	v_mfma_f32_16x16x32_bf16 v[102:105], v[146:149], v[206:209], 0
	v_mfma_f32_16x16x32_bf16 v[98:101], v[154:157], v[206:209], 0
	v_mfma_f32_16x16x32_bf16 v[86:89], v[146:149], v[216:219], 0
	v_mfma_f32_16x16x32_bf16 v[82:85], v[154:157], v[216:219], 0
	v_mfma_f32_16x16x32_bf16 v[70:73], v[146:149], v[224:227], 0
	v_mfma_f32_16x16x32_bf16 v[66:69], v[154:157], v[224:227], 0
	v_mfma_f32_16x16x32_bf16 v[118:121], v[150:153], v[198:201], v[118:121]
	v_mfma_f32_16x16x32_bf16 v[114:117], v[158:161], v[198:201], v[114:117]
	v_mfma_f32_16x16x32_bf16 v[102:105], v[150:153], v[212:215], v[102:105]
	v_mfma_f32_16x16x32_bf16 v[98:101], v[158:161], v[212:215], v[98:101]
	v_mfma_f32_16x16x32_bf16 v[86:89], v[150:153], v[220:223], v[86:89]
	v_mfma_f32_16x16x32_bf16 v[82:85], v[158:161], v[220:223], v[82:85]
	v_mfma_f32_16x16x32_bf16 v[70:73], v[150:153], v[228:231], v[70:73]
	v_mfma_f32_16x16x32_bf16 v[66:69], v[158:161], v[228:231], v[66:69]
	s_setprio 0
	s_barrier
	s_add_i32 s15, s66, s54
	v_lshl_add_u64 v[194:195], s[40:41], 0, v[164:165]
	s_mov_b32 m0, s15
	ds_read_b128 v[186:189], v197 offset:16384
	ds_read_b128 v[198:201], v197 offset:17408
	ds_read_b128 v[206:209], v197 offset:18432
	ds_read_b128 v[212:215], v197 offset:19456
	ds_read_b128 v[216:219], v197 offset:20480
	ds_read_b128 v[220:223], v197 offset:21504
	ds_read_b128 v[224:227], v197 offset:22528
	ds_read_b128 v[228:231], v197 offset:23552
	global_load_lds_dwordx4 v[194:195], off
	s_add_i32 m0, s15, 0x2000
	s_add_u32 s18, s40, 0x40000
	v_lshl_add_u64 v[232:233], s[40:41], 0, v[168:169]
	s_addc_u32 s19, s41, 0
	s_add_i32 s15, s67, s54
	global_load_lds_dwordx4 v[232:233], off
	v_lshl_add_u64 v[234:235], s[18:19], 0, v[164:165]
	s_mov_b32 m0, s15
	v_lshl_add_u64 v[236:237], s[42:43], 0, v[166:167]
	global_load_lds_dwordx4 v[234:235], off
	v_lshl_add_u64 v[234:235], s[18:19], 0, v[168:169]
	s_add_i32 m0, s15, 0x2000
	s_nop 0
	global_load_lds_dwordx4 v[234:235], off
	v_lshl_add_u64 v[234:235], s[42:43], 0, v[162:163]
	s_mov_b32 m0, s55
	s_nop 0
	global_load_lds_dwordx4 v[234:235], off
	s_mov_b32 m0, s56
	s_nop 0
	global_load_lds_dwordx4 v[236:237], off
	s_waitcnt vmcnt(8)
	s_waitcnt lgkmcnt(0)
	s_barrier
	s_setprio 1
	s_waitcnt lgkmcnt(0)
	v_mfma_f32_16x16x32_bf16 v[62:65], v[130:133], v[186:189], 0
	v_mfma_f32_16x16x32_bf16 v[58:61], v[138:141], v[186:189], 0
	v_mfma_f32_16x16x32_bf16 v[46:49], v[130:133], v[206:209], 0
	v_mfma_f32_16x16x32_bf16 v[42:45], v[138:141], v[206:209], 0
	v_mfma_f32_16x16x32_bf16 v[30:33], v[130:133], v[216:219], 0
	v_mfma_f32_16x16x32_bf16 v[26:29], v[138:141], v[216:219], 0
	v_mfma_f32_16x16x32_bf16 v[14:17], v[130:133], v[224:227], 0
	v_mfma_f32_16x16x32_bf16 v[10:13], v[138:141], v[224:227], 0
	v_mfma_f32_16x16x32_bf16 v[62:65], v[134:137], v[198:201], v[62:65]
	v_mfma_f32_16x16x32_bf16 v[58:61], v[142:145], v[198:201], v[58:61]
	v_mfma_f32_16x16x32_bf16 v[46:49], v[134:137], v[212:215], v[46:49]
	v_mfma_f32_16x16x32_bf16 v[42:45], v[142:145], v[212:215], v[42:45]
	v_mfma_f32_16x16x32_bf16 v[30:33], v[134:137], v[220:223], v[30:33]
	v_mfma_f32_16x16x32_bf16 v[26:29], v[142:145], v[220:223], v[26:29]
	v_mfma_f32_16x16x32_bf16 v[14:17], v[134:137], v[228:231], v[14:17]
	v_mfma_f32_16x16x32_bf16 v[10:13], v[142:145], v[228:231], v[10:13]
	s_setprio 0
	s_setprio 1
	v_mfma_f32_16x16x32_bf16 v[54:57], v[146:149], v[186:189], 0
	v_mfma_f32_16x16x32_bf16 v[50:53], v[154:157], v[186:189], 0
	v_mfma_f32_16x16x32_bf16 v[38:41], v[146:149], v[206:209], 0
	v_mfma_f32_16x16x32_bf16 v[34:37], v[154:157], v[206:209], 0
	v_mfma_f32_16x16x32_bf16 v[22:25], v[146:149], v[216:219], 0
	v_mfma_f32_16x16x32_bf16 v[18:21], v[154:157], v[216:219], 0
	v_mfma_f32_16x16x32_bf16 v[6:9], v[146:149], v[224:227], 0
	v_mfma_f32_16x16x32_bf16 v[2:5], v[154:157], v[224:227], 0
	v_mfma_f32_16x16x32_bf16 v[54:57], v[150:153], v[198:201], v[54:57]
	v_mfma_f32_16x16x32_bf16 v[50:53], v[158:161], v[198:201], v[50:53]
	v_mfma_f32_16x16x32_bf16 v[38:41], v[150:153], v[212:215], v[38:41]
	v_mfma_f32_16x16x32_bf16 v[34:37], v[158:161], v[212:215], v[34:37]
	v_mfma_f32_16x16x32_bf16 v[22:25], v[150:153], v[220:223], v[22:25]
	v_mfma_f32_16x16x32_bf16 v[18:21], v[158:161], v[220:223], v[18:21]
	v_mfma_f32_16x16x32_bf16 v[6:9], v[150:153], v[228:231], v[6:9]
	v_mfma_f32_16x16x32_bf16 v[2:5], v[158:161], v[228:231], v[2:5]
	s_setprio 0
	s_barrier
; #define PG8_STAGE(bufoff, gbase, voff) do { _Pragma("unroll") for (int _i = 0; _i < 2; ++_i) \
;         __builtin_amdgcn_global_load_lds((const unsigned*)((const char*)(gbase) + (voff)[_i]), (PG8_LAS unsigned*)(lds + (bufoff) + ldsw + _i * 8192), 16, 0, 0); } while (0)
; #define PG8_LDA(dst, b, h) do { _Pragma("unroll") for (int m = 0; m < 4; ++m) _Pragma("unroll") for (int k = 0; k < 2; ++k) dst[m][k] = *(const PG8_LAS bf16x8*)(lds + PG8_SA(b, h) + aoff + m * 2048 + k * 1024); } while (0)
; #define PG8_LDB(dst, b, h) do { _Pragma("unroll") for (int n = 0; n < 2; ++n) _Pragma("unroll") for (int k = 0; k < 2; ++k) dst[n][k] = *(const PG8_LAS bf16x8*)(lds + PG8_SB(b, h) + boff + n * 2048 + k * 1024); } while (0)
; #define PG8_MMA(ai, bj, At, Bt) do { __builtin_amdgcn_s_setprio(1); _Pragma("unroll") for (int m = 0; m < 4; ++m) _Pragma("unroll") for (int n = 0; n < 2; ++n) _Pragma("unroll") for (int k = 0; k < 2; ++k) \
;         acc[ai][bj][m][n] = __builtin_amdgcn_mfma_f32_16x16x32_bf16(Bt[n][k], At[m][k], acc[ai][bj][m][n], 0, 0, 0); __builtin_amdgcn_s_setprio(0); } while (0)
; #define PG8_WAIT_V(n) asm volatile("s_waitcnt vmcnt(" #n ")" ::: "memory")
; #define PG8_WAIT_L(n) asm volatile("s_waitcnt lgkmcnt(" #n ")" ::: "memory")
; #define PG8_BAR __builtin_amdgcn_s_barrier()
; #define PG8_SCHED __builtin_amdgcn_sched_barrier(0)
; template <class Epi, class Sched, bool ALIGN_EPI = false, bool SP2 = false>
; __device__ __forceinline__ void gemm_phase(PG8_LAS unsigned char* lds, const Gemm g, const Sched& S, const Epi& E, const int tid) {
;     ...
;             PG8_WAIT_V(8); PG8_WAIT_L(0); PG8_BAR; PG8_MMA(1, 0, At, B0); PG8_MMA(1, 1, At, B1); PG8_BAR; PG8_SCHED;
;             PG8_LDB(B0, 1, 0); PG8_LDB(B1, 1, 1); PG8_SCHED; PG8_LDA(At, 1, 0); PG8_STAGE(PG8_SA(0, 1), a2 + hstep, voffA);
;             PG8_WAIT_V(8); PG8_WAIT_L(0); PG8_BAR; PG8_MMA(0, 0, At, B0); PG8_MMA(0, 1, At, B1); PG8_BAR; PG8_SCHED;
;             PG8_LDA(At, 1, 1); PG8_STAGE(PG8_SB(1, 0), b3, voffB); PG8_STAGE(PG8_SB(1, 1), b3 + hstep, voffB); PG8_STAGE(PG8_SA(1, 0), a3, voffA);
	s_add_i32 s15, 0, 0x18000
	s_add_i32 s83, 0, 0x1c000
	v_add_u32_e32 v142, s15, v173
	v_add_u32_e32 v158, s83, v173
	ds_read_b128 v[130:133], v142
	ds_read_b128 v[134:137], v142 offset:1024
	ds_read_b128 v[138:141], v142 offset:2048
	ds_read_b128 v[142:145], v142 offset:3072
	ds_read_b128 v[146:149], v158
	ds_read_b128 v[150:153], v158 offset:1024
	ds_read_b128 v[154:157], v158 offset:2048
	ds_read_b128 v[158:161], v158 offset:3072
	s_add_u32 s18, s42, 0x40000
	s_addc_u32 s19, s43, 0
	s_mov_b32 m0, s57
	v_lshl_add_u64 v[238:239], s[18:19], 0, v[162:163]
	ds_read_b128 v[186:189], v197 offset:32768
	ds_read_b128 v[198:201], v197 offset:33792
	ds_read_b128 v[206:209], v197 offset:34816
	ds_read_b128 v[212:215], v197 offset:35840
	ds_read_b128 v[216:219], v197 offset:36864
	ds_read_b128 v[220:223], v197 offset:37888
	ds_read_b128 v[224:227], v197 offset:38912
	ds_read_b128 v[228:231], v197 offset:39936
	global_load_lds_dwordx4 v[238:239], off
	v_lshl_add_u64 v[238:239], s[18:19], 0, v[166:167]
	s_mov_b32 m0, s58
	s_nop 0
	global_load_lds_dwordx4 v[238:239], off
	s_waitcnt vmcnt(8)
	s_waitcnt lgkmcnt(0)
	s_barrier
	s_setprio 1
	s_waitcnt lgkmcnt(0)
	v_mfma_f32_16x16x32_bf16 v[126:129], v[130:133], v[186:189], v[126:129]
	v_mfma_f32_16x16x32_bf16 v[122:125], v[138:141], v[186:189], v[122:125]
	v_mfma_f32_16x16x32_bf16 v[110:113], v[130:133], v[206:209], v[110:113]
	v_mfma_f32_16x16x32_bf16 v[106:109], v[138:141], v[206:209], v[106:109]
	v_mfma_f32_16x16x32_bf16 v[94:97], v[130:133], v[216:219], v[94:97]
	v_mfma_f32_16x16x32_bf16 v[90:93], v[138:141], v[216:219], v[90:93]
	v_mfma_f32_16x16x32_bf16 v[78:81], v[130:133], v[224:227], v[78:81]
	v_mfma_f32_16x16x32_bf16 v[74:77], v[138:141], v[224:227], v[74:77]
	v_mfma_f32_16x16x32_bf16 v[126:129], v[134:137], v[198:201], v[126:129]
	v_mfma_f32_16x16x32_bf16 v[122:125], v[142:145], v[198:201], v[122:125]
	v_mfma_f32_16x16x32_bf16 v[110:113], v[134:137], v[212:215], v[110:113]
	v_mfma_f32_16x16x32_bf16 v[106:109], v[142:145], v[212:215], v[106:109]
	v_mfma_f32_16x16x32_bf16 v[94:97], v[134:137], v[220:223], v[94:97]
	v_mfma_f32_16x16x32_bf16 v[90:93], v[142:145], v[220:223], v[90:93]
	v_mfma_f32_16x16x32_bf16 v[78:81], v[134:137], v[228:231], v[78:81]
	v_mfma_f32_16x16x32_bf16 v[74:77], v[142:145], v[228:231], v[74:77]
	s_setprio 0
	s_setprio 1
	v_mfma_f32_16x16x32_bf16 v[118:121], v[146:149], v[186:189], v[118:121]
	v_mfma_f32_16x16x32_bf16 v[114:117], v[154:157], v[186:189], v[114:117]
	v_mfma_f32_16x16x32_bf16 v[102:105], v[146:149], v[206:209], v[102:105]
	v_mfma_f32_16x16x32_bf16 v[98:101], v[154:157], v[206:209], v[98:101]
	v_mfma_f32_16x16x32_bf16 v[86:89], v[146:149], v[216:219], v[86:89]
	v_mfma_f32_16x16x32_bf16 v[82:85], v[154:157], v[216:219], v[82:85]
	v_mfma_f32_16x16x32_bf16 v[70:73], v[146:149], v[224:227], v[70:73]
	v_mfma_f32_16x16x32_bf16 v[66:69], v[154:157], v[224:227], v[66:69]
	v_mfma_f32_16x16x32_bf16 v[118:121], v[150:153], v[198:201], v[118:121]
	v_mfma_f32_16x16x32_bf16 v[114:117], v[158:161], v[198:201], v[114:117]
	v_mfma_f32_16x16x32_bf16 v[102:105], v[150:153], v[212:215], v[102:105]
	v_mfma_f32_16x16x32_bf16 v[98:101], v[158:161], v[212:215], v[98:101]
	v_mfma_f32_16x16x32_bf16 v[86:89], v[150:153], v[220:223], v[86:89]
	v_mfma_f32_16x16x32_bf16 v[82:85], v[158:161], v[220:223], v[82:85]
	v_mfma_f32_16x16x32_bf16 v[70:73], v[150:153], v[228:231], v[70:73]
	v_mfma_f32_16x16x32_bf16 v[66:69], v[158:161], v[228:231], v[66:69]
	s_setprio 0
	s_barrier
	s_add_i32 s15, s15, s54
	v_lshl_add_u64 v[194:195], v[194:195], 0, s[10:11]
	s_mov_b32 m0, s15
	ds_read_b128 v[186:189], v197 offset:49152
	ds_read_b128 v[198:201], v197 offset:50176
	ds_read_b128 v[206:209], v197 offset:51200
	ds_read_b128 v[212:215], v197 offset:52224
	ds_read_b128 v[216:219], v197 offset:53248
	ds_read_b128 v[220:223], v197 offset:54272
	ds_read_b128 v[224:227], v197 offset:55296
	ds_read_b128 v[228:231], v197 offset:56320
	global_load_lds_dwordx4 v[194:195], off
	s_add_i32 m0, s15, 0x2000
	s_add_u32 s18, s40, 0x40080
	v_lshl_add_u64 v[194:195], v[232:233], 0, s[10:11]
	s_addc_u32 s19, s41, 0
	s_add_i32 s15, s83, s54
	global_load_lds_dwordx4 v[194:195], off
	v_lshl_add_u64 v[194:195], s[18:19], 0, v[164:165]
	s_mov_b32 m0, s15
	s_nop 0
	global_load_lds_dwordx4 v[194:195], off
	v_lshl_add_u64 v[194:195], s[18:19], 0, v[168:169]
	s_add_i32 m0, s15, 0x2000
	s_nop 0
	global_load_lds_dwordx4 v[194:195], off
	v_lshl_add_u64 v[194:195], v[234:235], 0, s[10:11]
	s_mov_b32 m0, s61
	s_nop 0
	global_load_lds_dwordx4 v[194:195], off
	v_lshl_add_u64 v[194:195], v[236:237], 0, s[10:11]
	s_mov_b32 m0, s62
	s_nop 0
	global_load_lds_dwordx4 v[194:195], off
	s_waitcnt vmcnt(8)
	s_waitcnt lgkmcnt(0)
	s_barrier
; #define PG8_STAGE(bufoff, gbase, voff) do { _Pragma("unroll") for (int _i = 0; _i < 2; ++_i) \
;         __builtin_amdgcn_global_load_lds((const unsigned*)((const char*)(gbase) + (voff)[_i]), (PG8_LAS unsigned*)(lds + (bufoff) + ldsw + _i * 8192), 16, 0, 0); } while (0)
; #define PG8_LDA(dst, b, h) do { _Pragma("unroll") for (int m = 0; m < 4; ++m) _Pragma("unroll") for (int k = 0; k < 2; ++k) dst[m][k] = *(const PG8_LAS bf16x8*)(lds + PG8_SA(b, h) + aoff + m * 2048 + k * 1024); } while (0)
; #define PG8_WAIT_V(n) asm volatile("s_waitcnt vmcnt(" #n ")" ::: "memory")
; #define PG8_WAIT_L(n) asm volatile("s_waitcnt lgkmcnt(" #n ")" ::: "memory")
; #define PG8_BAR __builtin_amdgcn_s_barrier()
; template <class Epi, class Sched, bool ALIGN_EPI = false, bool SP2 = false>
; __device__ __forceinline__ void gemm_phase(PG8_LAS unsigned char* lds, const Gemm g, const Sched& S, const Epi& E, const int tid) {
;     ...
;         for (int t = 0; t < nt; t += 2) {
;             const bool last = (t == nt - 2);
;             const char* a1 = cA + (size_t)(t + 1) * kstep;
;             const char* a2 = last ? nA : cA + (size_t)(t + 2) * kstep; const char* b2 = last ? nB : cB + (size_t)(t + 2) * kstep;
;             const char* a3 = a2 + kstep; const char* b3 = b2 + kstep;
;             if (last && has_next) S.a_ready(nxt);
;             if constexpr (SP2) {
;             PG8_LDB(B0, 0, 0); PG8_LDB(B1, 0, 1); PG8_SCHED; PG8_LDA(At, 0, 0); PG8_STAGE(PG8_SA(1, 1), a1 + hstep, voffA);
;             PG8_WAIT_V(8); PG8_WAIT_L(0); PG8_BAR; PG8_MMA(0, 0, At, B0); PG8_MMA(0, 1, At, B1); PG8_BAR; PG8_SCHED;
;             PG8_LDA(At, 0, 1); PG8_STAGE(PG8_SB(0, 0), b2, voffB); PG8_STAGE(PG8_SB(0, 1), b2 + hstep, voffB); PG8_STAGE(PG8_SA(0, 0), a2, voffA);
;             PG8_WAIT_V(8); PG8_WAIT_L(0); PG8_BAR; PG8_MMA(1, 0, At, B0); PG8_MMA(1, 1, At, B1); PG8_BAR; PG8_SCHED;
;             PG8_LDB(B0, 1, 0); PG8_LDB(B1, 1, 1); PG8_SCHED; PG8_LDA(At, 1, 0); PG8_STAGE(PG8_SA(0, 1), a2 + hstep, voffA);
;             PG8_WAIT_V(8); PG8_WAIT_L(0); PG8_BAR; PG8_MMA(0, 0, At, B0); PG8_MMA(0, 1, At, B1); PG8_BAR; PG8_SCHED;
;             PG8_LDA(At, 1, 1); PG8_STAGE(PG8_SB(1, 0), b3, voffB); PG8_STAGE(PG8_SB(1, 1), b3 + hstep, voffB); PG8_STAGE(PG8_SA(1, 0), a3, voffA);
;             PG8_WAIT_V(8); PG8_WAIT_L(0); PG8_BAR; PG8_MMA(1, 0, At, B0); PG8_MMA(1, 1, At, B1); PG8_BAR; PG8_SCHED;
	s_setprio 1
	s_waitcnt lgkmcnt(0)
	v_mfma_f32_16x16x32_bf16 v[62:65], v[130:133], v[186:189], v[62:65]
	v_mfma_f32_16x16x32_bf16 v[58:61], v[138:141], v[186:189], v[58:61]
	v_mfma_f32_16x16x32_bf16 v[46:49], v[130:133], v[206:209], v[46:49]
	v_mfma_f32_16x16x32_bf16 v[42:45], v[138:141], v[206:209], v[42:45]
	v_mfma_f32_16x16x32_bf16 v[30:33], v[130:133], v[216:219], v[30:33]
	v_mfma_f32_16x16x32_bf16 v[26:29], v[138:141], v[216:219], v[26:29]
	v_mfma_f32_16x16x32_bf16 v[14:17], v[130:133], v[224:227], v[14:17]
	v_mfma_f32_16x16x32_bf16 v[10:13], v[138:141], v[224:227], v[10:13]
	v_mfma_f32_16x16x32_bf16 v[62:65], v[134:137], v[198:201], v[62:65]
	v_mfma_f32_16x16x32_bf16 v[58:61], v[142:145], v[198:201], v[58:61]
	v_mfma_f32_16x16x32_bf16 v[46:49], v[134:137], v[212:215], v[46:49]
	v_mfma_f32_16x16x32_bf16 v[42:45], v[142:145], v[212:215], v[42:45]
	v_mfma_f32_16x16x32_bf16 v[30:33], v[134:137], v[220:223], v[30:33]
	v_mfma_f32_16x16x32_bf16 v[26:29], v[142:145], v[220:223], v[26:29]
	v_mfma_f32_16x16x32_bf16 v[14:17], v[134:137], v[228:231], v[14:17]
	v_mfma_f32_16x16x32_bf16 v[10:13], v[142:145], v[228:231], v[10:13]
	s_setprio 0
	s_setprio 1
	v_mfma_f32_16x16x32_bf16 v[54:57], v[146:149], v[186:189], v[54:57]
	v_mfma_f32_16x16x32_bf16 v[50:53], v[154:157], v[186:189], v[50:53]
	v_mfma_f32_16x16x32_bf16 v[38:41], v[146:149], v[206:209], v[38:41]
	v_mfma_f32_16x16x32_bf16 v[34:37], v[154:157], v[206:209], v[34:37]
	v_mfma_f32_16x16x32_bf16 v[22:25], v[146:149], v[216:219], v[22:25]
	v_mfma_f32_16x16x32_bf16 v[18:21], v[154:157], v[216:219], v[18:21]
	v_mfma_f32_16x16x32_bf16 v[6:9], v[146:149], v[224:227], v[6:9]
	v_mfma_f32_16x16x32_bf16 v[2:5], v[154:157], v[224:227], v[2:5]
	v_mfma_f32_16x16x32_bf16 v[54:57], v[150:153], v[198:201], v[54:57]
	v_mfma_f32_16x16x32_bf16 v[50:53], v[158:161], v[198:201], v[50:53]
	v_mfma_f32_16x16x32_bf16 v[38:41], v[150:153], v[212:215], v[38:41]
	v_mfma_f32_16x16x32_bf16 v[34:37], v[158:161], v[212:215], v[34:37]
	v_mfma_f32_16x16x32_bf16 v[22:25], v[150:153], v[220:223], v[22:25]
	v_mfma_f32_16x16x32_bf16 v[18:21], v[158:161], v[220:223], v[18:21]
	v_mfma_f32_16x16x32_bf16 v[6:9], v[150:153], v[228:231], v[6:9]
	v_mfma_f32_16x16x32_bf16 v[2:5], v[158:161], v[228:231], v[2:5]
	s_setprio 0
	s_add_i32 s82, s82, 2
	s_add_u32 s80, s80, 0x100
	s_addc_u32 s81, s81, 0
	s_add_u32 s38, s38, 0x100
	s_addc_u32 s39, s39, 0
	s_barrier
.LBB0_733:
	ds_read_b128 v[130:133], v191
	ds_read_b128 v[134:137], v191 offset:1024
	ds_read_b128 v[138:141], v191 offset:2048
	ds_read_b128 v[142:145], v191 offset:3072
	ds_read_b128 v[146:149], v193
	ds_read_b128 v[150:153], v193 offset:1024
	ds_read_b128 v[154:157], v193 offset:2048
	ds_read_b128 v[158:161], v193 offset:3072
	s_add_u32 s15, s38, 0xfffc0080
	s_addc_u32 s18, s39, -1
	s_cmp_eq_u32 s82, 12
	s_cselect_b32 s43, s29, s18
	s_cselect_b32 s42, s37, s15
	s_cselect_b32 s41, s27, s81
	s_cselect_b32 s40, s79, s80
	v_lshl_add_u64 v[194:195], s[38:39], 0, v[180:181]
	s_add_i32 m0, s55, 0xc000
	ds_read_b128 v[186:189], v197
	ds_read_b128 v[198:201], v197 offset:1024
	ds_read_b128 v[206:209], v197 offset:2048
	ds_read_b128 v[212:215], v197 offset:3072
	ds_read_b128 v[216:219], v197 offset:4096
	ds_read_b128 v[220:223], v197 offset:5120
	ds_read_b128 v[224:227], v197 offset:6144
	ds_read_b128 v[228:231], v197 offset:7168
	global_load_lds_dwordx4 v[194:195], off
	v_lshl_add_u64 v[194:195], s[38:39], 0, v[178:179]
	s_add_i32 m0, s55, 0xe000
	s_nop 0
	global_load_lds_dwordx4 v[194:195], off
	s_waitcnt vmcnt(8)
	s_waitcnt lgkmcnt(0)
	s_barrier
	s_setprio 1
	s_waitcnt lgkmcnt(0)
	v_mfma_f32_16x16x32_bf16 v[126:129], v[130:133], v[186:189], v[126:129]
	v_mfma_f32_16x16x32_bf16 v[122:125], v[138:141], v[186:189], v[122:125]
	v_mfma_f32_16x16x32_bf16 v[110:113], v[130:133], v[206:209], v[110:113]
	v_mfma_f32_16x16x32_bf16 v[106:109], v[138:141], v[206:209], v[106:109]
	v_mfma_f32_16x16x32_bf16 v[94:97], v[130:133], v[216:219], v[94:97]
	v_mfma_f32_16x16x32_bf16 v[90:93], v[138:141], v[216:219], v[90:93]
	v_mfma_f32_16x16x32_bf16 v[78:81], v[130:133], v[224:227], v[78:81]
	v_mfma_f32_16x16x32_bf16 v[74:77], v[138:141], v[224:227], v[74:77]
	v_mfma_f32_16x16x32_bf16 v[126:129], v[134:137], v[198:201], v[126:129]
	v_mfma_f32_16x16x32_bf16 v[122:125], v[142:145], v[198:201], v[122:125]
	v_mfma_f32_16x16x32_bf16 v[110:113], v[134:137], v[212:215], v[110:113]
	v_mfma_f32_16x16x32_bf16 v[106:109], v[142:145], v[212:215], v[106:109]
	v_mfma_f32_16x16x32_bf16 v[94:97], v[134:137], v[220:223], v[94:97]
	v_mfma_f32_16x16x32_bf16 v[90:93], v[142:145], v[220:223], v[90:93]
	v_mfma_f32_16x16x32_bf16 v[78:81], v[134:137], v[228:231], v[78:81]
	v_mfma_f32_16x16x32_bf16 v[74:77], v[142:145], v[228:231], v[74:77]
	s_setprio 0
	s_setprio 1
	v_mfma_f32_16x16x32_bf16 v[118:121], v[146:149], v[186:189], v[118:121]
	v_mfma_f32_16x16x32_bf16 v[114:117], v[154:157], v[186:189], v[114:117]
	v_mfma_f32_16x16x32_bf16 v[102:105], v[146:149], v[206:209], v[102:105]
	v_mfma_f32_16x16x32_bf16 v[98:101], v[154:157], v[206:209], v[98:101]
	v_mfma_f32_16x16x32_bf16 v[86:89], v[146:149], v[216:219], v[86:89]
	v_mfma_f32_16x16x32_bf16 v[82:85], v[154:157], v[216:219], v[82:85]
	v_mfma_f32_16x16x32_bf16 v[70:73], v[146:149], v[224:227], v[70:73]
	v_mfma_f32_16x16x32_bf16 v[66:69], v[154:157], v[224:227], v[66:69]
	v_mfma_f32_16x16x32_bf16 v[118:121], v[150:153], v[198:201], v[118:121]
	v_mfma_f32_16x16x32_bf16 v[114:117], v[158:161], v[198:201], v[114:117]
	v_mfma_f32_16x16x32_bf16 v[102:105], v[150:153], v[212:215], v[102:105]
	v_mfma_f32_16x16x32_bf16 v[98:101], v[158:161], v[212:215], v[98:101]
	v_mfma_f32_16x16x32_bf16 v[86:89], v[150:153], v[220:223], v[86:89]
	v_mfma_f32_16x16x32_bf16 v[82:85], v[158:161], v[220:223], v[82:85]
	v_mfma_f32_16x16x32_bf16 v[70:73], v[150:153], v[228:231], v[70:73]
	v_mfma_f32_16x16x32_bf16 v[66:69], v[158:161], v[228:231], v[66:69]
	s_setprio 0
	s_barrier
; #define PG8_STAGE(bufoff, gbase, voff) do { _Pragma("unroll") for (int _i = 0; _i < 2; ++_i) \
;         __builtin_amdgcn_global_load_lds((const unsigned*)((const char*)(gbase) + (voff)[_i]), (PG8_LAS unsigned*)(lds + (bufoff) + ldsw + _i * 8192), 16, 0, 0); } while (0)
; #define PG8_LDA(dst, b, h) do { _Pragma("unroll") for (int m = 0; m < 4; ++m) _Pragma("unroll") for (int k = 0; k < 2; ++k) dst[m][k] = *(const PG8_LAS bf16x8*)(lds + PG8_SA(b, h) + aoff + m * 2048 + k * 1024); } while (0)
; #define PG8_LDB(dst, b, h) do { _Pragma("unroll") for (int n = 0; n < 2; ++n) _Pragma("unroll") for (int k = 0; k < 2; ++k) dst[n][k] = *(const PG8_LAS bf16x8*)(lds + PG8_SB(b, h) + boff + n * 2048 + k * 1024); } while (0)
; #define PG8_MMA(ai, bj, At, Bt) do { __builtin_amdgcn_s_setprio(1); _Pragma("unroll") for (int m = 0; m < 4; ++m) _Pragma("unroll") for (int n = 0; n < 2; ++n) _Pragma("unroll") for (int k = 0; k < 2; ++k) \
;         acc[ai][bj][m][n] = __builtin_amdgcn_mfma_f32_16x16x32_bf16(Bt[n][k], At[m][k], acc[ai][bj][m][n], 0, 0, 0); __builtin_amdgcn_s_setprio(0); } while (0)
; #define PG8_WAIT_V(n) asm volatile("s_waitcnt vmcnt(" #n ")" ::: "memory")
; #define PG8_WAIT_L(n) asm volatile("s_waitcnt lgkmcnt(" #n ")" ::: "memory")
; #define PG8_BAR __builtin_amdgcn_s_barrier()
; #define PG8_SCHED __builtin_amdgcn_sched_barrier(0)
; template <class Epi, class Sched, bool ALIGN_EPI = false, bool SP2 = false>
; __device__ __forceinline__ void gemm_phase(PG8_LAS unsigned char* lds, const Gemm g, const Sched& S, const Epi& E, const int tid) {
;     ...
;             PG8_LDA(At, 0, 1); PG8_STAGE(PG8_SB(0, 0), b2, voffB); PG8_STAGE(PG8_SB(0, 1), b2 + hstep, voffB); PG8_STAGE(PG8_SA(0, 0), a2, voffA);
;             PG8_WAIT_V(8); PG8_WAIT_L(0); PG8_BAR; PG8_MMA(1, 0, At, B0); PG8_MMA(1, 1, At, B1); PG8_BAR; PG8_SCHED;
;             PG8_LDB(B0, 1, 0); PG8_LDB(B1, 1, 1); PG8_SCHED; PG8_LDA(At, 1, 0); PG8_STAGE(PG8_SA(0, 1), a2 + hstep, voffA);
;             PG8_WAIT_V(8); PG8_WAIT_L(0); PG8_BAR; PG8_MMA(0, 0, At, B0); PG8_MMA(0, 1, At, B1); PG8_BAR; PG8_SCHED;
	s_add_i32 s15, s66, s54
	v_lshl_add_u64 v[194:195], s[40:41], 0, v[164:165]
	s_mov_b32 m0, s15
	ds_read_b128 v[186:189], v197 offset:16384
	ds_read_b128 v[198:201], v197 offset:17408
	ds_read_b128 v[206:209], v197 offset:18432
	ds_read_b128 v[212:215], v197 offset:19456
	ds_read_b128 v[216:219], v197 offset:20480
	ds_read_b128 v[220:223], v197 offset:21504
	ds_read_b128 v[224:227], v197 offset:22528
	ds_read_b128 v[228:231], v197 offset:23552
	global_load_lds_dwordx4 v[194:195], off
	s_add_i32 m0, s15, 0x2000
	s_add_u32 s18, s40, 0x40000
	v_lshl_add_u64 v[232:233], s[40:41], 0, v[168:169]
	s_addc_u32 s19, s41, 0
	s_add_i32 s15, s67, s54
	global_load_lds_dwordx4 v[232:233], off
	v_lshl_add_u64 v[234:235], s[18:19], 0, v[164:165]
	s_mov_b32 m0, s15
	v_lshl_add_u64 v[236:237], s[42:43], 0, v[166:167]
	global_load_lds_dwordx4 v[234:235], off
	v_lshl_add_u64 v[234:235], s[18:19], 0, v[168:169]
	s_add_i32 m0, s15, 0x2000
	s_nop 0
	global_load_lds_dwordx4 v[234:235], off
	v_lshl_add_u64 v[234:235], s[42:43], 0, v[162:163]
	s_mov_b32 m0, s55
	s_nop 0
	global_load_lds_dwordx4 v[234:235], off
	s_mov_b32 m0, s56
	s_nop 0
	global_load_lds_dwordx4 v[236:237], off
	s_waitcnt vmcnt(8)
	s_waitcnt lgkmcnt(0)
	s_barrier
	s_setprio 1
	s_waitcnt lgkmcnt(0)
	v_mfma_f32_16x16x32_bf16 v[62:65], v[130:133], v[186:189], v[62:65]
	v_mfma_f32_16x16x32_bf16 v[58:61], v[138:141], v[186:189], v[58:61]
	v_mfma_f32_16x16x32_bf16 v[46:49], v[130:133], v[206:209], v[46:49]
	v_mfma_f32_16x16x32_bf16 v[42:45], v[138:141], v[206:209], v[42:45]
	v_mfma_f32_16x16x32_bf16 v[30:33], v[130:133], v[216:219], v[30:33]
	v_mfma_f32_16x16x32_bf16 v[26:29], v[138:141], v[216:219], v[26:29]
	v_mfma_f32_16x16x32_bf16 v[14:17], v[130:133], v[224:227], v[14:17]
	v_mfma_f32_16x16x32_bf16 v[10:13], v[138:141], v[224:227], v[10:13]
	v_mfma_f32_16x16x32_bf16 v[62:65], v[134:137], v[198:201], v[62:65]
	v_mfma_f32_16x16x32_bf16 v[58:61], v[142:145], v[198:201], v[58:61]
	v_mfma_f32_16x16x32_bf16 v[46:49], v[134:137], v[212:215], v[46:49]
	v_mfma_f32_16x16x32_bf16 v[42:45], v[142:145], v[212:215], v[42:45]
	v_mfma_f32_16x16x32_bf16 v[30:33], v[134:137], v[220:223], v[30:33]
	v_mfma_f32_16x16x32_bf16 v[26:29], v[142:145], v[220:223], v[26:29]
	v_mfma_f32_16x16x32_bf16 v[14:17], v[134:137], v[228:231], v[14:17]
	v_mfma_f32_16x16x32_bf16 v[10:13], v[142:145], v[228:231], v[10:13]
	s_setprio 0
	s_setprio 1
	v_mfma_f32_16x16x32_bf16 v[54:57], v[146:149], v[186:189], v[54:57]
	v_mfma_f32_16x16x32_bf16 v[50:53], v[154:157], v[186:189], v[50:53]
	v_mfma_f32_16x16x32_bf16 v[38:41], v[146:149], v[206:209], v[38:41]
	v_mfma_f32_16x16x32_bf16 v[34:37], v[154:157], v[206:209], v[34:37]
	v_mfma_f32_16x16x32_bf16 v[22:25], v[146:149], v[216:219], v[22:25]
	v_mfma_f32_16x16x32_bf16 v[18:21], v[154:157], v[216:219], v[18:21]
	v_mfma_f32_16x16x32_bf16 v[6:9], v[146:149], v[224:227], v[6:9]
	v_mfma_f32_16x16x32_bf16 v[2:5], v[154:157], v[224:227], v[2:5]
	v_mfma_f32_16x16x32_bf16 v[54:57], v[150:153], v[198:201], v[54:57]
	v_mfma_f32_16x16x32_bf16 v[50:53], v[158:161], v[198:201], v[50:53]
	v_mfma_f32_16x16x32_bf16 v[38:41], v[150:153], v[212:215], v[38:41]
	v_mfma_f32_16x16x32_bf16 v[34:37], v[158:161], v[212:215], v[34:37]
	v_mfma_f32_16x16x32_bf16 v[22:25], v[150:153], v[220:223], v[22:25]
	v_mfma_f32_16x16x32_bf16 v[18:21], v[158:161], v[220:223], v[18:21]
	v_mfma_f32_16x16x32_bf16 v[6:9], v[150:153], v[228:231], v[6:9]
	v_mfma_f32_16x16x32_bf16 v[2:5], v[158:161], v[228:231], v[2:5]
	s_setprio 0
	s_barrier
	s_add_i32 s15, 0, 0x18000
	s_add_i32 s83, 0, 0x1c000
	v_add_u32_e32 v142, s15, v173
	v_add_u32_e32 v158, s83, v173
	ds_read_b128 v[130:133], v142
	ds_read_b128 v[134:137], v142 offset:1024
	ds_read_b128 v[138:141], v142 offset:2048
	ds_read_b128 v[142:145], v142 offset:3072
	ds_read_b128 v[146:149], v158
	ds_read_b128 v[150:153], v158 offset:1024
	ds_read_b128 v[154:157], v158 offset:2048
	ds_read_b128 v[158:161], v158 offset:3072
	s_add_u32 s18, s42, 0x40000
	s_addc_u32 s19, s43, 0
	s_mov_b32 m0, s57
	v_lshl_add_u64 v[238:239], s[18:19], 0, v[162:163]
	ds_read_b128 v[186:189], v197 offset:32768
	ds_read_b128 v[198:201], v197 offset:33792
	ds_read_b128 v[206:209], v197 offset:34816
	ds_read_b128 v[212:215], v197 offset:35840
	ds_read_b128 v[216:219], v197 offset:36864
	ds_read_b128 v[220:223], v197 offset:37888
	ds_read_b128 v[224:227], v197 offset:38912
	ds_read_b128 v[228:231], v197 offset:39936
	global_load_lds_dwordx4 v[238:239], off
	v_lshl_add_u64 v[238:239], s[18:19], 0, v[166:167]
	s_mov_b32 m0, s58
	s_nop 0
	global_load_lds_dwordx4 v[238:239], off
	s_waitcnt vmcnt(8)
	s_waitcnt lgkmcnt(0)
	s_barrier
; #define PG8_STAGE(bufoff, gbase, voff) do { _Pragma("unroll") for (int _i = 0; _i < 2; ++_i) \
;         __builtin_amdgcn_global_load_lds((const unsigned*)((const char*)(gbase) + (voff)[_i]), (PG8_LAS unsigned*)(lds + (bufoff) + ldsw + _i * 8192), 16, 0, 0); } while (0)
; #define PG8_LDA(dst, b, h) do { _Pragma("unroll") for (int m = 0; m < 4; ++m) _Pragma("unroll") for (int k = 0; k < 2; ++k) dst[m][k] = *(const PG8_LAS bf16x8*)(lds + PG8_SA(b, h) + aoff + m * 2048 + k * 1024); } while (0)
; #define PG8_MMA(ai, bj, At, Bt) do { __builtin_amdgcn_s_setprio(1); _Pragma("unroll") for (int m = 0; m < 4; ++m) _Pragma("unroll") for (int n = 0; n < 2; ++n) _Pragma("unroll") for (int k = 0; k < 2; ++k) \
;         acc[ai][bj][m][n] = __builtin_amdgcn_mfma_f32_16x16x32_bf16(Bt[n][k], At[m][k], acc[ai][bj][m][n], 0, 0, 0); __builtin_amdgcn_s_setprio(0); } while (0)
; #define PG8_WAIT_V(n) asm volatile("s_waitcnt vmcnt(" #n ")" ::: "memory")
; #define PG8_WAIT_L(n) asm volatile("s_waitcnt lgkmcnt(" #n ")" ::: "memory")
; #define PG8_BAR __builtin_amdgcn_s_barrier()
; #define PG8_SCHED __builtin_amdgcn_sched_barrier(0)
; template <class Epi, class Sched, bool ALIGN_EPI = false, bool SP2 = false>
; __device__ __forceinline__ void gemm_phase(PG8_LAS unsigned char* lds, const Gemm g, const Sched& S, const Epi& E, const int tid) {
;     ...
;             PG8_WAIT_V(8); PG8_WAIT_L(0); PG8_BAR; PG8_MMA(0, 0, At, B0); PG8_MMA(0, 1, At, B1); PG8_BAR; PG8_SCHED;
;             PG8_LDA(At, 1, 1); PG8_STAGE(PG8_SB(1, 0), b3, voffB); PG8_STAGE(PG8_SB(1, 1), b3 + hstep, voffB); PG8_STAGE(PG8_SA(1, 0), a3, voffA);
;             PG8_WAIT_V(8); PG8_WAIT_L(0); PG8_BAR; PG8_MMA(1, 0, At, B0); PG8_MMA(1, 1, At, B1); PG8_BAR; PG8_SCHED;
;     ...
;         if constexpr (ALIGN_EPI) { if (wr == 0) PG8_BAR; }
	s_setprio 1
	s_waitcnt lgkmcnt(0)
	v_mfma_f32_16x16x32_bf16 v[126:129], v[130:133], v[186:189], v[126:129]
	v_mfma_f32_16x16x32_bf16 v[122:125], v[138:141], v[186:189], v[122:125]
	v_mfma_f32_16x16x32_bf16 v[110:113], v[130:133], v[206:209], v[110:113]
	v_mfma_f32_16x16x32_bf16 v[106:109], v[138:141], v[206:209], v[106:109]
	v_mfma_f32_16x16x32_bf16 v[94:97], v[130:133], v[216:219], v[94:97]
	v_mfma_f32_16x16x32_bf16 v[90:93], v[138:141], v[216:219], v[90:93]
	v_mfma_f32_16x16x32_bf16 v[78:81], v[130:133], v[224:227], v[78:81]
	v_mfma_f32_16x16x32_bf16 v[74:77], v[138:141], v[224:227], v[74:77]
	v_mfma_f32_16x16x32_bf16 v[126:129], v[134:137], v[198:201], v[126:129]
	v_mfma_f32_16x16x32_bf16 v[122:125], v[142:145], v[198:201], v[122:125]
	v_mfma_f32_16x16x32_bf16 v[110:113], v[134:137], v[212:215], v[110:113]
	v_mfma_f32_16x16x32_bf16 v[106:109], v[142:145], v[212:215], v[106:109]
	v_mfma_f32_16x16x32_bf16 v[94:97], v[134:137], v[220:223], v[94:97]
	v_mfma_f32_16x16x32_bf16 v[90:93], v[142:145], v[220:223], v[90:93]
	v_mfma_f32_16x16x32_bf16 v[78:81], v[134:137], v[228:231], v[78:81]
	v_mfma_f32_16x16x32_bf16 v[74:77], v[142:145], v[228:231], v[74:77]
	s_setprio 0
	s_setprio 1
	v_mfma_f32_16x16x32_bf16 v[118:121], v[146:149], v[186:189], v[118:121]
	v_mfma_f32_16x16x32_bf16 v[114:117], v[154:157], v[186:189], v[114:117]
	v_mfma_f32_16x16x32_bf16 v[102:105], v[146:149], v[206:209], v[102:105]
	v_mfma_f32_16x16x32_bf16 v[98:101], v[154:157], v[206:209], v[98:101]
	v_mfma_f32_16x16x32_bf16 v[86:89], v[146:149], v[216:219], v[86:89]
	v_mfma_f32_16x16x32_bf16 v[82:85], v[154:157], v[216:219], v[82:85]
	v_mfma_f32_16x16x32_bf16 v[70:73], v[146:149], v[224:227], v[70:73]
	v_mfma_f32_16x16x32_bf16 v[66:69], v[154:157], v[224:227], v[66:69]
	v_mfma_f32_16x16x32_bf16 v[118:121], v[150:153], v[198:201], v[118:121]
	v_mfma_f32_16x16x32_bf16 v[114:117], v[158:161], v[198:201], v[114:117]
	v_mfma_f32_16x16x32_bf16 v[102:105], v[150:153], v[212:215], v[102:105]
	v_mfma_f32_16x16x32_bf16 v[98:101], v[158:161], v[212:215], v[98:101]
	v_mfma_f32_16x16x32_bf16 v[86:89], v[150:153], v[220:223], v[86:89]
	v_mfma_f32_16x16x32_bf16 v[82:85], v[158:161], v[220:223], v[82:85]
	v_mfma_f32_16x16x32_bf16 v[70:73], v[150:153], v[228:231], v[70:73]
	v_mfma_f32_16x16x32_bf16 v[66:69], v[158:161], v[228:231], v[66:69]
	s_setprio 0
	s_barrier
	s_add_i32 s15, s15, s54
	v_lshl_add_u64 v[194:195], v[194:195], 0, s[10:11]
	s_mov_b32 m0, s15
	ds_read_b128 v[186:189], v197 offset:49152
	ds_read_b128 v[198:201], v197 offset:50176
	ds_read_b128 v[206:209], v197 offset:51200
	ds_read_b128 v[212:215], v197 offset:52224
	ds_read_b128 v[216:219], v197 offset:53248
	ds_read_b128 v[220:223], v197 offset:54272
	ds_read_b128 v[224:227], v197 offset:55296
	ds_read_b128 v[228:231], v197 offset:56320
	global_load_lds_dwordx4 v[194:195], off
	s_add_i32 m0, s15, 0x2000
	s_add_u32 s18, s40, 0x40080
	v_lshl_add_u64 v[194:195], v[232:233], 0, s[10:11]
	s_addc_u32 s19, s41, 0
	s_add_i32 s15, s83, s54
	global_load_lds_dwordx4 v[194:195], off
	v_lshl_add_u64 v[194:195], s[18:19], 0, v[164:165]
	s_mov_b32 m0, s15
	s_nop 0
	global_load_lds_dwordx4 v[194:195], off
	v_lshl_add_u64 v[194:195], s[18:19], 0, v[168:169]
	s_add_i32 m0, s15, 0x2000
	s_nop 0
	global_load_lds_dwordx4 v[194:195], off
	v_lshl_add_u64 v[194:195], v[234:235], 0, s[10:11]
	s_mov_b32 m0, s61
	s_nop 0
	global_load_lds_dwordx4 v[194:195], off
	v_lshl_add_u64 v[194:195], v[236:237], 0, s[10:11]
	s_mov_b32 m0, s62
	s_nop 0
	global_load_lds_dwordx4 v[194:195], off
	s_waitcnt vmcnt(8)
	s_waitcnt lgkmcnt(0)
	s_barrier
	s_setprio 1
	s_waitcnt lgkmcnt(0)
	v_mfma_f32_16x16x32_bf16 v[62:65], v[130:133], v[186:189], v[62:65]
	v_mfma_f32_16x16x32_bf16 v[58:61], v[138:141], v[186:189], v[58:61]
	v_mfma_f32_16x16x32_bf16 v[46:49], v[130:133], v[206:209], v[46:49]
	v_mfma_f32_16x16x32_bf16 v[42:45], v[138:141], v[206:209], v[42:45]
	v_mfma_f32_16x16x32_bf16 v[30:33], v[130:133], v[216:219], v[30:33]
	v_mfma_f32_16x16x32_bf16 v[26:29], v[138:141], v[216:219], v[26:29]
	v_mfma_f32_16x16x32_bf16 v[14:17], v[130:133], v[224:227], v[14:17]
	v_mfma_f32_16x16x32_bf16 v[10:13], v[138:141], v[224:227], v[10:13]
	v_mfma_f32_16x16x32_bf16 v[62:65], v[134:137], v[198:201], v[62:65]
	v_mfma_f32_16x16x32_bf16 v[58:61], v[142:145], v[198:201], v[58:61]
	v_mfma_f32_16x16x32_bf16 v[46:49], v[134:137], v[212:215], v[46:49]
	v_mfma_f32_16x16x32_bf16 v[42:45], v[142:145], v[212:215], v[42:45]
	v_mfma_f32_16x16x32_bf16 v[30:33], v[134:137], v[220:223], v[30:33]
	v_mfma_f32_16x16x32_bf16 v[26:29], v[142:145], v[220:223], v[26:29]
	v_mfma_f32_16x16x32_bf16 v[14:17], v[134:137], v[228:231], v[14:17]
	v_mfma_f32_16x16x32_bf16 v[10:13], v[142:145], v[228:231], v[10:13]
	s_setprio 0
	s_setprio 1
	v_mfma_f32_16x16x32_bf16 v[54:57], v[146:149], v[186:189], v[54:57]
	v_mfma_f32_16x16x32_bf16 v[50:53], v[154:157], v[186:189], v[50:53]
	v_mfma_f32_16x16x32_bf16 v[38:41], v[146:149], v[206:209], v[38:41]
	v_mfma_f32_16x16x32_bf16 v[34:37], v[154:157], v[206:209], v[34:37]
	v_mfma_f32_16x16x32_bf16 v[22:25], v[146:149], v[216:219], v[22:25]
	v_mfma_f32_16x16x32_bf16 v[18:21], v[154:157], v[216:219], v[18:21]
	v_mfma_f32_16x16x32_bf16 v[6:9], v[146:149], v[224:227], v[6:9]
	v_mfma_f32_16x16x32_bf16 v[2:5], v[154:157], v[224:227], v[2:5]
	v_mfma_f32_16x16x32_bf16 v[54:57], v[150:153], v[198:201], v[54:57]
	v_mfma_f32_16x16x32_bf16 v[50:53], v[158:161], v[198:201], v[50:53]
	v_mfma_f32_16x16x32_bf16 v[38:41], v[150:153], v[212:215], v[38:41]
	v_mfma_f32_16x16x32_bf16 v[34:37], v[158:161], v[212:215], v[34:37]
	v_mfma_f32_16x16x32_bf16 v[22:25], v[150:153], v[220:223], v[22:25]
	v_mfma_f32_16x16x32_bf16 v[18:21], v[158:161], v[220:223], v[18:21]
	v_mfma_f32_16x16x32_bf16 v[6:9], v[150:153], v[228:231], v[6:9]
	v_mfma_f32_16x16x32_bf16 v[2:5], v[158:161], v[228:231], v[2:5]
	s_setprio 0
	s_add_i32 s82, s82, 2
	s_add_u32 s80, s80, 0x100
	s_addc_u32 s81, s81, 0
	s_add_u32 s38, s38, 0x100
	s_addc_u32 s39, s39, 0
	s_cmp_gt_u32 s82, 13
	s_barrier
	s_cbranch_scc0 .LBB0_733
	s_and_b64 vcc, exec, s[24:25]
	s_cbranch_vccz .LBB0_736
	s_barrier

; #define PG8_STAGE(bufoff, gbase, voff) do { _Pragma("unroll") for (int _i = 0; _i < 2; ++_i) \
;         __builtin_amdgcn_global_load_lds((const unsigned*)((const char*)(gbase) + (voff)[_i]), (PG8_LAS unsigned*)(lds + (bufoff) + ldsw + _i * 8192), 16, 0, 0); } while (0)
; #define PG8_LDA(dst, b, h) do { _Pragma("unroll") for (int m = 0; m < 4; ++m) _Pragma("unroll") for (int k = 0; k < 2; ++k) dst[m][k] = *(const PG8_LAS bf16x8*)(lds + PG8_SA(b, h) + aoff + m * 2048 + k * 1024); } while (0)
; #define PG8_LDB(dst, b, h) do { _Pragma("unroll") for (int n = 0; n < 2; ++n) _Pragma("unroll") for (int k = 0; k < 2; ++k) dst[n][k] = *(const PG8_LAS bf16x8*)(lds + PG8_SB(b, h) + boff + n * 2048 + k * 1024); } while (0)
; #define PG8_MMA(ai, bj, At, Bt) do { __builtin_amdgcn_s_setprio(1); _Pragma("unroll") for (int m = 0; m < 4; ++m) _Pragma("unroll") for (int n = 0; n < 2; ++n) _Pragma("unroll") for (int k = 0; k < 2; ++k) \
;         acc[ai][bj][m][n] = __builtin_amdgcn_mfma_f32_16x16x32_bf16(Bt[n][k], At[m][k], acc[ai][bj][m][n], 0, 0, 0); __builtin_amdgcn_s_setprio(0); } while (0)
; #define PG8_WAIT_V(n) asm volatile("s_waitcnt vmcnt(" #n ")" ::: "memory")
; #define PG8_WAIT_L(n) asm volatile("s_waitcnt lgkmcnt(" #n ")" ::: "memory")
; template <class Epi, class Sched, bool ALIGN_EPI = false, bool SP2 = false>
; __device__ __forceinline__ void gemm_phase(PG8_LAS unsigned char* lds, const Gemm g, const Sched& S, const Epi& E, const int tid) {
;     ...
;             const bool last = (t == nt - 2);
;             const char* a1 = cA + (size_t)(t + 1) * kstep;
;             const char* a2 = last ? nA : cA + (size_t)(t + 2) * kstep; const char* b2 = last ? nB : cB + (size_t)(t + 2) * kstep;
;             const char* a3 = a2 + kstep; const char* b3 = b2 + kstep;
;             if (last && has_next) S.a_ready(nxt);
;             if constexpr (SP2) {
;             PG8_LDB(B0, 0, 0); PG8_LDB(B1, 0, 1); PG8_SCHED; PG8_LDA(At, 0, 0); PG8_STAGE(PG8_SA(1, 1), a1 + hstep, voffA);
;             PG8_WAIT_V(8); PG8_WAIT_L(0); PG8_BAR; PG8_MMA(0, 0, At, B0); PG8_MMA(0, 1, At, B1); PG8_BAR; PG8_SCHED;
;             PG8_LDA(At, 0, 1); PG8_STAGE(PG8_SB(0, 0), b2, voffB); PG8_STAGE(PG8_SB(0, 1), b2 + hstep, voffB); PG8_STAGE(PG8_SA(0, 0), a2, voffA);
;             PG8_WAIT_V(8); PG8_WAIT_L(0); PG8_BAR; PG8_MMA(1, 0, At, B0); PG8_MMA(1, 1, At, B1); PG8_BAR; PG8_SCHED;
.LBB0_1121:
	s_add_u32 s5, s56, 0x100
	s_addc_u32 s49, s57, 0
	s_add_u32 s56, s58, 0x40080
	s_addc_u32 s57, s59, 0
	s_mov_b32 s51, -2
	s_add_u32 s15, s56, 0xfffc0080
	s_addc_u32 s18, s57, -1
	s_cmp_eq_u32 s51, 12
	s_cselect_b32 s61, s1, s18
	s_cselect_b32 s60, s0, s15
	s_cselect_b32 s59, s53, s49
	s_cselect_b32 s58, s52, s5
	v_lshl_add_u64 v[170:171], s[56:57], 0, v[156:157]
	s_add_i32 m0, s67, 0xc000
	global_load_lds_dwordx4 v[170:171], off
	v_lshl_add_u64 v[170:171], s[56:57], 0, v[154:155]
	s_add_i32 m0, s67, 0xe000
	s_nop 0
	global_load_lds_dwordx4 v[170:171], off
	s_waitcnt vmcnt(8)
	s_waitcnt lgkmcnt(0)
	s_barrier
	s_setprio 1
	s_waitcnt lgkmcnt(0)
	v_mfma_f32_16x16x32_bf16 v[126:129], v[130:133], v[196:199], 0
	v_mfma_f32_16x16x32_bf16 v[122:125], v[162:165], v[196:199], 0
	v_mfma_f32_16x16x32_bf16 v[110:113], v[130:133], v[204:207], 0
	v_mfma_f32_16x16x32_bf16 v[106:109], v[162:165], v[204:207], 0
	v_mfma_f32_16x16x32_bf16 v[94:97], v[130:133], v[212:215], 0
	v_mfma_f32_16x16x32_bf16 v[90:93], v[162:165], v[212:215], 0
	v_mfma_f32_16x16x32_bf16 v[78:81], v[130:133], v[220:223], 0
	v_mfma_f32_16x16x32_bf16 v[74:77], v[162:165], v[220:223], 0
	v_mfma_f32_16x16x32_bf16 v[126:129], v[134:137], v[200:203], v[126:129]
	v_mfma_f32_16x16x32_bf16 v[122:125], v[166:169], v[200:203], v[122:125]
	v_mfma_f32_16x16x32_bf16 v[110:113], v[134:137], v[208:211], v[110:113]
	v_mfma_f32_16x16x32_bf16 v[106:109], v[166:169], v[208:211], v[106:109]
	v_mfma_f32_16x16x32_bf16 v[94:97], v[134:137], v[216:219], v[94:97]
	v_mfma_f32_16x16x32_bf16 v[90:93], v[166:169], v[216:219], v[90:93]
	v_mfma_f32_16x16x32_bf16 v[78:81], v[134:137], v[224:227], v[78:81]
	v_mfma_f32_16x16x32_bf16 v[74:77], v[166:169], v[224:227], v[74:77]
	s_setprio 0
	s_setprio 1
	v_mfma_f32_16x16x32_bf16 v[118:121], v[176:179], v[196:199], 0
	v_mfma_f32_16x16x32_bf16 v[114:117], v[184:187], v[196:199], 0
	v_mfma_f32_16x16x32_bf16 v[102:105], v[176:179], v[204:207], 0
	v_mfma_f32_16x16x32_bf16 v[98:101], v[184:187], v[204:207], 0
	v_mfma_f32_16x16x32_bf16 v[86:89], v[176:179], v[212:215], 0
	v_mfma_f32_16x16x32_bf16 v[82:85], v[184:187], v[212:215], 0
	v_mfma_f32_16x16x32_bf16 v[70:73], v[176:179], v[220:223], 0
	v_mfma_f32_16x16x32_bf16 v[66:69], v[184:187], v[220:223], 0
	v_mfma_f32_16x16x32_bf16 v[118:121], v[180:183], v[200:203], v[118:121]
	v_mfma_f32_16x16x32_bf16 v[114:117], v[192:195], v[200:203], v[114:117]
	v_mfma_f32_16x16x32_bf16 v[102:105], v[180:183], v[208:211], v[102:105]
	v_mfma_f32_16x16x32_bf16 v[98:101], v[192:195], v[208:211], v[98:101]
	v_mfma_f32_16x16x32_bf16 v[86:89], v[180:183], v[216:219], v[86:89]
	v_mfma_f32_16x16x32_bf16 v[82:85], v[192:195], v[216:219], v[82:85]
	v_mfma_f32_16x16x32_bf16 v[70:73], v[180:183], v[224:227], v[70:73]
	v_mfma_f32_16x16x32_bf16 v[66:69], v[192:195], v[224:227], v[66:69]
	s_setprio 0
	s_barrier
	s_add_i32 s15, s86, s66
	v_lshl_add_u64 v[170:171], s[58:59], 0, v[142:143]
	s_mov_b32 m0, s15
	ds_read_b128 v[196:199], v174 offset:16384
	ds_read_b128 v[200:203], v174 offset:17408
	ds_read_b128 v[204:207], v174 offset:18432
	ds_read_b128 v[208:211], v174 offset:19456
	ds_read_b128 v[212:215], v174 offset:20480
	ds_read_b128 v[216:219], v174 offset:21504
	ds_read_b128 v[220:223], v174 offset:22528
	ds_read_b128 v[224:227], v174 offset:23552
	global_load_lds_dwordx4 v[170:171], off
	s_add_i32 m0, s15, 0x2000
	s_add_u32 s18, s58, 0x40000
	v_lshl_add_u64 v[188:189], s[58:59], 0, v[146:147]
	s_addc_u32 s19, s59, 0
	s_add_i32 s15, s87, s66
	global_load_lds_dwordx4 v[188:189], off
	v_lshl_add_u64 v[228:229], s[18:19], 0, v[142:143]
	s_mov_b32 m0, s15
	v_lshl_add_u64 v[230:231], s[60:61], 0, v[144:145]
	global_load_lds_dwordx4 v[228:229], off
	v_lshl_add_u64 v[228:229], s[18:19], 0, v[146:147]
	s_add_i32 m0, s15, 0x2000
	s_nop 0
	global_load_lds_dwordx4 v[228:229], off
	v_lshl_add_u64 v[228:229], s[60:61], 0, v[140:141]
	s_mov_b32 m0, s67
	s_nop 0
	global_load_lds_dwordx4 v[228:229], off
	s_mov_b32 m0, s68
	s_nop 0
	global_load_lds_dwordx4 v[230:231], off
	s_waitcnt vmcnt(8)
	s_waitcnt lgkmcnt(0)
	s_barrier
	s_setprio 1
	s_waitcnt lgkmcnt(0)
	v_mfma_f32_16x16x32_bf16 v[62:65], v[130:133], v[196:199], 0
	v_mfma_f32_16x16x32_bf16 v[58:61], v[162:165], v[196:199], 0
	v_mfma_f32_16x16x32_bf16 v[46:49], v[130:133], v[204:207], 0
	v_mfma_f32_16x16x32_bf16 v[42:45], v[162:165], v[204:207], 0
	v_mfma_f32_16x16x32_bf16 v[30:33], v[130:133], v[212:215], 0
	v_mfma_f32_16x16x32_bf16 v[26:29], v[162:165], v[212:215], 0
	v_mfma_f32_16x16x32_bf16 v[14:17], v[130:133], v[220:223], 0
	v_mfma_f32_16x16x32_bf16 v[10:13], v[162:165], v[220:223], 0
	v_mfma_f32_16x16x32_bf16 v[62:65], v[134:137], v[200:203], v[62:65]
	v_mfma_f32_16x16x32_bf16 v[58:61], v[166:169], v[200:203], v[58:61]
	v_mfma_f32_16x16x32_bf16 v[46:49], v[134:137], v[208:211], v[46:49]
	v_mfma_f32_16x16x32_bf16 v[42:45], v[166:169], v[208:211], v[42:45]
	v_mfma_f32_16x16x32_bf16 v[30:33], v[134:137], v[216:219], v[30:33]
	v_mfma_f32_16x16x32_bf16 v[26:29], v[166:169], v[216:219], v[26:29]
	v_mfma_f32_16x16x32_bf16 v[14:17], v[134:137], v[224:227], v[14:17]
	v_mfma_f32_16x16x32_bf16 v[10:13], v[166:169], v[224:227], v[10:13]
	s_setprio 0
	s_setprio 1
	v_mfma_f32_16x16x32_bf16 v[54:57], v[176:179], v[196:199], 0
	v_mfma_f32_16x16x32_bf16 v[50:53], v[184:187], v[196:199], 0
	v_mfma_f32_16x16x32_bf16 v[38:41], v[176:179], v[204:207], 0
	v_mfma_f32_16x16x32_bf16 v[34:37], v[184:187], v[204:207], 0
	v_mfma_f32_16x16x32_bf16 v[22:25], v[176:179], v[212:215], 0
	v_mfma_f32_16x16x32_bf16 v[18:21], v[184:187], v[212:215], 0
	v_mfma_f32_16x16x32_bf16 v[6:9], v[176:179], v[220:223], 0
	v_mfma_f32_16x16x32_bf16 v[2:5], v[184:187], v[220:223], 0
	v_mfma_f32_16x16x32_bf16 v[54:57], v[180:183], v[200:203], v[54:57]
	v_mfma_f32_16x16x32_bf16 v[50:53], v[192:195], v[200:203], v[50:53]
	v_mfma_f32_16x16x32_bf16 v[38:41], v[180:183], v[208:211], v[38:41]
	v_mfma_f32_16x16x32_bf16 v[34:37], v[192:195], v[208:211], v[34:37]
	v_mfma_f32_16x16x32_bf16 v[22:25], v[180:183], v[216:219], v[22:25]
	v_mfma_f32_16x16x32_bf16 v[18:21], v[192:195], v[216:219], v[18:21]
	v_mfma_f32_16x16x32_bf16 v[6:9], v[180:183], v[224:227], v[6:9]
	v_mfma_f32_16x16x32_bf16 v[2:5], v[192:195], v[224:227], v[2:5]
	s_setprio 0
	s_barrier
; #define PG8_STAGE(bufoff, gbase, voff) do { _Pragma("unroll") for (int _i = 0; _i < 2; ++_i) \
;         __builtin_amdgcn_global_load_lds((const unsigned*)((const char*)(gbase) + (voff)[_i]), (PG8_LAS unsigned*)(lds + (bufoff) + ldsw + _i * 8192), 16, 0, 0); } while (0)
; #define PG8_LDA(dst, b, h) do { _Pragma("unroll") for (int m = 0; m < 4; ++m) _Pragma("unroll") for (int k = 0; k < 2; ++k) dst[m][k] = *(const PG8_LAS bf16x8*)(lds + PG8_SA(b, h) + aoff + m * 2048 + k * 1024); } while (0)
; #define PG8_LDB(dst, b, h) do { _Pragma("unroll") for (int n = 0; n < 2; ++n) _Pragma("unroll") for (int k = 0; k < 2; ++k) dst[n][k] = *(const PG8_LAS bf16x8*)(lds + PG8_SB(b, h) + boff + n * 2048 + k * 1024); } while (0)
; #define PG8_MMA(ai, bj, At, Bt) do { __builtin_amdgcn_s_setprio(1); _Pragma("unroll") for (int m = 0; m < 4; ++m) _Pragma("unroll") for (int n = 0; n < 2; ++n) _Pragma("unroll") for (int k = 0; k < 2; ++k) \
;         acc[ai][bj][m][n] = __builtin_amdgcn_mfma_f32_16x16x32_bf16(Bt[n][k], At[m][k], acc[ai][bj][m][n], 0, 0, 0); __builtin_amdgcn_s_setprio(0); } while (0)
; #define PG8_WAIT_V(n) asm volatile("s_waitcnt vmcnt(" #n ")" ::: "memory")
; #define PG8_WAIT_L(n) asm volatile("s_waitcnt lgkmcnt(" #n ")" ::: "memory")
; #define PG8_BAR __builtin_amdgcn_s_barrier()
; #define PG8_SCHED __builtin_amdgcn_sched_barrier(0)
; template <class Epi, class Sched, bool ALIGN_EPI = false, bool SP2 = false>
; __device__ __forceinline__ void gemm_phase(PG8_LAS unsigned char* lds, const Gemm g, const Sched& S, const Epi& E, const int tid) {
;     ...
;             PG8_LDB(B0, 1, 0); PG8_LDB(B1, 1, 1); PG8_SCHED; PG8_LDA(At, 1, 0); PG8_STAGE(PG8_SA(0, 1), a2 + hstep, voffA);
;             PG8_WAIT_V(8); PG8_WAIT_L(0); PG8_BAR; PG8_MMA(0, 0, At, B0); PG8_MMA(0, 1, At, B1); PG8_BAR; PG8_SCHED;
;             PG8_LDA(At, 1, 1); PG8_STAGE(PG8_SB(1, 0), b3, voffB); PG8_STAGE(PG8_SB(1, 1), b3 + hstep, voffB); PG8_STAGE(PG8_SA(1, 0), a3, voffA);
	s_add_i32 s15, 0, 0x18000
	s_add_i32 s62, 0, 0x1c000
	v_add_u32_e32 v166, s15, v172
	v_add_u32_e32 v191, s62, v172
	ds_read_b128 v[130:133], v166
	ds_read_b128 v[134:137], v166 offset:1024
	ds_read_b128 v[162:165], v166 offset:2048
	ds_read_b128 v[166:169], v166 offset:3072
	ds_read_b128 v[176:179], v191
	ds_read_b128 v[180:183], v191 offset:1024
	ds_read_b128 v[184:187], v191 offset:2048
	ds_read_b128 v[192:195], v191 offset:3072
	s_add_u32 s18, s60, 0x40000
	s_addc_u32 s19, s61, 0
	s_mov_b32 m0, s69
	v_lshl_add_u64 v[232:233], s[18:19], 0, v[140:141]
	ds_read_b128 v[196:199], v174 offset:32768
	ds_read_b128 v[200:203], v174 offset:33792
	ds_read_b128 v[204:207], v174 offset:34816
	ds_read_b128 v[208:211], v174 offset:35840
	ds_read_b128 v[212:215], v174 offset:36864
	ds_read_b128 v[216:219], v174 offset:37888
	ds_read_b128 v[220:223], v174 offset:38912
	ds_read_b128 v[224:227], v174 offset:39936
	global_load_lds_dwordx4 v[232:233], off
	v_lshl_add_u64 v[232:233], s[18:19], 0, v[144:145]
	s_mov_b32 m0, s71
	s_nop 0
	global_load_lds_dwordx4 v[232:233], off
	s_waitcnt vmcnt(8)
	s_waitcnt lgkmcnt(0)
	s_barrier
	s_setprio 1
	s_waitcnt lgkmcnt(0)
	v_mfma_f32_16x16x32_bf16 v[126:129], v[130:133], v[196:199], v[126:129]
	v_mfma_f32_16x16x32_bf16 v[122:125], v[162:165], v[196:199], v[122:125]
	v_mfma_f32_16x16x32_bf16 v[110:113], v[130:133], v[204:207], v[110:113]
	v_mfma_f32_16x16x32_bf16 v[106:109], v[162:165], v[204:207], v[106:109]
	v_mfma_f32_16x16x32_bf16 v[94:97], v[130:133], v[212:215], v[94:97]
	v_mfma_f32_16x16x32_bf16 v[90:93], v[162:165], v[212:215], v[90:93]
	v_mfma_f32_16x16x32_bf16 v[78:81], v[130:133], v[220:223], v[78:81]
	v_mfma_f32_16x16x32_bf16 v[74:77], v[162:165], v[220:223], v[74:77]
	v_mfma_f32_16x16x32_bf16 v[126:129], v[134:137], v[200:203], v[126:129]
	v_mfma_f32_16x16x32_bf16 v[122:125], v[166:169], v[200:203], v[122:125]
	v_mfma_f32_16x16x32_bf16 v[110:113], v[134:137], v[208:211], v[110:113]
	v_mfma_f32_16x16x32_bf16 v[106:109], v[166:169], v[208:211], v[106:109]
	v_mfma_f32_16x16x32_bf16 v[94:97], v[134:137], v[216:219], v[94:97]
	v_mfma_f32_16x16x32_bf16 v[90:93], v[166:169], v[216:219], v[90:93]
	v_mfma_f32_16x16x32_bf16 v[78:81], v[134:137], v[224:227], v[78:81]
	v_mfma_f32_16x16x32_bf16 v[74:77], v[166:169], v[224:227], v[74:77]
	s_setprio 0
	s_setprio 1
	v_mfma_f32_16x16x32_bf16 v[118:121], v[176:179], v[196:199], v[118:121]
	v_mfma_f32_16x16x32_bf16 v[114:117], v[184:187], v[196:199], v[114:117]
	v_mfma_f32_16x16x32_bf16 v[102:105], v[176:179], v[204:207], v[102:105]
	v_mfma_f32_16x16x32_bf16 v[98:101], v[184:187], v[204:207], v[98:101]
	v_mfma_f32_16x16x32_bf16 v[86:89], v[176:179], v[212:215], v[86:89]
	v_mfma_f32_16x16x32_bf16 v[82:85], v[184:187], v[212:215], v[82:85]
	v_mfma_f32_16x16x32_bf16 v[70:73], v[176:179], v[220:223], v[70:73]
	v_mfma_f32_16x16x32_bf16 v[66:69], v[184:187], v[220:223], v[66:69]
	v_mfma_f32_16x16x32_bf16 v[118:121], v[180:183], v[200:203], v[118:121]
	v_mfma_f32_16x16x32_bf16 v[114:117], v[192:195], v[200:203], v[114:117]
	v_mfma_f32_16x16x32_bf16 v[102:105], v[180:183], v[208:211], v[102:105]
	v_mfma_f32_16x16x32_bf16 v[98:101], v[192:195], v[208:211], v[98:101]
	v_mfma_f32_16x16x32_bf16 v[86:89], v[180:183], v[216:219], v[86:89]
	v_mfma_f32_16x16x32_bf16 v[82:85], v[192:195], v[216:219], v[82:85]
	v_mfma_f32_16x16x32_bf16 v[70:73], v[180:183], v[224:227], v[70:73]
	v_mfma_f32_16x16x32_bf16 v[66:69], v[192:195], v[224:227], v[66:69]
	s_setprio 0
	s_barrier
	s_add_i32 s15, s15, s66
	v_lshl_add_u64 v[170:171], v[170:171], 0, s[44:45]
	s_mov_b32 m0, s15
	ds_read_b128 v[196:199], v174 offset:49152
	ds_read_b128 v[200:203], v174 offset:50176
	ds_read_b128 v[204:207], v174 offset:51200
	ds_read_b128 v[208:211], v174 offset:52224
	ds_read_b128 v[212:215], v174 offset:53248
	ds_read_b128 v[216:219], v174 offset:54272
	ds_read_b128 v[220:223], v174 offset:55296
	ds_read_b128 v[224:227], v174 offset:56320
	global_load_lds_dwordx4 v[170:171], off
	s_add_i32 m0, s15, 0x2000
	s_add_u32 s18, s58, 0x40080
	v_lshl_add_u64 v[170:171], v[188:189], 0, s[44:45]
	s_addc_u32 s19, s59, 0
	s_add_i32 s15, s62, s66
	global_load_lds_dwordx4 v[170:171], off
	v_lshl_add_u64 v[170:171], s[18:19], 0, v[142:143]
	s_mov_b32 m0, s15
	s_nop 0
	global_load_lds_dwordx4 v[170:171], off
	v_lshl_add_u64 v[170:171], s[18:19], 0, v[146:147]
	s_add_i32 m0, s15, 0x2000
	s_nop 0
	global_load_lds_dwordx4 v[170:171], off
	v_lshl_add_u64 v[170:171], v[228:229], 0, s[44:45]
	s_mov_b32 m0, s77
	s_nop 0
	global_load_lds_dwordx4 v[170:171], off
	v_lshl_add_u64 v[170:171], v[230:231], 0, s[44:45]
	s_mov_b32 m0, s78
	s_nop 0
	global_load_lds_dwordx4 v[170:171], off
	s_waitcnt vmcnt(8)
	s_waitcnt lgkmcnt(0)
	s_barrier
; #define PG8_STAGE(bufoff, gbase, voff) do { _Pragma("unroll") for (int _i = 0; _i < 2; ++_i) \
;         __builtin_amdgcn_global_load_lds((const unsigned*)((const char*)(gbase) + (voff)[_i]), (PG8_LAS unsigned*)(lds + (bufoff) + ldsw + _i * 8192), 16, 0, 0); } while (0)
; #define PG8_LDA(dst, b, h) do { _Pragma("unroll") for (int m = 0; m < 4; ++m) _Pragma("unroll") for (int k = 0; k < 2; ++k) dst[m][k] = *(const PG8_LAS bf16x8*)(lds + PG8_SA(b, h) + aoff + m * 2048 + k * 1024); } while (0)
; #define PG8_LDB(dst, b, h) do { _Pragma("unroll") for (int n = 0; n < 2; ++n) _Pragma("unroll") for (int k = 0; k < 2; ++k) dst[n][k] = *(const PG8_LAS bf16x8*)(lds + PG8_SB(b, h) + boff + n * 2048 + k * 1024); } while (0)
; template <class Epi, class Sched, bool ALIGN_EPI = false, bool SP2 = false>
; __device__ __forceinline__ void gemm_phase(PG8_LAS unsigned char* lds, const Gemm g, const Sched& S, const Epi& E, const int tid) {
;     ...
;         for (int t = 0; t < nt; t += 2) {
;             const bool last = (t == nt - 2);
;             const char* a1 = cA + (size_t)(t + 1) * kstep;
;             const char* a2 = last ? nA : cA + (size_t)(t + 2) * kstep; const char* b2 = last ? nB : cB + (size_t)(t + 2) * kstep;
;             const char* a3 = a2 + kstep; const char* b3 = b2 + kstep;
;             if (last && has_next) S.a_ready(nxt);
;     ...
;             PG8_LDB(B0, 0, 0); PG8_LDB(B1, 0, 1); PG8_SCHED; PG8_LDA(At, 0, 0); PG8_STAGE(PG8_SA(1, 1), a1 + hstep, voffA);
;             PG8_WAIT_V(8); PG8_WAIT_L(0); PG8_BAR; PG8_MMA(0, 0, At, B0); PG8_MMA(0, 1, At, B1); PG8_BAR; PG8_SCHED;
;             PG8_LDA(At, 0, 1); PG8_STAGE(PG8_SB(0, 0), b2, voffB); PG8_STAGE(PG8_SB(0, 1), b2 + hstep, voffB); PG8_STAGE(PG8_SA(0, 0), a2, voffA);
;             PG8_WAIT_V(8); PG8_WAIT_L(0); PG8_BAR; PG8_MMA(1, 0, At, B0); PG8_MMA(1, 1, At, B1); PG8_BAR; PG8_SCHED;
;             PG8_LDB(B0, 1, 0); PG8_LDB(B1, 1, 1); PG8_SCHED; PG8_LDA(At, 1, 0); PG8_STAGE(PG8_SA(0, 1), a2 + hstep, voffA);
;             PG8_WAIT_V(8); PG8_WAIT_L(0); PG8_BAR; PG8_MMA(0, 0, At, B0); PG8_MMA(0, 1, At, B1); PG8_BAR; PG8_SCHED;
;             PG8_LDA(At, 1, 1); PG8_STAGE(PG8_SB(1, 0), b3, voffB); PG8_STAGE(PG8_SB(1, 1), b3 + hstep, voffB); PG8_STAGE(PG8_SA(1, 0), a3, voffA);
;             PG8_WAIT_V(8); PG8_WAIT_L(0); PG8_BAR; PG8_MMA(1, 0, At, B0); PG8_MMA(1, 1, At, B1); PG8_BAR; PG8_SCHED;
	s_setprio 1
	s_waitcnt lgkmcnt(0)
	v_mfma_f32_16x16x32_bf16 v[62:65], v[130:133], v[196:199], v[62:65]
	v_mfma_f32_16x16x32_bf16 v[58:61], v[162:165], v[196:199], v[58:61]
	v_mfma_f32_16x16x32_bf16 v[46:49], v[130:133], v[204:207], v[46:49]
	v_mfma_f32_16x16x32_bf16 v[42:45], v[162:165], v[204:207], v[42:45]
	v_mfma_f32_16x16x32_bf16 v[30:33], v[130:133], v[212:215], v[30:33]
	v_mfma_f32_16x16x32_bf16 v[26:29], v[162:165], v[212:215], v[26:29]
	v_mfma_f32_16x16x32_bf16 v[14:17], v[130:133], v[220:223], v[14:17]
	v_mfma_f32_16x16x32_bf16 v[10:13], v[162:165], v[220:223], v[10:13]
	v_mfma_f32_16x16x32_bf16 v[62:65], v[134:137], v[200:203], v[62:65]
	v_mfma_f32_16x16x32_bf16 v[58:61], v[166:169], v[200:203], v[58:61]
	v_mfma_f32_16x16x32_bf16 v[46:49], v[134:137], v[208:211], v[46:49]
	v_mfma_f32_16x16x32_bf16 v[42:45], v[166:169], v[208:211], v[42:45]
	v_mfma_f32_16x16x32_bf16 v[30:33], v[134:137], v[216:219], v[30:33]
	v_mfma_f32_16x16x32_bf16 v[26:29], v[166:169], v[216:219], v[26:29]
	v_mfma_f32_16x16x32_bf16 v[14:17], v[134:137], v[224:227], v[14:17]
	v_mfma_f32_16x16x32_bf16 v[10:13], v[166:169], v[224:227], v[10:13]
	s_setprio 0
	s_setprio 1
	v_mfma_f32_16x16x32_bf16 v[54:57], v[176:179], v[196:199], v[54:57]
	v_mfma_f32_16x16x32_bf16 v[50:53], v[184:187], v[196:199], v[50:53]
	v_mfma_f32_16x16x32_bf16 v[38:41], v[176:179], v[204:207], v[38:41]
	v_mfma_f32_16x16x32_bf16 v[34:37], v[184:187], v[204:207], v[34:37]
	v_mfma_f32_16x16x32_bf16 v[22:25], v[176:179], v[212:215], v[22:25]
	v_mfma_f32_16x16x32_bf16 v[18:21], v[184:187], v[212:215], v[18:21]
	v_mfma_f32_16x16x32_bf16 v[6:9], v[176:179], v[220:223], v[6:9]
	v_mfma_f32_16x16x32_bf16 v[2:5], v[184:187], v[220:223], v[2:5]
	v_mfma_f32_16x16x32_bf16 v[54:57], v[180:183], v[200:203], v[54:57]
	v_mfma_f32_16x16x32_bf16 v[50:53], v[192:195], v[200:203], v[50:53]
	v_mfma_f32_16x16x32_bf16 v[38:41], v[180:183], v[208:211], v[38:41]
	v_mfma_f32_16x16x32_bf16 v[34:37], v[192:195], v[208:211], v[34:37]
	v_mfma_f32_16x16x32_bf16 v[22:25], v[180:183], v[216:219], v[22:25]
	v_mfma_f32_16x16x32_bf16 v[18:21], v[192:195], v[216:219], v[18:21]
	v_mfma_f32_16x16x32_bf16 v[6:9], v[180:183], v[224:227], v[6:9]
	v_mfma_f32_16x16x32_bf16 v[2:5], v[192:195], v[224:227], v[2:5]
	s_setprio 0
	s_add_i32 s51, s51, 2
	s_add_u32 s5, s5, 0x100
	s_addc_u32 s49, s49, 0
	s_add_u32 s56, s56, 0x100
	s_addc_u32 s57, s57, 0
	s_barrier
.LBB0_1122:
	ds_read_b128 v[130:133], v139
	ds_read_b128 v[134:137], v139 offset:1024
	ds_read_b128 v[162:165], v139 offset:2048
	ds_read_b128 v[166:169], v139 offset:3072
	ds_read_b128 v[176:179], v173
	ds_read_b128 v[180:183], v173 offset:1024
	ds_read_b128 v[184:187], v173 offset:2048
	ds_read_b128 v[192:195], v173 offset:3072
	s_add_u32 s15, s56, 0xfffc0080
	s_addc_u32 s18, s57, -1
	s_cmp_eq_u32 s51, 12
	s_cselect_b32 s61, s1, s18
	s_cselect_b32 s60, s0, s15
	s_cselect_b32 s59, s53, s49
	s_cselect_b32 s58, s52, s5
	v_lshl_add_u64 v[170:171], s[56:57], 0, v[156:157]
	s_add_i32 m0, s67, 0xc000
	ds_read_b128 v[196:199], v174
	ds_read_b128 v[200:203], v174 offset:1024
	ds_read_b128 v[204:207], v174 offset:2048
	ds_read_b128 v[208:211], v174 offset:3072
	ds_read_b128 v[212:215], v174 offset:4096
	ds_read_b128 v[216:219], v174 offset:5120
	ds_read_b128 v[220:223], v174 offset:6144
	ds_read_b128 v[224:227], v174 offset:7168
	global_load_lds_dwordx4 v[170:171], off
	v_lshl_add_u64 v[170:171], s[56:57], 0, v[154:155]
	s_add_i32 m0, s67, 0xe000
	s_nop 0
	global_load_lds_dwordx4 v[170:171], off
	s_waitcnt vmcnt(8)
	s_waitcnt lgkmcnt(0)
	s_barrier
	s_setprio 1
	s_waitcnt lgkmcnt(0)
	v_mfma_f32_16x16x32_bf16 v[126:129], v[130:133], v[196:199], v[126:129]
	v_mfma_f32_16x16x32_bf16 v[122:125], v[162:165], v[196:199], v[122:125]
	v_mfma_f32_16x16x32_bf16 v[110:113], v[130:133], v[204:207], v[110:113]
	v_mfma_f32_16x16x32_bf16 v[106:109], v[162:165], v[204:207], v[106:109]
	v_mfma_f32_16x16x32_bf16 v[94:97], v[130:133], v[212:215], v[94:97]
	v_mfma_f32_16x16x32_bf16 v[90:93], v[162:165], v[212:215], v[90:93]
	v_mfma_f32_16x16x32_bf16 v[78:81], v[130:133], v[220:223], v[78:81]
	v_mfma_f32_16x16x32_bf16 v[74:77], v[162:165], v[220:223], v[74:77]
	v_mfma_f32_16x16x32_bf16 v[126:129], v[134:137], v[200:203], v[126:129]
	v_mfma_f32_16x16x32_bf16 v[122:125], v[166:169], v[200:203], v[122:125]
	v_mfma_f32_16x16x32_bf16 v[110:113], v[134:137], v[208:211], v[110:113]
	v_mfma_f32_16x16x32_bf16 v[106:109], v[166:169], v[208:211], v[106:109]
	v_mfma_f32_16x16x32_bf16 v[94:97], v[134:137], v[216:219], v[94:97]
	v_mfma_f32_16x16x32_bf16 v[90:93], v[166:169], v[216:219], v[90:93]
	v_mfma_f32_16x16x32_bf16 v[78:81], v[134:137], v[224:227], v[78:81]
	v_mfma_f32_16x16x32_bf16 v[74:77], v[166:169], v[224:227], v[74:77]
	s_setprio 0
	s_setprio 1
	v_mfma_f32_16x16x32_bf16 v[118:121], v[176:179], v[196:199], v[118:121]
	v_mfma_f32_16x16x32_bf16 v[114:117], v[184:187], v[196:199], v[114:117]
	v_mfma_f32_16x16x32_bf16 v[102:105], v[176:179], v[204:207], v[102:105]
	v_mfma_f32_16x16x32_bf16 v[98:101], v[184:187], v[204:207], v[98:101]
	v_mfma_f32_16x16x32_bf16 v[86:89], v[176:179], v[212:215], v[86:89]
	v_mfma_f32_16x16x32_bf16 v[82:85], v[184:187], v[212:215], v[82:85]
	v_mfma_f32_16x16x32_bf16 v[70:73], v[176:179], v[220:223], v[70:73]
	v_mfma_f32_16x16x32_bf16 v[66:69], v[184:187], v[220:223], v[66:69]
	v_mfma_f32_16x16x32_bf16 v[118:121], v[180:183], v[200:203], v[118:121]
	v_mfma_f32_16x16x32_bf16 v[114:117], v[192:195], v[200:203], v[114:117]
	v_mfma_f32_16x16x32_bf16 v[102:105], v[180:183], v[208:211], v[102:105]
	v_mfma_f32_16x16x32_bf16 v[98:101], v[192:195], v[208:211], v[98:101]
	v_mfma_f32_16x16x32_bf16 v[86:89], v[180:183], v[216:219], v[86:89]
	v_mfma_f32_16x16x32_bf16 v[82:85], v[192:195], v[216:219], v[82:85]
	v_mfma_f32_16x16x32_bf16 v[70:73], v[180:183], v[224:227], v[70:73]
	v_mfma_f32_16x16x32_bf16 v[66:69], v[192:195], v[224:227], v[66:69]
	s_setprio 0
	s_barrier
; #define PG8_STAGE(bufoff, gbase, voff) do { _Pragma("unroll") for (int _i = 0; _i < 2; ++_i) \
;         __builtin_amdgcn_global_load_lds((const unsigned*)((const char*)(gbase) + (voff)[_i]), (PG8_LAS unsigned*)(lds + (bufoff) + ldsw + _i * 8192), 16, 0, 0); } while (0)
; #define PG8_LDA(dst, b, h) do { _Pragma("unroll") for (int m = 0; m < 4; ++m) _Pragma("unroll") for (int k = 0; k < 2; ++k) dst[m][k] = *(const PG8_LAS bf16x8*)(lds + PG8_SA(b, h) + aoff + m * 2048 + k * 1024); } while (0)
; #define PG8_LDB(dst, b, h) do { _Pragma("unroll") for (int n = 0; n < 2; ++n) _Pragma("unroll") for (int k = 0; k < 2; ++k) dst[n][k] = *(const PG8_LAS bf16x8*)(lds + PG8_SB(b, h) + boff + n * 2048 + k * 1024); } while (0)
; #define PG8_MMA(ai, bj, At, Bt) do { __builtin_amdgcn_s_setprio(1); _Pragma("unroll") for (int m = 0; m < 4; ++m) _Pragma("unroll") for (int n = 0; n < 2; ++n) _Pragma("unroll") for (int k = 0; k < 2; ++k) \
;         acc[ai][bj][m][n] = __builtin_amdgcn_mfma_f32_16x16x32_bf16(Bt[n][k], At[m][k], acc[ai][bj][m][n], 0, 0, 0); __builtin_amdgcn_s_setprio(0); } while (0)
; #define PG8_WAIT_V(n) asm volatile("s_waitcnt vmcnt(" #n ")" ::: "memory")
; #define PG8_WAIT_L(n) asm volatile("s_waitcnt lgkmcnt(" #n ")" ::: "memory")
; #define PG8_BAR __builtin_amdgcn_s_barrier()
; #define PG8_SCHED __builtin_amdgcn_sched_barrier(0)
; template <class Epi, class Sched, bool ALIGN_EPI = false, bool SP2 = false>
; __device__ __forceinline__ void gemm_phase(PG8_LAS unsigned char* lds, const Gemm g, const Sched& S, const Epi& E, const int tid) {
;     ...
;             PG8_LDA(At, 0, 1); PG8_STAGE(PG8_SB(0, 0), b2, voffB); PG8_STAGE(PG8_SB(0, 1), b2 + hstep, voffB); PG8_STAGE(PG8_SA(0, 0), a2, voffA);
;             PG8_WAIT_V(8); PG8_WAIT_L(0); PG8_BAR; PG8_MMA(1, 0, At, B0); PG8_MMA(1, 1, At, B1); PG8_BAR; PG8_SCHED;
;             PG8_LDB(B0, 1, 0); PG8_LDB(B1, 1, 1); PG8_SCHED; PG8_LDA(At, 1, 0); PG8_STAGE(PG8_SA(0, 1), a2 + hstep, voffA);
	s_add_i32 s15, s86, s66
	v_lshl_add_u64 v[170:171], s[58:59], 0, v[142:143]
	s_mov_b32 m0, s15
	ds_read_b128 v[196:199], v174 offset:16384
	ds_read_b128 v[200:203], v174 offset:17408
	ds_read_b128 v[204:207], v174 offset:18432
	ds_read_b128 v[208:211], v174 offset:19456
	ds_read_b128 v[212:215], v174 offset:20480
	ds_read_b128 v[216:219], v174 offset:21504
	ds_read_b128 v[220:223], v174 offset:22528
	ds_read_b128 v[224:227], v174 offset:23552
	global_load_lds_dwordx4 v[170:171], off
	s_add_i32 m0, s15, 0x2000
	s_add_u32 s18, s58, 0x40000
	v_lshl_add_u64 v[188:189], s[58:59], 0, v[146:147]
	s_addc_u32 s19, s59, 0
	s_add_i32 s15, s87, s66
	global_load_lds_dwordx4 v[188:189], off
	v_lshl_add_u64 v[228:229], s[18:19], 0, v[142:143]
	s_mov_b32 m0, s15
	v_lshl_add_u64 v[230:231], s[60:61], 0, v[144:145]
	global_load_lds_dwordx4 v[228:229], off
	v_lshl_add_u64 v[228:229], s[18:19], 0, v[146:147]
	s_add_i32 m0, s15, 0x2000
	s_nop 0
	global_load_lds_dwordx4 v[228:229], off
	v_lshl_add_u64 v[228:229], s[60:61], 0, v[140:141]
	s_mov_b32 m0, s67
	s_nop 0
	global_load_lds_dwordx4 v[228:229], off
	s_mov_b32 m0, s68
	s_nop 0
	global_load_lds_dwordx4 v[230:231], off
	s_waitcnt vmcnt(8)
	s_waitcnt lgkmcnt(0)
	s_barrier
	s_setprio 1
	s_waitcnt lgkmcnt(0)
	v_mfma_f32_16x16x32_bf16 v[62:65], v[130:133], v[196:199], v[62:65]
	v_mfma_f32_16x16x32_bf16 v[58:61], v[162:165], v[196:199], v[58:61]
	v_mfma_f32_16x16x32_bf16 v[46:49], v[130:133], v[204:207], v[46:49]
	v_mfma_f32_16x16x32_bf16 v[42:45], v[162:165], v[204:207], v[42:45]
	v_mfma_f32_16x16x32_bf16 v[30:33], v[130:133], v[212:215], v[30:33]
	v_mfma_f32_16x16x32_bf16 v[26:29], v[162:165], v[212:215], v[26:29]
	v_mfma_f32_16x16x32_bf16 v[14:17], v[130:133], v[220:223], v[14:17]
	v_mfma_f32_16x16x32_bf16 v[10:13], v[162:165], v[220:223], v[10:13]
	v_mfma_f32_16x16x32_bf16 v[62:65], v[134:137], v[200:203], v[62:65]
	v_mfma_f32_16x16x32_bf16 v[58:61], v[166:169], v[200:203], v[58:61]
	v_mfma_f32_16x16x32_bf16 v[46:49], v[134:137], v[208:211], v[46:49]
	v_mfma_f32_16x16x32_bf16 v[42:45], v[166:169], v[208:211], v[42:45]
	v_mfma_f32_16x16x32_bf16 v[30:33], v[134:137], v[216:219], v[30:33]
	v_mfma_f32_16x16x32_bf16 v[26:29], v[166:169], v[216:219], v[26:29]
	v_mfma_f32_16x16x32_bf16 v[14:17], v[134:137], v[224:227], v[14:17]
	v_mfma_f32_16x16x32_bf16 v[10:13], v[166:169], v[224:227], v[10:13]
	s_setprio 0
	s_setprio 1
	v_mfma_f32_16x16x32_bf16 v[54:57], v[176:179], v[196:199], v[54:57]
	v_mfma_f32_16x16x32_bf16 v[50:53], v[184:187], v[196:199], v[50:53]
	v_mfma_f32_16x16x32_bf16 v[38:41], v[176:179], v[204:207], v[38:41]
	v_mfma_f32_16x16x32_bf16 v[34:37], v[184:187], v[204:207], v[34:37]
	v_mfma_f32_16x16x32_bf16 v[22:25], v[176:179], v[212:215], v[22:25]
	v_mfma_f32_16x16x32_bf16 v[18:21], v[184:187], v[212:215], v[18:21]
	v_mfma_f32_16x16x32_bf16 v[6:9], v[176:179], v[220:223], v[6:9]
	v_mfma_f32_16x16x32_bf16 v[2:5], v[184:187], v[220:223], v[2:5]
	v_mfma_f32_16x16x32_bf16 v[54:57], v[180:183], v[200:203], v[54:57]
	v_mfma_f32_16x16x32_bf16 v[50:53], v[192:195], v[200:203], v[50:53]
	v_mfma_f32_16x16x32_bf16 v[38:41], v[180:183], v[208:211], v[38:41]
	v_mfma_f32_16x16x32_bf16 v[34:37], v[192:195], v[208:211], v[34:37]
	v_mfma_f32_16x16x32_bf16 v[22:25], v[180:183], v[216:219], v[22:25]
	v_mfma_f32_16x16x32_bf16 v[18:21], v[192:195], v[216:219], v[18:21]
	v_mfma_f32_16x16x32_bf16 v[6:9], v[180:183], v[224:227], v[6:9]
	v_mfma_f32_16x16x32_bf16 v[2:5], v[192:195], v[224:227], v[2:5]
	s_setprio 0
	s_barrier
	s_add_i32 s15, 0, 0x18000
	s_add_i32 s62, 0, 0x1c000
	v_add_u32_e32 v166, s15, v172
	v_add_u32_e32 v191, s62, v172
	ds_read_b128 v[130:133], v166
	ds_read_b128 v[134:137], v166 offset:1024
	ds_read_b128 v[162:165], v166 offset:2048
	ds_read_b128 v[166:169], v166 offset:3072
	ds_read_b128 v[176:179], v191
	ds_read_b128 v[180:183], v191 offset:1024
	ds_read_b128 v[184:187], v191 offset:2048
	ds_read_b128 v[192:195], v191 offset:3072
	s_add_u32 s18, s60, 0x40000
	s_addc_u32 s19, s61, 0
	s_mov_b32 m0, s69
	v_lshl_add_u64 v[232:233], s[18:19], 0, v[140:141]
	ds_read_b128 v[196:199], v174 offset:32768
	ds_read_b128 v[200:203], v174 offset:33792
	ds_read_b128 v[204:207], v174 offset:34816
	ds_read_b128 v[208:211], v174 offset:35840
	ds_read_b128 v[212:215], v174 offset:36864
	ds_read_b128 v[216:219], v174 offset:37888
	ds_read_b128 v[220:223], v174 offset:38912
	ds_read_b128 v[224:227], v174 offset:39936
	global_load_lds_dwordx4 v[232:233], off
	v_lshl_add_u64 v[232:233], s[18:19], 0, v[144:145]
	s_mov_b32 m0, s71
	s_nop 0
	global_load_lds_dwordx4 v[232:233], off
	s_waitcnt vmcnt(8)
	s_waitcnt lgkmcnt(0)
	s_barrier
; #define PG8_STAGE(bufoff, gbase, voff) do { _Pragma("unroll") for (int _i = 0; _i < 2; ++_i) \
;         __builtin_amdgcn_global_load_lds((const unsigned*)((const char*)(gbase) + (voff)[_i]), (PG8_LAS unsigned*)(lds + (bufoff) + ldsw + _i * 8192), 16, 0, 0); } while (0)
; #define PG8_LDA(dst, b, h) do { _Pragma("unroll") for (int m = 0; m < 4; ++m) _Pragma("unroll") for (int k = 0; k < 2; ++k) dst[m][k] = *(const PG8_LAS bf16x8*)(lds + PG8_SA(b, h) + aoff + m * 2048 + k * 1024); } while (0)
; #define PG8_MMA(ai, bj, At, Bt) do { __builtin_amdgcn_s_setprio(1); _Pragma("unroll") for (int m = 0; m < 4; ++m) _Pragma("unroll") for (int n = 0; n < 2; ++n) _Pragma("unroll") for (int k = 0; k < 2; ++k) \
;         acc[ai][bj][m][n] = __builtin_amdgcn_mfma_f32_16x16x32_bf16(Bt[n][k], At[m][k], acc[ai][bj][m][n], 0, 0, 0); __builtin_amdgcn_s_setprio(0); } while (0)
; #define PG8_WAIT_V(n) asm volatile("s_waitcnt vmcnt(" #n ")" ::: "memory")
; #define PG8_WAIT_L(n) asm volatile("s_waitcnt lgkmcnt(" #n ")" ::: "memory")
; #define PG8_BAR __builtin_amdgcn_s_barrier()
; #define PG8_SCHED __builtin_amdgcn_sched_barrier(0)
; template <class Epi, class Sched, bool ALIGN_EPI = false, bool SP2 = false>
; __device__ __forceinline__ void gemm_phase(PG8_LAS unsigned char* lds, const Gemm g, const Sched& S, const Epi& E, const int tid) {
;     ...
;         for (int t = 0; t < nt; t += 2) {
;     ...
;             PG8_WAIT_V(8); PG8_WAIT_L(0); PG8_BAR; PG8_MMA(0, 0, At, B0); PG8_MMA(0, 1, At, B1); PG8_BAR; PG8_SCHED;
;             PG8_LDA(At, 1, 1); PG8_STAGE(PG8_SB(1, 0), b3, voffB); PG8_STAGE(PG8_SB(1, 1), b3 + hstep, voffB); PG8_STAGE(PG8_SA(1, 0), a3, voffA);
;             PG8_WAIT_V(8); PG8_WAIT_L(0); PG8_BAR; PG8_MMA(1, 0, At, B0); PG8_MMA(1, 1, At, B1); PG8_BAR; PG8_SCHED;
	s_setprio 1
	s_waitcnt lgkmcnt(0)
	v_mfma_f32_16x16x32_bf16 v[126:129], v[130:133], v[196:199], v[126:129]
	v_mfma_f32_16x16x32_bf16 v[122:125], v[162:165], v[196:199], v[122:125]
	v_mfma_f32_16x16x32_bf16 v[110:113], v[130:133], v[204:207], v[110:113]
	v_mfma_f32_16x16x32_bf16 v[106:109], v[162:165], v[204:207], v[106:109]
	v_mfma_f32_16x16x32_bf16 v[94:97], v[130:133], v[212:215], v[94:97]
	v_mfma_f32_16x16x32_bf16 v[90:93], v[162:165], v[212:215], v[90:93]
	v_mfma_f32_16x16x32_bf16 v[78:81], v[130:133], v[220:223], v[78:81]
	v_mfma_f32_16x16x32_bf16 v[74:77], v[162:165], v[220:223], v[74:77]
	v_mfma_f32_16x16x32_bf16 v[126:129], v[134:137], v[200:203], v[126:129]
	v_mfma_f32_16x16x32_bf16 v[122:125], v[166:169], v[200:203], v[122:125]
	v_mfma_f32_16x16x32_bf16 v[110:113], v[134:137], v[208:211], v[110:113]
	v_mfma_f32_16x16x32_bf16 v[106:109], v[166:169], v[208:211], v[106:109]
	v_mfma_f32_16x16x32_bf16 v[94:97], v[134:137], v[216:219], v[94:97]
	v_mfma_f32_16x16x32_bf16 v[90:93], v[166:169], v[216:219], v[90:93]
	v_mfma_f32_16x16x32_bf16 v[78:81], v[134:137], v[224:227], v[78:81]
	v_mfma_f32_16x16x32_bf16 v[74:77], v[166:169], v[224:227], v[74:77]
	s_setprio 0
	s_setprio 1
	v_mfma_f32_16x16x32_bf16 v[118:121], v[176:179], v[196:199], v[118:121]
	v_mfma_f32_16x16x32_bf16 v[114:117], v[184:187], v[196:199], v[114:117]
	v_mfma_f32_16x16x32_bf16 v[102:105], v[176:179], v[204:207], v[102:105]
	v_mfma_f32_16x16x32_bf16 v[98:101], v[184:187], v[204:207], v[98:101]
	v_mfma_f32_16x16x32_bf16 v[86:89], v[176:179], v[212:215], v[86:89]
	v_mfma_f32_16x16x32_bf16 v[82:85], v[184:187], v[212:215], v[82:85]
	v_mfma_f32_16x16x32_bf16 v[70:73], v[176:179], v[220:223], v[70:73]
	v_mfma_f32_16x16x32_bf16 v[66:69], v[184:187], v[220:223], v[66:69]
	v_mfma_f32_16x16x32_bf16 v[118:121], v[180:183], v[200:203], v[118:121]
	v_mfma_f32_16x16x32_bf16 v[114:117], v[192:195], v[200:203], v[114:117]
	v_mfma_f32_16x16x32_bf16 v[102:105], v[180:183], v[208:211], v[102:105]
	v_mfma_f32_16x16x32_bf16 v[98:101], v[192:195], v[208:211], v[98:101]
	v_mfma_f32_16x16x32_bf16 v[86:89], v[180:183], v[216:219], v[86:89]
	v_mfma_f32_16x16x32_bf16 v[82:85], v[192:195], v[216:219], v[82:85]
	v_mfma_f32_16x16x32_bf16 v[70:73], v[180:183], v[224:227], v[70:73]
	v_mfma_f32_16x16x32_bf16 v[66:69], v[192:195], v[224:227], v[66:69]
	s_setprio 0
	s_barrier
	s_add_i32 s15, s15, s66
	v_lshl_add_u64 v[170:171], v[170:171], 0, s[44:45]
	s_mov_b32 m0, s15
	ds_read_b128 v[196:199], v174 offset:49152
	ds_read_b128 v[200:203], v174 offset:50176
	ds_read_b128 v[204:207], v174 offset:51200
	ds_read_b128 v[208:211], v174 offset:52224
	ds_read_b128 v[212:215], v174 offset:53248
	ds_read_b128 v[216:219], v174 offset:54272
	ds_read_b128 v[220:223], v174 offset:55296
	ds_read_b128 v[224:227], v174 offset:56320
	global_load_lds_dwordx4 v[170:171], off
	s_add_i32 m0, s15, 0x2000
	s_add_u32 s18, s58, 0x40080
	v_lshl_add_u64 v[170:171], v[188:189], 0, s[44:45]
	s_addc_u32 s19, s59, 0
	s_add_i32 s15, s62, s66
	global_load_lds_dwordx4 v[170:171], off
	v_lshl_add_u64 v[170:171], s[18:19], 0, v[142:143]
	s_mov_b32 m0, s15
	s_nop 0
	global_load_lds_dwordx4 v[170:171], off
	v_lshl_add_u64 v[170:171], s[18:19], 0, v[146:147]
	s_add_i32 m0, s15, 0x2000
	s_nop 0
	global_load_lds_dwordx4 v[170:171], off
	v_lshl_add_u64 v[170:171], v[228:229], 0, s[44:45]
	s_mov_b32 m0, s77
	s_nop 0
	global_load_lds_dwordx4 v[170:171], off
	v_lshl_add_u64 v[170:171], v[230:231], 0, s[44:45]
	s_mov_b32 m0, s78
	s_nop 0
	global_load_lds_dwordx4 v[170:171], off
	s_waitcnt vmcnt(8)
	s_waitcnt lgkmcnt(0)
	s_barrier
	s_setprio 1
	s_waitcnt lgkmcnt(0)
	v_mfma_f32_16x16x32_bf16 v[62:65], v[130:133], v[196:199], v[62:65]
	v_mfma_f32_16x16x32_bf16 v[58:61], v[162:165], v[196:199], v[58:61]
	v_mfma_f32_16x16x32_bf16 v[46:49], v[130:133], v[204:207], v[46:49]
	v_mfma_f32_16x16x32_bf16 v[42:45], v[162:165], v[204:207], v[42:45]
	v_mfma_f32_16x16x32_bf16 v[30:33], v[130:133], v[212:215], v[30:33]
	v_mfma_f32_16x16x32_bf16 v[26:29], v[162:165], v[212:215], v[26:29]
	v_mfma_f32_16x16x32_bf16 v[14:17], v[130:133], v[220:223], v[14:17]
	v_mfma_f32_16x16x32_bf16 v[10:13], v[162:165], v[220:223], v[10:13]
	v_mfma_f32_16x16x32_bf16 v[62:65], v[134:137], v[200:203], v[62:65]
	v_mfma_f32_16x16x32_bf16 v[58:61], v[166:169], v[200:203], v[58:61]
	v_mfma_f32_16x16x32_bf16 v[46:49], v[134:137], v[208:211], v[46:49]
	v_mfma_f32_16x16x32_bf16 v[42:45], v[166:169], v[208:211], v[42:45]
	v_mfma_f32_16x16x32_bf16 v[30:33], v[134:137], v[216:219], v[30:33]
	v_mfma_f32_16x16x32_bf16 v[26:29], v[166:169], v[216:219], v[26:29]
	v_mfma_f32_16x16x32_bf16 v[14:17], v[134:137], v[224:227], v[14:17]
	v_mfma_f32_16x16x32_bf16 v[10:13], v[166:169], v[224:227], v[10:13]
	s_setprio 0
	s_setprio 1
	v_mfma_f32_16x16x32_bf16 v[54:57], v[176:179], v[196:199], v[54:57]
	v_mfma_f32_16x16x32_bf16 v[50:53], v[184:187], v[196:199], v[50:53]
	v_mfma_f32_16x16x32_bf16 v[38:41], v[176:179], v[204:207], v[38:41]
	v_mfma_f32_16x16x32_bf16 v[34:37], v[184:187], v[204:207], v[34:37]
	v_mfma_f32_16x16x32_bf16 v[22:25], v[176:179], v[212:215], v[22:25]
	v_mfma_f32_16x16x32_bf16 v[18:21], v[184:187], v[212:215], v[18:21]
	v_mfma_f32_16x16x32_bf16 v[6:9], v[176:179], v[220:223], v[6:9]
	v_mfma_f32_16x16x32_bf16 v[2:5], v[184:187], v[220:223], v[2:5]
	v_mfma_f32_16x16x32_bf16 v[54:57], v[180:183], v[200:203], v[54:57]
	v_mfma_f32_16x16x32_bf16 v[50:53], v[192:195], v[200:203], v[50:53]
	v_mfma_f32_16x16x32_bf16 v[38:41], v[180:183], v[208:211], v[38:41]
	v_mfma_f32_16x16x32_bf16 v[34:37], v[192:195], v[208:211], v[34:37]
	v_mfma_f32_16x16x32_bf16 v[22:25], v[180:183], v[216:219], v[22:25]
	v_mfma_f32_16x16x32_bf16 v[18:21], v[192:195], v[216:219], v[18:21]
	v_mfma_f32_16x16x32_bf16 v[6:9], v[180:183], v[224:227], v[6:9]
	v_mfma_f32_16x16x32_bf16 v[2:5], v[192:195], v[224:227], v[2:5]
	s_setprio 0
	s_add_i32 s51, s51, 2
	s_add_u32 s5, s5, 0x100
	s_addc_u32 s49, s49, 0
	s_add_u32 s56, s56, 0x100
	s_addc_u32 s57, s57, 0
	s_cmp_gt_u32 s51, 13
	s_barrier
	s_cbranch_scc0 .LBB0_1122
	s_and_b64 vcc, exec, s[46:47]
	s_cbranch_vccz .LBB0_1125
	s_barrier

; #define PG8_STAGE(bufoff, gbase, voff) do { _Pragma("unroll") for (int _i = 0; _i < 2; ++_i) \
;         __builtin_amdgcn_global_load_lds((const unsigned*)((const char*)(gbase) + (voff)[_i]), (PG8_LAS unsigned*)(lds + (bufoff) + ldsw + _i * 8192), 16, 0, 0); } while (0)
; #define PG8_LDA(dst, b, h) do { _Pragma("unroll") for (int m = 0; m < 4; ++m) _Pragma("unroll") for (int k = 0; k < 2; ++k) dst[m][k] = *(const PG8_LAS bf16x8*)(lds + PG8_SA(b, h) + aoff + m * 2048 + k * 1024); } while (0)
; #define PG8_LDB(dst, b, h) do { _Pragma("unroll") for (int n = 0; n < 2; ++n) _Pragma("unroll") for (int k = 0; k < 2; ++k) dst[n][k] = *(const PG8_LAS bf16x8*)(lds + PG8_SB(b, h) + boff + n * 2048 + k * 1024); } while (0)
; #define PG8_WAIT_V(n) asm volatile("s_waitcnt vmcnt(" #n ")" ::: "memory")
; #define PG8_WAIT_L(n) asm volatile("s_waitcnt lgkmcnt(" #n ")" ::: "memory")
; #define PG8_BAR __builtin_amdgcn_s_barrier()
; #define PG8_SCHED __builtin_amdgcn_sched_barrier(0)
; template <class Epi, class Sched, bool ALIGN_EPI = false, bool SP2 = false>
; __device__ __forceinline__ void gemm_phase(PG8_LAS unsigned char* lds, const Gemm g, const Sched& S, const Epi& E, const int tid) {
;     ...
;         const bool has_next = S.next(ui + 1, nxt);
;         const char* nA = has_next ? S.aptr(nxt) : cA; const char* nB = has_next ? S.bptr(nxt) : cB;
;         for (int t = 0; t < nt; t += 2) {
;             const bool last = (t == nt - 2);
;             const char* a1 = cA + (size_t)(t + 1) * kstep;
;             const char* a2 = last ? nA : cA + (size_t)(t + 2) * kstep; const char* b2 = last ? nB : cB + (size_t)(t + 2) * kstep;
;             const char* a3 = a2 + kstep; const char* b3 = b2 + kstep;
;             if (last && has_next) S.a_ready(nxt);
;             if constexpr (SP2) {
;             PG8_LDB(B0, 0, 0); PG8_LDB(B1, 0, 1); PG8_SCHED; PG8_LDA(At, 0, 0); PG8_STAGE(PG8_SA(1, 1), a1 + hstep, voffA);
;             PG8_WAIT_V(8); PG8_WAIT_L(0); PG8_BAR; PG8_MMA(0, 0, At, B0); PG8_MMA(0, 1, At, B1); PG8_BAR; PG8_SCHED;
;             PG8_LDA(At, 0, 1); PG8_STAGE(PG8_SB(0, 0), b2, voffB); PG8_STAGE(PG8_SB(0, 1), b2 + hstep, voffB); PG8_STAGE(PG8_SA(0, 0), a2, voffA);
;             PG8_WAIT_V(8); PG8_WAIT_L(0); PG8_BAR; PG8_MMA(1, 0, At, B0); PG8_MMA(1, 1, At, B1); PG8_BAR; PG8_SCHED;
.LBB0_1373:
	s_ashr_i32 s39, s38, 31
	s_lshl_b64 s[18:19], s[38:39], 19
	s_add_u32 s40, s52, s18
	s_addc_u32 s41, s53, s19
	s_and_b64 s[18:19], s[4:5], exec
	s_cselect_b32 s7, s41, s11
	s_cselect_b32 s39, s40, s10
	s_ashr_i32 s37, s36, 31
	s_lshl_b64 s[18:19], s[36:37], 19
	s_add_u32 s42, s54, s18
	s_addc_u32 s43, s55, s19
	s_and_b64 s[18:19], s[4:5], exec
	s_cselect_b32 s37, s43, s9
	s_cselect_b32 s45, s42, s8
	s_add_u32 s48, s8, 0x100
	s_addc_u32 s49, s9, 0
	s_add_u32 s8, s10, 0x40080
	s_addc_u32 s9, s11, 0
	s_mov_b32 s76, -2
	s_add_u32 s10, s8, 0xfffc0080
	s_addc_u32 s11, s9, -1
	s_cmp_eq_u32 s76, 12
	s_cselect_b32 s47, s7, s11
	s_cselect_b32 s46, s39, s10
	s_cselect_b32 s11, s37, s49
	s_cselect_b32 s10, s45, s48
	v_lshl_add_u64 v[220:221], s[8:9], 0, v[176:177]
	s_add_i32 m0, s57, 0xc000
	global_load_lds_dwordx4 v[220:221], off
	v_lshl_add_u64 v[220:221], s[8:9], 0, v[174:175]
	s_add_i32 m0, s57, 0xe000
	s_nop 0
	global_load_lds_dwordx4 v[220:221], off
	s_waitcnt vmcnt(8)
	s_waitcnt lgkmcnt(0)
	s_barrier
	s_setprio 1
	s_waitcnt lgkmcnt(0)
	v_mfma_f32_16x16x32_bf16 v[126:129], v[130:133], v[182:185], 0
	v_mfma_f32_16x16x32_bf16 v[122:125], v[138:141], v[182:185], 0
	v_mfma_f32_16x16x32_bf16 v[110:113], v[130:133], v[192:195], 0
	v_mfma_f32_16x16x32_bf16 v[106:109], v[138:141], v[192:195], 0
	v_mfma_f32_16x16x32_bf16 v[94:97], v[130:133], v[200:203], 0
	v_mfma_f32_16x16x32_bf16 v[90:93], v[138:141], v[200:203], 0
	v_mfma_f32_16x16x32_bf16 v[78:81], v[130:133], v[212:215], 0
	v_mfma_f32_16x16x32_bf16 v[74:77], v[138:141], v[212:215], 0
	v_mfma_f32_16x16x32_bf16 v[126:129], v[134:137], v[186:189], v[126:129]
	v_mfma_f32_16x16x32_bf16 v[122:125], v[142:145], v[186:189], v[122:125]
	v_mfma_f32_16x16x32_bf16 v[110:113], v[134:137], v[196:199], v[110:113]
	v_mfma_f32_16x16x32_bf16 v[106:109], v[142:145], v[196:199], v[106:109]
	v_mfma_f32_16x16x32_bf16 v[94:97], v[134:137], v[208:211], v[94:97]
	v_mfma_f32_16x16x32_bf16 v[90:93], v[142:145], v[208:211], v[90:93]
	v_mfma_f32_16x16x32_bf16 v[78:81], v[134:137], v[216:219], v[78:81]
	v_mfma_f32_16x16x32_bf16 v[74:77], v[142:145], v[216:219], v[74:77]
	s_setprio 0
	s_setprio 1
	v_mfma_f32_16x16x32_bf16 v[118:121], v[146:149], v[182:185], 0
	v_mfma_f32_16x16x32_bf16 v[114:117], v[154:157], v[182:185], 0
	v_mfma_f32_16x16x32_bf16 v[102:105], v[146:149], v[192:195], 0
	v_mfma_f32_16x16x32_bf16 v[98:101], v[154:157], v[192:195], 0
	v_mfma_f32_16x16x32_bf16 v[86:89], v[146:149], v[200:203], 0
	v_mfma_f32_16x16x32_bf16 v[82:85], v[154:157], v[200:203], 0
	v_mfma_f32_16x16x32_bf16 v[70:73], v[146:149], v[212:215], 0
	v_mfma_f32_16x16x32_bf16 v[66:69], v[154:157], v[212:215], 0
	v_mfma_f32_16x16x32_bf16 v[118:121], v[150:153], v[186:189], v[118:121]
	v_mfma_f32_16x16x32_bf16 v[114:117], v[158:161], v[186:189], v[114:117]
	v_mfma_f32_16x16x32_bf16 v[102:105], v[150:153], v[196:199], v[102:105]
	v_mfma_f32_16x16x32_bf16 v[98:101], v[158:161], v[196:199], v[98:101]
	v_mfma_f32_16x16x32_bf16 v[86:89], v[150:153], v[208:211], v[86:89]
	v_mfma_f32_16x16x32_bf16 v[82:85], v[158:161], v[208:211], v[82:85]
	v_mfma_f32_16x16x32_bf16 v[70:73], v[150:153], v[216:219], v[70:73]
	v_mfma_f32_16x16x32_bf16 v[66:69], v[158:161], v[216:219], v[66:69]
	s_setprio 0
	s_barrier
	s_add_i32 s15, s67, s56
	v_lshl_add_u64 v[220:221], s[10:11], 0, v[164:165]
	s_mov_b32 m0, s15
	ds_read_b128 v[182:185], v206 offset:16384
	ds_read_b128 v[186:189], v206 offset:17408
	ds_read_b128 v[192:195], v206 offset:18432
	ds_read_b128 v[196:199], v206 offset:19456
	ds_read_b128 v[200:203], v206 offset:20480
	ds_read_b128 v[208:211], v206 offset:21504
	ds_read_b128 v[212:215], v206 offset:22528
	ds_read_b128 v[216:219], v206 offset:23552
	global_load_lds_dwordx4 v[220:221], off
	s_add_i32 m0, s15, 0x2000
	s_add_u32 s18, s10, 0x40000
	v_lshl_add_u64 v[222:223], s[10:11], 0, v[168:169]
	s_addc_u32 s19, s11, 0
	s_add_i32 s15, s68, s56
	global_load_lds_dwordx4 v[222:223], off
	v_lshl_add_u64 v[224:225], s[18:19], 0, v[164:165]
	s_mov_b32 m0, s15
	v_lshl_add_u64 v[226:227], s[46:47], 0, v[166:167]
	global_load_lds_dwordx4 v[224:225], off
	v_lshl_add_u64 v[224:225], s[18:19], 0, v[168:169]
	s_add_i32 m0, s15, 0x2000
	s_nop 0
	global_load_lds_dwordx4 v[224:225], off
	v_lshl_add_u64 v[224:225], s[46:47], 0, v[162:163]
	s_mov_b32 m0, s57
	s_nop 0
	global_load_lds_dwordx4 v[224:225], off
	s_mov_b32 m0, s58
	s_nop 0
	global_load_lds_dwordx4 v[226:227], off
	s_waitcnt vmcnt(8)
	s_waitcnt lgkmcnt(0)
	s_barrier
	s_setprio 1
	s_waitcnt lgkmcnt(0)
	v_mfma_f32_16x16x32_bf16 v[62:65], v[130:133], v[182:185], 0
	v_mfma_f32_16x16x32_bf16 v[58:61], v[138:141], v[182:185], 0
	v_mfma_f32_16x16x32_bf16 v[46:49], v[130:133], v[192:195], 0
	v_mfma_f32_16x16x32_bf16 v[42:45], v[138:141], v[192:195], 0
	v_mfma_f32_16x16x32_bf16 v[30:33], v[130:133], v[200:203], 0
	v_mfma_f32_16x16x32_bf16 v[26:29], v[138:141], v[200:203], 0
	v_mfma_f32_16x16x32_bf16 v[14:17], v[130:133], v[212:215], 0
	v_mfma_f32_16x16x32_bf16 v[10:13], v[138:141], v[212:215], 0
	v_mfma_f32_16x16x32_bf16 v[62:65], v[134:137], v[186:189], v[62:65]
	v_mfma_f32_16x16x32_bf16 v[58:61], v[142:145], v[186:189], v[58:61]
	v_mfma_f32_16x16x32_bf16 v[46:49], v[134:137], v[196:199], v[46:49]
	v_mfma_f32_16x16x32_bf16 v[42:45], v[142:145], v[196:199], v[42:45]
	v_mfma_f32_16x16x32_bf16 v[30:33], v[134:137], v[208:211], v[30:33]
	v_mfma_f32_16x16x32_bf16 v[26:29], v[142:145], v[208:211], v[26:29]
	v_mfma_f32_16x16x32_bf16 v[14:17], v[134:137], v[216:219], v[14:17]
	v_mfma_f32_16x16x32_bf16 v[10:13], v[142:145], v[216:219], v[10:13]
	s_setprio 0
	s_setprio 1
	v_mfma_f32_16x16x32_bf16 v[54:57], v[146:149], v[182:185], 0
	v_mfma_f32_16x16x32_bf16 v[50:53], v[154:157], v[182:185], 0
	v_mfma_f32_16x16x32_bf16 v[38:41], v[146:149], v[192:195], 0
	v_mfma_f32_16x16x32_bf16 v[34:37], v[154:157], v[192:195], 0
	v_mfma_f32_16x16x32_bf16 v[22:25], v[146:149], v[200:203], 0
	v_mfma_f32_16x16x32_bf16 v[18:21], v[154:157], v[200:203], 0
	v_mfma_f32_16x16x32_bf16 v[6:9], v[146:149], v[212:215], 0
	v_mfma_f32_16x16x32_bf16 v[2:5], v[154:157], v[212:215], 0
	v_mfma_f32_16x16x32_bf16 v[54:57], v[150:153], v[186:189], v[54:57]
	v_mfma_f32_16x16x32_bf16 v[50:53], v[158:161], v[186:189], v[50:53]
	v_mfma_f32_16x16x32_bf16 v[38:41], v[150:153], v[196:199], v[38:41]
	v_mfma_f32_16x16x32_bf16 v[34:37], v[158:161], v[196:199], v[34:37]
	v_mfma_f32_16x16x32_bf16 v[22:25], v[150:153], v[208:211], v[22:25]
	v_mfma_f32_16x16x32_bf16 v[18:21], v[158:161], v[208:211], v[18:21]
	v_mfma_f32_16x16x32_bf16 v[6:9], v[150:153], v[216:219], v[6:9]
	v_mfma_f32_16x16x32_bf16 v[2:5], v[158:161], v[216:219], v[2:5]
	s_setprio 0
	s_barrier
; #define PG8_STAGE(bufoff, gbase, voff) do { _Pragma("unroll") for (int _i = 0; _i < 2; ++_i) \
;         __builtin_amdgcn_global_load_lds((const unsigned*)((const char*)(gbase) + (voff)[_i]), (PG8_LAS unsigned*)(lds + (bufoff) + ldsw + _i * 8192), 16, 0, 0); } while (0)
; #define PG8_LDA(dst, b, h) do { _Pragma("unroll") for (int m = 0; m < 4; ++m) _Pragma("unroll") for (int k = 0; k < 2; ++k) dst[m][k] = *(const PG8_LAS bf16x8*)(lds + PG8_SA(b, h) + aoff + m * 2048 + k * 1024); } while (0)
; #define PG8_LDB(dst, b, h) do { _Pragma("unroll") for (int n = 0; n < 2; ++n) _Pragma("unroll") for (int k = 0; k < 2; ++k) dst[n][k] = *(const PG8_LAS bf16x8*)(lds + PG8_SB(b, h) + boff + n * 2048 + k * 1024); } while (0)
; #define PG8_MMA(ai, bj, At, Bt) do { __builtin_amdgcn_s_setprio(1); _Pragma("unroll") for (int m = 0; m < 4; ++m) _Pragma("unroll") for (int n = 0; n < 2; ++n) _Pragma("unroll") for (int k = 0; k < 2; ++k) \
;         acc[ai][bj][m][n] = __builtin_amdgcn_mfma_f32_16x16x32_bf16(Bt[n][k], At[m][k], acc[ai][bj][m][n], 0, 0, 0); __builtin_amdgcn_s_setprio(0); } while (0)
; #define PG8_WAIT_V(n) asm volatile("s_waitcnt vmcnt(" #n ")" ::: "memory")
; #define PG8_WAIT_L(n) asm volatile("s_waitcnt lgkmcnt(" #n ")" ::: "memory")
; #define PG8_BAR __builtin_amdgcn_s_barrier()
; #define PG8_SCHED __builtin_amdgcn_sched_barrier(0)
; template <class Epi, class Sched, bool ALIGN_EPI = false, bool SP2 = false>
; __device__ __forceinline__ void gemm_phase(PG8_LAS unsigned char* lds, const Gemm g, const Sched& S, const Epi& E, const int tid) {
;     ...
;             PG8_LDB(B0, 1, 0); PG8_LDB(B1, 1, 1); PG8_SCHED; PG8_LDA(At, 1, 0); PG8_STAGE(PG8_SA(0, 1), a2 + hstep, voffA);
;             PG8_WAIT_V(8); PG8_WAIT_L(0); PG8_BAR; PG8_MMA(0, 0, At, B0); PG8_MMA(0, 1, At, B1); PG8_BAR; PG8_SCHED;
;             PG8_LDA(At, 1, 1); PG8_STAGE(PG8_SB(1, 0), b3, voffB); PG8_STAGE(PG8_SB(1, 1), b3 + hstep, voffB); PG8_STAGE(PG8_SA(1, 0), a3, voffA);
	s_add_i32 s15, 0, 0x18000
	s_add_i32 s77, 0, 0x1c000
	v_add_u32_e32 v142, s15, v191
	v_add_u32_e32 v158, s77, v191
	ds_read_b128 v[130:133], v142
	ds_read_b128 v[134:137], v142 offset:1024
	ds_read_b128 v[138:141], v142 offset:2048
	ds_read_b128 v[142:145], v142 offset:3072
	ds_read_b128 v[146:149], v158
	ds_read_b128 v[150:153], v158 offset:1024
	ds_read_b128 v[154:157], v158 offset:2048
	ds_read_b128 v[158:161], v158 offset:3072
	s_add_u32 s18, s46, 0x40000
	s_addc_u32 s19, s47, 0
	s_mov_b32 m0, s59
	v_lshl_add_u64 v[228:229], s[18:19], 0, v[162:163]
	ds_read_b128 v[182:185], v206 offset:32768
	ds_read_b128 v[186:189], v206 offset:33792
	ds_read_b128 v[192:195], v206 offset:34816
	ds_read_b128 v[196:199], v206 offset:35840
	ds_read_b128 v[200:203], v206 offset:36864
	ds_read_b128 v[208:211], v206 offset:37888
	ds_read_b128 v[212:215], v206 offset:38912
	ds_read_b128 v[216:219], v206 offset:39936
	global_load_lds_dwordx4 v[228:229], off
	v_lshl_add_u64 v[228:229], s[18:19], 0, v[166:167]
	s_mov_b32 m0, s60
	s_nop 0
	global_load_lds_dwordx4 v[228:229], off
	s_waitcnt vmcnt(8)
	s_waitcnt lgkmcnt(0)
	s_barrier
	s_setprio 1
	s_waitcnt lgkmcnt(0)
	v_mfma_f32_16x16x32_bf16 v[126:129], v[130:133], v[182:185], v[126:129]
	v_mfma_f32_16x16x32_bf16 v[122:125], v[138:141], v[182:185], v[122:125]
	v_mfma_f32_16x16x32_bf16 v[110:113], v[130:133], v[192:195], v[110:113]
	v_mfma_f32_16x16x32_bf16 v[106:109], v[138:141], v[192:195], v[106:109]
	v_mfma_f32_16x16x32_bf16 v[94:97], v[130:133], v[200:203], v[94:97]
	v_mfma_f32_16x16x32_bf16 v[90:93], v[138:141], v[200:203], v[90:93]
	v_mfma_f32_16x16x32_bf16 v[78:81], v[130:133], v[212:215], v[78:81]
	v_mfma_f32_16x16x32_bf16 v[74:77], v[138:141], v[212:215], v[74:77]
	v_mfma_f32_16x16x32_bf16 v[126:129], v[134:137], v[186:189], v[126:129]
	v_mfma_f32_16x16x32_bf16 v[122:125], v[142:145], v[186:189], v[122:125]
	v_mfma_f32_16x16x32_bf16 v[110:113], v[134:137], v[196:199], v[110:113]
	v_mfma_f32_16x16x32_bf16 v[106:109], v[142:145], v[196:199], v[106:109]
	v_mfma_f32_16x16x32_bf16 v[94:97], v[134:137], v[208:211], v[94:97]
	v_mfma_f32_16x16x32_bf16 v[90:93], v[142:145], v[208:211], v[90:93]
	v_mfma_f32_16x16x32_bf16 v[78:81], v[134:137], v[216:219], v[78:81]
	v_mfma_f32_16x16x32_bf16 v[74:77], v[142:145], v[216:219], v[74:77]
	s_setprio 0
	s_setprio 1
	v_mfma_f32_16x16x32_bf16 v[118:121], v[146:149], v[182:185], v[118:121]
	v_mfma_f32_16x16x32_bf16 v[114:117], v[154:157], v[182:185], v[114:117]
	v_mfma_f32_16x16x32_bf16 v[102:105], v[146:149], v[192:195], v[102:105]
	v_mfma_f32_16x16x32_bf16 v[98:101], v[154:157], v[192:195], v[98:101]
	v_mfma_f32_16x16x32_bf16 v[86:89], v[146:149], v[200:203], v[86:89]
	v_mfma_f32_16x16x32_bf16 v[82:85], v[154:157], v[200:203], v[82:85]
	v_mfma_f32_16x16x32_bf16 v[70:73], v[146:149], v[212:215], v[70:73]
	v_mfma_f32_16x16x32_bf16 v[66:69], v[154:157], v[212:215], v[66:69]
	v_mfma_f32_16x16x32_bf16 v[118:121], v[150:153], v[186:189], v[118:121]
	v_mfma_f32_16x16x32_bf16 v[114:117], v[158:161], v[186:189], v[114:117]
	v_mfma_f32_16x16x32_bf16 v[102:105], v[150:153], v[196:199], v[102:105]
	v_mfma_f32_16x16x32_bf16 v[98:101], v[158:161], v[196:199], v[98:101]
	v_mfma_f32_16x16x32_bf16 v[86:89], v[150:153], v[208:211], v[86:89]
	v_mfma_f32_16x16x32_bf16 v[82:85], v[158:161], v[208:211], v[82:85]
	v_mfma_f32_16x16x32_bf16 v[70:73], v[150:153], v[216:219], v[70:73]
	v_mfma_f32_16x16x32_bf16 v[66:69], v[158:161], v[216:219], v[66:69]
	s_setprio 0
	s_barrier
	s_add_i32 s15, s15, s56
	v_lshl_add_u64 v[220:221], v[220:221], 0, s[30:31]
	s_mov_b32 m0, s15
	ds_read_b128 v[182:185], v206 offset:49152
	ds_read_b128 v[186:189], v206 offset:50176
	ds_read_b128 v[192:195], v206 offset:51200
	ds_read_b128 v[196:199], v206 offset:52224
	ds_read_b128 v[200:203], v206 offset:53248
	ds_read_b128 v[208:211], v206 offset:54272
	ds_read_b128 v[212:215], v206 offset:55296
	ds_read_b128 v[216:219], v206 offset:56320
	global_load_lds_dwordx4 v[220:221], off
	s_add_i32 m0, s15, 0x2000
	s_add_u32 s10, s10, 0x40080
	v_lshl_add_u64 v[220:221], v[222:223], 0, s[30:31]
	s_addc_u32 s11, s11, 0
	s_add_i32 s15, s77, s56
	global_load_lds_dwordx4 v[220:221], off
	v_lshl_add_u64 v[220:221], s[10:11], 0, v[164:165]
	s_mov_b32 m0, s15
	s_nop 0
	global_load_lds_dwordx4 v[220:221], off
	v_lshl_add_u64 v[220:221], s[10:11], 0, v[168:169]
	s_add_i32 m0, s15, 0x2000
	s_nop 0
	global_load_lds_dwordx4 v[220:221], off
	v_lshl_add_u64 v[220:221], v[224:225], 0, s[30:31]
	s_mov_b32 m0, s62
	s_nop 0
	global_load_lds_dwordx4 v[220:221], off
	v_lshl_add_u64 v[220:221], v[226:227], 0, s[30:31]
	s_mov_b32 m0, s63
	s_nop 0
	global_load_lds_dwordx4 v[220:221], off
	s_waitcnt vmcnt(8)
	s_waitcnt lgkmcnt(0)
	s_barrier
; #define PG8_STAGE(bufoff, gbase, voff) do { _Pragma("unroll") for (int _i = 0; _i < 2; ++_i) \
;         __builtin_amdgcn_global_load_lds((const unsigned*)((const char*)(gbase) + (voff)[_i]), (PG8_LAS unsigned*)(lds + (bufoff) + ldsw + _i * 8192), 16, 0, 0); } while (0)
; #define PG8_LDA(dst, b, h) do { _Pragma("unroll") for (int m = 0; m < 4; ++m) _Pragma("unroll") for (int k = 0; k < 2; ++k) dst[m][k] = *(const PG8_LAS bf16x8*)(lds + PG8_SA(b, h) + aoff + m * 2048 + k * 1024); } while (0)
; #define PG8_LDB(dst, b, h) do { _Pragma("unroll") for (int n = 0; n < 2; ++n) _Pragma("unroll") for (int k = 0; k < 2; ++k) dst[n][k] = *(const PG8_LAS bf16x8*)(lds + PG8_SB(b, h) + boff + n * 2048 + k * 1024); } while (0)
; template <class Epi, class Sched, bool ALIGN_EPI = false, bool SP2 = false>
; __device__ __forceinline__ void gemm_phase(PG8_LAS unsigned char* lds, const Gemm g, const Sched& S, const Epi& E, const int tid) {
;     ...
;         for (int t = 0; t < nt; t += 2) {
;             const bool last = (t == nt - 2);
;             const char* a1 = cA + (size_t)(t + 1) * kstep;
;             const char* a2 = last ? nA : cA + (size_t)(t + 2) * kstep; const char* b2 = last ? nB : cB + (size_t)(t + 2) * kstep;
;             const char* a3 = a2 + kstep; const char* b3 = b2 + kstep;
;             if (last && has_next) S.a_ready(nxt);
;     ...
;             PG8_LDB(B0, 0, 0); PG8_LDB(B1, 0, 1); PG8_SCHED; PG8_LDA(At, 0, 0); PG8_STAGE(PG8_SA(1, 1), a1 + hstep, voffA);
;             PG8_WAIT_V(8); PG8_WAIT_L(0); PG8_BAR; PG8_MMA(0, 0, At, B0); PG8_MMA(0, 1, At, B1); PG8_BAR; PG8_SCHED;
;             PG8_LDA(At, 0, 1); PG8_STAGE(PG8_SB(0, 0), b2, voffB); PG8_STAGE(PG8_SB(0, 1), b2 + hstep, voffB); PG8_STAGE(PG8_SA(0, 0), a2, voffA);
;             PG8_WAIT_V(8); PG8_WAIT_L(0); PG8_BAR; PG8_MMA(1, 0, At, B0); PG8_MMA(1, 1, At, B1); PG8_BAR; PG8_SCHED;
;             PG8_LDB(B0, 1, 0); PG8_LDB(B1, 1, 1); PG8_SCHED; PG8_LDA(At, 1, 0); PG8_STAGE(PG8_SA(0, 1), a2 + hstep, voffA);
;             PG8_WAIT_V(8); PG8_WAIT_L(0); PG8_BAR; PG8_MMA(0, 0, At, B0); PG8_MMA(0, 1, At, B1); PG8_BAR; PG8_SCHED;
;             PG8_LDA(At, 1, 1); PG8_STAGE(PG8_SB(1, 0), b3, voffB); PG8_STAGE(PG8_SB(1, 1), b3 + hstep, voffB); PG8_STAGE(PG8_SA(1, 0), a3, voffA);
;             PG8_WAIT_V(8); PG8_WAIT_L(0); PG8_BAR; PG8_MMA(1, 0, At, B0); PG8_MMA(1, 1, At, B1); PG8_BAR; PG8_SCHED;
	s_setprio 1
	s_waitcnt lgkmcnt(0)
	v_mfma_f32_16x16x32_bf16 v[62:65], v[130:133], v[182:185], v[62:65]
	v_mfma_f32_16x16x32_bf16 v[58:61], v[138:141], v[182:185], v[58:61]
	v_mfma_f32_16x16x32_bf16 v[46:49], v[130:133], v[192:195], v[46:49]
	v_mfma_f32_16x16x32_bf16 v[42:45], v[138:141], v[192:195], v[42:45]
	v_mfma_f32_16x16x32_bf16 v[30:33], v[130:133], v[200:203], v[30:33]
	v_mfma_f32_16x16x32_bf16 v[26:29], v[138:141], v[200:203], v[26:29]
	v_mfma_f32_16x16x32_bf16 v[14:17], v[130:133], v[212:215], v[14:17]
	v_mfma_f32_16x16x32_bf16 v[10:13], v[138:141], v[212:215], v[10:13]
	v_mfma_f32_16x16x32_bf16 v[62:65], v[134:137], v[186:189], v[62:65]
	v_mfma_f32_16x16x32_bf16 v[58:61], v[142:145], v[186:189], v[58:61]
	v_mfma_f32_16x16x32_bf16 v[46:49], v[134:137], v[196:199], v[46:49]
	v_mfma_f32_16x16x32_bf16 v[42:45], v[142:145], v[196:199], v[42:45]
	v_mfma_f32_16x16x32_bf16 v[30:33], v[134:137], v[208:211], v[30:33]
	v_mfma_f32_16x16x32_bf16 v[26:29], v[142:145], v[208:211], v[26:29]
	v_mfma_f32_16x16x32_bf16 v[14:17], v[134:137], v[216:219], v[14:17]
	v_mfma_f32_16x16x32_bf16 v[10:13], v[142:145], v[216:219], v[10:13]
	s_setprio 0
	s_setprio 1
	v_mfma_f32_16x16x32_bf16 v[54:57], v[146:149], v[182:185], v[54:57]
	v_mfma_f32_16x16x32_bf16 v[50:53], v[154:157], v[182:185], v[50:53]
	v_mfma_f32_16x16x32_bf16 v[38:41], v[146:149], v[192:195], v[38:41]
	v_mfma_f32_16x16x32_bf16 v[34:37], v[154:157], v[192:195], v[34:37]
	v_mfma_f32_16x16x32_bf16 v[22:25], v[146:149], v[200:203], v[22:25]
	v_mfma_f32_16x16x32_bf16 v[18:21], v[154:157], v[200:203], v[18:21]
	v_mfma_f32_16x16x32_bf16 v[6:9], v[146:149], v[212:215], v[6:9]
	v_mfma_f32_16x16x32_bf16 v[2:5], v[154:157], v[212:215], v[2:5]
	v_mfma_f32_16x16x32_bf16 v[54:57], v[150:153], v[186:189], v[54:57]
	v_mfma_f32_16x16x32_bf16 v[50:53], v[158:161], v[186:189], v[50:53]
	v_mfma_f32_16x16x32_bf16 v[38:41], v[150:153], v[196:199], v[38:41]
	v_mfma_f32_16x16x32_bf16 v[34:37], v[158:161], v[196:199], v[34:37]
	v_mfma_f32_16x16x32_bf16 v[22:25], v[150:153], v[208:211], v[22:25]
	v_mfma_f32_16x16x32_bf16 v[18:21], v[158:161], v[208:211], v[18:21]
	v_mfma_f32_16x16x32_bf16 v[6:9], v[150:153], v[216:219], v[6:9]
	v_mfma_f32_16x16x32_bf16 v[2:5], v[158:161], v[216:219], v[2:5]
	s_setprio 0
	s_add_i32 s76, s76, 2
	s_add_u32 s48, s48, 0x100
	s_addc_u32 s49, s49, 0
	s_add_u32 s8, s8, 0x100
	s_addc_u32 s9, s9, 0
	s_barrier
.LBB0_1374:
	ds_read_b128 v[130:133], v204
	ds_read_b128 v[134:137], v204 offset:1024
	ds_read_b128 v[138:141], v204 offset:2048
	ds_read_b128 v[142:145], v204 offset:3072
	ds_read_b128 v[146:149], v205
	ds_read_b128 v[150:153], v205 offset:1024
	ds_read_b128 v[154:157], v205 offset:2048
	ds_read_b128 v[158:161], v205 offset:3072
	s_add_u32 s10, s8, 0xfffc0080
	s_addc_u32 s11, s9, -1
	s_cmp_eq_u32 s76, 12
	s_cselect_b32 s47, s7, s11
	s_cselect_b32 s46, s39, s10
	s_cselect_b32 s11, s37, s49
	s_cselect_b32 s10, s45, s48
	v_lshl_add_u64 v[220:221], s[8:9], 0, v[176:177]
	s_add_i32 m0, s57, 0xc000
	ds_read_b128 v[182:185], v206
	ds_read_b128 v[186:189], v206 offset:1024
	ds_read_b128 v[192:195], v206 offset:2048
	ds_read_b128 v[196:199], v206 offset:3072
	ds_read_b128 v[200:203], v206 offset:4096
	ds_read_b128 v[208:211], v206 offset:5120
	ds_read_b128 v[212:215], v206 offset:6144
	ds_read_b128 v[216:219], v206 offset:7168
	global_load_lds_dwordx4 v[220:221], off
	v_lshl_add_u64 v[220:221], s[8:9], 0, v[174:175]
	s_add_i32 m0, s57, 0xe000
	s_nop 0
	global_load_lds_dwordx4 v[220:221], off
	s_waitcnt vmcnt(8)
	s_waitcnt lgkmcnt(0)
	s_barrier
	s_setprio 1
	s_waitcnt lgkmcnt(0)
	v_mfma_f32_16x16x32_bf16 v[126:129], v[130:133], v[182:185], v[126:129]
	v_mfma_f32_16x16x32_bf16 v[122:125], v[138:141], v[182:185], v[122:125]
	v_mfma_f32_16x16x32_bf16 v[110:113], v[130:133], v[192:195], v[110:113]
	v_mfma_f32_16x16x32_bf16 v[106:109], v[138:141], v[192:195], v[106:109]
	v_mfma_f32_16x16x32_bf16 v[94:97], v[130:133], v[200:203], v[94:97]
	v_mfma_f32_16x16x32_bf16 v[90:93], v[138:141], v[200:203], v[90:93]
	v_mfma_f32_16x16x32_bf16 v[78:81], v[130:133], v[212:215], v[78:81]
	v_mfma_f32_16x16x32_bf16 v[74:77], v[138:141], v[212:215], v[74:77]
	v_mfma_f32_16x16x32_bf16 v[126:129], v[134:137], v[186:189], v[126:129]
	v_mfma_f32_16x16x32_bf16 v[122:125], v[142:145], v[186:189], v[122:125]
	v_mfma_f32_16x16x32_bf16 v[110:113], v[134:137], v[196:199], v[110:113]
	v_mfma_f32_16x16x32_bf16 v[106:109], v[142:145], v[196:199], v[106:109]
	v_mfma_f32_16x16x32_bf16 v[94:97], v[134:137], v[208:211], v[94:97]
	v_mfma_f32_16x16x32_bf16 v[90:93], v[142:145], v[208:211], v[90:93]
	v_mfma_f32_16x16x32_bf16 v[78:81], v[134:137], v[216:219], v[78:81]
	v_mfma_f32_16x16x32_bf16 v[74:77], v[142:145], v[216:219], v[74:77]
	s_setprio 0
	s_setprio 1
	v_mfma_f32_16x16x32_bf16 v[118:121], v[146:149], v[182:185], v[118:121]
	v_mfma_f32_16x16x32_bf16 v[114:117], v[154:157], v[182:185], v[114:117]
	v_mfma_f32_16x16x32_bf16 v[102:105], v[146:149], v[192:195], v[102:105]
	v_mfma_f32_16x16x32_bf16 v[98:101], v[154:157], v[192:195], v[98:101]
	v_mfma_f32_16x16x32_bf16 v[86:89], v[146:149], v[200:203], v[86:89]
	v_mfma_f32_16x16x32_bf16 v[82:85], v[154:157], v[200:203], v[82:85]
	v_mfma_f32_16x16x32_bf16 v[70:73], v[146:149], v[212:215], v[70:73]
	v_mfma_f32_16x16x32_bf16 v[66:69], v[154:157], v[212:215], v[66:69]
	v_mfma_f32_16x16x32_bf16 v[118:121], v[150:153], v[186:189], v[118:121]
	v_mfma_f32_16x16x32_bf16 v[114:117], v[158:161], v[186:189], v[114:117]
	v_mfma_f32_16x16x32_bf16 v[102:105], v[150:153], v[196:199], v[102:105]
	v_mfma_f32_16x16x32_bf16 v[98:101], v[158:161], v[196:199], v[98:101]
	v_mfma_f32_16x16x32_bf16 v[86:89], v[150:153], v[208:211], v[86:89]
	v_mfma_f32_16x16x32_bf16 v[82:85], v[158:161], v[208:211], v[82:85]
	v_mfma_f32_16x16x32_bf16 v[70:73], v[150:153], v[216:219], v[70:73]
	v_mfma_f32_16x16x32_bf16 v[66:69], v[158:161], v[216:219], v[66:69]
	s_setprio 0
	s_barrier
; #define PG8_STAGE(bufoff, gbase, voff) do { _Pragma("unroll") for (int _i = 0; _i < 2; ++_i) \
;         __builtin_amdgcn_global_load_lds((const unsigned*)((const char*)(gbase) + (voff)[_i]), (PG8_LAS unsigned*)(lds + (bufoff) + ldsw + _i * 8192), 16, 0, 0); } while (0)
; #define PG8_LDA(dst, b, h) do { _Pragma("unroll") for (int m = 0; m < 4; ++m) _Pragma("unroll") for (int k = 0; k < 2; ++k) dst[m][k] = *(const PG8_LAS bf16x8*)(lds + PG8_SA(b, h) + aoff + m * 2048 + k * 1024); } while (0)
; #define PG8_LDB(dst, b, h) do { _Pragma("unroll") for (int n = 0; n < 2; ++n) _Pragma("unroll") for (int k = 0; k < 2; ++k) dst[n][k] = *(const PG8_LAS bf16x8*)(lds + PG8_SB(b, h) + boff + n * 2048 + k * 1024); } while (0)
; #define PG8_MMA(ai, bj, At, Bt) do { __builtin_amdgcn_s_setprio(1); _Pragma("unroll") for (int m = 0; m < 4; ++m) _Pragma("unroll") for (int n = 0; n < 2; ++n) _Pragma("unroll") for (int k = 0; k < 2; ++k) \
;         acc[ai][bj][m][n] = __builtin_amdgcn_mfma_f32_16x16x32_bf16(Bt[n][k], At[m][k], acc[ai][bj][m][n], 0, 0, 0); __builtin_amdgcn_s_setprio(0); } while (0)
; #define PG8_WAIT_V(n) asm volatile("s_waitcnt vmcnt(" #n ")" ::: "memory")
; #define PG8_WAIT_L(n) asm volatile("s_waitcnt lgkmcnt(" #n ")" ::: "memory")
; #define PG8_BAR __builtin_amdgcn_s_barrier()
; #define PG8_SCHED __builtin_amdgcn_sched_barrier(0)
; template <class Epi, class Sched, bool ALIGN_EPI = false, bool SP2 = false>
; __device__ __forceinline__ void gemm_phase(PG8_LAS unsigned char* lds, const Gemm g, const Sched& S, const Epi& E, const int tid) {
;     ...
;             PG8_LDA(At, 0, 1); PG8_STAGE(PG8_SB(0, 0), b2, voffB); PG8_STAGE(PG8_SB(0, 1), b2 + hstep, voffB); PG8_STAGE(PG8_SA(0, 0), a2, voffA);
;             PG8_WAIT_V(8); PG8_WAIT_L(0); PG8_BAR; PG8_MMA(1, 0, At, B0); PG8_MMA(1, 1, At, B1); PG8_BAR; PG8_SCHED;
;             PG8_LDB(B0, 1, 0); PG8_LDB(B1, 1, 1); PG8_SCHED; PG8_LDA(At, 1, 0); PG8_STAGE(PG8_SA(0, 1), a2 + hstep, voffA);
	s_add_i32 s15, s67, s56
	v_lshl_add_u64 v[220:221], s[10:11], 0, v[164:165]
	s_mov_b32 m0, s15
	ds_read_b128 v[182:185], v206 offset:16384
	ds_read_b128 v[186:189], v206 offset:17408
	ds_read_b128 v[192:195], v206 offset:18432
	ds_read_b128 v[196:199], v206 offset:19456
	ds_read_b128 v[200:203], v206 offset:20480
	ds_read_b128 v[208:211], v206 offset:21504
	ds_read_b128 v[212:215], v206 offset:22528
	ds_read_b128 v[216:219], v206 offset:23552
	global_load_lds_dwordx4 v[220:221], off
	s_add_i32 m0, s15, 0x2000
	s_add_u32 s18, s10, 0x40000
	v_lshl_add_u64 v[222:223], s[10:11], 0, v[168:169]
	s_addc_u32 s19, s11, 0
	s_add_i32 s15, s68, s56
	global_load_lds_dwordx4 v[222:223], off
	v_lshl_add_u64 v[224:225], s[18:19], 0, v[164:165]
	s_mov_b32 m0, s15
	v_lshl_add_u64 v[226:227], s[46:47], 0, v[166:167]
	global_load_lds_dwordx4 v[224:225], off
	v_lshl_add_u64 v[224:225], s[18:19], 0, v[168:169]
	s_add_i32 m0, s15, 0x2000
	s_nop 0
	global_load_lds_dwordx4 v[224:225], off
	v_lshl_add_u64 v[224:225], s[46:47], 0, v[162:163]
	s_mov_b32 m0, s57
	s_nop 0
	global_load_lds_dwordx4 v[224:225], off
	s_mov_b32 m0, s58
	s_nop 0
	global_load_lds_dwordx4 v[226:227], off
	s_waitcnt vmcnt(8)
	s_waitcnt lgkmcnt(0)
	s_barrier
	s_setprio 1
	s_waitcnt lgkmcnt(0)
	v_mfma_f32_16x16x32_bf16 v[62:65], v[130:133], v[182:185], v[62:65]
	v_mfma_f32_16x16x32_bf16 v[58:61], v[138:141], v[182:185], v[58:61]
	v_mfma_f32_16x16x32_bf16 v[46:49], v[130:133], v[192:195], v[46:49]
	v_mfma_f32_16x16x32_bf16 v[42:45], v[138:141], v[192:195], v[42:45]
	v_mfma_f32_16x16x32_bf16 v[30:33], v[130:133], v[200:203], v[30:33]
	v_mfma_f32_16x16x32_bf16 v[26:29], v[138:141], v[200:203], v[26:29]
	v_mfma_f32_16x16x32_bf16 v[14:17], v[130:133], v[212:215], v[14:17]
	v_mfma_f32_16x16x32_bf16 v[10:13], v[138:141], v[212:215], v[10:13]
	v_mfma_f32_16x16x32_bf16 v[62:65], v[134:137], v[186:189], v[62:65]
	v_mfma_f32_16x16x32_bf16 v[58:61], v[142:145], v[186:189], v[58:61]
	v_mfma_f32_16x16x32_bf16 v[46:49], v[134:137], v[196:199], v[46:49]
	v_mfma_f32_16x16x32_bf16 v[42:45], v[142:145], v[196:199], v[42:45]
	v_mfma_f32_16x16x32_bf16 v[30:33], v[134:137], v[208:211], v[30:33]
	v_mfma_f32_16x16x32_bf16 v[26:29], v[142:145], v[208:211], v[26:29]
	v_mfma_f32_16x16x32_bf16 v[14:17], v[134:137], v[216:219], v[14:17]
	v_mfma_f32_16x16x32_bf16 v[10:13], v[142:145], v[216:219], v[10:13]
	s_setprio 0
	s_setprio 1
	v_mfma_f32_16x16x32_bf16 v[54:57], v[146:149], v[182:185], v[54:57]
	v_mfma_f32_16x16x32_bf16 v[50:53], v[154:157], v[182:185], v[50:53]
	v_mfma_f32_16x16x32_bf16 v[38:41], v[146:149], v[192:195], v[38:41]
	v_mfma_f32_16x16x32_bf16 v[34:37], v[154:157], v[192:195], v[34:37]
	v_mfma_f32_16x16x32_bf16 v[22:25], v[146:149], v[200:203], v[22:25]
	v_mfma_f32_16x16x32_bf16 v[18:21], v[154:157], v[200:203], v[18:21]
	v_mfma_f32_16x16x32_bf16 v[6:9], v[146:149], v[212:215], v[6:9]
	v_mfma_f32_16x16x32_bf16 v[2:5], v[154:157], v[212:215], v[2:5]
	v_mfma_f32_16x16x32_bf16 v[54:57], v[150:153], v[186:189], v[54:57]
	v_mfma_f32_16x16x32_bf16 v[50:53], v[158:161], v[186:189], v[50:53]
	v_mfma_f32_16x16x32_bf16 v[38:41], v[150:153], v[196:199], v[38:41]
	v_mfma_f32_16x16x32_bf16 v[34:37], v[158:161], v[196:199], v[34:37]
	v_mfma_f32_16x16x32_bf16 v[22:25], v[150:153], v[208:211], v[22:25]
	v_mfma_f32_16x16x32_bf16 v[18:21], v[158:161], v[208:211], v[18:21]
	v_mfma_f32_16x16x32_bf16 v[6:9], v[150:153], v[216:219], v[6:9]
	v_mfma_f32_16x16x32_bf16 v[2:5], v[158:161], v[216:219], v[2:5]
	s_setprio 0
	s_barrier
	s_add_i32 s15, 0, 0x18000
	s_add_i32 s77, 0, 0x1c000
	v_add_u32_e32 v142, s15, v191
	v_add_u32_e32 v158, s77, v191
	ds_read_b128 v[130:133], v142
	ds_read_b128 v[134:137], v142 offset:1024
	ds_read_b128 v[138:141], v142 offset:2048
	ds_read_b128 v[142:145], v142 offset:3072
	ds_read_b128 v[146:149], v158
	ds_read_b128 v[150:153], v158 offset:1024
	ds_read_b128 v[154:157], v158 offset:2048
	ds_read_b128 v[158:161], v158 offset:3072
	s_add_u32 s18, s46, 0x40000
	s_addc_u32 s19, s47, 0
	s_mov_b32 m0, s59
	v_lshl_add_u64 v[228:229], s[18:19], 0, v[162:163]
	ds_read_b128 v[182:185], v206 offset:32768
	ds_read_b128 v[186:189], v206 offset:33792
	ds_read_b128 v[192:195], v206 offset:34816
	ds_read_b128 v[196:199], v206 offset:35840
	ds_read_b128 v[200:203], v206 offset:36864
	ds_read_b128 v[208:211], v206 offset:37888
	ds_read_b128 v[212:215], v206 offset:38912
	ds_read_b128 v[216:219], v206 offset:39936
	global_load_lds_dwordx4 v[228:229], off
	v_lshl_add_u64 v[228:229], s[18:19], 0, v[166:167]
	s_mov_b32 m0, s60
	s_nop 0
	global_load_lds_dwordx4 v[228:229], off
	s_waitcnt vmcnt(8)
	s_waitcnt lgkmcnt(0)
	s_barrier
; #define PG8_STAGE(bufoff, gbase, voff) do { _Pragma("unroll") for (int _i = 0; _i < 2; ++_i) \
;         __builtin_amdgcn_global_load_lds((const unsigned*)((const char*)(gbase) + (voff)[_i]), (PG8_LAS unsigned*)(lds + (bufoff) + ldsw + _i * 8192), 16, 0, 0); } while (0)
; #define PG8_LDA(dst, b, h) do { _Pragma("unroll") for (int m = 0; m < 4; ++m) _Pragma("unroll") for (int k = 0; k < 2; ++k) dst[m][k] = *(const PG8_LAS bf16x8*)(lds + PG8_SA(b, h) + aoff + m * 2048 + k * 1024); } while (0)
; #define PG8_MMA(ai, bj, At, Bt) do { __builtin_amdgcn_s_setprio(1); _Pragma("unroll") for (int m = 0; m < 4; ++m) _Pragma("unroll") for (int n = 0; n < 2; ++n) _Pragma("unroll") for (int k = 0; k < 2; ++k) \
;         acc[ai][bj][m][n] = __builtin_amdgcn_mfma_f32_16x16x32_bf16(Bt[n][k], At[m][k], acc[ai][bj][m][n], 0, 0, 0); __builtin_amdgcn_s_setprio(0); } while (0)
; #define PG8_WAIT_V(n) asm volatile("s_waitcnt vmcnt(" #n ")" ::: "memory")
; #define PG8_WAIT_L(n) asm volatile("s_waitcnt lgkmcnt(" #n ")" ::: "memory")
; #define PG8_BAR __builtin_amdgcn_s_barrier()
; #define PG8_SCHED __builtin_amdgcn_sched_barrier(0)
; template <class Epi, class Sched, bool ALIGN_EPI = false, bool SP2 = false>
; __device__ __forceinline__ void gemm_phase(PG8_LAS unsigned char* lds, const Gemm g, const Sched& S, const Epi& E, const int tid) {
;     ...
;         for (int t = 0; t < nt; t += 2) {
;     ...
;             PG8_WAIT_V(8); PG8_WAIT_L(0); PG8_BAR; PG8_MMA(0, 0, At, B0); PG8_MMA(0, 1, At, B1); PG8_BAR; PG8_SCHED;
;             PG8_LDA(At, 1, 1); PG8_STAGE(PG8_SB(1, 0), b3, voffB); PG8_STAGE(PG8_SB(1, 1), b3 + hstep, voffB); PG8_STAGE(PG8_SA(1, 0), a3, voffA);
;             PG8_WAIT_V(8); PG8_WAIT_L(0); PG8_BAR; PG8_MMA(1, 0, At, B0); PG8_MMA(1, 1, At, B1); PG8_BAR; PG8_SCHED;
	s_setprio 1
	s_waitcnt lgkmcnt(0)
	v_mfma_f32_16x16x32_bf16 v[126:129], v[130:133], v[182:185], v[126:129]
	v_mfma_f32_16x16x32_bf16 v[122:125], v[138:141], v[182:185], v[122:125]
	v_mfma_f32_16x16x32_bf16 v[110:113], v[130:133], v[192:195], v[110:113]
	v_mfma_f32_16x16x32_bf16 v[106:109], v[138:141], v[192:195], v[106:109]
	v_mfma_f32_16x16x32_bf16 v[94:97], v[130:133], v[200:203], v[94:97]
	v_mfma_f32_16x16x32_bf16 v[90:93], v[138:141], v[200:203], v[90:93]
	v_mfma_f32_16x16x32_bf16 v[78:81], v[130:133], v[212:215], v[78:81]
	v_mfma_f32_16x16x32_bf16 v[74:77], v[138:141], v[212:215], v[74:77]
	v_mfma_f32_16x16x32_bf16 v[126:129], v[134:137], v[186:189], v[126:129]
	v_mfma_f32_16x16x32_bf16 v[122:125], v[142:145], v[186:189], v[122:125]
	v_mfma_f32_16x16x32_bf16 v[110:113], v[134:137], v[196:199], v[110:113]
	v_mfma_f32_16x16x32_bf16 v[106:109], v[142:145], v[196:199], v[106:109]
	v_mfma_f32_16x16x32_bf16 v[94:97], v[134:137], v[208:211], v[94:97]
	v_mfma_f32_16x16x32_bf16 v[90:93], v[142:145], v[208:211], v[90:93]
	v_mfma_f32_16x16x32_bf16 v[78:81], v[134:137], v[216:219], v[78:81]
	v_mfma_f32_16x16x32_bf16 v[74:77], v[142:145], v[216:219], v[74:77]
	s_setprio 0
	s_setprio 1
	v_mfma_f32_16x16x32_bf16 v[118:121], v[146:149], v[182:185], v[118:121]
	v_mfma_f32_16x16x32_bf16 v[114:117], v[154:157], v[182:185], v[114:117]
	v_mfma_f32_16x16x32_bf16 v[102:105], v[146:149], v[192:195], v[102:105]
	v_mfma_f32_16x16x32_bf16 v[98:101], v[154:157], v[192:195], v[98:101]
	v_mfma_f32_16x16x32_bf16 v[86:89], v[146:149], v[200:203], v[86:89]
	v_mfma_f32_16x16x32_bf16 v[82:85], v[154:157], v[200:203], v[82:85]
	v_mfma_f32_16x16x32_bf16 v[70:73], v[146:149], v[212:215], v[70:73]
	v_mfma_f32_16x16x32_bf16 v[66:69], v[154:157], v[212:215], v[66:69]
	v_mfma_f32_16x16x32_bf16 v[118:121], v[150:153], v[186:189], v[118:121]
	v_mfma_f32_16x16x32_bf16 v[114:117], v[158:161], v[186:189], v[114:117]
	v_mfma_f32_16x16x32_bf16 v[102:105], v[150:153], v[196:199], v[102:105]
	v_mfma_f32_16x16x32_bf16 v[98:101], v[158:161], v[196:199], v[98:101]
	v_mfma_f32_16x16x32_bf16 v[86:89], v[150:153], v[208:211], v[86:89]
	v_mfma_f32_16x16x32_bf16 v[82:85], v[158:161], v[208:211], v[82:85]
	v_mfma_f32_16x16x32_bf16 v[70:73], v[150:153], v[216:219], v[70:73]
	v_mfma_f32_16x16x32_bf16 v[66:69], v[158:161], v[216:219], v[66:69]
	s_setprio 0
	s_barrier
	s_add_i32 s15, s15, s56
	v_lshl_add_u64 v[220:221], v[220:221], 0, s[30:31]
	s_mov_b32 m0, s15
	ds_read_b128 v[182:185], v206 offset:49152
	ds_read_b128 v[186:189], v206 offset:50176
	ds_read_b128 v[192:195], v206 offset:51200
	ds_read_b128 v[196:199], v206 offset:52224
	ds_read_b128 v[200:203], v206 offset:53248
	ds_read_b128 v[208:211], v206 offset:54272
	ds_read_b128 v[212:215], v206 offset:55296
	ds_read_b128 v[216:219], v206 offset:56320
	global_load_lds_dwordx4 v[220:221], off
	s_add_i32 m0, s15, 0x2000
	s_add_u32 s10, s10, 0x40080
	v_lshl_add_u64 v[220:221], v[222:223], 0, s[30:31]
	s_addc_u32 s11, s11, 0
	s_add_i32 s15, s77, s56
	global_load_lds_dwordx4 v[220:221], off
	v_lshl_add_u64 v[220:221], s[10:11], 0, v[164:165]
	s_mov_b32 m0, s15
	s_nop 0
	global_load_lds_dwordx4 v[220:221], off
	v_lshl_add_u64 v[220:221], s[10:11], 0, v[168:169]
	s_add_i32 m0, s15, 0x2000
	s_nop 0
	global_load_lds_dwordx4 v[220:221], off
	v_lshl_add_u64 v[220:221], v[224:225], 0, s[30:31]
	s_mov_b32 m0, s62
	s_nop 0
	global_load_lds_dwordx4 v[220:221], off
	v_lshl_add_u64 v[220:221], v[226:227], 0, s[30:31]
	s_mov_b32 m0, s63
	s_nop 0
	global_load_lds_dwordx4 v[220:221], off
	s_waitcnt vmcnt(8)
	s_waitcnt lgkmcnt(0)
	s_barrier
	s_setprio 1
	s_waitcnt lgkmcnt(0)
	v_mfma_f32_16x16x32_bf16 v[62:65], v[130:133], v[182:185], v[62:65]
	v_mfma_f32_16x16x32_bf16 v[58:61], v[138:141], v[182:185], v[58:61]
	v_mfma_f32_16x16x32_bf16 v[46:49], v[130:133], v[192:195], v[46:49]
	v_mfma_f32_16x16x32_bf16 v[42:45], v[138:141], v[192:195], v[42:45]
	v_mfma_f32_16x16x32_bf16 v[30:33], v[130:133], v[200:203], v[30:33]
	v_mfma_f32_16x16x32_bf16 v[26:29], v[138:141], v[200:203], v[26:29]
	v_mfma_f32_16x16x32_bf16 v[14:17], v[130:133], v[212:215], v[14:17]
	v_mfma_f32_16x16x32_bf16 v[10:13], v[138:141], v[212:215], v[10:13]
	v_mfma_f32_16x16x32_bf16 v[62:65], v[134:137], v[186:189], v[62:65]
	v_mfma_f32_16x16x32_bf16 v[58:61], v[142:145], v[186:189], v[58:61]
	v_mfma_f32_16x16x32_bf16 v[46:49], v[134:137], v[196:199], v[46:49]
	v_mfma_f32_16x16x32_bf16 v[42:45], v[142:145], v[196:199], v[42:45]
	v_mfma_f32_16x16x32_bf16 v[30:33], v[134:137], v[208:211], v[30:33]
	v_mfma_f32_16x16x32_bf16 v[26:29], v[142:145], v[208:211], v[26:29]
	v_mfma_f32_16x16x32_bf16 v[14:17], v[134:137], v[216:219], v[14:17]
	v_mfma_f32_16x16x32_bf16 v[10:13], v[142:145], v[216:219], v[10:13]
	s_setprio 0
	s_setprio 1
	v_mfma_f32_16x16x32_bf16 v[54:57], v[146:149], v[182:185], v[54:57]
	v_mfma_f32_16x16x32_bf16 v[50:53], v[154:157], v[182:185], v[50:53]
	v_mfma_f32_16x16x32_bf16 v[38:41], v[146:149], v[192:195], v[38:41]
	v_mfma_f32_16x16x32_bf16 v[34:37], v[154:157], v[192:195], v[34:37]
	v_mfma_f32_16x16x32_bf16 v[22:25], v[146:149], v[200:203], v[22:25]
	v_mfma_f32_16x16x32_bf16 v[18:21], v[154:157], v[200:203], v[18:21]
	v_mfma_f32_16x16x32_bf16 v[6:9], v[146:149], v[212:215], v[6:9]
	v_mfma_f32_16x16x32_bf16 v[2:5], v[154:157], v[212:215], v[2:5]
	v_mfma_f32_16x16x32_bf16 v[54:57], v[150:153], v[186:189], v[54:57]
	v_mfma_f32_16x16x32_bf16 v[50:53], v[158:161], v[186:189], v[50:53]
	v_mfma_f32_16x16x32_bf16 v[38:41], v[150:153], v[196:199], v[38:41]
	v_mfma_f32_16x16x32_bf16 v[34:37], v[158:161], v[196:199], v[34:37]
	v_mfma_f32_16x16x32_bf16 v[22:25], v[150:153], v[208:211], v[22:25]
	v_mfma_f32_16x16x32_bf16 v[18:21], v[158:161], v[208:211], v[18:21]
	v_mfma_f32_16x16x32_bf16 v[6:9], v[150:153], v[216:219], v[6:9]
	v_mfma_f32_16x16x32_bf16 v[2:5], v[158:161], v[216:219], v[2:5]
	s_setprio 0
	s_add_i32 s76, s76, 2
	s_add_u32 s48, s48, 0x100
	s_addc_u32 s49, s49, 0
	s_add_u32 s8, s8, 0x100
	s_addc_u32 s9, s9, 0
	s_cmp_gt_u32 s76, 13
	s_barrier
	s_cbranch_scc0 .LBB0_1374
	s_and_b64 vcc, exec, s[34:35]
	s_cbranch_vccz .LBB0_1377
	s_barrier

; #define PG8_STAGE(bufoff, gbase, voff) do { _Pragma("unroll") for (int _i = 0; _i < 2; ++_i) \
;         __builtin_amdgcn_global_load_lds((const unsigned*)((const char*)(gbase) + (voff)[_i]), (PG8_LAS unsigned*)(lds + (bufoff) + ldsw + _i * 8192), 16, 0, 0); } while (0)
; #define PG8_LDA(dst, b, h) do { _Pragma("unroll") for (int m = 0; m < 4; ++m) _Pragma("unroll") for (int k = 0; k < 2; ++k) dst[m][k] = *(const PG8_LAS bf16x8*)(lds + PG8_SA(b, h) + aoff + m * 2048 + k * 1024); } while (0)
; #define PG8_LDB(dst, b, h) do { _Pragma("unroll") for (int n = 0; n < 2; ++n) _Pragma("unroll") for (int k = 0; k < 2; ++k) dst[n][k] = *(const PG8_LAS bf16x8*)(lds + PG8_SB(b, h) + boff + n * 2048 + k * 1024); } while (0)
; #define PG8_MMA(ai, bj, At, Bt) do { __builtin_amdgcn_s_setprio(1); _Pragma("unroll") for (int m = 0; m < 4; ++m) _Pragma("unroll") for (int n = 0; n < 2; ++n) _Pragma("unroll") for (int k = 0; k < 2; ++k) \
;         acc[ai][bj][m][n] = __builtin_amdgcn_mfma_f32_16x16x32_bf16(Bt[n][k], At[m][k], acc[ai][bj][m][n], 0, 0, 0); __builtin_amdgcn_s_setprio(0); } while (0)
; #define PG8_WAIT_V(n) asm volatile("s_waitcnt vmcnt(" #n ")" ::: "memory")
; #define PG8_WAIT_L(n) asm volatile("s_waitcnt lgkmcnt(" #n ")" ::: "memory")
; template <class Epi, class Sched, bool ALIGN_EPI = false, bool SP2 = false>
; __device__ __forceinline__ void gemm_phase(PG8_LAS unsigned char* lds, const Gemm g, const Sched& S, const Epi& E, const int tid) {
;     ...
;             const bool last = (t == nt - 2);
;             const char* a1 = cA + (size_t)(t + 1) * kstep;
;             const char* a2 = last ? nA : cA + (size_t)(t + 2) * kstep; const char* b2 = last ? nB : cB + (size_t)(t + 2) * kstep;
;             const char* a3 = a2 + kstep; const char* b3 = b2 + kstep;
;             if (last && has_next) S.a_ready(nxt);
;             if constexpr (SP2) {
;             PG8_LDB(B0, 0, 0); PG8_LDB(B1, 0, 1); PG8_SCHED; PG8_LDA(At, 0, 0); PG8_STAGE(PG8_SA(1, 1), a1 + hstep, voffA);
;             PG8_WAIT_V(8); PG8_WAIT_L(0); PG8_BAR; PG8_MMA(0, 0, At, B0); PG8_MMA(0, 1, At, B1); PG8_BAR; PG8_SCHED;
;             PG8_LDA(At, 0, 1); PG8_STAGE(PG8_SB(0, 0), b2, voffB); PG8_STAGE(PG8_SB(0, 1), b2 + hstep, voffB); PG8_STAGE(PG8_SA(0, 0), a2, voffA);
;             PG8_WAIT_V(8); PG8_WAIT_L(0); PG8_BAR; PG8_MMA(1, 0, At, B0); PG8_MMA(1, 1, At, B1); PG8_BAR; PG8_SCHED;
.LBB0_5219:
	s_add_u32 s43, s8, 0x100
	s_addc_u32 s45, s9, 0
	s_mov_b32 s74, -2
	s_add_u32 s8, s6, 0x100
	s_addc_u32 s9, s7, 0
	s_cmp_eq_u32 s74, 40
	s_cselect_b32 s41, s1, s9
	s_cselect_b32 s40, s0, s8
	s_cselect_b32 s11, s39, s45
	s_cselect_b32 s10, s38, s43
	v_lshl_add_u64 v[220:221], s[6:7], 0, v[176:177]
	s_add_i32 m0, s53, 0xc000
	global_load_lds_dwordx4 v[220:221], off
	v_lshl_add_u64 v[220:221], s[6:7], 0, v[174:175]
	s_add_i32 m0, s53, 0xe000
	s_nop 0
	global_load_lds_dwordx4 v[220:221], off
	s_waitcnt vmcnt(8)
	s_waitcnt lgkmcnt(0)
	s_barrier
	s_setprio 1
	s_waitcnt lgkmcnt(0)
	v_mfma_f32_16x16x32_bf16 v[126:129], v[130:133], v[182:185], 0
	v_mfma_f32_16x16x32_bf16 v[122:125], v[138:141], v[182:185], 0
	v_mfma_f32_16x16x32_bf16 v[110:113], v[130:133], v[192:195], 0
	v_mfma_f32_16x16x32_bf16 v[106:109], v[138:141], v[192:195], 0
	v_mfma_f32_16x16x32_bf16 v[94:97], v[130:133], v[200:203], 0
	v_mfma_f32_16x16x32_bf16 v[90:93], v[138:141], v[200:203], 0
	v_mfma_f32_16x16x32_bf16 v[78:81], v[130:133], v[212:215], 0
	v_mfma_f32_16x16x32_bf16 v[74:77], v[138:141], v[212:215], 0
	v_mfma_f32_16x16x32_bf16 v[126:129], v[134:137], v[186:189], v[126:129]
	v_mfma_f32_16x16x32_bf16 v[122:125], v[142:145], v[186:189], v[122:125]
	v_mfma_f32_16x16x32_bf16 v[110:113], v[134:137], v[196:199], v[110:113]
	v_mfma_f32_16x16x32_bf16 v[106:109], v[142:145], v[196:199], v[106:109]
	v_mfma_f32_16x16x32_bf16 v[94:97], v[134:137], v[208:211], v[94:97]
	v_mfma_f32_16x16x32_bf16 v[90:93], v[142:145], v[208:211], v[90:93]
	v_mfma_f32_16x16x32_bf16 v[78:81], v[134:137], v[216:219], v[78:81]
	v_mfma_f32_16x16x32_bf16 v[74:77], v[142:145], v[216:219], v[74:77]
	s_setprio 0
	s_setprio 1
	v_mfma_f32_16x16x32_bf16 v[118:121], v[146:149], v[182:185], 0
	v_mfma_f32_16x16x32_bf16 v[114:117], v[154:157], v[182:185], 0
	v_mfma_f32_16x16x32_bf16 v[102:105], v[146:149], v[192:195], 0
	v_mfma_f32_16x16x32_bf16 v[98:101], v[154:157], v[192:195], 0
	v_mfma_f32_16x16x32_bf16 v[86:89], v[146:149], v[200:203], 0
	v_mfma_f32_16x16x32_bf16 v[82:85], v[154:157], v[200:203], 0
	v_mfma_f32_16x16x32_bf16 v[70:73], v[146:149], v[212:215], 0
	v_mfma_f32_16x16x32_bf16 v[66:69], v[154:157], v[212:215], 0
	v_mfma_f32_16x16x32_bf16 v[118:121], v[150:153], v[186:189], v[118:121]
	v_mfma_f32_16x16x32_bf16 v[114:117], v[158:161], v[186:189], v[114:117]
	v_mfma_f32_16x16x32_bf16 v[102:105], v[150:153], v[196:199], v[102:105]
	v_mfma_f32_16x16x32_bf16 v[98:101], v[158:161], v[196:199], v[98:101]
	v_mfma_f32_16x16x32_bf16 v[86:89], v[150:153], v[208:211], v[86:89]
	v_mfma_f32_16x16x32_bf16 v[82:85], v[158:161], v[208:211], v[82:85]
	v_mfma_f32_16x16x32_bf16 v[70:73], v[150:153], v[216:219], v[70:73]
	v_mfma_f32_16x16x32_bf16 v[66:69], v[158:161], v[216:219], v[66:69]
	s_setprio 0
	s_barrier
	s_add_i32 s6, s63, s52
	v_lshl_add_u64 v[220:221], s[10:11], 0, v[164:165]
	s_mov_b32 m0, s6
	ds_read_b128 v[182:185], v206 offset:16384
	ds_read_b128 v[186:189], v206 offset:17408
	ds_read_b128 v[192:195], v206 offset:18432
	ds_read_b128 v[196:199], v206 offset:19456
	ds_read_b128 v[200:203], v206 offset:20480
	ds_read_b128 v[208:211], v206 offset:21504
	ds_read_b128 v[212:215], v206 offset:22528
	ds_read_b128 v[216:219], v206 offset:23552
	global_load_lds_dwordx4 v[220:221], off
	s_add_i32 m0, s6, 0x2000
	s_add_u32 s6, s10, 0xb0000
	v_lshl_add_u64 v[222:223], s[10:11], 0, v[168:169]
	s_addc_u32 s7, s11, 0
	s_add_i32 s15, s64, s52
	global_load_lds_dwordx4 v[222:223], off
	v_lshl_add_u64 v[224:225], s[6:7], 0, v[164:165]
	s_mov_b32 m0, s15
	v_lshl_add_u64 v[226:227], s[40:41], 0, v[166:167]
	global_load_lds_dwordx4 v[224:225], off
	v_lshl_add_u64 v[224:225], s[6:7], 0, v[168:169]
	s_add_i32 m0, s15, 0x2000
	s_nop 0
	global_load_lds_dwordx4 v[224:225], off
	v_lshl_add_u64 v[224:225], s[40:41], 0, v[162:163]
	s_mov_b32 m0, s53
	s_nop 0
	global_load_lds_dwordx4 v[224:225], off
	s_mov_b32 m0, s54
	s_nop 0
	global_load_lds_dwordx4 v[226:227], off
	s_waitcnt vmcnt(8)
	s_waitcnt lgkmcnt(0)
	s_barrier
	s_setprio 1
	s_waitcnt lgkmcnt(0)
	v_mfma_f32_16x16x32_bf16 v[62:65], v[130:133], v[182:185], 0
	v_mfma_f32_16x16x32_bf16 v[58:61], v[138:141], v[182:185], 0
	v_mfma_f32_16x16x32_bf16 v[46:49], v[130:133], v[192:195], 0
	v_mfma_f32_16x16x32_bf16 v[42:45], v[138:141], v[192:195], 0
	v_mfma_f32_16x16x32_bf16 v[30:33], v[130:133], v[200:203], 0
	v_mfma_f32_16x16x32_bf16 v[26:29], v[138:141], v[200:203], 0
	v_mfma_f32_16x16x32_bf16 v[14:17], v[130:133], v[212:215], 0
	v_mfma_f32_16x16x32_bf16 v[10:13], v[138:141], v[212:215], 0
	v_mfma_f32_16x16x32_bf16 v[62:65], v[134:137], v[186:189], v[62:65]
	v_mfma_f32_16x16x32_bf16 v[58:61], v[142:145], v[186:189], v[58:61]
	v_mfma_f32_16x16x32_bf16 v[46:49], v[134:137], v[196:199], v[46:49]
	v_mfma_f32_16x16x32_bf16 v[42:45], v[142:145], v[196:199], v[42:45]
	v_mfma_f32_16x16x32_bf16 v[30:33], v[134:137], v[208:211], v[30:33]
	v_mfma_f32_16x16x32_bf16 v[26:29], v[142:145], v[208:211], v[26:29]
	v_mfma_f32_16x16x32_bf16 v[14:17], v[134:137], v[216:219], v[14:17]
	v_mfma_f32_16x16x32_bf16 v[10:13], v[142:145], v[216:219], v[10:13]
	s_setprio 0
	s_setprio 1
	v_mfma_f32_16x16x32_bf16 v[54:57], v[146:149], v[182:185], 0
	v_mfma_f32_16x16x32_bf16 v[50:53], v[154:157], v[182:185], 0
	v_mfma_f32_16x16x32_bf16 v[38:41], v[146:149], v[192:195], 0
	v_mfma_f32_16x16x32_bf16 v[34:37], v[154:157], v[192:195], 0
	v_mfma_f32_16x16x32_bf16 v[22:25], v[146:149], v[200:203], 0
	v_mfma_f32_16x16x32_bf16 v[18:21], v[154:157], v[200:203], 0
	v_mfma_f32_16x16x32_bf16 v[6:9], v[146:149], v[212:215], 0
	v_mfma_f32_16x16x32_bf16 v[2:5], v[154:157], v[212:215], 0
	v_mfma_f32_16x16x32_bf16 v[54:57], v[150:153], v[186:189], v[54:57]
	v_mfma_f32_16x16x32_bf16 v[50:53], v[158:161], v[186:189], v[50:53]
	v_mfma_f32_16x16x32_bf16 v[38:41], v[150:153], v[196:199], v[38:41]
	v_mfma_f32_16x16x32_bf16 v[34:37], v[158:161], v[196:199], v[34:37]
	v_mfma_f32_16x16x32_bf16 v[22:25], v[150:153], v[208:211], v[22:25]
	v_mfma_f32_16x16x32_bf16 v[18:21], v[158:161], v[208:211], v[18:21]
	v_mfma_f32_16x16x32_bf16 v[6:9], v[150:153], v[216:219], v[6:9]
	v_mfma_f32_16x16x32_bf16 v[2:5], v[158:161], v[216:219], v[2:5]
	s_setprio 0
	s_barrier
; #define PG8_STAGE(bufoff, gbase, voff) do { _Pragma("unroll") for (int _i = 0; _i < 2; ++_i) \
;         __builtin_amdgcn_global_load_lds((const unsigned*)((const char*)(gbase) + (voff)[_i]), (PG8_LAS unsigned*)(lds + (bufoff) + ldsw + _i * 8192), 16, 0, 0); } while (0)
; #define PG8_LDA(dst, b, h) do { _Pragma("unroll") for (int m = 0; m < 4; ++m) _Pragma("unroll") for (int k = 0; k < 2; ++k) dst[m][k] = *(const PG8_LAS bf16x8*)(lds + PG8_SA(b, h) + aoff + m * 2048 + k * 1024); } while (0)
; #define PG8_LDB(dst, b, h) do { _Pragma("unroll") for (int n = 0; n < 2; ++n) _Pragma("unroll") for (int k = 0; k < 2; ++k) dst[n][k] = *(const PG8_LAS bf16x8*)(lds + PG8_SB(b, h) + boff + n * 2048 + k * 1024); } while (0)
; #define PG8_MMA(ai, bj, At, Bt) do { __builtin_amdgcn_s_setprio(1); _Pragma("unroll") for (int m = 0; m < 4; ++m) _Pragma("unroll") for (int n = 0; n < 2; ++n) _Pragma("unroll") for (int k = 0; k < 2; ++k) \
;         acc[ai][bj][m][n] = __builtin_amdgcn_mfma_f32_16x16x32_bf16(Bt[n][k], At[m][k], acc[ai][bj][m][n], 0, 0, 0); __builtin_amdgcn_s_setprio(0); } while (0)
; #define PG8_WAIT_V(n) asm volatile("s_waitcnt vmcnt(" #n ")" ::: "memory")
; #define PG8_WAIT_L(n) asm volatile("s_waitcnt lgkmcnt(" #n ")" ::: "memory")
; #define PG8_BAR __builtin_amdgcn_s_barrier()
; #define PG8_SCHED __builtin_amdgcn_sched_barrier(0)
; template <class Epi, class Sched, bool ALIGN_EPI = false, bool SP2 = false>
; __device__ __forceinline__ void gemm_phase(PG8_LAS unsigned char* lds, const Gemm g, const Sched& S, const Epi& E, const int tid) {
;     ...
;             PG8_LDB(B0, 1, 0); PG8_LDB(B1, 1, 1); PG8_SCHED; PG8_LDA(At, 1, 0); PG8_STAGE(PG8_SA(0, 1), a2 + hstep, voffA);
;             PG8_WAIT_V(8); PG8_WAIT_L(0); PG8_BAR; PG8_MMA(0, 0, At, B0); PG8_MMA(0, 1, At, B1); PG8_BAR; PG8_SCHED;
;             PG8_LDA(At, 1, 1); PG8_STAGE(PG8_SB(1, 0), b3, voffB); PG8_STAGE(PG8_SB(1, 1), b3 + hstep, voffB); PG8_STAGE(PG8_SA(1, 0), a3, voffA);
	s_add_i32 s15, 0, 0x18000
	s_add_i32 s18, 0, 0x1c000
	v_add_u32_e32 v142, s15, v191
	v_add_u32_e32 v158, s18, v191
	ds_read_b128 v[130:133], v142
	ds_read_b128 v[134:137], v142 offset:1024
	ds_read_b128 v[138:141], v142 offset:2048
	ds_read_b128 v[142:145], v142 offset:3072
	ds_read_b128 v[146:149], v158
	ds_read_b128 v[150:153], v158 offset:1024
	ds_read_b128 v[154:157], v158 offset:2048
	ds_read_b128 v[158:161], v158 offset:3072
	s_add_u32 s6, s40, 0xb0000
	s_addc_u32 s7, s41, 0
	s_mov_b32 m0, s55
	v_lshl_add_u64 v[228:229], s[6:7], 0, v[162:163]
	ds_read_b128 v[182:185], v206 offset:32768
	ds_read_b128 v[186:189], v206 offset:33792
	ds_read_b128 v[192:195], v206 offset:34816
	ds_read_b128 v[196:199], v206 offset:35840
	ds_read_b128 v[200:203], v206 offset:36864
	ds_read_b128 v[208:211], v206 offset:37888
	ds_read_b128 v[212:215], v206 offset:38912
	ds_read_b128 v[216:219], v206 offset:39936
	global_load_lds_dwordx4 v[228:229], off
	v_lshl_add_u64 v[228:229], s[6:7], 0, v[166:167]
	s_mov_b32 m0, s56
	s_nop 0
	global_load_lds_dwordx4 v[228:229], off
	s_waitcnt vmcnt(8)
	s_waitcnt lgkmcnt(0)
	s_barrier
	s_setprio 1
	s_waitcnt lgkmcnt(0)
	v_mfma_f32_16x16x32_bf16 v[126:129], v[130:133], v[182:185], v[126:129]
	v_mfma_f32_16x16x32_bf16 v[122:125], v[138:141], v[182:185], v[122:125]
	v_mfma_f32_16x16x32_bf16 v[110:113], v[130:133], v[192:195], v[110:113]
	v_mfma_f32_16x16x32_bf16 v[106:109], v[138:141], v[192:195], v[106:109]
	v_mfma_f32_16x16x32_bf16 v[94:97], v[130:133], v[200:203], v[94:97]
	v_mfma_f32_16x16x32_bf16 v[90:93], v[138:141], v[200:203], v[90:93]
	v_mfma_f32_16x16x32_bf16 v[78:81], v[130:133], v[212:215], v[78:81]
	v_mfma_f32_16x16x32_bf16 v[74:77], v[138:141], v[212:215], v[74:77]
	v_mfma_f32_16x16x32_bf16 v[126:129], v[134:137], v[186:189], v[126:129]
	v_mfma_f32_16x16x32_bf16 v[122:125], v[142:145], v[186:189], v[122:125]
	v_mfma_f32_16x16x32_bf16 v[110:113], v[134:137], v[196:199], v[110:113]
	v_mfma_f32_16x16x32_bf16 v[106:109], v[142:145], v[196:199], v[106:109]
	v_mfma_f32_16x16x32_bf16 v[94:97], v[134:137], v[208:211], v[94:97]
	v_mfma_f32_16x16x32_bf16 v[90:93], v[142:145], v[208:211], v[90:93]
	v_mfma_f32_16x16x32_bf16 v[78:81], v[134:137], v[216:219], v[78:81]
	v_mfma_f32_16x16x32_bf16 v[74:77], v[142:145], v[216:219], v[74:77]
	s_setprio 0
	s_setprio 1
	v_mfma_f32_16x16x32_bf16 v[118:121], v[146:149], v[182:185], v[118:121]
	v_mfma_f32_16x16x32_bf16 v[114:117], v[154:157], v[182:185], v[114:117]
	v_mfma_f32_16x16x32_bf16 v[102:105], v[146:149], v[192:195], v[102:105]
	v_mfma_f32_16x16x32_bf16 v[98:101], v[154:157], v[192:195], v[98:101]
	v_mfma_f32_16x16x32_bf16 v[86:89], v[146:149], v[200:203], v[86:89]
	v_mfma_f32_16x16x32_bf16 v[82:85], v[154:157], v[200:203], v[82:85]
	v_mfma_f32_16x16x32_bf16 v[70:73], v[146:149], v[212:215], v[70:73]
	v_mfma_f32_16x16x32_bf16 v[66:69], v[154:157], v[212:215], v[66:69]
	v_mfma_f32_16x16x32_bf16 v[118:121], v[150:153], v[186:189], v[118:121]
	v_mfma_f32_16x16x32_bf16 v[114:117], v[158:161], v[186:189], v[114:117]
	v_mfma_f32_16x16x32_bf16 v[102:105], v[150:153], v[196:199], v[102:105]
	v_mfma_f32_16x16x32_bf16 v[98:101], v[158:161], v[196:199], v[98:101]
	v_mfma_f32_16x16x32_bf16 v[86:89], v[150:153], v[208:211], v[86:89]
	v_mfma_f32_16x16x32_bf16 v[82:85], v[158:161], v[208:211], v[82:85]
	v_mfma_f32_16x16x32_bf16 v[70:73], v[150:153], v[216:219], v[70:73]
	v_mfma_f32_16x16x32_bf16 v[66:69], v[158:161], v[216:219], v[66:69]
	s_setprio 0
	s_barrier
	s_add_i32 s6, s15, s52
	v_lshl_add_u64 v[220:221], v[220:221], 0, s[34:35]
	s_mov_b32 m0, s6
	ds_read_b128 v[182:185], v206 offset:49152
	ds_read_b128 v[186:189], v206 offset:50176
	ds_read_b128 v[192:195], v206 offset:51200
	ds_read_b128 v[196:199], v206 offset:52224
	ds_read_b128 v[200:203], v206 offset:53248
	ds_read_b128 v[208:211], v206 offset:54272
	ds_read_b128 v[212:215], v206 offset:55296
	ds_read_b128 v[216:219], v206 offset:56320
	global_load_lds_dwordx4 v[220:221], off
	s_add_i32 m0, s6, 0x2000
	s_add_u32 s6, s10, 0xb0080
	v_lshl_add_u64 v[220:221], v[222:223], 0, s[34:35]
	s_addc_u32 s7, s11, 0
	s_add_i32 s10, s18, s52
	global_load_lds_dwordx4 v[220:221], off
	v_lshl_add_u64 v[220:221], s[6:7], 0, v[164:165]
	s_mov_b32 m0, s10
	s_nop 0
	global_load_lds_dwordx4 v[220:221], off
	v_lshl_add_u64 v[220:221], s[6:7], 0, v[168:169]
	s_add_i32 m0, s10, 0x2000
	s_nop 0
	global_load_lds_dwordx4 v[220:221], off
	v_lshl_add_u64 v[220:221], v[224:225], 0, s[34:35]
	s_mov_b32 m0, s58
	s_nop 0
	global_load_lds_dwordx4 v[220:221], off
	v_lshl_add_u64 v[220:221], v[226:227], 0, s[34:35]
	s_mov_b32 m0, s59
	s_nop 0
	global_load_lds_dwordx4 v[220:221], off
	s_waitcnt vmcnt(8)
	s_waitcnt lgkmcnt(0)
	s_barrier
; #define PG8_STAGE(bufoff, gbase, voff) do { _Pragma("unroll") for (int _i = 0; _i < 2; ++_i) \
;         __builtin_amdgcn_global_load_lds((const unsigned*)((const char*)(gbase) + (voff)[_i]), (PG8_LAS unsigned*)(lds + (bufoff) + ldsw + _i * 8192), 16, 0, 0); } while (0)
; #define PG8_LDA(dst, b, h) do { _Pragma("unroll") for (int m = 0; m < 4; ++m) _Pragma("unroll") for (int k = 0; k < 2; ++k) dst[m][k] = *(const PG8_LAS bf16x8*)(lds + PG8_SA(b, h) + aoff + m * 2048 + k * 1024); } while (0)
; #define PG8_LDB(dst, b, h) do { _Pragma("unroll") for (int n = 0; n < 2; ++n) _Pragma("unroll") for (int k = 0; k < 2; ++k) dst[n][k] = *(const PG8_LAS bf16x8*)(lds + PG8_SB(b, h) + boff + n * 2048 + k * 1024); } while (0)
; template <class Epi, class Sched, bool ALIGN_EPI = false, bool SP2 = false>
; __device__ __forceinline__ void gemm_phase(PG8_LAS unsigned char* lds, const Gemm g, const Sched& S, const Epi& E, const int tid) {
;     ...
;         for (int t = 0; t < nt; t += 2) {
;             const bool last = (t == nt - 2);
;             const char* a1 = cA + (size_t)(t + 1) * kstep;
;             const char* a2 = last ? nA : cA + (size_t)(t + 2) * kstep; const char* b2 = last ? nB : cB + (size_t)(t + 2) * kstep;
;             const char* a3 = a2 + kstep; const char* b3 = b2 + kstep;
;             if (last && has_next) S.a_ready(nxt);
;     ...
;             PG8_LDB(B0, 0, 0); PG8_LDB(B1, 0, 1); PG8_SCHED; PG8_LDA(At, 0, 0); PG8_STAGE(PG8_SA(1, 1), a1 + hstep, voffA);
;             PG8_WAIT_V(8); PG8_WAIT_L(0); PG8_BAR; PG8_MMA(0, 0, At, B0); PG8_MMA(0, 1, At, B1); PG8_BAR; PG8_SCHED;
;             PG8_LDA(At, 0, 1); PG8_STAGE(PG8_SB(0, 0), b2, voffB); PG8_STAGE(PG8_SB(0, 1), b2 + hstep, voffB); PG8_STAGE(PG8_SA(0, 0), a2, voffA);
;             PG8_WAIT_V(8); PG8_WAIT_L(0); PG8_BAR; PG8_MMA(1, 0, At, B0); PG8_MMA(1, 1, At, B1); PG8_BAR; PG8_SCHED;
;             PG8_LDB(B0, 1, 0); PG8_LDB(B1, 1, 1); PG8_SCHED; PG8_LDA(At, 1, 0); PG8_STAGE(PG8_SA(0, 1), a2 + hstep, voffA);
;             PG8_WAIT_V(8); PG8_WAIT_L(0); PG8_BAR; PG8_MMA(0, 0, At, B0); PG8_MMA(0, 1, At, B1); PG8_BAR; PG8_SCHED;
;             PG8_LDA(At, 1, 1); PG8_STAGE(PG8_SB(1, 0), b3, voffB); PG8_STAGE(PG8_SB(1, 1), b3 + hstep, voffB); PG8_STAGE(PG8_SA(1, 0), a3, voffA);
;             PG8_WAIT_V(8); PG8_WAIT_L(0); PG8_BAR; PG8_MMA(1, 0, At, B0); PG8_MMA(1, 1, At, B1); PG8_BAR; PG8_SCHED;
	s_setprio 1
	s_waitcnt lgkmcnt(0)
	v_mfma_f32_16x16x32_bf16 v[62:65], v[130:133], v[182:185], v[62:65]
	v_mfma_f32_16x16x32_bf16 v[58:61], v[138:141], v[182:185], v[58:61]
	v_mfma_f32_16x16x32_bf16 v[46:49], v[130:133], v[192:195], v[46:49]
	v_mfma_f32_16x16x32_bf16 v[42:45], v[138:141], v[192:195], v[42:45]
	v_mfma_f32_16x16x32_bf16 v[30:33], v[130:133], v[200:203], v[30:33]
	v_mfma_f32_16x16x32_bf16 v[26:29], v[138:141], v[200:203], v[26:29]
	v_mfma_f32_16x16x32_bf16 v[14:17], v[130:133], v[212:215], v[14:17]
	v_mfma_f32_16x16x32_bf16 v[10:13], v[138:141], v[212:215], v[10:13]
	v_mfma_f32_16x16x32_bf16 v[62:65], v[134:137], v[186:189], v[62:65]
	v_mfma_f32_16x16x32_bf16 v[58:61], v[142:145], v[186:189], v[58:61]
	v_mfma_f32_16x16x32_bf16 v[46:49], v[134:137], v[196:199], v[46:49]
	v_mfma_f32_16x16x32_bf16 v[42:45], v[142:145], v[196:199], v[42:45]
	v_mfma_f32_16x16x32_bf16 v[30:33], v[134:137], v[208:211], v[30:33]
	v_mfma_f32_16x16x32_bf16 v[26:29], v[142:145], v[208:211], v[26:29]
	v_mfma_f32_16x16x32_bf16 v[14:17], v[134:137], v[216:219], v[14:17]
	v_mfma_f32_16x16x32_bf16 v[10:13], v[142:145], v[216:219], v[10:13]
	s_setprio 0
	s_setprio 1
	v_mfma_f32_16x16x32_bf16 v[54:57], v[146:149], v[182:185], v[54:57]
	v_mfma_f32_16x16x32_bf16 v[50:53], v[154:157], v[182:185], v[50:53]
	v_mfma_f32_16x16x32_bf16 v[38:41], v[146:149], v[192:195], v[38:41]
	v_mfma_f32_16x16x32_bf16 v[34:37], v[154:157], v[192:195], v[34:37]
	v_mfma_f32_16x16x32_bf16 v[22:25], v[146:149], v[200:203], v[22:25]
	v_mfma_f32_16x16x32_bf16 v[18:21], v[154:157], v[200:203], v[18:21]
	v_mfma_f32_16x16x32_bf16 v[6:9], v[146:149], v[212:215], v[6:9]
	v_mfma_f32_16x16x32_bf16 v[2:5], v[154:157], v[212:215], v[2:5]
	v_mfma_f32_16x16x32_bf16 v[54:57], v[150:153], v[186:189], v[54:57]
	v_mfma_f32_16x16x32_bf16 v[50:53], v[158:161], v[186:189], v[50:53]
	v_mfma_f32_16x16x32_bf16 v[38:41], v[150:153], v[196:199], v[38:41]
	v_mfma_f32_16x16x32_bf16 v[34:37], v[158:161], v[196:199], v[34:37]
	v_mfma_f32_16x16x32_bf16 v[22:25], v[150:153], v[208:211], v[22:25]
	v_mfma_f32_16x16x32_bf16 v[18:21], v[158:161], v[208:211], v[18:21]
	v_mfma_f32_16x16x32_bf16 v[6:9], v[150:153], v[216:219], v[6:9]
	v_mfma_f32_16x16x32_bf16 v[2:5], v[158:161], v[216:219], v[2:5]
	s_setprio 0
	s_add_i32 s74, s74, 2
	s_add_u32 s43, s43, 0x100
	s_addc_u32 s45, s45, 0
	s_mov_b64 s[6:7], s[8:9]
	s_barrier
.LBB0_5220:
	ds_read_b128 v[130:133], v204
	ds_read_b128 v[134:137], v204 offset:1024
	ds_read_b128 v[138:141], v204 offset:2048
	ds_read_b128 v[142:145], v204 offset:3072
	ds_read_b128 v[146:149], v205
	ds_read_b128 v[150:153], v205 offset:1024
	ds_read_b128 v[154:157], v205 offset:2048
	ds_read_b128 v[158:161], v205 offset:3072
	s_add_u32 s8, s6, 0x100
	s_addc_u32 s9, s7, 0
	s_cmp_eq_u32 s74, 40
	s_cselect_b32 s41, s1, s9
	s_cselect_b32 s40, s0, s8
	s_cselect_b32 s11, s39, s45
	s_cselect_b32 s10, s38, s43
	v_lshl_add_u64 v[220:221], s[6:7], 0, v[176:177]
	s_add_i32 m0, s53, 0xc000
	ds_read_b128 v[182:185], v206
	ds_read_b128 v[186:189], v206 offset:1024
	ds_read_b128 v[192:195], v206 offset:2048
	ds_read_b128 v[196:199], v206 offset:3072
	ds_read_b128 v[200:203], v206 offset:4096
	ds_read_b128 v[208:211], v206 offset:5120
	ds_read_b128 v[212:215], v206 offset:6144
	ds_read_b128 v[216:219], v206 offset:7168
	global_load_lds_dwordx4 v[220:221], off
	v_lshl_add_u64 v[220:221], s[6:7], 0, v[174:175]
	s_add_i32 m0, s53, 0xe000
	s_nop 0
	global_load_lds_dwordx4 v[220:221], off
	s_waitcnt vmcnt(8)
	s_waitcnt lgkmcnt(0)
	s_barrier
	s_setprio 1
	s_waitcnt lgkmcnt(0)
	v_mfma_f32_16x16x32_bf16 v[126:129], v[130:133], v[182:185], v[126:129]
	v_mfma_f32_16x16x32_bf16 v[122:125], v[138:141], v[182:185], v[122:125]
	v_mfma_f32_16x16x32_bf16 v[110:113], v[130:133], v[192:195], v[110:113]
	v_mfma_f32_16x16x32_bf16 v[106:109], v[138:141], v[192:195], v[106:109]
	v_mfma_f32_16x16x32_bf16 v[94:97], v[130:133], v[200:203], v[94:97]
	v_mfma_f32_16x16x32_bf16 v[90:93], v[138:141], v[200:203], v[90:93]
	v_mfma_f32_16x16x32_bf16 v[78:81], v[130:133], v[212:215], v[78:81]
	v_mfma_f32_16x16x32_bf16 v[74:77], v[138:141], v[212:215], v[74:77]
	v_mfma_f32_16x16x32_bf16 v[126:129], v[134:137], v[186:189], v[126:129]
	v_mfma_f32_16x16x32_bf16 v[122:125], v[142:145], v[186:189], v[122:125]
	v_mfma_f32_16x16x32_bf16 v[110:113], v[134:137], v[196:199], v[110:113]
	v_mfma_f32_16x16x32_bf16 v[106:109], v[142:145], v[196:199], v[106:109]
	v_mfma_f32_16x16x32_bf16 v[94:97], v[134:137], v[208:211], v[94:97]
	v_mfma_f32_16x16x32_bf16 v[90:93], v[142:145], v[208:211], v[90:93]
	v_mfma_f32_16x16x32_bf16 v[78:81], v[134:137], v[216:219], v[78:81]
	v_mfma_f32_16x16x32_bf16 v[74:77], v[142:145], v[216:219], v[74:77]
	s_setprio 0
	s_setprio 1
	v_mfma_f32_16x16x32_bf16 v[118:121], v[146:149], v[182:185], v[118:121]
	v_mfma_f32_16x16x32_bf16 v[114:117], v[154:157], v[182:185], v[114:117]
	v_mfma_f32_16x16x32_bf16 v[102:105], v[146:149], v[192:195], v[102:105]
	v_mfma_f32_16x16x32_bf16 v[98:101], v[154:157], v[192:195], v[98:101]
	v_mfma_f32_16x16x32_bf16 v[86:89], v[146:149], v[200:203], v[86:89]
	v_mfma_f32_16x16x32_bf16 v[82:85], v[154:157], v[200:203], v[82:85]
	v_mfma_f32_16x16x32_bf16 v[70:73], v[146:149], v[212:215], v[70:73]
	v_mfma_f32_16x16x32_bf16 v[66:69], v[154:157], v[212:215], v[66:69]
	v_mfma_f32_16x16x32_bf16 v[118:121], v[150:153], v[186:189], v[118:121]
	v_mfma_f32_16x16x32_bf16 v[114:117], v[158:161], v[186:189], v[114:117]
	v_mfma_f32_16x16x32_bf16 v[102:105], v[150:153], v[196:199], v[102:105]
	v_mfma_f32_16x16x32_bf16 v[98:101], v[158:161], v[196:199], v[98:101]
	v_mfma_f32_16x16x32_bf16 v[86:89], v[150:153], v[208:211], v[86:89]
	v_mfma_f32_16x16x32_bf16 v[82:85], v[158:161], v[208:211], v[82:85]
	v_mfma_f32_16x16x32_bf16 v[70:73], v[150:153], v[216:219], v[70:73]
	v_mfma_f32_16x16x32_bf16 v[66:69], v[158:161], v[216:219], v[66:69]
	s_setprio 0
	s_barrier
; #define PG8_STAGE(bufoff, gbase, voff) do { _Pragma("unroll") for (int _i = 0; _i < 2; ++_i) \
;         __builtin_amdgcn_global_load_lds((const unsigned*)((const char*)(gbase) + (voff)[_i]), (PG8_LAS unsigned*)(lds + (bufoff) + ldsw + _i * 8192), 16, 0, 0); } while (0)
; #define PG8_LDA(dst, b, h) do { _Pragma("unroll") for (int m = 0; m < 4; ++m) _Pragma("unroll") for (int k = 0; k < 2; ++k) dst[m][k] = *(const PG8_LAS bf16x8*)(lds + PG8_SA(b, h) + aoff + m * 2048 + k * 1024); } while (0)
; #define PG8_LDB(dst, b, h) do { _Pragma("unroll") for (int n = 0; n < 2; ++n) _Pragma("unroll") for (int k = 0; k < 2; ++k) dst[n][k] = *(const PG8_LAS bf16x8*)(lds + PG8_SB(b, h) + boff + n * 2048 + k * 1024); } while (0)
; #define PG8_MMA(ai, bj, At, Bt) do { __builtin_amdgcn_s_setprio(1); _Pragma("unroll") for (int m = 0; m < 4; ++m) _Pragma("unroll") for (int n = 0; n < 2; ++n) _Pragma("unroll") for (int k = 0; k < 2; ++k) \
;         acc[ai][bj][m][n] = __builtin_amdgcn_mfma_f32_16x16x32_bf16(Bt[n][k], At[m][k], acc[ai][bj][m][n], 0, 0, 0); __builtin_amdgcn_s_setprio(0); } while (0)
; #define PG8_WAIT_V(n) asm volatile("s_waitcnt vmcnt(" #n ")" ::: "memory")
; #define PG8_WAIT_L(n) asm volatile("s_waitcnt lgkmcnt(" #n ")" ::: "memory")
; #define PG8_BAR __builtin_amdgcn_s_barrier()
; #define PG8_SCHED __builtin_amdgcn_sched_barrier(0)
; template <class Epi, class Sched, bool ALIGN_EPI = false, bool SP2 = false>
; __device__ __forceinline__ void gemm_phase(PG8_LAS unsigned char* lds, const Gemm g, const Sched& S, const Epi& E, const int tid) {
;     ...
;             PG8_LDA(At, 0, 1); PG8_STAGE(PG8_SB(0, 0), b2, voffB); PG8_STAGE(PG8_SB(0, 1), b2 + hstep, voffB); PG8_STAGE(PG8_SA(0, 0), a2, voffA);
;             PG8_WAIT_V(8); PG8_WAIT_L(0); PG8_BAR; PG8_MMA(1, 0, At, B0); PG8_MMA(1, 1, At, B1); PG8_BAR; PG8_SCHED;
;             PG8_LDB(B0, 1, 0); PG8_LDB(B1, 1, 1); PG8_SCHED; PG8_LDA(At, 1, 0); PG8_STAGE(PG8_SA(0, 1), a2 + hstep, voffA);
	s_add_i32 s6, s63, s52
	v_lshl_add_u64 v[220:221], s[10:11], 0, v[164:165]
	s_mov_b32 m0, s6
	ds_read_b128 v[182:185], v206 offset:16384
	ds_read_b128 v[186:189], v206 offset:17408
	ds_read_b128 v[192:195], v206 offset:18432
	ds_read_b128 v[196:199], v206 offset:19456
	ds_read_b128 v[200:203], v206 offset:20480
	ds_read_b128 v[208:211], v206 offset:21504
	ds_read_b128 v[212:215], v206 offset:22528
	ds_read_b128 v[216:219], v206 offset:23552
	global_load_lds_dwordx4 v[220:221], off
	s_add_i32 m0, s6, 0x2000
	s_add_u32 s6, s10, 0xb0000
	v_lshl_add_u64 v[222:223], s[10:11], 0, v[168:169]
	s_addc_u32 s7, s11, 0
	s_add_i32 s15, s64, s52
	global_load_lds_dwordx4 v[222:223], off
	v_lshl_add_u64 v[224:225], s[6:7], 0, v[164:165]
	s_mov_b32 m0, s15
	v_lshl_add_u64 v[226:227], s[40:41], 0, v[166:167]
	global_load_lds_dwordx4 v[224:225], off
	v_lshl_add_u64 v[224:225], s[6:7], 0, v[168:169]
	s_add_i32 m0, s15, 0x2000
	s_nop 0
	global_load_lds_dwordx4 v[224:225], off
	v_lshl_add_u64 v[224:225], s[40:41], 0, v[162:163]
	s_mov_b32 m0, s53
	s_nop 0
	global_load_lds_dwordx4 v[224:225], off
	s_mov_b32 m0, s54
	s_nop 0
	global_load_lds_dwordx4 v[226:227], off
	s_waitcnt vmcnt(8)
	s_waitcnt lgkmcnt(0)
	s_barrier
	s_setprio 1
	s_waitcnt lgkmcnt(0)
	v_mfma_f32_16x16x32_bf16 v[62:65], v[130:133], v[182:185], v[62:65]
	v_mfma_f32_16x16x32_bf16 v[58:61], v[138:141], v[182:185], v[58:61]
	v_mfma_f32_16x16x32_bf16 v[46:49], v[130:133], v[192:195], v[46:49]
	v_mfma_f32_16x16x32_bf16 v[42:45], v[138:141], v[192:195], v[42:45]
	v_mfma_f32_16x16x32_bf16 v[30:33], v[130:133], v[200:203], v[30:33]
	v_mfma_f32_16x16x32_bf16 v[26:29], v[138:141], v[200:203], v[26:29]
	v_mfma_f32_16x16x32_bf16 v[14:17], v[130:133], v[212:215], v[14:17]
	v_mfma_f32_16x16x32_bf16 v[10:13], v[138:141], v[212:215], v[10:13]
	v_mfma_f32_16x16x32_bf16 v[62:65], v[134:137], v[186:189], v[62:65]
	v_mfma_f32_16x16x32_bf16 v[58:61], v[142:145], v[186:189], v[58:61]
	v_mfma_f32_16x16x32_bf16 v[46:49], v[134:137], v[196:199], v[46:49]
	v_mfma_f32_16x16x32_bf16 v[42:45], v[142:145], v[196:199], v[42:45]
	v_mfma_f32_16x16x32_bf16 v[30:33], v[134:137], v[208:211], v[30:33]
	v_mfma_f32_16x16x32_bf16 v[26:29], v[142:145], v[208:211], v[26:29]
	v_mfma_f32_16x16x32_bf16 v[14:17], v[134:137], v[216:219], v[14:17]
	v_mfma_f32_16x16x32_bf16 v[10:13], v[142:145], v[216:219], v[10:13]
	s_setprio 0
	s_setprio 1
	v_mfma_f32_16x16x32_bf16 v[54:57], v[146:149], v[182:185], v[54:57]
	v_mfma_f32_16x16x32_bf16 v[50:53], v[154:157], v[182:185], v[50:53]
	v_mfma_f32_16x16x32_bf16 v[38:41], v[146:149], v[192:195], v[38:41]
	v_mfma_f32_16x16x32_bf16 v[34:37], v[154:157], v[192:195], v[34:37]
	v_mfma_f32_16x16x32_bf16 v[22:25], v[146:149], v[200:203], v[22:25]
	v_mfma_f32_16x16x32_bf16 v[18:21], v[154:157], v[200:203], v[18:21]
	v_mfma_f32_16x16x32_bf16 v[6:9], v[146:149], v[212:215], v[6:9]
	v_mfma_f32_16x16x32_bf16 v[2:5], v[154:157], v[212:215], v[2:5]
	v_mfma_f32_16x16x32_bf16 v[54:57], v[150:153], v[186:189], v[54:57]
	v_mfma_f32_16x16x32_bf16 v[50:53], v[158:161], v[186:189], v[50:53]
	v_mfma_f32_16x16x32_bf16 v[38:41], v[150:153], v[196:199], v[38:41]
	v_mfma_f32_16x16x32_bf16 v[34:37], v[158:161], v[196:199], v[34:37]
	v_mfma_f32_16x16x32_bf16 v[22:25], v[150:153], v[208:211], v[22:25]
	v_mfma_f32_16x16x32_bf16 v[18:21], v[158:161], v[208:211], v[18:21]
	v_mfma_f32_16x16x32_bf16 v[6:9], v[150:153], v[216:219], v[6:9]
	v_mfma_f32_16x16x32_bf16 v[2:5], v[158:161], v[216:219], v[2:5]
	s_setprio 0
	s_barrier
	s_add_i32 s15, 0, 0x18000
	s_add_i32 s18, 0, 0x1c000
	v_add_u32_e32 v142, s15, v191
	v_add_u32_e32 v158, s18, v191
	ds_read_b128 v[130:133], v142
	ds_read_b128 v[134:137], v142 offset:1024
	ds_read_b128 v[138:141], v142 offset:2048
	ds_read_b128 v[142:145], v142 offset:3072
	ds_read_b128 v[146:149], v158
	ds_read_b128 v[150:153], v158 offset:1024
	ds_read_b128 v[154:157], v158 offset:2048
	ds_read_b128 v[158:161], v158 offset:3072
	s_add_u32 s6, s40, 0xb0000
	s_addc_u32 s7, s41, 0
	s_mov_b32 m0, s55
	v_lshl_add_u64 v[228:229], s[6:7], 0, v[162:163]
	ds_read_b128 v[182:185], v206 offset:32768
	ds_read_b128 v[186:189], v206 offset:33792
	ds_read_b128 v[192:195], v206 offset:34816
	ds_read_b128 v[196:199], v206 offset:35840
	ds_read_b128 v[200:203], v206 offset:36864
	ds_read_b128 v[208:211], v206 offset:37888
	ds_read_b128 v[212:215], v206 offset:38912
	ds_read_b128 v[216:219], v206 offset:39936
	global_load_lds_dwordx4 v[228:229], off
	v_lshl_add_u64 v[228:229], s[6:7], 0, v[166:167]
	s_mov_b32 m0, s56
	s_nop 0
	global_load_lds_dwordx4 v[228:229], off
	s_waitcnt vmcnt(8)
	s_waitcnt lgkmcnt(0)
	s_barrier
; #define PG8_STAGE(bufoff, gbase, voff) do { _Pragma("unroll") for (int _i = 0; _i < 2; ++_i) \
;         __builtin_amdgcn_global_load_lds((const unsigned*)((const char*)(gbase) + (voff)[_i]), (PG8_LAS unsigned*)(lds + (bufoff) + ldsw + _i * 8192), 16, 0, 0); } while (0)
; #define PG8_LDA(dst, b, h) do { _Pragma("unroll") for (int m = 0; m < 4; ++m) _Pragma("unroll") for (int k = 0; k < 2; ++k) dst[m][k] = *(const PG8_LAS bf16x8*)(lds + PG8_SA(b, h) + aoff + m * 2048 + k * 1024); } while (0)
; #define PG8_MMA(ai, bj, At, Bt) do { __builtin_amdgcn_s_setprio(1); _Pragma("unroll") for (int m = 0; m < 4; ++m) _Pragma("unroll") for (int n = 0; n < 2; ++n) _Pragma("unroll") for (int k = 0; k < 2; ++k) \
;         acc[ai][bj][m][n] = __builtin_amdgcn_mfma_f32_16x16x32_bf16(Bt[n][k], At[m][k], acc[ai][bj][m][n], 0, 0, 0); __builtin_amdgcn_s_setprio(0); } while (0)
; #define PG8_WAIT_V(n) asm volatile("s_waitcnt vmcnt(" #n ")" ::: "memory")
; #define PG8_WAIT_L(n) asm volatile("s_waitcnt lgkmcnt(" #n ")" ::: "memory")
; #define PG8_BAR __builtin_amdgcn_s_barrier()
; #define PG8_SCHED __builtin_amdgcn_sched_barrier(0)
; template <class Epi, class Sched, bool ALIGN_EPI = false, bool SP2 = false>
; __device__ __forceinline__ void gemm_phase(PG8_LAS unsigned char* lds, const Gemm g, const Sched& S, const Epi& E, const int tid) {
;     ...
;         for (int t = 0; t < nt; t += 2) {
;     ...
;             PG8_WAIT_V(8); PG8_WAIT_L(0); PG8_BAR; PG8_MMA(0, 0, At, B0); PG8_MMA(0, 1, At, B1); PG8_BAR; PG8_SCHED;
;             PG8_LDA(At, 1, 1); PG8_STAGE(PG8_SB(1, 0), b3, voffB); PG8_STAGE(PG8_SB(1, 1), b3 + hstep, voffB); PG8_STAGE(PG8_SA(1, 0), a3, voffA);
;             PG8_WAIT_V(8); PG8_WAIT_L(0); PG8_BAR; PG8_MMA(1, 0, At, B0); PG8_MMA(1, 1, At, B1); PG8_BAR; PG8_SCHED;
	s_setprio 1
	s_waitcnt lgkmcnt(0)
	v_mfma_f32_16x16x32_bf16 v[126:129], v[130:133], v[182:185], v[126:129]
	v_mfma_f32_16x16x32_bf16 v[122:125], v[138:141], v[182:185], v[122:125]
	v_mfma_f32_16x16x32_bf16 v[110:113], v[130:133], v[192:195], v[110:113]
	v_mfma_f32_16x16x32_bf16 v[106:109], v[138:141], v[192:195], v[106:109]
	v_mfma_f32_16x16x32_bf16 v[94:97], v[130:133], v[200:203], v[94:97]
	v_mfma_f32_16x16x32_bf16 v[90:93], v[138:141], v[200:203], v[90:93]
	v_mfma_f32_16x16x32_bf16 v[78:81], v[130:133], v[212:215], v[78:81]
	v_mfma_f32_16x16x32_bf16 v[74:77], v[138:141], v[212:215], v[74:77]
	v_mfma_f32_16x16x32_bf16 v[126:129], v[134:137], v[186:189], v[126:129]
	v_mfma_f32_16x16x32_bf16 v[122:125], v[142:145], v[186:189], v[122:125]
	v_mfma_f32_16x16x32_bf16 v[110:113], v[134:137], v[196:199], v[110:113]
	v_mfma_f32_16x16x32_bf16 v[106:109], v[142:145], v[196:199], v[106:109]
	v_mfma_f32_16x16x32_bf16 v[94:97], v[134:137], v[208:211], v[94:97]
	v_mfma_f32_16x16x32_bf16 v[90:93], v[142:145], v[208:211], v[90:93]
	v_mfma_f32_16x16x32_bf16 v[78:81], v[134:137], v[216:219], v[78:81]
	v_mfma_f32_16x16x32_bf16 v[74:77], v[142:145], v[216:219], v[74:77]
	s_setprio 0
	s_setprio 1
	v_mfma_f32_16x16x32_bf16 v[118:121], v[146:149], v[182:185], v[118:121]
	v_mfma_f32_16x16x32_bf16 v[114:117], v[154:157], v[182:185], v[114:117]
	v_mfma_f32_16x16x32_bf16 v[102:105], v[146:149], v[192:195], v[102:105]
	v_mfma_f32_16x16x32_bf16 v[98:101], v[154:157], v[192:195], v[98:101]
	v_mfma_f32_16x16x32_bf16 v[86:89], v[146:149], v[200:203], v[86:89]
	v_mfma_f32_16x16x32_bf16 v[82:85], v[154:157], v[200:203], v[82:85]
	v_mfma_f32_16x16x32_bf16 v[70:73], v[146:149], v[212:215], v[70:73]
	v_mfma_f32_16x16x32_bf16 v[66:69], v[154:157], v[212:215], v[66:69]
	v_mfma_f32_16x16x32_bf16 v[118:121], v[150:153], v[186:189], v[118:121]
	v_mfma_f32_16x16x32_bf16 v[114:117], v[158:161], v[186:189], v[114:117]
	v_mfma_f32_16x16x32_bf16 v[102:105], v[150:153], v[196:199], v[102:105]
	v_mfma_f32_16x16x32_bf16 v[98:101], v[158:161], v[196:199], v[98:101]
	v_mfma_f32_16x16x32_bf16 v[86:89], v[150:153], v[208:211], v[86:89]
	v_mfma_f32_16x16x32_bf16 v[82:85], v[158:161], v[208:211], v[82:85]
	v_mfma_f32_16x16x32_bf16 v[70:73], v[150:153], v[216:219], v[70:73]
	v_mfma_f32_16x16x32_bf16 v[66:69], v[158:161], v[216:219], v[66:69]
	s_setprio 0
	s_barrier
	s_add_i32 s6, s15, s52
	v_lshl_add_u64 v[220:221], v[220:221], 0, s[34:35]
	s_mov_b32 m0, s6
	ds_read_b128 v[182:185], v206 offset:49152
	ds_read_b128 v[186:189], v206 offset:50176
	ds_read_b128 v[192:195], v206 offset:51200
	ds_read_b128 v[196:199], v206 offset:52224
	ds_read_b128 v[200:203], v206 offset:53248
	ds_read_b128 v[208:211], v206 offset:54272
	ds_read_b128 v[212:215], v206 offset:55296
	ds_read_b128 v[216:219], v206 offset:56320
	global_load_lds_dwordx4 v[220:221], off
	s_add_i32 m0, s6, 0x2000
	s_add_u32 s6, s10, 0xb0080
	v_lshl_add_u64 v[220:221], v[222:223], 0, s[34:35]
	s_addc_u32 s7, s11, 0
	s_add_i32 s10, s18, s52
	global_load_lds_dwordx4 v[220:221], off
	v_lshl_add_u64 v[220:221], s[6:7], 0, v[164:165]
	s_mov_b32 m0, s10
	s_nop 0
	global_load_lds_dwordx4 v[220:221], off
	v_lshl_add_u64 v[220:221], s[6:7], 0, v[168:169]
	s_add_i32 m0, s10, 0x2000
	s_nop 0
	global_load_lds_dwordx4 v[220:221], off
	v_lshl_add_u64 v[220:221], v[224:225], 0, s[34:35]
	s_mov_b32 m0, s58
	s_nop 0
	global_load_lds_dwordx4 v[220:221], off
	v_lshl_add_u64 v[220:221], v[226:227], 0, s[34:35]
	s_mov_b32 m0, s59
	s_nop 0
	global_load_lds_dwordx4 v[220:221], off
	s_waitcnt vmcnt(8)
	s_waitcnt lgkmcnt(0)
	s_barrier
	s_setprio 1
	s_waitcnt lgkmcnt(0)
	v_mfma_f32_16x16x32_bf16 v[62:65], v[130:133], v[182:185], v[62:65]
	v_mfma_f32_16x16x32_bf16 v[58:61], v[138:141], v[182:185], v[58:61]
	v_mfma_f32_16x16x32_bf16 v[46:49], v[130:133], v[192:195], v[46:49]
	v_mfma_f32_16x16x32_bf16 v[42:45], v[138:141], v[192:195], v[42:45]
	v_mfma_f32_16x16x32_bf16 v[30:33], v[130:133], v[200:203], v[30:33]
	v_mfma_f32_16x16x32_bf16 v[26:29], v[138:141], v[200:203], v[26:29]
	v_mfma_f32_16x16x32_bf16 v[14:17], v[130:133], v[212:215], v[14:17]
	v_mfma_f32_16x16x32_bf16 v[10:13], v[138:141], v[212:215], v[10:13]
	v_mfma_f32_16x16x32_bf16 v[62:65], v[134:137], v[186:189], v[62:65]
	v_mfma_f32_16x16x32_bf16 v[58:61], v[142:145], v[186:189], v[58:61]
	v_mfma_f32_16x16x32_bf16 v[46:49], v[134:137], v[196:199], v[46:49]
	v_mfma_f32_16x16x32_bf16 v[42:45], v[142:145], v[196:199], v[42:45]
	v_mfma_f32_16x16x32_bf16 v[30:33], v[134:137], v[208:211], v[30:33]
	v_mfma_f32_16x16x32_bf16 v[26:29], v[142:145], v[208:211], v[26:29]
	v_mfma_f32_16x16x32_bf16 v[14:17], v[134:137], v[216:219], v[14:17]
	v_mfma_f32_16x16x32_bf16 v[10:13], v[142:145], v[216:219], v[10:13]
	s_setprio 0
	s_setprio 1
	v_mfma_f32_16x16x32_bf16 v[54:57], v[146:149], v[182:185], v[54:57]
	v_mfma_f32_16x16x32_bf16 v[50:53], v[154:157], v[182:185], v[50:53]
	v_mfma_f32_16x16x32_bf16 v[38:41], v[146:149], v[192:195], v[38:41]
	v_mfma_f32_16x16x32_bf16 v[34:37], v[154:157], v[192:195], v[34:37]
	v_mfma_f32_16x16x32_bf16 v[22:25], v[146:149], v[200:203], v[22:25]
	v_mfma_f32_16x16x32_bf16 v[18:21], v[154:157], v[200:203], v[18:21]
	v_mfma_f32_16x16x32_bf16 v[6:9], v[146:149], v[212:215], v[6:9]
	v_mfma_f32_16x16x32_bf16 v[2:5], v[154:157], v[212:215], v[2:5]
	v_mfma_f32_16x16x32_bf16 v[54:57], v[150:153], v[186:189], v[54:57]
	v_mfma_f32_16x16x32_bf16 v[50:53], v[158:161], v[186:189], v[50:53]
	v_mfma_f32_16x16x32_bf16 v[38:41], v[150:153], v[196:199], v[38:41]
	v_mfma_f32_16x16x32_bf16 v[34:37], v[158:161], v[196:199], v[34:37]
	v_mfma_f32_16x16x32_bf16 v[22:25], v[150:153], v[208:211], v[22:25]
	v_mfma_f32_16x16x32_bf16 v[18:21], v[158:161], v[208:211], v[18:21]
	v_mfma_f32_16x16x32_bf16 v[6:9], v[150:153], v[216:219], v[6:9]
	v_mfma_f32_16x16x32_bf16 v[2:5], v[158:161], v[216:219], v[2:5]
	s_setprio 0
	s_add_i32 s74, s74, 2
	s_add_u32 s43, s43, 0x100
	s_addc_u32 s45, s45, 0
	s_cmp_gt_u32 s74, 41
	s_mov_b64 s[6:7], s[8:9]
	s_barrier
	s_cbranch_scc0 .LBB0_5220
	s_and_b64 vcc, exec, s[36:37]
	s_cbranch_vccz .LBB0_5223
	s_barrier

; #define PG8_STAGE(bufoff, gbase, voff) do { _Pragma("unroll") for (int _i = 0; _i < 2; ++_i) \
;         __builtin_amdgcn_global_load_lds((const unsigned*)((const char*)(gbase) + (voff)[_i]), (PG8_LAS unsigned*)(lds + (bufoff) + ldsw + _i * 8192), 16, 0, 0); } while (0)
; #define PG8_LDA(dst, b, h) do { _Pragma("unroll") for (int m = 0; m < 4; ++m) _Pragma("unroll") for (int k = 0; k < 2; ++k) dst[m][k] = *(const PG8_LAS bf16x8*)(lds + PG8_SA(b, h) + aoff + m * 2048 + k * 1024); } while (0)
; #define PG8_LDB(dst, b, h) do { _Pragma("unroll") for (int n = 0; n < 2; ++n) _Pragma("unroll") for (int k = 0; k < 2; ++k) dst[n][k] = *(const PG8_LAS bf16x8*)(lds + PG8_SB(b, h) + boff + n * 2048 + k * 1024); } while (0)
; #define PG8_MMA(ai, bj, At, Bt) do { __builtin_amdgcn_s_setprio(1); _Pragma("unroll") for (int m = 0; m < 4; ++m) _Pragma("unroll") for (int n = 0; n < 2; ++n) _Pragma("unroll") for (int k = 0; k < 2; ++k) \
;         acc[ai][bj][m][n] = __builtin_amdgcn_mfma_f32_16x16x32_bf16(Bt[n][k], At[m][k], acc[ai][bj][m][n], 0, 0, 0); __builtin_amdgcn_s_setprio(0); } while (0)
; #define PG8_WAIT_V(n) asm volatile("s_waitcnt vmcnt(" #n ")" ::: "memory")
; #define PG8_WAIT_L(n) asm volatile("s_waitcnt lgkmcnt(" #n ")" ::: "memory")
; template <class Epi, class Sched, bool ALIGN_EPI = false, bool SP2 = false>
; __device__ __forceinline__ void gemm_phase(PG8_LAS unsigned char* lds, const Gemm g, const Sched& S, const Epi& E, const int tid) {
;     ...
;             const bool last = (t == nt - 2);
;             const char* a1 = cA + (size_t)(t + 1) * kstep;
;             const char* a2 = last ? nA : cA + (size_t)(t + 2) * kstep; const char* b2 = last ? nB : cB + (size_t)(t + 2) * kstep;
;             const char* a3 = a2 + kstep; const char* b3 = b2 + kstep;
;             if (last && has_next) S.a_ready(nxt);
;             if constexpr (SP2) {
;             PG8_LDB(B0, 0, 0); PG8_LDB(B1, 0, 1); PG8_SCHED; PG8_LDA(At, 0, 0); PG8_STAGE(PG8_SA(1, 1), a1 + hstep, voffA);
;             PG8_WAIT_V(8); PG8_WAIT_L(0); PG8_BAR; PG8_MMA(0, 0, At, B0); PG8_MMA(0, 1, At, B1); PG8_BAR; PG8_SCHED;
;             PG8_LDA(At, 0, 1); PG8_STAGE(PG8_SB(0, 0), b2, voffB); PG8_STAGE(PG8_SB(0, 1), b2 + hstep, voffB); PG8_STAGE(PG8_SA(0, 0), a2, voffA);
;             PG8_WAIT_V(8); PG8_WAIT_L(0); PG8_BAR; PG8_MMA(1, 0, At, B0); PG8_MMA(1, 1, At, B1); PG8_BAR; PG8_SCHED;
.LBB0_5776:
	s_add_u32 s5, s54, 0x100
	s_addc_u32 s47, s55, 0
	s_add_u32 s54, s56, 0x40080
	s_addc_u32 s55, s57, 0
	s_mov_b32 s49, -2
	s_add_u32 s15, s54, 0xfffc0080
	s_addc_u32 s18, s55, -1
	s_cmp_eq_u32 s49, 12
	s_cselect_b32 s59, s1, s18
	s_cselect_b32 s58, s0, s15
	s_cselect_b32 s57, s51, s47
	s_cselect_b32 s56, s50, s5
	v_lshl_add_u64 v[168:169], s[54:55], 0, v[154:155]
	s_add_i32 m0, s64, 0xc000
	global_load_lds_dwordx4 v[168:169], off
	v_lshl_add_u64 v[168:169], s[54:55], 0, v[152:153]
	s_add_i32 m0, s64, 0xe000
	s_nop 0
	global_load_lds_dwordx4 v[168:169], off
	s_waitcnt vmcnt(8)
	s_waitcnt lgkmcnt(0)
	s_barrier
	s_setprio 1
	s_waitcnt lgkmcnt(0)
	v_mfma_f32_16x16x32_bf16 v[126:129], v[130:133], v[196:199], 0
	v_mfma_f32_16x16x32_bf16 v[122:125], v[160:163], v[196:199], 0
	v_mfma_f32_16x16x32_bf16 v[110:113], v[130:133], v[204:207], 0
	v_mfma_f32_16x16x32_bf16 v[106:109], v[160:163], v[204:207], 0
	v_mfma_f32_16x16x32_bf16 v[94:97], v[130:133], v[212:215], 0
	v_mfma_f32_16x16x32_bf16 v[90:93], v[160:163], v[212:215], 0
	v_mfma_f32_16x16x32_bf16 v[78:81], v[130:133], v[220:223], 0
	v_mfma_f32_16x16x32_bf16 v[74:77], v[160:163], v[220:223], 0
	v_mfma_f32_16x16x32_bf16 v[126:129], v[134:137], v[200:203], v[126:129]
	v_mfma_f32_16x16x32_bf16 v[122:125], v[164:167], v[200:203], v[122:125]
	v_mfma_f32_16x16x32_bf16 v[110:113], v[134:137], v[208:211], v[110:113]
	v_mfma_f32_16x16x32_bf16 v[106:109], v[164:167], v[208:211], v[106:109]
	v_mfma_f32_16x16x32_bf16 v[94:97], v[134:137], v[216:219], v[94:97]
	v_mfma_f32_16x16x32_bf16 v[90:93], v[164:167], v[216:219], v[90:93]
	v_mfma_f32_16x16x32_bf16 v[78:81], v[134:137], v[224:227], v[78:81]
	v_mfma_f32_16x16x32_bf16 v[74:77], v[164:167], v[224:227], v[74:77]
	s_setprio 0
	s_setprio 1
	v_mfma_f32_16x16x32_bf16 v[118:121], v[176:179], v[196:199], 0
	v_mfma_f32_16x16x32_bf16 v[114:117], v[184:187], v[196:199], 0
	v_mfma_f32_16x16x32_bf16 v[102:105], v[176:179], v[204:207], 0
	v_mfma_f32_16x16x32_bf16 v[98:101], v[184:187], v[204:207], 0
	v_mfma_f32_16x16x32_bf16 v[86:89], v[176:179], v[212:215], 0
	v_mfma_f32_16x16x32_bf16 v[82:85], v[184:187], v[212:215], 0
	v_mfma_f32_16x16x32_bf16 v[70:73], v[176:179], v[220:223], 0
	v_mfma_f32_16x16x32_bf16 v[66:69], v[184:187], v[220:223], 0
	v_mfma_f32_16x16x32_bf16 v[118:121], v[180:183], v[200:203], v[118:121]
	v_mfma_f32_16x16x32_bf16 v[114:117], v[192:195], v[200:203], v[114:117]
	v_mfma_f32_16x16x32_bf16 v[102:105], v[180:183], v[208:211], v[102:105]
	v_mfma_f32_16x16x32_bf16 v[98:101], v[192:195], v[208:211], v[98:101]
	v_mfma_f32_16x16x32_bf16 v[86:89], v[180:183], v[216:219], v[86:89]
	v_mfma_f32_16x16x32_bf16 v[82:85], v[192:195], v[216:219], v[82:85]
	v_mfma_f32_16x16x32_bf16 v[70:73], v[180:183], v[224:227], v[70:73]
	v_mfma_f32_16x16x32_bf16 v[66:69], v[192:195], v[224:227], v[66:69]
	s_setprio 0
	s_barrier
	s_add_i32 s15, s83, s63
	v_lshl_add_u64 v[168:169], s[56:57], 0, v[140:141]
	s_mov_b32 m0, s15
	ds_read_b128 v[196:199], v173 offset:16384
	ds_read_b128 v[200:203], v173 offset:17408
	ds_read_b128 v[204:207], v173 offset:18432
	ds_read_b128 v[208:211], v173 offset:19456
	ds_read_b128 v[212:215], v173 offset:20480
	ds_read_b128 v[216:219], v173 offset:21504
	ds_read_b128 v[220:223], v173 offset:22528
	ds_read_b128 v[224:227], v173 offset:23552
	global_load_lds_dwordx4 v[168:169], off
	s_add_i32 m0, s15, 0x2000
	s_add_u32 s18, s56, 0x40000
	v_lshl_add_u64 v[188:189], s[56:57], 0, v[144:145]
	s_addc_u32 s19, s57, 0
	s_add_i32 s15, s84, s63
	global_load_lds_dwordx4 v[188:189], off
	v_lshl_add_u64 v[228:229], s[18:19], 0, v[140:141]
	s_mov_b32 m0, s15
	v_lshl_add_u64 v[230:231], s[58:59], 0, v[142:143]
	global_load_lds_dwordx4 v[228:229], off
	v_lshl_add_u64 v[228:229], s[18:19], 0, v[144:145]
	s_add_i32 m0, s15, 0x2000
	s_nop 0
	global_load_lds_dwordx4 v[228:229], off
	v_lshl_add_u64 v[228:229], s[58:59], 0, v[138:139]
	s_mov_b32 m0, s64
	s_nop 0
	global_load_lds_dwordx4 v[228:229], off
	s_mov_b32 m0, s65
	s_nop 0
	global_load_lds_dwordx4 v[230:231], off
	s_waitcnt vmcnt(8)
	s_waitcnt lgkmcnt(0)
	s_barrier
	s_setprio 1
	s_waitcnt lgkmcnt(0)
	v_mfma_f32_16x16x32_bf16 v[62:65], v[130:133], v[196:199], 0
	v_mfma_f32_16x16x32_bf16 v[58:61], v[160:163], v[196:199], 0
	v_mfma_f32_16x16x32_bf16 v[46:49], v[130:133], v[204:207], 0
	v_mfma_f32_16x16x32_bf16 v[42:45], v[160:163], v[204:207], 0
	v_mfma_f32_16x16x32_bf16 v[30:33], v[130:133], v[212:215], 0
	v_mfma_f32_16x16x32_bf16 v[26:29], v[160:163], v[212:215], 0
	v_mfma_f32_16x16x32_bf16 v[14:17], v[130:133], v[220:223], 0
	v_mfma_f32_16x16x32_bf16 v[10:13], v[160:163], v[220:223], 0
	v_mfma_f32_16x16x32_bf16 v[62:65], v[134:137], v[200:203], v[62:65]
	v_mfma_f32_16x16x32_bf16 v[58:61], v[164:167], v[200:203], v[58:61]
	v_mfma_f32_16x16x32_bf16 v[46:49], v[134:137], v[208:211], v[46:49]
	v_mfma_f32_16x16x32_bf16 v[42:45], v[164:167], v[208:211], v[42:45]
	v_mfma_f32_16x16x32_bf16 v[30:33], v[134:137], v[216:219], v[30:33]
	v_mfma_f32_16x16x32_bf16 v[26:29], v[164:167], v[216:219], v[26:29]
	v_mfma_f32_16x16x32_bf16 v[14:17], v[134:137], v[224:227], v[14:17]
	v_mfma_f32_16x16x32_bf16 v[10:13], v[164:167], v[224:227], v[10:13]
	s_setprio 0
	s_setprio 1
	v_mfma_f32_16x16x32_bf16 v[54:57], v[176:179], v[196:199], 0
	v_mfma_f32_16x16x32_bf16 v[50:53], v[184:187], v[196:199], 0
	v_mfma_f32_16x16x32_bf16 v[38:41], v[176:179], v[204:207], 0
	v_mfma_f32_16x16x32_bf16 v[34:37], v[184:187], v[204:207], 0
	v_mfma_f32_16x16x32_bf16 v[22:25], v[176:179], v[212:215], 0
	v_mfma_f32_16x16x32_bf16 v[18:21], v[184:187], v[212:215], 0
	v_mfma_f32_16x16x32_bf16 v[6:9], v[176:179], v[220:223], 0
	v_mfma_f32_16x16x32_bf16 v[2:5], v[184:187], v[220:223], 0
	v_mfma_f32_16x16x32_bf16 v[54:57], v[180:183], v[200:203], v[54:57]
	v_mfma_f32_16x16x32_bf16 v[50:53], v[192:195], v[200:203], v[50:53]
	v_mfma_f32_16x16x32_bf16 v[38:41], v[180:183], v[208:211], v[38:41]
	v_mfma_f32_16x16x32_bf16 v[34:37], v[192:195], v[208:211], v[34:37]
	v_mfma_f32_16x16x32_bf16 v[22:25], v[180:183], v[216:219], v[22:25]
	v_mfma_f32_16x16x32_bf16 v[18:21], v[192:195], v[216:219], v[18:21]
	v_mfma_f32_16x16x32_bf16 v[6:9], v[180:183], v[224:227], v[6:9]
	v_mfma_f32_16x16x32_bf16 v[2:5], v[192:195], v[224:227], v[2:5]
	s_setprio 0
	s_barrier
; #define PG8_STAGE(bufoff, gbase, voff) do { _Pragma("unroll") for (int _i = 0; _i < 2; ++_i) \
;         __builtin_amdgcn_global_load_lds((const unsigned*)((const char*)(gbase) + (voff)[_i]), (PG8_LAS unsigned*)(lds + (bufoff) + ldsw + _i * 8192), 16, 0, 0); } while (0)
; #define PG8_LDA(dst, b, h) do { _Pragma("unroll") for (int m = 0; m < 4; ++m) _Pragma("unroll") for (int k = 0; k < 2; ++k) dst[m][k] = *(const PG8_LAS bf16x8*)(lds + PG8_SA(b, h) + aoff + m * 2048 + k * 1024); } while (0)
; #define PG8_LDB(dst, b, h) do { _Pragma("unroll") for (int n = 0; n < 2; ++n) _Pragma("unroll") for (int k = 0; k < 2; ++k) dst[n][k] = *(const PG8_LAS bf16x8*)(lds + PG8_SB(b, h) + boff + n * 2048 + k * 1024); } while (0)
; #define PG8_MMA(ai, bj, At, Bt) do { __builtin_amdgcn_s_setprio(1); _Pragma("unroll") for (int m = 0; m < 4; ++m) _Pragma("unroll") for (int n = 0; n < 2; ++n) _Pragma("unroll") for (int k = 0; k < 2; ++k) \
;         acc[ai][bj][m][n] = __builtin_amdgcn_mfma_f32_16x16x32_bf16(Bt[n][k], At[m][k], acc[ai][bj][m][n], 0, 0, 0); __builtin_amdgcn_s_setprio(0); } while (0)
; #define PG8_WAIT_V(n) asm volatile("s_waitcnt vmcnt(" #n ")" ::: "memory")
; #define PG8_WAIT_L(n) asm volatile("s_waitcnt lgkmcnt(" #n ")" ::: "memory")
; #define PG8_BAR __builtin_amdgcn_s_barrier()
; #define PG8_SCHED __builtin_amdgcn_sched_barrier(0)
; template <class Epi, class Sched, bool ALIGN_EPI = false, bool SP2 = false>
; __device__ __forceinline__ void gemm_phase(PG8_LAS unsigned char* lds, const Gemm g, const Sched& S, const Epi& E, const int tid) {
;     ...
;             PG8_LDB(B0, 1, 0); PG8_LDB(B1, 1, 1); PG8_SCHED; PG8_LDA(At, 1, 0); PG8_STAGE(PG8_SA(0, 1), a2 + hstep, voffA);
;             PG8_WAIT_V(8); PG8_WAIT_L(0); PG8_BAR; PG8_MMA(0, 0, At, B0); PG8_MMA(0, 1, At, B1); PG8_BAR; PG8_SCHED;
;             PG8_LDA(At, 1, 1); PG8_STAGE(PG8_SB(1, 0), b3, voffB); PG8_STAGE(PG8_SB(1, 1), b3 + hstep, voffB); PG8_STAGE(PG8_SA(1, 0), a3, voffA);
	s_add_i32 s15, 0, 0x18000
	s_add_i32 s60, 0, 0x1c000
	v_add_u32_e32 v164, s15, v170
	v_add_u32_e32 v175, s60, v170
	ds_read_b128 v[130:133], v164
	ds_read_b128 v[134:137], v164 offset:1024
	ds_read_b128 v[160:163], v164 offset:2048
	ds_read_b128 v[164:167], v164 offset:3072
	ds_read_b128 v[176:179], v175
	ds_read_b128 v[180:183], v175 offset:1024
	ds_read_b128 v[184:187], v175 offset:2048
	ds_read_b128 v[192:195], v175 offset:3072
	s_add_u32 s18, s58, 0x40000
	s_addc_u32 s19, s59, 0
	s_mov_b32 m0, s66
	v_lshl_add_u64 v[232:233], s[18:19], 0, v[138:139]
	ds_read_b128 v[196:199], v173 offset:32768
	ds_read_b128 v[200:203], v173 offset:33792
	ds_read_b128 v[204:207], v173 offset:34816
	ds_read_b128 v[208:211], v173 offset:35840
	ds_read_b128 v[212:215], v173 offset:36864
	ds_read_b128 v[216:219], v173 offset:37888
	ds_read_b128 v[220:223], v173 offset:38912
	ds_read_b128 v[224:227], v173 offset:39936
	global_load_lds_dwordx4 v[232:233], off
	v_lshl_add_u64 v[232:233], s[18:19], 0, v[142:143]
	s_mov_b32 m0, s67
	s_nop 0
	global_load_lds_dwordx4 v[232:233], off
	s_waitcnt vmcnt(8)
	s_waitcnt lgkmcnt(0)
	s_barrier
	s_setprio 1
	s_waitcnt lgkmcnt(0)
	v_mfma_f32_16x16x32_bf16 v[126:129], v[130:133], v[196:199], v[126:129]
	v_mfma_f32_16x16x32_bf16 v[122:125], v[160:163], v[196:199], v[122:125]
	v_mfma_f32_16x16x32_bf16 v[110:113], v[130:133], v[204:207], v[110:113]
	v_mfma_f32_16x16x32_bf16 v[106:109], v[160:163], v[204:207], v[106:109]
	v_mfma_f32_16x16x32_bf16 v[94:97], v[130:133], v[212:215], v[94:97]
	v_mfma_f32_16x16x32_bf16 v[90:93], v[160:163], v[212:215], v[90:93]
	v_mfma_f32_16x16x32_bf16 v[78:81], v[130:133], v[220:223], v[78:81]
	v_mfma_f32_16x16x32_bf16 v[74:77], v[160:163], v[220:223], v[74:77]
	v_mfma_f32_16x16x32_bf16 v[126:129], v[134:137], v[200:203], v[126:129]
	v_mfma_f32_16x16x32_bf16 v[122:125], v[164:167], v[200:203], v[122:125]
	v_mfma_f32_16x16x32_bf16 v[110:113], v[134:137], v[208:211], v[110:113]
	v_mfma_f32_16x16x32_bf16 v[106:109], v[164:167], v[208:211], v[106:109]
	v_mfma_f32_16x16x32_bf16 v[94:97], v[134:137], v[216:219], v[94:97]
	v_mfma_f32_16x16x32_bf16 v[90:93], v[164:167], v[216:219], v[90:93]
	v_mfma_f32_16x16x32_bf16 v[78:81], v[134:137], v[224:227], v[78:81]
	v_mfma_f32_16x16x32_bf16 v[74:77], v[164:167], v[224:227], v[74:77]
	s_setprio 0
	s_setprio 1
	v_mfma_f32_16x16x32_bf16 v[118:121], v[176:179], v[196:199], v[118:121]
	v_mfma_f32_16x16x32_bf16 v[114:117], v[184:187], v[196:199], v[114:117]
	v_mfma_f32_16x16x32_bf16 v[102:105], v[176:179], v[204:207], v[102:105]
	v_mfma_f32_16x16x32_bf16 v[98:101], v[184:187], v[204:207], v[98:101]
	v_mfma_f32_16x16x32_bf16 v[86:89], v[176:179], v[212:215], v[86:89]
	v_mfma_f32_16x16x32_bf16 v[82:85], v[184:187], v[212:215], v[82:85]
	v_mfma_f32_16x16x32_bf16 v[70:73], v[176:179], v[220:223], v[70:73]
	v_mfma_f32_16x16x32_bf16 v[66:69], v[184:187], v[220:223], v[66:69]
	v_mfma_f32_16x16x32_bf16 v[118:121], v[180:183], v[200:203], v[118:121]
	v_mfma_f32_16x16x32_bf16 v[114:117], v[192:195], v[200:203], v[114:117]
	v_mfma_f32_16x16x32_bf16 v[102:105], v[180:183], v[208:211], v[102:105]
	v_mfma_f32_16x16x32_bf16 v[98:101], v[192:195], v[208:211], v[98:101]
	v_mfma_f32_16x16x32_bf16 v[86:89], v[180:183], v[216:219], v[86:89]
	v_mfma_f32_16x16x32_bf16 v[82:85], v[192:195], v[216:219], v[82:85]
	v_mfma_f32_16x16x32_bf16 v[70:73], v[180:183], v[224:227], v[70:73]
	v_mfma_f32_16x16x32_bf16 v[66:69], v[192:195], v[224:227], v[66:69]
	s_setprio 0
	s_barrier
	s_add_i32 s15, s15, s63
	v_lshl_add_u64 v[168:169], v[168:169], 0, s[42:43]
	s_mov_b32 m0, s15
	ds_read_b128 v[196:199], v173 offset:49152
	ds_read_b128 v[200:203], v173 offset:50176
	ds_read_b128 v[204:207], v173 offset:51200
	ds_read_b128 v[208:211], v173 offset:52224
	ds_read_b128 v[212:215], v173 offset:53248
	ds_read_b128 v[216:219], v173 offset:54272
	ds_read_b128 v[220:223], v173 offset:55296
	ds_read_b128 v[224:227], v173 offset:56320
	global_load_lds_dwordx4 v[168:169], off
	s_add_i32 m0, s15, 0x2000
	s_add_u32 s18, s56, 0x40080
	v_lshl_add_u64 v[168:169], v[188:189], 0, s[42:43]
	s_addc_u32 s19, s57, 0
	s_add_i32 s15, s60, s63
	global_load_lds_dwordx4 v[168:169], off
	v_lshl_add_u64 v[168:169], s[18:19], 0, v[140:141]
	s_mov_b32 m0, s15
	s_nop 0
	global_load_lds_dwordx4 v[168:169], off
	v_lshl_add_u64 v[168:169], s[18:19], 0, v[144:145]
	s_add_i32 m0, s15, 0x2000
	s_nop 0
	global_load_lds_dwordx4 v[168:169], off
	v_lshl_add_u64 v[168:169], v[228:229], 0, s[42:43]
	s_mov_b32 m0, s74
	s_nop 0
	global_load_lds_dwordx4 v[168:169], off
	v_lshl_add_u64 v[168:169], v[230:231], 0, s[42:43]
	s_mov_b32 m0, s75
	s_nop 0
	global_load_lds_dwordx4 v[168:169], off
	s_waitcnt vmcnt(8)
	s_waitcnt lgkmcnt(0)
	s_barrier
; #define PG8_STAGE(bufoff, gbase, voff) do { _Pragma("unroll") for (int _i = 0; _i < 2; ++_i) \
;         __builtin_amdgcn_global_load_lds((const unsigned*)((const char*)(gbase) + (voff)[_i]), (PG8_LAS unsigned*)(lds + (bufoff) + ldsw + _i * 8192), 16, 0, 0); } while (0)
; #define PG8_LDA(dst, b, h) do { _Pragma("unroll") for (int m = 0; m < 4; ++m) _Pragma("unroll") for (int k = 0; k < 2; ++k) dst[m][k] = *(const PG8_LAS bf16x8*)(lds + PG8_SA(b, h) + aoff + m * 2048 + k * 1024); } while (0)
; #define PG8_LDB(dst, b, h) do { _Pragma("unroll") for (int n = 0; n < 2; ++n) _Pragma("unroll") for (int k = 0; k < 2; ++k) dst[n][k] = *(const PG8_LAS bf16x8*)(lds + PG8_SB(b, h) + boff + n * 2048 + k * 1024); } while (0)
; template <class Epi, class Sched, bool ALIGN_EPI = false, bool SP2 = false>
; __device__ __forceinline__ void gemm_phase(PG8_LAS unsigned char* lds, const Gemm g, const Sched& S, const Epi& E, const int tid) {
;     ...
;         for (int t = 0; t < nt; t += 2) {
;             const bool last = (t == nt - 2);
;             const char* a1 = cA + (size_t)(t + 1) * kstep;
;             const char* a2 = last ? nA : cA + (size_t)(t + 2) * kstep; const char* b2 = last ? nB : cB + (size_t)(t + 2) * kstep;
;             const char* a3 = a2 + kstep; const char* b3 = b2 + kstep;
;             if (last && has_next) S.a_ready(nxt);
;     ...
;             PG8_LDB(B0, 0, 0); PG8_LDB(B1, 0, 1); PG8_SCHED; PG8_LDA(At, 0, 0); PG8_STAGE(PG8_SA(1, 1), a1 + hstep, voffA);
;             PG8_WAIT_V(8); PG8_WAIT_L(0); PG8_BAR; PG8_MMA(0, 0, At, B0); PG8_MMA(0, 1, At, B1); PG8_BAR; PG8_SCHED;
;             PG8_LDA(At, 0, 1); PG8_STAGE(PG8_SB(0, 0), b2, voffB); PG8_STAGE(PG8_SB(0, 1), b2 + hstep, voffB); PG8_STAGE(PG8_SA(0, 0), a2, voffA);
;             PG8_WAIT_V(8); PG8_WAIT_L(0); PG8_BAR; PG8_MMA(1, 0, At, B0); PG8_MMA(1, 1, At, B1); PG8_BAR; PG8_SCHED;
;             PG8_LDB(B0, 1, 0); PG8_LDB(B1, 1, 1); PG8_SCHED; PG8_LDA(At, 1, 0); PG8_STAGE(PG8_SA(0, 1), a2 + hstep, voffA);
;             PG8_WAIT_V(8); PG8_WAIT_L(0); PG8_BAR; PG8_MMA(0, 0, At, B0); PG8_MMA(0, 1, At, B1); PG8_BAR; PG8_SCHED;
;             PG8_LDA(At, 1, 1); PG8_STAGE(PG8_SB(1, 0), b3, voffB); PG8_STAGE(PG8_SB(1, 1), b3 + hstep, voffB); PG8_STAGE(PG8_SA(1, 0), a3, voffA);
;             PG8_WAIT_V(8); PG8_WAIT_L(0); PG8_BAR; PG8_MMA(1, 0, At, B0); PG8_MMA(1, 1, At, B1); PG8_BAR; PG8_SCHED;
	s_setprio 1
	s_waitcnt lgkmcnt(0)
	v_mfma_f32_16x16x32_bf16 v[62:65], v[130:133], v[196:199], v[62:65]
	v_mfma_f32_16x16x32_bf16 v[58:61], v[160:163], v[196:199], v[58:61]
	v_mfma_f32_16x16x32_bf16 v[46:49], v[130:133], v[204:207], v[46:49]
	v_mfma_f32_16x16x32_bf16 v[42:45], v[160:163], v[204:207], v[42:45]
	v_mfma_f32_16x16x32_bf16 v[30:33], v[130:133], v[212:215], v[30:33]
	v_mfma_f32_16x16x32_bf16 v[26:29], v[160:163], v[212:215], v[26:29]
	v_mfma_f32_16x16x32_bf16 v[14:17], v[130:133], v[220:223], v[14:17]
	v_mfma_f32_16x16x32_bf16 v[10:13], v[160:163], v[220:223], v[10:13]
	v_mfma_f32_16x16x32_bf16 v[62:65], v[134:137], v[200:203], v[62:65]
	v_mfma_f32_16x16x32_bf16 v[58:61], v[164:167], v[200:203], v[58:61]
	v_mfma_f32_16x16x32_bf16 v[46:49], v[134:137], v[208:211], v[46:49]
	v_mfma_f32_16x16x32_bf16 v[42:45], v[164:167], v[208:211], v[42:45]
	v_mfma_f32_16x16x32_bf16 v[30:33], v[134:137], v[216:219], v[30:33]
	v_mfma_f32_16x16x32_bf16 v[26:29], v[164:167], v[216:219], v[26:29]
	v_mfma_f32_16x16x32_bf16 v[14:17], v[134:137], v[224:227], v[14:17]
	v_mfma_f32_16x16x32_bf16 v[10:13], v[164:167], v[224:227], v[10:13]
	s_setprio 0
	s_setprio 1
	v_mfma_f32_16x16x32_bf16 v[54:57], v[176:179], v[196:199], v[54:57]
	v_mfma_f32_16x16x32_bf16 v[50:53], v[184:187], v[196:199], v[50:53]
	v_mfma_f32_16x16x32_bf16 v[38:41], v[176:179], v[204:207], v[38:41]
	v_mfma_f32_16x16x32_bf16 v[34:37], v[184:187], v[204:207], v[34:37]
	v_mfma_f32_16x16x32_bf16 v[22:25], v[176:179], v[212:215], v[22:25]
	v_mfma_f32_16x16x32_bf16 v[18:21], v[184:187], v[212:215], v[18:21]
	v_mfma_f32_16x16x32_bf16 v[6:9], v[176:179], v[220:223], v[6:9]
	v_mfma_f32_16x16x32_bf16 v[2:5], v[184:187], v[220:223], v[2:5]
	v_mfma_f32_16x16x32_bf16 v[54:57], v[180:183], v[200:203], v[54:57]
	v_mfma_f32_16x16x32_bf16 v[50:53], v[192:195], v[200:203], v[50:53]
	v_mfma_f32_16x16x32_bf16 v[38:41], v[180:183], v[208:211], v[38:41]
	v_mfma_f32_16x16x32_bf16 v[34:37], v[192:195], v[208:211], v[34:37]
	v_mfma_f32_16x16x32_bf16 v[22:25], v[180:183], v[216:219], v[22:25]
	v_mfma_f32_16x16x32_bf16 v[18:21], v[192:195], v[216:219], v[18:21]
	v_mfma_f32_16x16x32_bf16 v[6:9], v[180:183], v[224:227], v[6:9]
	v_mfma_f32_16x16x32_bf16 v[2:5], v[192:195], v[224:227], v[2:5]
	s_setprio 0
	s_add_i32 s49, s49, 2
	s_add_u32 s5, s5, 0x100
	s_addc_u32 s47, s47, 0
	s_add_u32 s54, s54, 0x100
	s_addc_u32 s55, s55, 0
	s_barrier
.LBB0_5777:
	ds_read_b128 v[130:133], v171
	ds_read_b128 v[134:137], v171 offset:1024
	ds_read_b128 v[160:163], v171 offset:2048
	ds_read_b128 v[164:167], v171 offset:3072
	ds_read_b128 v[176:179], v172
	ds_read_b128 v[180:183], v172 offset:1024
	ds_read_b128 v[184:187], v172 offset:2048
	ds_read_b128 v[192:195], v172 offset:3072
	s_add_u32 s15, s54, 0xfffc0080
	s_addc_u32 s18, s55, -1
	s_cmp_eq_u32 s49, 12
	s_cselect_b32 s59, s1, s18
	s_cselect_b32 s58, s0, s15
	s_cselect_b32 s57, s51, s47
	s_cselect_b32 s56, s50, s5
	v_lshl_add_u64 v[168:169], s[54:55], 0, v[154:155]
	s_add_i32 m0, s64, 0xc000
	ds_read_b128 v[196:199], v173
	ds_read_b128 v[200:203], v173 offset:1024
	ds_read_b128 v[204:207], v173 offset:2048
	ds_read_b128 v[208:211], v173 offset:3072
	ds_read_b128 v[212:215], v173 offset:4096
	ds_read_b128 v[216:219], v173 offset:5120
	ds_read_b128 v[220:223], v173 offset:6144
	ds_read_b128 v[224:227], v173 offset:7168
	global_load_lds_dwordx4 v[168:169], off
	v_lshl_add_u64 v[168:169], s[54:55], 0, v[152:153]
	s_add_i32 m0, s64, 0xe000
	s_nop 0
	global_load_lds_dwordx4 v[168:169], off
	s_waitcnt vmcnt(8)
	s_waitcnt lgkmcnt(0)
	s_barrier
	s_setprio 1
	s_waitcnt lgkmcnt(0)
	v_mfma_f32_16x16x32_bf16 v[126:129], v[130:133], v[196:199], v[126:129]
	v_mfma_f32_16x16x32_bf16 v[122:125], v[160:163], v[196:199], v[122:125]
	v_mfma_f32_16x16x32_bf16 v[110:113], v[130:133], v[204:207], v[110:113]
	v_mfma_f32_16x16x32_bf16 v[106:109], v[160:163], v[204:207], v[106:109]
	v_mfma_f32_16x16x32_bf16 v[94:97], v[130:133], v[212:215], v[94:97]
	v_mfma_f32_16x16x32_bf16 v[90:93], v[160:163], v[212:215], v[90:93]
	v_mfma_f32_16x16x32_bf16 v[78:81], v[130:133], v[220:223], v[78:81]
	v_mfma_f32_16x16x32_bf16 v[74:77], v[160:163], v[220:223], v[74:77]
	v_mfma_f32_16x16x32_bf16 v[126:129], v[134:137], v[200:203], v[126:129]
	v_mfma_f32_16x16x32_bf16 v[122:125], v[164:167], v[200:203], v[122:125]
	v_mfma_f32_16x16x32_bf16 v[110:113], v[134:137], v[208:211], v[110:113]
	v_mfma_f32_16x16x32_bf16 v[106:109], v[164:167], v[208:211], v[106:109]
	v_mfma_f32_16x16x32_bf16 v[94:97], v[134:137], v[216:219], v[94:97]
	v_mfma_f32_16x16x32_bf16 v[90:93], v[164:167], v[216:219], v[90:93]
	v_mfma_f32_16x16x32_bf16 v[78:81], v[134:137], v[224:227], v[78:81]
	v_mfma_f32_16x16x32_bf16 v[74:77], v[164:167], v[224:227], v[74:77]
	s_setprio 0
	s_setprio 1
	v_mfma_f32_16x16x32_bf16 v[118:121], v[176:179], v[196:199], v[118:121]
	v_mfma_f32_16x16x32_bf16 v[114:117], v[184:187], v[196:199], v[114:117]
	v_mfma_f32_16x16x32_bf16 v[102:105], v[176:179], v[204:207], v[102:105]
	v_mfma_f32_16x16x32_bf16 v[98:101], v[184:187], v[204:207], v[98:101]
	v_mfma_f32_16x16x32_bf16 v[86:89], v[176:179], v[212:215], v[86:89]
	v_mfma_f32_16x16x32_bf16 v[82:85], v[184:187], v[212:215], v[82:85]
	v_mfma_f32_16x16x32_bf16 v[70:73], v[176:179], v[220:223], v[70:73]
	v_mfma_f32_16x16x32_bf16 v[66:69], v[184:187], v[220:223], v[66:69]
	v_mfma_f32_16x16x32_bf16 v[118:121], v[180:183], v[200:203], v[118:121]
	v_mfma_f32_16x16x32_bf16 v[114:117], v[192:195], v[200:203], v[114:117]
	v_mfma_f32_16x16x32_bf16 v[102:105], v[180:183], v[208:211], v[102:105]
	v_mfma_f32_16x16x32_bf16 v[98:101], v[192:195], v[208:211], v[98:101]
	v_mfma_f32_16x16x32_bf16 v[86:89], v[180:183], v[216:219], v[86:89]
	v_mfma_f32_16x16x32_bf16 v[82:85], v[192:195], v[216:219], v[82:85]
	v_mfma_f32_16x16x32_bf16 v[70:73], v[180:183], v[224:227], v[70:73]
	v_mfma_f32_16x16x32_bf16 v[66:69], v[192:195], v[224:227], v[66:69]
	s_setprio 0
	s_barrier
; #define PG8_STAGE(bufoff, gbase, voff) do { _Pragma("unroll") for (int _i = 0; _i < 2; ++_i) \
;         __builtin_amdgcn_global_load_lds((const unsigned*)((const char*)(gbase) + (voff)[_i]), (PG8_LAS unsigned*)(lds + (bufoff) + ldsw + _i * 8192), 16, 0, 0); } while (0)
; #define PG8_LDA(dst, b, h) do { _Pragma("unroll") for (int m = 0; m < 4; ++m) _Pragma("unroll") for (int k = 0; k < 2; ++k) dst[m][k] = *(const PG8_LAS bf16x8*)(lds + PG8_SA(b, h) + aoff + m * 2048 + k * 1024); } while (0)
; #define PG8_LDB(dst, b, h) do { _Pragma("unroll") for (int n = 0; n < 2; ++n) _Pragma("unroll") for (int k = 0; k < 2; ++k) dst[n][k] = *(const PG8_LAS bf16x8*)(lds + PG8_SB(b, h) + boff + n * 2048 + k * 1024); } while (0)
; #define PG8_MMA(ai, bj, At, Bt) do { __builtin_amdgcn_s_setprio(1); _Pragma("unroll") for (int m = 0; m < 4; ++m) _Pragma("unroll") for (int n = 0; n < 2; ++n) _Pragma("unroll") for (int k = 0; k < 2; ++k) \
;         acc[ai][bj][m][n] = __builtin_amdgcn_mfma_f32_16x16x32_bf16(Bt[n][k], At[m][k], acc[ai][bj][m][n], 0, 0, 0); __builtin_amdgcn_s_setprio(0); } while (0)
; #define PG8_WAIT_V(n) asm volatile("s_waitcnt vmcnt(" #n ")" ::: "memory")
; #define PG8_WAIT_L(n) asm volatile("s_waitcnt lgkmcnt(" #n ")" ::: "memory")
; #define PG8_BAR __builtin_amdgcn_s_barrier()
; #define PG8_SCHED __builtin_amdgcn_sched_barrier(0)
; template <class Epi, class Sched, bool ALIGN_EPI = false, bool SP2 = false>
; __device__ __forceinline__ void gemm_phase(PG8_LAS unsigned char* lds, const Gemm g, const Sched& S, const Epi& E, const int tid) {
;     ...
;             PG8_LDA(At, 0, 1); PG8_STAGE(PG8_SB(0, 0), b2, voffB); PG8_STAGE(PG8_SB(0, 1), b2 + hstep, voffB); PG8_STAGE(PG8_SA(0, 0), a2, voffA);
;             PG8_WAIT_V(8); PG8_WAIT_L(0); PG8_BAR; PG8_MMA(1, 0, At, B0); PG8_MMA(1, 1, At, B1); PG8_BAR; PG8_SCHED;
;             PG8_LDB(B0, 1, 0); PG8_LDB(B1, 1, 1); PG8_SCHED; PG8_LDA(At, 1, 0); PG8_STAGE(PG8_SA(0, 1), a2 + hstep, voffA);
	s_add_i32 s15, s83, s63
	v_lshl_add_u64 v[168:169], s[56:57], 0, v[140:141]
	s_mov_b32 m0, s15
	ds_read_b128 v[196:199], v173 offset:16384
	ds_read_b128 v[200:203], v173 offset:17408
	ds_read_b128 v[204:207], v173 offset:18432
	ds_read_b128 v[208:211], v173 offset:19456
	ds_read_b128 v[212:215], v173 offset:20480
	ds_read_b128 v[216:219], v173 offset:21504
	ds_read_b128 v[220:223], v173 offset:22528
	ds_read_b128 v[224:227], v173 offset:23552
	global_load_lds_dwordx4 v[168:169], off
	s_add_i32 m0, s15, 0x2000
	s_add_u32 s18, s56, 0x40000
	v_lshl_add_u64 v[188:189], s[56:57], 0, v[144:145]
	s_addc_u32 s19, s57, 0
	s_add_i32 s15, s84, s63
	global_load_lds_dwordx4 v[188:189], off
	v_lshl_add_u64 v[228:229], s[18:19], 0, v[140:141]
	s_mov_b32 m0, s15
	v_lshl_add_u64 v[230:231], s[58:59], 0, v[142:143]
	global_load_lds_dwordx4 v[228:229], off
	v_lshl_add_u64 v[228:229], s[18:19], 0, v[144:145]
	s_add_i32 m0, s15, 0x2000
	s_nop 0
	global_load_lds_dwordx4 v[228:229], off
	v_lshl_add_u64 v[228:229], s[58:59], 0, v[138:139]
	s_mov_b32 m0, s64
	s_nop 0
	global_load_lds_dwordx4 v[228:229], off
	s_mov_b32 m0, s65
	s_nop 0
	global_load_lds_dwordx4 v[230:231], off
	s_waitcnt vmcnt(8)
	s_waitcnt lgkmcnt(0)
	s_barrier
	s_setprio 1
	s_waitcnt lgkmcnt(0)
	v_mfma_f32_16x16x32_bf16 v[62:65], v[130:133], v[196:199], v[62:65]
	v_mfma_f32_16x16x32_bf16 v[58:61], v[160:163], v[196:199], v[58:61]
	v_mfma_f32_16x16x32_bf16 v[46:49], v[130:133], v[204:207], v[46:49]
	v_mfma_f32_16x16x32_bf16 v[42:45], v[160:163], v[204:207], v[42:45]
	v_mfma_f32_16x16x32_bf16 v[30:33], v[130:133], v[212:215], v[30:33]
	v_mfma_f32_16x16x32_bf16 v[26:29], v[160:163], v[212:215], v[26:29]
	v_mfma_f32_16x16x32_bf16 v[14:17], v[130:133], v[220:223], v[14:17]
	v_mfma_f32_16x16x32_bf16 v[10:13], v[160:163], v[220:223], v[10:13]
	v_mfma_f32_16x16x32_bf16 v[62:65], v[134:137], v[200:203], v[62:65]
	v_mfma_f32_16x16x32_bf16 v[58:61], v[164:167], v[200:203], v[58:61]
	v_mfma_f32_16x16x32_bf16 v[46:49], v[134:137], v[208:211], v[46:49]
	v_mfma_f32_16x16x32_bf16 v[42:45], v[164:167], v[208:211], v[42:45]
	v_mfma_f32_16x16x32_bf16 v[30:33], v[134:137], v[216:219], v[30:33]
	v_mfma_f32_16x16x32_bf16 v[26:29], v[164:167], v[216:219], v[26:29]
	v_mfma_f32_16x16x32_bf16 v[14:17], v[134:137], v[224:227], v[14:17]
	v_mfma_f32_16x16x32_bf16 v[10:13], v[164:167], v[224:227], v[10:13]
	s_setprio 0
	s_setprio 1
	v_mfma_f32_16x16x32_bf16 v[54:57], v[176:179], v[196:199], v[54:57]
	v_mfma_f32_16x16x32_bf16 v[50:53], v[184:187], v[196:199], v[50:53]
	v_mfma_f32_16x16x32_bf16 v[38:41], v[176:179], v[204:207], v[38:41]
	v_mfma_f32_16x16x32_bf16 v[34:37], v[184:187], v[204:207], v[34:37]
	v_mfma_f32_16x16x32_bf16 v[22:25], v[176:179], v[212:215], v[22:25]
	v_mfma_f32_16x16x32_bf16 v[18:21], v[184:187], v[212:215], v[18:21]
	v_mfma_f32_16x16x32_bf16 v[6:9], v[176:179], v[220:223], v[6:9]
	v_mfma_f32_16x16x32_bf16 v[2:5], v[184:187], v[220:223], v[2:5]
	v_mfma_f32_16x16x32_bf16 v[54:57], v[180:183], v[200:203], v[54:57]
	v_mfma_f32_16x16x32_bf16 v[50:53], v[192:195], v[200:203], v[50:53]
	v_mfma_f32_16x16x32_bf16 v[38:41], v[180:183], v[208:211], v[38:41]
	v_mfma_f32_16x16x32_bf16 v[34:37], v[192:195], v[208:211], v[34:37]
	v_mfma_f32_16x16x32_bf16 v[22:25], v[180:183], v[216:219], v[22:25]
	v_mfma_f32_16x16x32_bf16 v[18:21], v[192:195], v[216:219], v[18:21]
	v_mfma_f32_16x16x32_bf16 v[6:9], v[180:183], v[224:227], v[6:9]
	v_mfma_f32_16x16x32_bf16 v[2:5], v[192:195], v[224:227], v[2:5]
	s_setprio 0
	s_barrier
	s_add_i32 s15, 0, 0x18000
	s_add_i32 s60, 0, 0x1c000
	v_add_u32_e32 v164, s15, v170
	v_add_u32_e32 v175, s60, v170
	ds_read_b128 v[130:133], v164
	ds_read_b128 v[134:137], v164 offset:1024
	ds_read_b128 v[160:163], v164 offset:2048
	ds_read_b128 v[164:167], v164 offset:3072
	ds_read_b128 v[176:179], v175
	ds_read_b128 v[180:183], v175 offset:1024
	ds_read_b128 v[184:187], v175 offset:2048
	ds_read_b128 v[192:195], v175 offset:3072
	s_add_u32 s18, s58, 0x40000
	s_addc_u32 s19, s59, 0
	s_mov_b32 m0, s66
	v_lshl_add_u64 v[232:233], s[18:19], 0, v[138:139]
	ds_read_b128 v[196:199], v173 offset:32768
	ds_read_b128 v[200:203], v173 offset:33792
	ds_read_b128 v[204:207], v173 offset:34816
	ds_read_b128 v[208:211], v173 offset:35840
	ds_read_b128 v[212:215], v173 offset:36864
	ds_read_b128 v[216:219], v173 offset:37888
	ds_read_b128 v[220:223], v173 offset:38912
	ds_read_b128 v[224:227], v173 offset:39936
	global_load_lds_dwordx4 v[232:233], off
	v_lshl_add_u64 v[232:233], s[18:19], 0, v[142:143]
	s_mov_b32 m0, s67
	s_nop 0
	global_load_lds_dwordx4 v[232:233], off
	s_waitcnt vmcnt(8)
	s_waitcnt lgkmcnt(0)
	s_barrier
; #define PG8_STAGE(bufoff, gbase, voff) do { _Pragma("unroll") for (int _i = 0; _i < 2; ++_i) \
;         __builtin_amdgcn_global_load_lds((const unsigned*)((const char*)(gbase) + (voff)[_i]), (PG8_LAS unsigned*)(lds + (bufoff) + ldsw + _i * 8192), 16, 0, 0); } while (0)
; #define PG8_LDA(dst, b, h) do { _Pragma("unroll") for (int m = 0; m < 4; ++m) _Pragma("unroll") for (int k = 0; k < 2; ++k) dst[m][k] = *(const PG8_LAS bf16x8*)(lds + PG8_SA(b, h) + aoff + m * 2048 + k * 1024); } while (0)
; #define PG8_MMA(ai, bj, At, Bt) do { __builtin_amdgcn_s_setprio(1); _Pragma("unroll") for (int m = 0; m < 4; ++m) _Pragma("unroll") for (int n = 0; n < 2; ++n) _Pragma("unroll") for (int k = 0; k < 2; ++k) \
;         acc[ai][bj][m][n] = __builtin_amdgcn_mfma_f32_16x16x32_bf16(Bt[n][k], At[m][k], acc[ai][bj][m][n], 0, 0, 0); __builtin_amdgcn_s_setprio(0); } while (0)
; #define PG8_WAIT_V(n) asm volatile("s_waitcnt vmcnt(" #n ")" ::: "memory")
; #define PG8_WAIT_L(n) asm volatile("s_waitcnt lgkmcnt(" #n ")" ::: "memory")
; #define PG8_BAR __builtin_amdgcn_s_barrier()
; #define PG8_SCHED __builtin_amdgcn_sched_barrier(0)
; template <class Epi, class Sched, bool ALIGN_EPI = false, bool SP2 = false>
; __device__ __forceinline__ void gemm_phase(PG8_LAS unsigned char* lds, const Gemm g, const Sched& S, const Epi& E, const int tid) {
;     ...
;         for (int t = 0; t < nt; t += 2) {
;     ...
;             PG8_WAIT_V(8); PG8_WAIT_L(0); PG8_BAR; PG8_MMA(0, 0, At, B0); PG8_MMA(0, 1, At, B1); PG8_BAR; PG8_SCHED;
;             PG8_LDA(At, 1, 1); PG8_STAGE(PG8_SB(1, 0), b3, voffB); PG8_STAGE(PG8_SB(1, 1), b3 + hstep, voffB); PG8_STAGE(PG8_SA(1, 0), a3, voffA);
;             PG8_WAIT_V(8); PG8_WAIT_L(0); PG8_BAR; PG8_MMA(1, 0, At, B0); PG8_MMA(1, 1, At, B1); PG8_BAR; PG8_SCHED;
	s_setprio 1
	s_waitcnt lgkmcnt(0)
	v_mfma_f32_16x16x32_bf16 v[126:129], v[130:133], v[196:199], v[126:129]
	v_mfma_f32_16x16x32_bf16 v[122:125], v[160:163], v[196:199], v[122:125]
	v_mfma_f32_16x16x32_bf16 v[110:113], v[130:133], v[204:207], v[110:113]
	v_mfma_f32_16x16x32_bf16 v[106:109], v[160:163], v[204:207], v[106:109]
	v_mfma_f32_16x16x32_bf16 v[94:97], v[130:133], v[212:215], v[94:97]
	v_mfma_f32_16x16x32_bf16 v[90:93], v[160:163], v[212:215], v[90:93]
	v_mfma_f32_16x16x32_bf16 v[78:81], v[130:133], v[220:223], v[78:81]
	v_mfma_f32_16x16x32_bf16 v[74:77], v[160:163], v[220:223], v[74:77]
	v_mfma_f32_16x16x32_bf16 v[126:129], v[134:137], v[200:203], v[126:129]
	v_mfma_f32_16x16x32_bf16 v[122:125], v[164:167], v[200:203], v[122:125]
	v_mfma_f32_16x16x32_bf16 v[110:113], v[134:137], v[208:211], v[110:113]
	v_mfma_f32_16x16x32_bf16 v[106:109], v[164:167], v[208:211], v[106:109]
	v_mfma_f32_16x16x32_bf16 v[94:97], v[134:137], v[216:219], v[94:97]
	v_mfma_f32_16x16x32_bf16 v[90:93], v[164:167], v[216:219], v[90:93]
	v_mfma_f32_16x16x32_bf16 v[78:81], v[134:137], v[224:227], v[78:81]
	v_mfma_f32_16x16x32_bf16 v[74:77], v[164:167], v[224:227], v[74:77]
	s_setprio 0
	s_setprio 1
	v_mfma_f32_16x16x32_bf16 v[118:121], v[176:179], v[196:199], v[118:121]
	v_mfma_f32_16x16x32_bf16 v[114:117], v[184:187], v[196:199], v[114:117]
	v_mfma_f32_16x16x32_bf16 v[102:105], v[176:179], v[204:207], v[102:105]
	v_mfma_f32_16x16x32_bf16 v[98:101], v[184:187], v[204:207], v[98:101]
	v_mfma_f32_16x16x32_bf16 v[86:89], v[176:179], v[212:215], v[86:89]
	v_mfma_f32_16x16x32_bf16 v[82:85], v[184:187], v[212:215], v[82:85]
	v_mfma_f32_16x16x32_bf16 v[70:73], v[176:179], v[220:223], v[70:73]
	v_mfma_f32_16x16x32_bf16 v[66:69], v[184:187], v[220:223], v[66:69]
	v_mfma_f32_16x16x32_bf16 v[118:121], v[180:183], v[200:203], v[118:121]
	v_mfma_f32_16x16x32_bf16 v[114:117], v[192:195], v[200:203], v[114:117]
	v_mfma_f32_16x16x32_bf16 v[102:105], v[180:183], v[208:211], v[102:105]
	v_mfma_f32_16x16x32_bf16 v[98:101], v[192:195], v[208:211], v[98:101]
	v_mfma_f32_16x16x32_bf16 v[86:89], v[180:183], v[216:219], v[86:89]
	v_mfma_f32_16x16x32_bf16 v[82:85], v[192:195], v[216:219], v[82:85]
	v_mfma_f32_16x16x32_bf16 v[70:73], v[180:183], v[224:227], v[70:73]
	v_mfma_f32_16x16x32_bf16 v[66:69], v[192:195], v[224:227], v[66:69]
	s_setprio 0
	s_barrier
	s_add_i32 s15, s15, s63
	v_lshl_add_u64 v[168:169], v[168:169], 0, s[42:43]
	s_mov_b32 m0, s15
	ds_read_b128 v[196:199], v173 offset:49152
	ds_read_b128 v[200:203], v173 offset:50176
	ds_read_b128 v[204:207], v173 offset:51200
	ds_read_b128 v[208:211], v173 offset:52224
	ds_read_b128 v[212:215], v173 offset:53248
	ds_read_b128 v[216:219], v173 offset:54272
	ds_read_b128 v[220:223], v173 offset:55296
	ds_read_b128 v[224:227], v173 offset:56320
	global_load_lds_dwordx4 v[168:169], off
	s_add_i32 m0, s15, 0x2000
	s_add_u32 s18, s56, 0x40080
	v_lshl_add_u64 v[168:169], v[188:189], 0, s[42:43]
	s_addc_u32 s19, s57, 0
	s_add_i32 s15, s60, s63
	global_load_lds_dwordx4 v[168:169], off
	v_lshl_add_u64 v[168:169], s[18:19], 0, v[140:141]
	s_mov_b32 m0, s15
	s_nop 0
	global_load_lds_dwordx4 v[168:169], off
	v_lshl_add_u64 v[168:169], s[18:19], 0, v[144:145]
	s_add_i32 m0, s15, 0x2000
	s_nop 0
	global_load_lds_dwordx4 v[168:169], off
	v_lshl_add_u64 v[168:169], v[228:229], 0, s[42:43]
	s_mov_b32 m0, s74
	s_nop 0
	global_load_lds_dwordx4 v[168:169], off
	v_lshl_add_u64 v[168:169], v[230:231], 0, s[42:43]
	s_mov_b32 m0, s75
	s_nop 0
	global_load_lds_dwordx4 v[168:169], off
	s_waitcnt vmcnt(8)
	s_waitcnt lgkmcnt(0)
	s_barrier
	s_setprio 1
	s_waitcnt lgkmcnt(0)
	v_mfma_f32_16x16x32_bf16 v[62:65], v[130:133], v[196:199], v[62:65]
	v_mfma_f32_16x16x32_bf16 v[58:61], v[160:163], v[196:199], v[58:61]
	v_mfma_f32_16x16x32_bf16 v[46:49], v[130:133], v[204:207], v[46:49]
	v_mfma_f32_16x16x32_bf16 v[42:45], v[160:163], v[204:207], v[42:45]
	v_mfma_f32_16x16x32_bf16 v[30:33], v[130:133], v[212:215], v[30:33]
	v_mfma_f32_16x16x32_bf16 v[26:29], v[160:163], v[212:215], v[26:29]
	v_mfma_f32_16x16x32_bf16 v[14:17], v[130:133], v[220:223], v[14:17]
	v_mfma_f32_16x16x32_bf16 v[10:13], v[160:163], v[220:223], v[10:13]
	v_mfma_f32_16x16x32_bf16 v[62:65], v[134:137], v[200:203], v[62:65]
	v_mfma_f32_16x16x32_bf16 v[58:61], v[164:167], v[200:203], v[58:61]
	v_mfma_f32_16x16x32_bf16 v[46:49], v[134:137], v[208:211], v[46:49]
	v_mfma_f32_16x16x32_bf16 v[42:45], v[164:167], v[208:211], v[42:45]
	v_mfma_f32_16x16x32_bf16 v[30:33], v[134:137], v[216:219], v[30:33]
	v_mfma_f32_16x16x32_bf16 v[26:29], v[164:167], v[216:219], v[26:29]
	v_mfma_f32_16x16x32_bf16 v[14:17], v[134:137], v[224:227], v[14:17]
	v_mfma_f32_16x16x32_bf16 v[10:13], v[164:167], v[224:227], v[10:13]
	s_setprio 0
	s_setprio 1
	v_mfma_f32_16x16x32_bf16 v[54:57], v[176:179], v[196:199], v[54:57]
	v_mfma_f32_16x16x32_bf16 v[50:53], v[184:187], v[196:199], v[50:53]
	v_mfma_f32_16x16x32_bf16 v[38:41], v[176:179], v[204:207], v[38:41]
	v_mfma_f32_16x16x32_bf16 v[34:37], v[184:187], v[204:207], v[34:37]
	v_mfma_f32_16x16x32_bf16 v[22:25], v[176:179], v[212:215], v[22:25]
	v_mfma_f32_16x16x32_bf16 v[18:21], v[184:187], v[212:215], v[18:21]
	v_mfma_f32_16x16x32_bf16 v[6:9], v[176:179], v[220:223], v[6:9]
	v_mfma_f32_16x16x32_bf16 v[2:5], v[184:187], v[220:223], v[2:5]
	v_mfma_f32_16x16x32_bf16 v[54:57], v[180:183], v[200:203], v[54:57]
	v_mfma_f32_16x16x32_bf16 v[50:53], v[192:195], v[200:203], v[50:53]
	v_mfma_f32_16x16x32_bf16 v[38:41], v[180:183], v[208:211], v[38:41]
	v_mfma_f32_16x16x32_bf16 v[34:37], v[192:195], v[208:211], v[34:37]
	v_mfma_f32_16x16x32_bf16 v[22:25], v[180:183], v[216:219], v[22:25]
	v_mfma_f32_16x16x32_bf16 v[18:21], v[192:195], v[216:219], v[18:21]
	v_mfma_f32_16x16x32_bf16 v[6:9], v[180:183], v[224:227], v[6:9]
	v_mfma_f32_16x16x32_bf16 v[2:5], v[192:195], v[224:227], v[2:5]
	s_setprio 0
	s_add_i32 s49, s49, 2
	s_add_u32 s5, s5, 0x100
	s_addc_u32 s47, s47, 0
	s_add_u32 s54, s54, 0x100
	s_addc_u32 s55, s55, 0
	s_cmp_gt_u32 s49, 13
	s_barrier
	s_cbranch_scc0 .LBB0_5777
	s_and_b64 vcc, exec, s[44:45]
	s_cbranch_vccz .LBB0_5780
	s_barrier
